# FFT phase: sign-flip/copy shuffles (v_xor/v_mov) folded into op_sel/neg modifiers of the packed-f32 ops, dead copies dropped, wait states re-derived; also barrier set-up loads issued together
# speedup vs baseline: 1.2063x; 1.0211x over previous
.LBB0_29:
	global_load_dword v3, v177, s[94:95] sc1
	global_load_dword v0, v177, s[94:95] offset:256 sc1
	global_load_dword v1, v177, s[94:95] offset:512 sc1
	global_load_dword v2, v177, s[94:95] offset:768 sc1
	global_load_dword v4, v177, s[94:95] offset:1024 sc1
	global_load_dword v5, v177, s[94:95] offset:1280 sc1
	global_load_dword v6, v177, s[94:95] offset:1536 sc1
	global_load_dword v7, v177, s[94:95] offset:1792 sc1
	global_load_dword v8, v177, s[94:95] offset:2048 sc1
	global_load_dword v9, v177, s[94:95] offset:2304 sc1
	global_load_dword v10, v177, s[94:95] offset:2560 sc1
	global_load_dword v11, v177, s[94:95] offset:2816 sc1
	global_load_dword v12, v177, s[94:95] offset:3072 sc1
	global_load_dword v13, v177, s[94:95] offset:3328 sc1
	global_load_dword v14, v177, s[94:95] offset:3584 sc1
	global_load_dword v15, v177, s[94:95] offset:3840 sc1
	s_mov_b64 s[28:29], -1
	s_mov_b64 s[38:39], -1
	s_waitcnt vmcnt(0)
	v_add_u32_e32 v16, v0, v3
	v_add_u32_e32 v16, v16, v1
	v_add_u32_e32 v16, v16, v2
	v_add_u32_e32 v16, v16, v4
	v_add_u32_e32 v16, v16, v5
	v_add_u32_e32 v16, v16, v6
	v_add_u32_e32 v16, v16, v7
	v_add_u32_e32 v16, v16, v8
	v_add_u32_e32 v16, v16, v9
	v_add_u32_e32 v16, v16, v10
	v_add_u32_e32 v16, v16, v11
	v_add_u32_e32 v16, v16, v12
	v_add_u32_e32 v16, v16, v13
	v_add_u32_e32 v16, v16, v14
	v_add_u32_e32 v16, v16, v15
	v_cmp_eq_u32_e32 vcc, s2, v16
	s_cbranch_vccnz .LBB0_28
	s_and_b32 s6, s3, 0xff
	s_cmp_eq_u32 s6, 0
	s_mov_b64 s[40:41], -1
	s_sleep 1
	s_cbranch_scc1 .LBB0_33
	s_and_b64 vcc, exec, s[40:41]
	s_cbranch_vccz .LBB0_28

.LBB0_201:
	s_andn2_b64 vcc, exec, s[0:1]
	s_cbranch_vccnz .LBB0_278
	v_mov_b32_e32 v212, v179
	v_readlane_b32 s0, v254, 60
	v_readlane_b32 s2, v255, 4
	v_readlane_b32 s3, v255, 5
	s_waitcnt lgkmcnt(0)
	v_mov_b32_e32 v1, s0
	v_and_b32_e32 v206, 0xff, v179
	v_and_b32_e32 v0, 15, v179
	v_readlane_b32 s0, v255, 2
	v_cvt_f32_ubyte0_e32 v3, v206
	v_cvt_f32_ubyte0_e32 v2, v0
	s_mov_b32 s3, s0
	v_readlane_b32 s1, v255, 3
	v_writelane_b32 v255, s2, 4
	s_movk_i32 s0, 0x100
	s_nop 0
	v_pk_mul_f32 v[2:3], v[2:3], s[2:3]
	v_writelane_b32 v255, s3, 5
	v_pk_mul_f32 v[4:5], v[2:3], 0.5 op_sel_hi:[1,0]
	s_mov_b32 s2, 0x7f800000
	v_fract_f32_e32 v6, v5
	v_add_f32_e32 v6, v6, v6
	v_cmp_neq_f32_e32 vcc, s2, v5
	s_brev_b32 s3, 1
	s_nop 0
	v_cndmask_b32_e32 v5, 0, v6, vcc
	v_cmp_lt_f32_e32 vcc, 1.0, v3
	s_nop 1
	v_cndmask_b32_e32 v5, v3, v5, vcc
	v_add_f32_e32 v6, v5, v5
	v_rndne_f32_e32 v6, v6
	v_fmac_f32_e32 v5, -0.5, v6
	v_cvt_i32_f32_e32 v7, v6
	v_mul_f32_e32 v6, v5, v5
	s_waitcnt vmcnt(0)
	v_fmamk_f32 v8, v6, 0x3e75aa41, v180
	v_fmaak_f32 v8, v6, v8, 0x40234736
	v_fmaak_f32 v8, v6, v8, 0xc0a55e0e
	v_mul_f32_e32 v9, v5, v6
	v_mul_f32_e32 v8, v9, v8
	v_fmac_f32_e32 v8, 0x40490fdb, v5
	v_fmamk_f32 v5, v6, 0x3d4be544, v182
	v_fmaak_f32 v5, v6, v5, 0xbfaad1da
	v_fmaak_f32 v5, v6, v5, 0x4081e0d3
	v_fmaak_f32 v5, v6, v5, 0xc09de9e6
	v_cmp_gt_u32_e32 vcc, s0, v179
	v_fma_f32 v5, v6, v5, 1.0
	v_and_b32_e32 v6, 1, v7
	v_cndmask_b32_e64 v207, v1, 0, vcc
	v_and_b32_e32 v1, 2, v7
	v_cmp_eq_u32_e32 vcc, 0, v6
	v_cmp_eq_u32_e64 s[0:1], 0, v1
	s_nop 0
	v_cndmask_b32_e64 v6, -v8, v5, vcc
	v_cndmask_b32_e64 v1, -v6, v6, s[0:1]
	v_cmp_lg_f32_e64 s[0:1], s2, v3
	v_lshlrev_b32_e32 v3, 30, v7
	s_nop 0
	v_cndmask_b32_e64 v208, v226, v1, s[0:1]
	v_cndmask_b32_e32 v1, v5, v8, vcc
	v_fract_f32_e32 v5, v4
	v_add_f32_e32 v5, v5, v5
	v_cmp_neq_f32_e32 vcc, s2, v4
	v_bitop3_b32 v1, v3, v1, s3 bitop3:0x6c
	v_cndmask_b32_e64 v209, v227, -v1, s[0:1]
	v_cndmask_b32_e32 v4, 0, v5, vcc
	v_cmp_lt_f32_e32 vcc, 1.0, v2
	s_nop 1
	v_cndmask_b32_e32 v4, v2, v4, vcc
	v_add_f32_e32 v5, v4, v4
	v_rndne_f32_e32 v5, v5
	v_fmac_f32_e32 v4, -0.5, v5
	v_mul_f32_e32 v3, v4, v4
	v_cvt_i32_f32_e32 v6, v5
	v_fmamk_f32 v5, v3, 0x3e75aa41, v180
	v_fmaak_f32 v5, v3, v5, 0x40234736
	v_fmaak_f32 v5, v3, v5, 0xc0a55e0e
	v_mul_f32_e32 v7, v4, v3
	v_mul_f32_e32 v5, v7, v5
	v_fmac_f32_e32 v5, 0x40490fdb, v4
	v_fmamk_f32 v4, v3, 0x3d4be544, v182
	v_fmaak_f32 v4, v3, v4, 0xbfaad1da
	v_fmaak_f32 v4, v3, v4, 0x4081e0d3
	v_fmaak_f32 v4, v3, v4, 0xc09de9e6
	v_fma_f32 v3, v3, v4, 1.0
	v_and_b32_e32 v4, 1, v6
	v_and_b32_e32 v1, 2, v6
	v_cmp_eq_u32_e32 vcc, 0, v4
	v_cmp_eq_u32_e64 s[0:1], 0, v1
	s_nop 0
	v_cndmask_b32_e64 v4, -v5, v3, vcc
	v_cndmask_b32_e64 v1, -v4, v4, s[0:1]
	v_cmp_lg_f32_e64 s[0:1], s2, v2
	v_lshlrev_b32_e32 v2, 30, v6
	s_nop 0
	v_cndmask_b32_e64 v210, v226, v1, s[0:1]
	v_cndmask_b32_e32 v1, v3, v5, vcc
	v_bitop3_b32 v1, v2, v1, s3 bitop3:0x6c
	v_readlane_b32 s2, v253, 29
	v_readlane_b32 s3, v253, 30
	s_andn2_b64 vcc, exec, s[2:3]
	v_cndmask_b32_e64 v211, v227, -v1, s[0:1]
	s_cbranch_vccnz .LBB0_211
	v_cvt_f32_i32_e32 v1, v212
	s_mov_b32 s2, 0x7f800000
	v_readlane_b32 s6, v255, 4
	v_readlane_b32 s7, v255, 5
	v_mul_f32_e32 v2, 0x3b000000, v1
	v_mul_f32_e64 v1, |v2|, 0.5
	v_fract_f32_e32 v4, v1
	v_add_f32_e32 v4, v4, v4
	v_cmp_neq_f32_e32 vcc, s2, v1
	v_cmp_gt_f32_e64 s[0:1], |v2|, 1.0
	v_and_b32_e32 v3, 0x7fffffff, v2
	v_cndmask_b32_e32 v1, 0, v4, vcc
	v_cndmask_b32_e64 v1, |v2|, v1, s[0:1]
	v_add_f32_e32 v4, v1, v1
	v_rndne_f32_e32 v4, v4
	v_fmac_f32_e32 v1, -0.5, v4
	v_cvt_i32_f32_e32 v5, v4
	v_mul_f32_e32 v4, v1, v1
	v_fmamk_f32 v6, v4, 0x3e75aa41, v180
	v_fmaak_f32 v6, v4, v6, 0x40234736
	v_fmaak_f32 v6, v4, v6, 0xc0a55e0e
	v_mul_f32_e32 v8, v1, v4
	v_mul_f32_e32 v6, v8, v6
	v_fmac_f32_e32 v6, 0x40490fdb, v1
	v_fmamk_f32 v1, v4, 0x3d4be544, v182
	v_fmaak_f32 v1, v4, v1, 0xbfaad1da
	v_fmaak_f32 v1, v4, v1, 0x4081e0d3
	v_fmaak_f32 v1, v4, v1, 0xc09de9e6
	v_fma_f32 v1, v4, v1, 1.0
	v_and_b32_e32 v4, 1, v5
	v_and_b32_e32 v7, 2, v5
	v_cmp_eq_u32_e32 vcc, 0, v4
	v_cmp_eq_u32_e64 s[0:1], 0, v7
	s_brev_b32 s3, 1
	v_cndmask_b32_e64 v4, -v6, v1, vcc
	v_cndmask_b32_e64 v4, -v4, v4, s[0:1]
	s_movk_i32 s0, 0x1f8
	v_cmp_class_f32_e64 s[0:1], v2, s0
	s_mov_b32 s38, s96
	s_nop 0
	v_cndmask_b32_e64 v213, v226, v4, s[0:1]
	v_cndmask_b32_e32 v4, v1, v6, vcc
	v_lshrrev_b32_e32 v6, 4, v206
	v_lshlrev_b32_e32 v1, 30, v5
	v_mul_u32_u24_e32 v0, v6, v0
	v_and_b32_e32 v5, 0x80000000, v1
	v_cvt_f32_u32_e32 v1, v0
	v_xor_b32_e32 v0, v3, v2
	v_xor_b32_e32 v5, v0, v5
	v_cvt_f32_ubyte0_e32 v0, v6
	v_pk_mul_f32 v[0:1], v[0:1], s[6:7]
	v_xor_b32_e32 v4, v5, v4
	v_pk_mul_f32 v[2:3], v[0:1], 0.5 op_sel_hi:[1,0]
	v_cndmask_b32_e64 v214, v227, -v4, s[0:1]
	v_fract_f32_e32 v6, v3
	v_add_f32_e32 v6, v6, v6
	v_cmp_neq_f32_e32 vcc, s2, v3
	s_nop 1
	v_cndmask_b32_e32 v3, 0, v6, vcc
	v_cmp_lt_f32_e32 vcc, 1.0, v1
	s_nop 1
	v_cndmask_b32_e32 v3, v1, v3, vcc
	v_add_f32_e32 v6, v3, v3
	v_rndne_f32_e32 v6, v6
	v_fmac_f32_e32 v3, -0.5, v6
	v_mul_f32_e32 v5, v3, v3
	v_cvt_i32_f32_e32 v7, v6
	v_fmamk_f32 v6, v5, 0x3e75aa41, v180
	v_fmaak_f32 v6, v5, v6, 0x40234736
	v_fmaak_f32 v6, v5, v6, 0xc0a55e0e
	v_mul_f32_e32 v8, v3, v5
	v_mul_f32_e32 v6, v8, v6
	v_fmac_f32_e32 v6, 0x40490fdb, v3
	v_fmamk_f32 v3, v5, 0x3d4be544, v182
	v_fmaak_f32 v3, v5, v3, 0xbfaad1da
	v_fmaak_f32 v3, v5, v3, 0x4081e0d3
	v_fmaak_f32 v3, v5, v3, 0xc09de9e6
	v_fma_f32 v3, v5, v3, 1.0
	v_and_b32_e32 v5, 1, v7
	v_and_b32_e32 v4, 2, v7
	v_cmp_eq_u32_e32 vcc, 0, v5
	v_cmp_eq_u32_e64 s[0:1], 0, v4
	s_nop 0
	v_cndmask_b32_e64 v5, -v6, v3, vcc
	v_cndmask_b32_e64 v4, -v5, v5, s[0:1]
	v_cmp_lg_f32_e64 s[0:1], s2, v1
	v_cndmask_b32_e32 v1, v3, v6, vcc
	v_cmp_neq_f32_e32 vcc, s2, v2
	v_cndmask_b32_e64 v215, v226, v4, s[0:1]
	v_fract_f32_e32 v4, v2
	v_add_f32_e32 v4, v4, v4
	v_cndmask_b32_e32 v2, 0, v4, vcc
	v_cmp_lt_f32_e32 vcc, 1.0, v0
	v_lshlrev_b32_e32 v3, 30, v7
	v_bitop3_b32 v1, v3, v1, s3 bitop3:0x6c
	v_cndmask_b32_e32 v2, v0, v2, vcc
	v_add_f32_e32 v4, v2, v2
	v_rndne_f32_e32 v4, v4
	v_fmac_f32_e32 v2, -0.5, v4
	v_mul_f32_e32 v3, v2, v2
	v_cvt_i32_f32_e32 v5, v4
	v_fmamk_f32 v4, v3, 0x3e75aa41, v180
	v_fmaak_f32 v4, v3, v4, 0x40234736
	v_fmaak_f32 v4, v3, v4, 0xc0a55e0e
	v_mul_f32_e32 v6, v2, v3
	v_mul_f32_e32 v4, v6, v4
	v_fmac_f32_e32 v4, 0x40490fdb, v2
	v_fmamk_f32 v2, v3, 0x3d4be544, v182
	v_fmaak_f32 v2, v3, v2, 0xbfaad1da
	v_fmaak_f32 v2, v3, v2, 0x4081e0d3
	v_fmaak_f32 v2, v3, v2, 0xc09de9e6
	v_fma_f32 v2, v3, v2, 1.0
	v_and_b32_e32 v3, 1, v5
	v_cndmask_b32_e64 v216, v226, v1, s[0:1]
	v_and_b32_e32 v1, 2, v5
	v_cmp_eq_u32_e32 vcc, 0, v3
	v_cmp_eq_u32_e64 s[0:1], 0, v1
	s_nop 0
	v_cndmask_b32_e64 v3, -v4, v2, vcc
	v_cndmask_b32_e64 v1, -v3, v3, s[0:1]
	v_cmp_lg_f32_e64 s[0:1], s2, v0
	v_cndmask_b32_e32 v0, v2, v4, vcc
	s_nop 0
	v_cndmask_b32_e64 v217, v226, v1, s[0:1]
	v_lshlrev_b32_e32 v1, 30, v5
	v_bitop3_b32 v0, v1, v0, s3 bitop3:0x6c
	v_cndmask_b32_e64 v218, v226, v0, s[0:1]
.LBB0_204:
	s_ashr_i32 s39, s38, 31
	v_readlane_b32 s56, v252, 10
	s_lshl_b64 s[40:41], s[38:39], 2
	v_readlane_b32 s62, v252, 16
	v_readlane_b32 s63, v252, 17
	s_add_u32 s2, s62, s40
	s_addc_u32 s3, s63, s41
	s_add_i32 s28, s38, 0x600
	v_readlane_b32 s64, v252, 18
	s_ashr_i32 s29, s28, 31
	v_readlane_b32 s65, v252, 19
	s_add_u32 s6, s64, s40
	s_addc_u32 s7, s65, s41
	s_add_i32 s42, s38, 0x400
	s_add_i32 s0, s38, 0x200
	s_ashr_i32 s43, s42, 31
	s_waitcnt vmcnt(0)
	s_ashr_i32 s1, s0, 31
	global_load_dword v24, v177, s[2:3]
	global_load_dword v26, v197, s[2:3]
	global_load_dword v28, v177, s[6:7]
	global_load_dword v31, v177, s[2:3] offset:2048
	global_load_dword v30, v220, s[2:3]
	global_load_dword v33, v220, s[2:3] offset:2048
	global_load_dword v32, v221, s[2:3]
	global_load_dword v34, v197, s[2:3] offset:2048
	global_load_dword v36, v177, s[6:7] offset:2048
	global_load_dword v38, v183, s[2:3] offset:2048
	global_load_dword v219, v183, s[6:7]
	global_load_dword v41, v183, s[2:3]
	s_lshl_b64 s[2:3], s[42:43], 14
	s_add_u32 s2, s54, s2
	v_lshlrev_b32_e32 v1, 3, v212
	v_lshlrev_b32_e32 v0, 5, v212
	s_addc_u32 s3, s55, s3
	s_lshl_b64 s[6:7], s[28:29], 14
	v_and_b32_e32 v2, 0x3fe0, v0
	v_sub_u32_e32 v0, 0, v1
	s_add_u32 s6, s54, s6
	v_and_b32_e32 v0, 0xff8, v0
	s_addc_u32 s7, s55, s7
	v_lshlrev_b32_e32 v0, 2, v0
	global_load_dwordx4 v[44:47], v2, s[2:3]
	global_load_dword v27, v0, s[6:7]
	v_mov_b32_e32 v0, s7
	v_sub_co_u32_e32 v4, vcc, s6, v2
	s_mov_b64 s[20:21], 0x3fe0
	s_nop 0
	v_subbrev_co_u32_e32 v5, vcc, 0, v0, vcc
	v_lshl_add_u64 v[0:1], v[4:5], 0, s[20:21]
	global_load_dwordx4 v[48:51], v[0:1], off offset:16
	s_nop 0
	global_load_dwordx4 v[0:3], v2, s[2:3] offset:16
	s_lshl_b64 s[2:3], s[38:39], 14
	s_add_u32 s2, s54, s2
	s_addc_u32 s3, s55, s3
	s_lshl_b64 s[6:7], s[0:1], 14
	s_movk_i32 s9, 0x3000
	s_add_u32 s6, s54, s6
	v_add_co_u32_e32 v4, vcc, s9, v4
	s_addc_u32 s7, s55, s7
	s_nop 0
	v_addc_co_u32_e32 v5, vcc, 0, v5, vcc
	s_add_u32 s44, s82, s40
	global_load_dwordx4 v[4:7], v[4:5], off offset:4064
	v_mov_b32_e32 v43, v212
	s_addc_u32 s45, s83, s41
	global_load_dword v4, v177, s[44:45] offset:2048
	v_mov_b32_e32 v52, v213
	v_and_b32_e32 v42, 0x1ff, v212
	v_mov_b32_e32 v53, v214
	v_bfe_u32 v8, v212, 1, 8
	v_lshlrev_b32_e32 v14, 3, v42
	v_lshlrev_b32_e32 v12, 5, v42
	v_mov_b32_e32 v13, s7
	v_add_u32_e32 v29, v14, v8
	global_load_dwordx4 v[8:11], v12, s[2:3] offset:16
	global_load_dwordx4 v[20:23], v12, s[2:3]
	v_sub_co_u32_e32 v12, vcc, s6, v12
	v_sub_u32_e32 v14, 0, v14
	s_nop 0
	v_subbrev_co_u32_e32 v13, vcc, 0, v13, vcc
	v_lshl_add_u64 v[16:17], v[12:13], 0, s[20:21]
	v_add_co_u32_e32 v12, vcc, s9, v12
	v_and_b32_e32 v25, 0xff8, v14
	s_nop 0
	v_addc_co_u32_e32 v13, vcc, 0, v13, vcc
	global_load_dwordx4 v[12:15], v[12:13], off offset:4064
	s_nop 0
	global_load_dwordx4 v[16:19], v[16:17], off offset:16
	s_waitcnt vmcnt(0)
	v_lshlrev_b32_e32 v12, 2, v25
	global_load_dword v25, v12, s[6:7]
	v_cmp_eq_u32_e32 vcc, 0, v42
	s_mov_b32 s9, s30
	v_lshl_add_u32 v40, v29, 3, 0
	v_add_u32_e32 v29, 0x8800, v40
	v_readlane_b32 s57, v252, 11
	v_readlane_b32 s58, v252, 12
	v_readlane_b32 s59, v252, 13
	v_readlane_b32 s60, v252, 14
	v_readlane_b32 s61, v252, 15
	v_readlane_b32 s66, v252, 20
	v_readlane_b32 s67, v252, 21
	v_readlane_b32 s68, v252, 22
	v_readlane_b32 s69, v252, 23
	v_readlane_b32 s70, v252, 24
	v_readlane_b32 s71, v252, 25
	v_add_f32_e32 v12, v44, v44
	v_mul_f32_e32 v12, v12, v27
	v_add_f32_e32 v176, v44, v27
	v_sub_f32_e32 v35, v44, v27
	v_mul_f32_e32 v27, v27, v27
	v_cndmask_b32_e32 v12, 0, v12, vcc
	v_fmac_f32_e32 v27, v44, v44
	v_add_f32_e32 v27, v27, v12
	v_cndmask_b32_e32 v12, v35, v176, vcc
	v_mul_f32_e32 v35, v51, v51
	v_add_f32_e32 v44, v45, v51
	v_fmac_f32_e32 v35, v45, v45
	v_add_f32_e32 v27, v35, v27
	v_mul_f32_e32 v35, v49, v49
	v_fmac_f32_e32 v35, v47, v47
	v_pk_mul_f32 v[54:55], v[52:53], v[12:13] op_sel_hi:[1,0]
	v_pk_mul_f32 v[56:57], v[214:215], s[8:9] op_sel_hi:[0,1]
	v_pk_fma_f32 v[52:53], v[212:213], s[30:31], v[56:57] op_sel:[1,0,0]
	v_sub_f32_e32 v12, v45, v51
	v_mov_b32_e32 v45, v177
	ds_write2_b64 v40, v[176:177], v[44:45] offset1:1
	v_pk_mul_f32 v[44:45], v[12:13], v[52:53] op_sel_hi:[0,1]
	ds_write2_b64 v29, v[54:55], v[44:45] offset1:1
	v_pk_mul_f32 v[44:45], v[52:53], s[8:9] op_sel:[1,0]
	v_sub_f32_e32 v12, v46, v50
	v_pk_fma_f32 v[44:45], v[52:53], s[30:31], v[44:45] op_sel_hi:[0,1,1]
	v_mul_f32_e32 v29, v50, v50
	v_pk_mul_f32 v[52:53], v[44:45], s[8:9] op_sel:[1,0]
	v_add_f32_e32 v176, v46, v50
	v_fmac_f32_e32 v29, v46, v46
	v_pk_mul_f32 v[50:51], v[12:13], v[44:45] op_sel_hi:[0,1]
	v_pk_fma_f32 v[44:45], v[44:45], s[30:31], v[52:53] op_sel_hi:[0,1,1]
	v_add_f32_e32 v46, v47, v49
	v_sub_f32_e32 v12, v47, v49
	v_mov_b32_e32 v47, v177
	v_add_f32_e32 v27, v29, v27
	v_add_u32_e32 v29, 0x8810, v40
	ds_write2_b64 v40, v[176:177], v[46:47] offset0:2 offset1:3
	v_pk_mul_f32 v[46:47], v[12:13], v[44:45] op_sel_hi:[0,1]
	ds_write2_b64 v29, v[50:51], v[46:47] offset1:1
	v_pk_mul_f32 v[46:47], v[44:45], s[8:9] op_sel:[1,0]
	v_sub_f32_e32 v12, v0, v48
	v_pk_fma_f32 v[44:45], v[44:45], s[30:31], v[46:47] op_sel_hi:[0,1,1]
	v_mul_f32_e32 v29, v48, v48
	v_add_f32_e32 v27, v35, v27
	v_fmac_f32_e32 v29, v0, v0
	v_pk_mul_f32 v[46:47], v[12:13], v[44:45] op_sel_hi:[0,1]
	v_mul_f32_e32 v12, v7, v7
	v_add_f32_e32 v176, v0, v48
	v_add_f32_e32 v0, v29, v27
	v_fmac_f32_e32 v12, v1, v1
	v_add_f32_e32 v0, v12, v0
	v_mul_f32_e32 v12, v6, v6
	v_fmac_f32_e32 v12, v2, v2
	v_add_f32_e32 v0, v12, v0
	v_mul_f32_e32 v12, v5, v5
	v_fmac_f32_e32 v12, v3, v3
	v_add_f32_e32 v29, v12, v0
	v_and_b32_e32 v0, 64, v225
	v_add_u32_e32 v50, 64, v0
	v_xor_b32_e32 v0, 32, v225
	v_cmp_lt_i32_e32 vcc, v0, v50
	v_sub_f32_e32 v12, v1, v7
	v_pk_mul_f32 v[48:49], v[44:45], s[8:9] op_sel:[1,0]
	v_cndmask_b32_e32 v0, v225, v0, vcc
	v_lshlrev_b32_e32 v27, 2, v0
	ds_bpermute_b32 v37, v27, v29
	v_add_f32_e32 v0, v1, v7
	v_xor_b32_e32 v1, 16, v225
	v_cmp_lt_i32_e32 vcc, v1, v50
	v_pk_fma_f32 v[44:45], v[44:45], s[30:31], v[48:49] op_sel_hi:[0,1,1]
	s_waitcnt lgkmcnt(0)
	v_add_f32_e32 v7, v29, v37
	v_cndmask_b32_e32 v1, v225, v1, vcc
	v_lshlrev_b32_e32 v29, 2, v1
	ds_bpermute_b32 v37, v29, v7
	v_mov_b32_e32 v1, v177
	v_add_u32_e32 v35, 0x8820, v40
	ds_write2_b64 v40, v[176:177], v[0:1] offset0:4 offset1:5
	v_pk_mul_f32 v[0:1], v[12:13], v[44:45] op_sel_hi:[0,1]
	ds_write2_b64 v35, v[46:47], v[0:1] offset1:1
	v_xor_b32_e32 v0, 8, v225
	v_cmp_lt_i32_e32 vcc, v0, v50
	s_waitcnt lgkmcnt(2)
	v_add_f32_e32 v7, v7, v37
	v_add_f32_e32 v176, v2, v6
	v_cndmask_b32_e32 v0, v225, v0, vcc
	v_lshlrev_b32_e32 v35, 2, v0
	ds_bpermute_b32 v12, v35, v7
	v_sub_f32_e32 v2, v2, v6
	v_xor_b32_e32 v6, 4, v225
	v_cmp_lt_i32_e32 vcc, v6, v50
	v_pk_mul_f32 v[0:1], v[44:45], s[8:9] op_sel:[1,0]
	s_waitcnt lgkmcnt(0)
	v_add_f32_e32 v12, v7, v12
	v_cndmask_b32_e32 v6, v225, v6, vcc
	v_lshlrev_b32_e32 v37, 2, v6
	v_pk_fma_f32 v[0:1], v[44:45], s[30:31], v[0:1] op_sel_hi:[0,1,1]
	ds_bpermute_b32 v39, v37, v12
	v_pk_mul_f32 v[44:45], v[0:1], s[8:9] op_sel:[1,0]
	v_pk_mul_f32 v[6:7], v[2:3], v[0:1] op_sel_hi:[0,1]
	v_pk_fma_f32 v[44:45], v[0:1], s[30:31], v[44:45] op_sel_hi:[0,1,1]
	v_xor_b32_e32 v0, 2, v225
	v_cmp_lt_i32_e32 vcc, v0, v50
	s_waitcnt lgkmcnt(0)
	v_add_f32_e32 v12, v12, v39
	v_mov_b32_e32 v1, v177
	v_cndmask_b32_e32 v0, v225, v0, vcc
	v_lshlrev_b32_e32 v39, 2, v0
	ds_bpermute_b32 v47, v39, v12
	v_add_f32_e32 v0, v3, v5
	ds_write2_b64 v40, v[176:177], v[0:1] offset0:6 offset1:7
	v_xor_b32_e32 v1, 1, v225
	v_cmp_lt_i32_e32 vcc, v1, v50
	v_add_u32_e32 v46, 0x8830, v40
	s_waitcnt lgkmcnt(1)
	v_add_f32_e32 v0, v12, v47
	v_cndmask_b32_e32 v1, v225, v1, vcc
	v_lshlrev_b32_e32 v40, 2, v1
	ds_bpermute_b32 v1, v40, v0
	v_sub_f32_e32 v2, v3, v5
	v_pk_mul_f32 v[2:3], v[2:3], v[44:45] op_sel_hi:[0,1]
	ds_write2_b64 v46, v[6:7], v[2:3] offset1:1
	v_and_b32_e32 v2, 63, v212
	v_cmp_eq_u32_e32 vcc, 0, v2
	s_and_saveexec_b64 s[40:41], vcc
	s_cbranch_execz .LBB0_206
	v_lshrrev_b32_e32 v2, 4, v42
	v_add_u32_e32 v2, 0, v2
	v_add_u32_e32 v2, 0x11000, v2
	s_waitcnt lgkmcnt(1)
	v_add_f32_e32 v0, v0, v1
	ds_write_b32 v2, v0
.LBB0_206:
	s_or_b64 exec, exec, s[40:41]
	s_waitcnt lgkmcnt(1)
	s_lshl_b64 s[2:3], s[28:29], 16
	v_pk_mul_f32 v[2:3], v[208:209], v[208:209] op_sel:[1,1] op_sel_hi:[0,1] neg_lo:[1,0]
	v_readlane_b32 s6, v254, 43
	v_mov_b32_e32 v54, 1.0
	v_mov_b32_e32 v55, v177
	v_pk_fma_f32 v[2:3], v[208:209], v[208:209], v[2:3] op_sel_hi:[0,1,1]
	v_readlane_b32 s7, v254, 44
	s_add_u32 s40, s6, s2
	s_addc_u32 s41, s7, s3
	v_pk_mul_f32 v[44:45], v[2:3], v[2:3] op_sel:[1,1] op_sel_hi:[1,0] neg_lo:[0,1]
	v_pk_mul_f32 v[6:7], v[208:209], v[176:177] op_sel:[1,1] op_sel_hi:[0,1] neg_lo:[1,0]
	s_add_i32 s3, 0, 0x11000
	v_pk_fma_f32 v[44:45], v[2:3], v[2:3], v[44:45] op_sel_hi:[1,0,1]
	v_pk_fma_f32 v[70:71], v[208:209], v[54:55], v[6:7] op_sel_hi:[1,0,1]
	v_pk_mul_f32 v[0:1], v[176:177], v[2:3] op_sel:[1,1] op_sel_hi:[1,0] neg_lo:[0,1]
	v_mov_b32_e32 v5, s3
	v_pk_fma_f32 v[72:73], v[54:55], v[2:3], v[0:1] op_sel_hi:[0,1,1]
	v_pk_mul_f32 v[0:1], v[70:71], v[2:3] op_sel:[1,1] op_sel_hi:[1,0] neg_lo:[0,1]
	s_waitcnt lgkmcnt(0)
	s_barrier
	ds_read_b128 v[62:65], v5
	v_pk_fma_f32 v[60:61], v[2:3], v[70:71], v[0:1] op_sel_hi:[1,0,1]
	v_pk_mul_f32 v[0:1], v[176:177], v[44:45] op_sel:[1,1] op_sel_hi:[1,0] neg_lo:[0,1]
	s_nop 0
	v_pk_fma_f32 v[58:59], v[54:55], v[44:45], v[0:1] op_sel_hi:[0,1,1]
	v_pk_mul_f32 v[0:1], v[70:71], v[44:45] op_sel:[1,1] op_sel_hi:[1,0] neg_lo:[0,1]
	v_readlane_b32 s2, v254, 61
	v_pk_fma_f32 v[52:53], v[70:71], v[44:45], v[0:1] op_sel_hi:[0,1,1]
	v_pk_mul_f32 v[0:1], v[72:73], v[44:45] op_sel:[1,1] op_sel_hi:[1,0] neg_lo:[0,1]
	v_mov_b32_e32 v5, s2
	v_pk_mul_f32 v[50:51], v[44:45], v[44:45] op_sel:[1,1] op_sel_hi:[1,0] neg_lo:[0,1]
	v_pk_fma_f32 v[48:49], v[44:45], v[72:73], v[0:1] op_sel_hi:[1,0,1]
	v_pk_mul_f32 v[0:1], v[60:61], v[44:45] op_sel:[1,1] op_sel_hi:[1,0] neg_lo:[0,1]
	ds_read_b128 v[66:69], v5
	v_pk_fma_f32 v[42:43], v[44:45], v[60:61], v[0:1] op_sel_hi:[1,0,1]
	v_pk_fma_f32 v[0:1], v[44:45], v[44:45], v[50:51] op_sel_hi:[1,0,1]
	s_waitcnt lgkmcnt(1)
	v_add_f32_e32 v5, 0, v62
	v_add_f32_e32 v5, v5, v63
	v_pk_mul_f32 v[2:3], v[176:177], v[0:1] op_sel:[1,1] op_sel_hi:[1,0] neg_lo:[0,1]
	v_add_f32_e32 v5, v5, v64
	v_mov_b32_e32 v12, v206
	v_add_f32_e32 v5, v5, v65
	s_waitcnt lgkmcnt(0)
	v_add_f32_e32 v5, v5, v66
	v_lshlrev_b32_sdwa v64, v228, v12 dst_sel:DWORD dst_unused:UNUSED_PAD src0_sel:DWORD src1_sel:BYTE_0
	v_lshrrev_b32_e32 v12, 1, v206
	v_add_f32_e32 v5, v5, v67
	v_and_b32_e32 v12, 0x78, v12
	v_pk_fma_f32 v[44:45], v[54:55], v[0:1], v[2:3] op_sel_hi:[0,1,1]
	v_pk_mul_f32 v[46:47], v[70:71], v[0:1] op_sel:[1,1] op_sel_hi:[1,0] neg_lo:[0,1]
	v_pk_mul_f32 v[2:3], v[72:73], v[0:1] op_sel:[1,1] op_sel_hi:[1,0] neg_lo:[0,1]
	v_pk_mul_f32 v[50:51], v[60:61], v[0:1] op_sel:[1,1] op_sel_hi:[1,0] neg_lo:[0,1]
	v_pk_mul_f32 v[74:75], v[58:59], v[0:1] op_sel:[1,1] op_sel_hi:[1,0] neg_lo:[0,1]
	v_pk_mul_f32 v[76:77], v[52:53], v[0:1] op_sel:[1,1] op_sel_hi:[1,0] neg_lo:[0,1]
	v_pk_mul_f32 v[78:79], v[48:49], v[0:1] op_sel:[1,1] op_sel_hi:[1,0] neg_lo:[0,1]
	v_pk_mul_f32 v[80:81], v[42:43], v[0:1] op_sel:[1,1] op_sel_hi:[1,0] neg_lo:[0,1]
	v_add_f32_e32 v5, v5, v68
	v_add3_u32 v12, v207, v64, v12
	v_pk_fma_f32 v[2:3], v[72:73], v[0:1], v[2:3] op_sel_hi:[0,1,1]
	v_add_f32_e32 v5, v5, v69
	v_pk_fma_f32 v[62:63], v[70:71], v[0:1], v[46:47] op_sel_hi:[0,1,1]
	v_pk_fma_f32 v[56:57], v[60:61], v[0:1], v[50:51] op_sel_hi:[0,1,1]
	v_pk_fma_f32 v[50:51], v[0:1], v[58:59], v[74:75] op_sel_hi:[1,0,1]
	v_pk_fma_f32 v[46:47], v[0:1], v[52:53], v[76:77] op_sel_hi:[1,0,1]
	v_pk_fma_f32 v[6:7], v[0:1], v[48:49], v[78:79] op_sel_hi:[1,0,1]
	v_pk_fma_f32 v[0:1], v[0:1], v[42:43], v[80:81] op_sel_hi:[1,0,1]
	ds_read_b64 v[64:65], v12
	ds_read_b64 v[66:67], v12 offset:2176
	ds_read_b64 v[68:69], v12 offset:4352
	ds_read_b64 v[74:75], v12 offset:6528
	ds_read_b64 v[76:77], v12 offset:8704
	ds_read_b64 v[78:79], v12 offset:10880
	ds_read_b64 v[80:81], v12 offset:13056
	ds_read_b64 v[82:83], v12 offset:15232
	ds_read_b64 v[84:85], v12 offset:17408
	ds_read_b64 v[86:87], v12 offset:19584
	ds_read_b64 v[88:89], v12 offset:21760
	ds_read_b64 v[90:91], v12 offset:23936
	ds_read_b64 v[92:93], v12 offset:26112
	ds_read_b64 v[94:95], v12 offset:28288
	ds_read_b64 v[96:97], v12 offset:30464
	ds_read_b64 v[98:99], v12 offset:32640
	s_waitcnt lgkmcnt(7)
	v_pk_add_f32 v[100:101], v[64:65], v[84:85]
	v_pk_add_f32 v[64:65], v[64:65], v[84:85] neg_lo:[0,1] neg_hi:[0,1]
	s_waitcnt lgkmcnt(3)
	v_pk_add_f32 v[84:85], v[76:77], v[92:93]
	v_pk_add_f32 v[76:77], v[76:77], v[92:93] neg_lo:[0,1] neg_hi:[0,1]
	s_nop 0
	v_pk_add_f32 v[102:103], v[64:65], v[76:77] op_sel:[0,1] op_sel_hi:[1,0] neg_hi:[0,1]
	v_pk_add_f32 v[64:65], v[64:65], v[76:77] op_sel:[0,1] op_sel_hi:[1,0] neg_lo:[0,1]
	v_pk_add_f32 v[92:93], v[66:67], v[86:87]
	v_pk_add_f32 v[66:67], v[66:67], v[86:87] neg_lo:[0,1] neg_hi:[0,1]
	s_waitcnt lgkmcnt(2)
	v_pk_add_f32 v[86:87], v[78:79], v[94:95]
	v_pk_add_f32 v[78:79], v[78:79], v[94:95] neg_lo:[0,1] neg_hi:[0,1]
	v_pk_add_f32 v[76:77], v[100:101], v[84:85]
	v_xor_b32_e32 v95, 0x80000000, v78
	v_mov_b32_e32 v94, v79
	v_pk_add_f32 v[78:79], v[92:93], v[86:87]
	v_pk_add_f32 v[86:87], v[92:93], v[86:87] neg_lo:[0,1] neg_hi:[0,1]
	v_pk_add_f32 v[92:93], v[68:69], v[88:89]
	v_pk_add_f32 v[68:69], v[68:69], v[88:89] neg_lo:[0,1] neg_hi:[0,1]
	s_waitcnt lgkmcnt(1)
	v_pk_add_f32 v[88:89], v[80:81], v[96:97]
	v_pk_add_f32 v[80:81], v[80:81], v[96:97] neg_lo:[0,1] neg_hi:[0,1]
	v_pk_add_f32 v[84:85], v[100:101], v[84:85] neg_lo:[0,1] neg_hi:[0,1]
	v_pk_add_f32 v[100:101], v[66:67], v[94:95]
	v_pk_add_f32 v[66:67], v[66:67], v[94:95] neg_lo:[0,1] neg_hi:[0,1]
	v_xor_b32_e32 v95, 0x80000000, v80
	v_mov_b32_e32 v94, v81
	v_pk_add_f32 v[80:81], v[92:93], v[88:89]
	v_pk_add_f32 v[88:89], v[92:93], v[88:89] neg_lo:[0,1] neg_hi:[0,1]
	v_pk_add_f32 v[92:93], v[74:75], v[90:91]
	v_pk_add_f32 v[74:75], v[74:75], v[90:91] neg_lo:[0,1] neg_hi:[0,1]
	s_waitcnt lgkmcnt(0)
	v_pk_add_f32 v[90:91], v[82:83], v[98:99]
	v_pk_add_f32 v[82:83], v[82:83], v[98:99] neg_lo:[0,1] neg_hi:[0,1]
	v_pk_add_f32 v[96:97], v[68:69], v[94:95]
	v_pk_add_f32 v[68:69], v[68:69], v[94:95] neg_lo:[0,1] neg_hi:[0,1]
	v_pk_add_f32 v[98:99], v[74:75], v[82:83] op_sel:[0,1] op_sel_hi:[1,0] neg_hi:[0,1]
	v_pk_add_f32 v[74:75], v[74:75], v[82:83] op_sel:[0,1] op_sel_hi:[1,0] neg_lo:[0,1]
	v_pk_mul_f32 v[94:95], v[86:87], s[12:13] op_sel:[1,0] op_sel_hi:[0,0] neg_lo:[1,0]
	v_pk_add_f32 v[82:83], v[92:93], v[90:91]
	v_pk_fma_f32 v[86:87], v[86:87], s[12:13], v[94:95] op_sel_hi:[1,0,1] neg_lo:[0,0,1] neg_hi:[0,0,1]
	v_pk_mul_f32 v[94:95], v[66:67], s[36:37] op_sel:[1,0] op_sel_hi:[0,0] neg_lo:[1,0]
	v_pk_add_f32 v[90:91], v[92:93], v[90:91] neg_lo:[0,1] neg_hi:[0,1]
	v_pk_fma_f32 v[66:67], v[66:67], s[22:23], v[94:95] op_sel_hi:[1,0,1] neg_lo:[0,0,1] neg_hi:[0,0,1]
	v_pk_mul_f32 v[94:95], v[96:97], s[12:13] op_sel:[1,0] op_sel_hi:[0,0] neg_lo:[1,0]
	v_pk_fma_f32 v[94:95], v[96:97], s[12:13], v[94:95] op_sel_hi:[1,0,1] neg_lo:[0,0,1] neg_hi:[0,0,1]
	v_pk_fma_f32 v[88:89], v[88:89], 0, v[88:89] op_sel:[0,0,1] op_sel_hi:[1,0,0] neg_hi:[0,0,1]
	v_pk_mul_f32 v[96:97], v[68:69], s[12:13] op_sel:[1,0] op_sel_hi:[0,0] neg_lo:[1,0]
	v_pk_fma_f32 v[68:69], v[68:69], s[18:19], v[96:97] op_sel_hi:[1,0,1] neg_lo:[0,0,1] neg_hi:[0,0,1]
	v_pk_mul_f32 v[96:97], v[98:99], s[36:37] op_sel:[1,0] op_sel_hi:[0,0] neg_lo:[1,0]
	v_pk_mul_f32 v[92:93], v[100:101], s[22:23] op_sel:[1,0] op_sel_hi:[0,0] neg_lo:[1,0]
	v_pk_fma_f32 v[96:97], v[98:99], s[22:23], v[96:97] op_sel_hi:[1,0,1] neg_lo:[0,0,1] neg_hi:[0,0,1]
	v_pk_mul_f32 v[98:99], v[90:91], s[12:13] op_sel:[1,0] op_sel_hi:[0,0] neg_lo:[1,0]
	v_pk_fma_f32 v[92:93], v[100:101], s[36:37], v[92:93] op_sel_hi:[1,0,1] neg_lo:[0,0,1] neg_hi:[0,0,1]
	v_pk_fma_f32 v[90:91], v[90:91], s[18:19], v[98:99] op_sel_hi:[1,0,1] neg_lo:[0,0,1] neg_hi:[0,0,1]
	v_xor_b32_e32 v98, 0x80000000, v75
	v_mov_b32_e32 v99, v74
	v_pk_mul_f32 v[74:75], v[74:75], s[36:37] op_sel_hi:[1,0]
	s_nop 0
	v_pk_fma_f32 v[74:75], v[98:99], s[22:23], v[74:75] op_sel_hi:[1,0,1] neg_lo:[0,0,1] neg_hi:[0,0,1]
	v_pk_add_f32 v[98:99], v[76:77], v[80:81]
	v_pk_add_f32 v[76:77], v[76:77], v[80:81] neg_lo:[0,1] neg_hi:[0,1]
	v_pk_add_f32 v[80:81], v[78:79], v[82:83]
	v_pk_add_f32 v[78:79], v[78:79], v[82:83] neg_lo:[0,1] neg_hi:[0,1]
	s_nop 0
	v_xor_b32_e32 v83, 0x80000000, v78
	v_mov_b32_e32 v82, v79
	v_pk_add_f32 v[78:79], v[98:99], v[80:81]
	v_pk_add_f32 v[80:81], v[98:99], v[80:81] neg_lo:[0,1] neg_hi:[0,1]
	v_pk_add_f32 v[98:99], v[92:93], v[96:97]
	v_pk_add_f32 v[92:93], v[92:93], v[96:97] neg_lo:[0,1] neg_hi:[0,1]
	v_pk_add_f32 v[100:101], v[76:77], v[82:83]
	v_pk_add_f32 v[76:77], v[76:77], v[82:83] neg_lo:[0,1] neg_hi:[0,1]
	v_pk_add_f32 v[82:83], v[102:103], v[94:95]
	v_pk_add_f32 v[94:95], v[102:103], v[94:95] neg_lo:[0,1] neg_hi:[0,1]
	s_nop 0
	v_pk_add_f32 v[102:103], v[94:95], v[92:93] op_sel:[0,1] op_sel_hi:[1,0] neg_hi:[0,1]
	v_pk_add_f32 v[94:95], v[94:95], v[92:93] op_sel:[0,1] op_sel_hi:[1,0] neg_lo:[0,1]
	v_pk_add_f32 v[96:97], v[84:85], v[88:89]
	v_pk_add_f32 v[84:85], v[84:85], v[88:89] neg_lo:[0,1] neg_hi:[0,1]
	v_pk_add_f32 v[88:89], v[86:87], v[90:91]
	v_pk_add_f32 v[86:87], v[86:87], v[90:91] neg_lo:[0,1] neg_hi:[0,1]
	v_pk_add_f32 v[92:93], v[82:83], v[98:99]
	v_pk_add_f32 v[82:83], v[82:83], v[98:99] neg_lo:[0,1] neg_hi:[0,1]
	v_pk_add_f32 v[98:99], v[84:85], v[86:87] op_sel:[0,1] op_sel_hi:[1,0] neg_hi:[0,1]
	v_pk_add_f32 v[84:85], v[84:85], v[86:87] op_sel:[0,1] op_sel_hi:[1,0] neg_lo:[0,1]
	v_pk_add_f32 v[90:91], v[64:65], v[68:69]
	v_pk_add_f32 v[64:65], v[64:65], v[68:69] neg_lo:[0,1] neg_hi:[0,1]
	v_pk_add_f32 v[68:69], v[66:67], v[74:75]
	v_pk_add_f32 v[66:67], v[66:67], v[74:75] neg_lo:[0,1] neg_hi:[0,1]
	v_pk_add_f32 v[86:87], v[96:97], v[88:89]
	v_pk_add_f32 v[88:89], v[96:97], v[88:89] neg_lo:[0,1] neg_hi:[0,1]
	v_pk_add_f32 v[96:97], v[64:65], v[66:67] op_sel:[0,1] op_sel_hi:[1,0] neg_hi:[0,1]
	v_pk_add_f32 v[64:65], v[64:65], v[66:67] op_sel:[0,1] op_sel_hi:[1,0] neg_lo:[0,1]
	v_xor_b32_e32 v74, 0x80000000, v55
	v_mov_b32_e32 v75, v54
	v_pk_mul_f32 v[74:75], v[74:75], v[78:79] op_sel:[0,1]
	v_pk_add_f32 v[66:67], v[90:91], v[68:69]
	v_pk_fma_f32 v[54:55], v[54:55], v[78:79], v[74:75] op_sel_hi:[1,0,1]
	ds_write_b64 v12, v[54:55]
	v_pk_mul_f32 v[54:55], v[70:71], v[92:93] op_sel:[1,1] op_sel_hi:[0,1] neg_lo:[1,0]
	v_pk_add_f32 v[68:69], v[90:91], v[68:69] neg_lo:[0,1] neg_hi:[0,1]
	v_pk_fma_f32 v[54:55], v[70:71], v[92:93], v[54:55] op_sel_hi:[1,0,1]
	ds_write_b64 v12, v[54:55] offset:2176
	v_pk_mul_f32 v[54:55], v[72:73], v[86:87] op_sel:[1,1] op_sel_hi:[0,1] neg_lo:[1,0]
	v_pk_fma_f32 v[54:55], v[72:73], v[86:87], v[54:55] op_sel_hi:[1,0,1]
	ds_write_b64 v12, v[54:55] offset:4352
	v_pk_mul_f32 v[54:55], v[60:61], v[66:67] op_sel:[1,1] op_sel_hi:[0,1] neg_lo:[1,0]
	v_pk_fma_f32 v[54:55], v[60:61], v[66:67], v[54:55] op_sel_hi:[1,0,1]
	ds_write_b64 v12, v[54:55] offset:6528
	v_pk_mul_f32 v[54:55], v[58:59], v[100:101] op_sel:[1,1] op_sel_hi:[0,1] neg_lo:[1,0]
	v_pk_fma_f32 v[54:55], v[58:59], v[100:101], v[54:55] op_sel_hi:[1,0,1]
	ds_write_b64 v12, v[54:55] offset:8704
	v_pk_mul_f32 v[54:55], v[52:53], v[102:103] op_sel:[1,1] op_sel_hi:[0,1] neg_lo:[1,0]
	v_pk_fma_f32 v[52:53], v[52:53], v[102:103], v[54:55] op_sel_hi:[1,0,1]
	ds_write_b64 v12, v[52:53] offset:10880
	v_pk_mul_f32 v[52:53], v[48:49], v[98:99] op_sel:[1,1] op_sel_hi:[0,1] neg_lo:[1,0]
	v_pk_fma_f32 v[48:49], v[48:49], v[98:99], v[52:53] op_sel_hi:[1,0,1]
	ds_write_b64 v12, v[48:49] offset:13056
	v_pk_mul_f32 v[48:49], v[42:43], v[96:97] op_sel:[1,1] op_sel_hi:[0,1] neg_lo:[1,0]
	v_pk_fma_f32 v[42:43], v[42:43], v[96:97], v[48:49] op_sel_hi:[1,0,1]
	ds_write_b64 v12, v[42:43] offset:15232
	v_pk_mul_f32 v[42:43], v[44:45], v[80:81] op_sel:[1,1] op_sel_hi:[0,1] neg_lo:[1,0]
	v_pk_fma_f32 v[42:43], v[44:45], v[80:81], v[42:43] op_sel_hi:[1,0,1]
	ds_write_b64 v12, v[42:43] offset:17408
	v_pk_mul_f32 v[42:43], v[62:63], v[82:83] op_sel:[1,1] op_sel_hi:[0,1] neg_lo:[1,0]
	v_pk_fma_f32 v[42:43], v[62:63], v[82:83], v[42:43] op_sel_hi:[1,0,1]
	ds_write_b64 v12, v[42:43] offset:19584
	v_pk_mul_f32 v[42:43], v[2:3], v[88:89] op_sel:[1,1] op_sel_hi:[0,1] neg_lo:[1,0]
	v_pk_fma_f32 v[2:3], v[2:3], v[88:89], v[42:43] op_sel_hi:[1,0,1]
	ds_write_b64 v12, v[2:3] offset:21760
	v_pk_mul_f32 v[2:3], v[56:57], v[68:69] op_sel:[1,1] op_sel_hi:[0,1] neg_lo:[1,0]
	v_pk_fma_f32 v[2:3], v[56:57], v[68:69], v[2:3] op_sel_hi:[1,0,1]
	ds_write_b64 v12, v[2:3] offset:23936
	v_pk_mul_f32 v[2:3], v[50:51], v[76:77] op_sel:[1,1] op_sel_hi:[0,1] neg_lo:[1,0]
	v_pk_fma_f32 v[2:3], v[50:51], v[76:77], v[2:3] op_sel_hi:[1,0,1]
	ds_write_b64 v12, v[2:3] offset:26112
	v_pk_mul_f32 v[2:3], v[46:47], v[94:95] op_sel:[1,1] op_sel_hi:[0,1] neg_lo:[1,0]
	v_pk_fma_f32 v[2:3], v[46:47], v[94:95], v[2:3] op_sel_hi:[1,0,1]
	ds_write_b64 v12, v[2:3] offset:28288
	v_pk_mul_f32 v[2:3], v[6:7], v[84:85] op_sel:[1,1] op_sel_hi:[0,1] neg_lo:[1,0]
	v_pk_fma_f32 v[2:3], v[6:7], v[84:85], v[2:3] op_sel_hi:[1,0,1]
	ds_write_b64 v12, v[2:3] offset:30464
	v_pk_mul_f32 v[2:3], v[0:1], v[64:65] op_sel:[1,1] op_sel_hi:[0,1] neg_lo:[1,0]
	v_pk_fma_f32 v[0:1], v[0:1], v[64:65], v[2:3] op_sel_hi:[1,0,1]
	ds_write_b64 v12, v[0:1] offset:32640
	v_mov_b32_e32 v78, 1.0
	v_pk_mul_f32 v[2:3], v[210:211], v[210:211] op_sel:[1,1] op_sel_hi:[0,1] neg_lo:[1,0]
	v_mov_b32_e32 v79, v177
	v_pk_fma_f32 v[2:3], v[210:211], v[210:211], v[2:3] op_sel_hi:[0,1,1]
	v_pk_mul_f32 v[44:45], v[2:3], v[2:3] op_sel:[1,1] op_sel_hi:[1,0] neg_lo:[0,1]
	v_pk_mul_f32 v[6:7], v[210:211], v[176:177] op_sel:[1,1] op_sel_hi:[0,1] neg_lo:[1,0]
	v_pk_fma_f32 v[44:45], v[2:3], v[2:3], v[44:45] op_sel_hi:[1,0,1]
	v_pk_fma_f32 v[80:81], v[210:211], v[78:79], v[6:7] op_sel_hi:[1,0,1]
	v_pk_mul_f32 v[0:1], v[176:177], v[2:3] op_sel:[1,1] op_sel_hi:[1,0] neg_lo:[0,1]
	s_nop 0
	v_pk_fma_f32 v[82:83], v[78:79], v[2:3], v[0:1] op_sel_hi:[0,1,1]
	v_pk_mul_f32 v[0:1], v[80:81], v[2:3] op_sel:[1,1] op_sel_hi:[1,0] neg_lo:[0,1]
	v_pk_mul_f32 v[48:49], v[44:45], v[44:45] op_sel:[1,1] op_sel_hi:[1,0] neg_lo:[0,1]
	v_pk_fma_f32 v[84:85], v[2:3], v[80:81], v[0:1] op_sel_hi:[1,0,1]
	v_pk_mul_f32 v[0:1], v[176:177], v[44:45] op_sel:[1,1] op_sel_hi:[1,0] neg_lo:[0,1]
	s_nop 0
	v_pk_fma_f32 v[86:87], v[78:79], v[44:45], v[0:1] op_sel_hi:[0,1,1]
	v_pk_mul_f32 v[0:1], v[80:81], v[44:45] op_sel:[1,1] op_sel_hi:[1,0] neg_lo:[0,1]
	s_waitcnt lgkmcnt(0)
	v_pk_fma_f32 v[88:89], v[80:81], v[44:45], v[0:1] op_sel_hi:[0,1,1]
	v_pk_mul_f32 v[0:1], v[82:83], v[44:45] op_sel:[1,1] op_sel_hi:[1,0] neg_lo:[0,1]
	s_barrier
	v_pk_fma_f32 v[90:91], v[44:45], v[82:83], v[0:1] op_sel_hi:[1,0,1]
	v_pk_mul_f32 v[0:1], v[84:85], v[44:45] op_sel:[1,1] op_sel_hi:[1,0] neg_lo:[0,1]
	s_nop 0
	v_pk_fma_f32 v[92:93], v[44:45], v[84:85], v[0:1] op_sel_hi:[1,0,1]
	v_pk_fma_f32 v[0:1], v[44:45], v[44:45], v[48:49] op_sel_hi:[1,0,1]
	v_add_f32_e32 v5, 0x3727c5ac, v5
	v_pk_mul_f32 v[2:3], v[176:177], v[0:1] op_sel:[1,1] op_sel_hi:[1,0] neg_lo:[0,1]
	s_nop 0
	v_pk_fma_f32 v[94:95], v[78:79], v[0:1], v[2:3] op_sel_hi:[0,1,1]
	v_pk_mul_f32 v[2:3], v[80:81], v[0:1] op_sel:[1,1] op_sel_hi:[1,0] neg_lo:[0,1]
	s_nop 0
	v_pk_fma_f32 v[96:97], v[80:81], v[0:1], v[2:3] op_sel_hi:[0,1,1]
	v_pk_mul_f32 v[2:3], v[82:83], v[0:1] op_sel:[1,1] op_sel_hi:[1,0] neg_lo:[0,1]
	v_cmp_gt_f32_e32 vcc, s23, v5
	v_pk_fma_f32 v[98:99], v[82:83], v[0:1], v[2:3] op_sel_hi:[0,1,1]
	v_pk_mul_f32 v[2:3], v[84:85], v[0:1] op_sel:[1,1] op_sel_hi:[1,0] neg_lo:[0,1]
	s_mov_b32 s2, 0x39000000
	v_pk_fma_f32 v[44:45], v[84:85], v[0:1], v[2:3] op_sel_hi:[0,1,1]
	v_pk_mul_f32 v[2:3], v[86:87], v[0:1] op_sel:[1,1] op_sel_hi:[1,0] neg_lo:[0,1]
	s_add_u32 s6, s40, 0x2000
	v_pk_fma_f32 v[42:43], v[0:1], v[86:87], v[2:3] op_sel_hi:[1,0,1]
	v_pk_mul_f32 v[2:3], v[88:89], v[0:1] op_sel:[1,1] op_sel_hi:[1,0] neg_lo:[0,1]
	s_addc_u32 s7, s41, 0
	v_pk_fma_f32 v[6:7], v[0:1], v[88:89], v[2:3] op_sel_hi:[1,0,1]
	v_pk_mul_f32 v[2:3], v[90:91], v[0:1] op_sel:[1,1] op_sel_hi:[1,0] neg_lo:[0,1]
	v_pk_mul_f32 v[46:47], v[92:93], v[0:1] op_sel:[1,1] op_sel_hi:[1,0] neg_lo:[0,1]
	v_pk_fma_f32 v[2:3], v[0:1], v[90:91], v[2:3] op_sel_hi:[1,0,1]
	v_pk_fma_f32 v[0:1], v[0:1], v[92:93], v[46:47] op_sel_hi:[1,0,1]
	v_bfe_u32 v46, v206, 4, 4
	v_and_b32_e32 v12, 15, v206
	v_mul_u32_u24_e32 v46, 0x880, v46
	v_lshlrev_b32_e32 v12, 3, v12
	v_add3_u32 v12, v207, v46, v12
	ds_read2_b64 v[46:49], v12 offset1:17
	ds_read2_b64 v[50:53], v12 offset0:34 offset1:51
	ds_read2_b64 v[54:57], v12 offset0:68 offset1:85
	ds_read2_b64 v[58:61], v12 offset0:136 offset1:153
	ds_read2_b64 v[62:65], v12 offset0:102 offset1:119
	ds_read2_b64 v[66:69], v12 offset0:204 offset1:221
	ds_read2_b64 v[70:73], v12 offset0:170 offset1:187
	ds_read2_b64 v[74:77], v12 offset0:238 offset1:255
	s_waitcnt lgkmcnt(4)
	v_pk_add_f32 v[100:101], v[46:47], v[58:59]
	v_pk_add_f32 v[46:47], v[46:47], v[58:59] neg_lo:[0,1] neg_hi:[0,1]
	s_waitcnt lgkmcnt(2)
	v_pk_add_f32 v[58:59], v[54:55], v[66:67]
	v_pk_add_f32 v[54:55], v[54:55], v[66:67] neg_lo:[0,1] neg_hi:[0,1]
	s_nop 0
	v_pk_add_f32 v[102:103], v[46:47], v[54:55] op_sel:[0,1] op_sel_hi:[1,0] neg_hi:[0,1]
	v_pk_add_f32 v[46:47], v[46:47], v[54:55] op_sel:[0,1] op_sel_hi:[1,0] neg_lo:[0,1]
	v_pk_add_f32 v[66:67], v[48:49], v[60:61]
	v_pk_add_f32 v[48:49], v[48:49], v[60:61] neg_lo:[0,1] neg_hi:[0,1]
	v_pk_add_f32 v[60:61], v[56:57], v[68:69]
	v_pk_add_f32 v[56:57], v[56:57], v[68:69] neg_lo:[0,1] neg_hi:[0,1]
	v_pk_add_f32 v[54:55], v[100:101], v[58:59]
	v_pk_add_f32 v[58:59], v[100:101], v[58:59] neg_lo:[0,1] neg_hi:[0,1]
	v_pk_add_f32 v[100:101], v[48:49], v[56:57] op_sel:[0,1] op_sel_hi:[1,0] neg_hi:[0,1]
	v_pk_add_f32 v[48:49], v[48:49], v[56:57] op_sel:[0,1] op_sel_hi:[1,0] neg_lo:[0,1]
	s_waitcnt lgkmcnt(0)
	v_pk_add_f32 v[68:69], v[62:63], v[74:75]
	v_pk_add_f32 v[62:63], v[62:63], v[74:75] neg_lo:[0,1] neg_hi:[0,1]
	v_pk_add_f32 v[56:57], v[66:67], v[60:61]
	v_pk_add_f32 v[60:61], v[66:67], v[60:61] neg_lo:[0,1] neg_hi:[0,1]
	v_pk_add_f32 v[66:67], v[50:51], v[70:71]
	v_pk_add_f32 v[50:51], v[50:51], v[70:71] neg_lo:[0,1] neg_hi:[0,1]
	s_nop 0
	v_pk_add_f32 v[74:75], v[50:51], v[62:63] op_sel:[0,1] op_sel_hi:[1,0] neg_hi:[0,1]
	v_pk_add_f32 v[50:51], v[50:51], v[62:63] op_sel:[0,1] op_sel_hi:[1,0] neg_lo:[0,1]
	v_pk_add_f32 v[70:71], v[64:65], v[76:77]
	v_pk_add_f32 v[64:65], v[64:65], v[76:77] neg_lo:[0,1] neg_hi:[0,1]
	v_pk_add_f32 v[62:63], v[66:67], v[68:69]
	v_pk_add_f32 v[66:67], v[66:67], v[68:69] neg_lo:[0,1] neg_hi:[0,1]
	v_pk_add_f32 v[68:69], v[52:53], v[72:73]
	v_pk_add_f32 v[52:53], v[52:53], v[72:73] neg_lo:[0,1] neg_hi:[0,1]
	s_nop 0
	v_pk_add_f32 v[76:77], v[52:53], v[64:65] op_sel:[0,1] op_sel_hi:[1,0] neg_hi:[0,1]
	v_pk_add_f32 v[52:53], v[52:53], v[64:65] op_sel:[0,1] op_sel_hi:[1,0] neg_lo:[0,1]
	v_pk_mul_f32 v[72:73], v[60:61], s[12:13] op_sel:[1,0] op_sel_hi:[0,0] neg_lo:[1,0]
	v_pk_add_f32 v[64:65], v[68:69], v[70:71]
	v_pk_fma_f32 v[60:61], v[60:61], s[12:13], v[72:73] op_sel_hi:[1,0,1] neg_lo:[0,0,1] neg_hi:[0,0,1]
	v_pk_mul_f32 v[72:73], v[48:49], s[36:37] op_sel:[1,0] op_sel_hi:[0,0] neg_lo:[1,0]
	v_pk_add_f32 v[68:69], v[68:69], v[70:71] neg_lo:[0,1] neg_hi:[0,1]
	v_pk_fma_f32 v[48:49], v[48:49], s[22:23], v[72:73] op_sel_hi:[1,0,1] neg_lo:[0,0,1] neg_hi:[0,0,1]
	v_pk_mul_f32 v[72:73], v[74:75], s[12:13] op_sel:[1,0] op_sel_hi:[0,0] neg_lo:[1,0]
	v_pk_fma_f32 v[72:73], v[74:75], s[12:13], v[72:73] op_sel_hi:[1,0,1] neg_lo:[0,0,1] neg_hi:[0,0,1]
	v_pk_fma_f32 v[66:67], v[66:67], 0, v[66:67] op_sel:[0,0,1] op_sel_hi:[1,0,0] neg_hi:[0,0,1]
	v_pk_mul_f32 v[74:75], v[50:51], s[12:13] op_sel:[1,0] op_sel_hi:[0,0] neg_lo:[1,0]
	v_pk_fma_f32 v[50:51], v[50:51], s[18:19], v[74:75] op_sel_hi:[1,0,1] neg_lo:[0,0,1] neg_hi:[0,0,1]
	v_pk_mul_f32 v[74:75], v[76:77], s[36:37] op_sel:[1,0] op_sel_hi:[0,0] neg_lo:[1,0]
	v_pk_mul_f32 v[70:71], v[100:101], s[22:23] op_sel:[1,0] op_sel_hi:[0,0] neg_lo:[1,0]
	v_pk_fma_f32 v[74:75], v[76:77], s[22:23], v[74:75] op_sel_hi:[1,0,1] neg_lo:[0,0,1] neg_hi:[0,0,1]
	v_pk_mul_f32 v[76:77], v[68:69], s[12:13] op_sel:[1,0] op_sel_hi:[0,0] neg_lo:[1,0]
	v_pk_fma_f32 v[70:71], v[100:101], s[36:37], v[70:71] op_sel_hi:[1,0,1] neg_lo:[0,0,1] neg_hi:[0,0,1]
	v_pk_fma_f32 v[68:69], v[68:69], s[18:19], v[76:77] op_sel_hi:[1,0,1] neg_lo:[0,0,1] neg_hi:[0,0,1]
	v_xor_b32_e32 v76, 0x80000000, v53
	v_mov_b32_e32 v77, v52
	v_pk_mul_f32 v[52:53], v[52:53], s[36:37] op_sel_hi:[1,0]
	s_nop 0
	v_pk_fma_f32 v[52:53], v[76:77], s[22:23], v[52:53] op_sel_hi:[1,0,1] neg_lo:[0,0,1] neg_hi:[0,0,1]
	v_pk_add_f32 v[76:77], v[54:55], v[62:63]
	v_pk_add_f32 v[54:55], v[54:55], v[62:63] neg_lo:[0,1] neg_hi:[0,1]
	v_pk_add_f32 v[62:63], v[56:57], v[64:65]
	v_pk_add_f32 v[56:57], v[56:57], v[64:65] neg_lo:[0,1] neg_hi:[0,1]
	s_nop 0
	v_xor_b32_e32 v65, 0x80000000, v56
	v_mov_b32_e32 v64, v57
	v_pk_add_f32 v[56:57], v[76:77], v[62:63]
	v_pk_add_f32 v[62:63], v[76:77], v[62:63] neg_lo:[0,1] neg_hi:[0,1]
	v_pk_add_f32 v[76:77], v[70:71], v[74:75]
	v_pk_add_f32 v[70:71], v[70:71], v[74:75] neg_lo:[0,1] neg_hi:[0,1]
	v_pk_add_f32 v[100:101], v[54:55], v[64:65]
	v_pk_add_f32 v[54:55], v[54:55], v[64:65] neg_lo:[0,1] neg_hi:[0,1]
	v_pk_add_f32 v[64:65], v[102:103], v[72:73]
	v_pk_add_f32 v[72:73], v[102:103], v[72:73] neg_lo:[0,1] neg_hi:[0,1]
	s_nop 0
	v_pk_add_f32 v[102:103], v[72:73], v[70:71] op_sel:[0,1] op_sel_hi:[1,0] neg_hi:[0,1]
	v_pk_add_f32 v[72:73], v[72:73], v[70:71] op_sel:[0,1] op_sel_hi:[1,0] neg_lo:[0,1]
	v_pk_add_f32 v[74:75], v[58:59], v[66:67]
	v_pk_add_f32 v[58:59], v[58:59], v[66:67] neg_lo:[0,1] neg_hi:[0,1]
	v_pk_add_f32 v[66:67], v[60:61], v[68:69]
	v_pk_add_f32 v[60:61], v[60:61], v[68:69] neg_lo:[0,1] neg_hi:[0,1]
	v_pk_add_f32 v[70:71], v[64:65], v[76:77]
	v_pk_add_f32 v[64:65], v[64:65], v[76:77] neg_lo:[0,1] neg_hi:[0,1]
	v_pk_add_f32 v[76:77], v[58:59], v[60:61] op_sel:[0,1] op_sel_hi:[1,0] neg_hi:[0,1]
	v_pk_add_f32 v[58:59], v[58:59], v[60:61] op_sel:[0,1] op_sel_hi:[1,0] neg_lo:[0,1]
	v_pk_add_f32 v[68:69], v[46:47], v[50:51]
	v_pk_add_f32 v[46:47], v[46:47], v[50:51] neg_lo:[0,1] neg_hi:[0,1]
	v_pk_add_f32 v[50:51], v[48:49], v[52:53]
	v_pk_add_f32 v[48:49], v[48:49], v[52:53] neg_lo:[0,1] neg_hi:[0,1]
	v_pk_add_f32 v[60:61], v[74:75], v[66:67]
	v_pk_add_f32 v[66:67], v[74:75], v[66:67] neg_lo:[0,1] neg_hi:[0,1]
	v_pk_add_f32 v[74:75], v[46:47], v[48:49] op_sel:[0,1] op_sel_hi:[1,0] neg_hi:[0,1]
	v_pk_add_f32 v[46:47], v[46:47], v[48:49] op_sel:[0,1] op_sel_hi:[1,0] neg_lo:[0,1]
	v_xor_b32_e32 v52, 0x80000000, v79
	v_mov_b32_e32 v53, v78
	v_pk_mul_f32 v[52:53], v[52:53], v[56:57] op_sel:[0,1]
	v_pk_add_f32 v[48:49], v[68:69], v[50:51]
	v_pk_fma_f32 v[52:53], v[78:79], v[56:57], v[52:53] op_sel_hi:[1,0,1]
	v_pk_mul_f32 v[56:57], v[80:81], v[70:71] op_sel:[1,1] op_sel_hi:[0,1] neg_lo:[1,0]
	v_pk_add_f32 v[50:51], v[68:69], v[50:51] neg_lo:[0,1] neg_hi:[0,1]
	v_pk_fma_f32 v[56:57], v[80:81], v[70:71], v[56:57] op_sel_hi:[1,0,1]
	ds_write2_b64 v12, v[52:53], v[56:57] offset1:17
	v_pk_mul_f32 v[52:53], v[82:83], v[60:61] op_sel:[1,1] op_sel_hi:[0,1] neg_lo:[1,0]
	v_pk_mul_f32 v[56:57], v[84:85], v[48:49] op_sel:[1,1] op_sel_hi:[0,1] neg_lo:[1,0]
	v_pk_fma_f32 v[52:53], v[82:83], v[60:61], v[52:53] op_sel_hi:[1,0,1]
	v_pk_fma_f32 v[48:49], v[84:85], v[48:49], v[56:57] op_sel_hi:[1,0,1]
	ds_write2_b64 v12, v[52:53], v[48:49] offset0:34 offset1:51
	v_pk_mul_f32 v[48:49], v[86:87], v[100:101] op_sel:[1,1] op_sel_hi:[0,1] neg_lo:[1,0]
	v_pk_mul_f32 v[52:53], v[88:89], v[102:103] op_sel:[1,1] op_sel_hi:[0,1] neg_lo:[1,0]
	v_pk_fma_f32 v[48:49], v[86:87], v[100:101], v[48:49] op_sel_hi:[1,0,1]
	v_pk_fma_f32 v[52:53], v[88:89], v[102:103], v[52:53] op_sel_hi:[1,0,1]
	ds_write2_b64 v12, v[48:49], v[52:53] offset0:68 offset1:85
	v_pk_mul_f32 v[48:49], v[90:91], v[76:77] op_sel:[1,1] op_sel_hi:[0,1] neg_lo:[1,0]
	v_pk_mul_f32 v[52:53], v[92:93], v[74:75] op_sel:[1,1] op_sel_hi:[0,1] neg_lo:[1,0]
	v_pk_fma_f32 v[48:49], v[90:91], v[76:77], v[48:49] op_sel_hi:[1,0,1]
	v_pk_fma_f32 v[52:53], v[92:93], v[74:75], v[52:53] op_sel_hi:[1,0,1]
	ds_write2_b64 v12, v[48:49], v[52:53] offset0:102 offset1:119
	v_pk_mul_f32 v[48:49], v[94:95], v[62:63] op_sel:[1,1] op_sel_hi:[0,1] neg_lo:[1,0]
	v_pk_mul_f32 v[52:53], v[96:97], v[64:65] op_sel:[1,1] op_sel_hi:[0,1] neg_lo:[1,0]
	v_pk_fma_f32 v[48:49], v[94:95], v[62:63], v[48:49] op_sel_hi:[1,0,1]
	v_pk_fma_f32 v[52:53], v[96:97], v[64:65], v[52:53] op_sel_hi:[1,0,1]
	ds_write2_b64 v12, v[48:49], v[52:53] offset0:136 offset1:153
	v_pk_mul_f32 v[48:49], v[98:99], v[66:67] op_sel:[1,1] op_sel_hi:[0,1] neg_lo:[1,0]
	v_pk_mul_f32 v[52:53], v[44:45], v[50:51] op_sel:[1,1] op_sel_hi:[0,1] neg_lo:[1,0]
	v_pk_fma_f32 v[48:49], v[98:99], v[66:67], v[48:49] op_sel_hi:[1,0,1]
	v_pk_fma_f32 v[44:45], v[44:45], v[50:51], v[52:53] op_sel_hi:[1,0,1]
	ds_write2_b64 v12, v[48:49], v[44:45] offset0:170 offset1:187
	v_pk_mul_f32 v[44:45], v[42:43], v[54:55] op_sel:[1,1] op_sel_hi:[0,1] neg_lo:[1,0]
	v_pk_fma_f32 v[42:43], v[42:43], v[54:55], v[44:45] op_sel_hi:[1,0,1]
	v_pk_mul_f32 v[44:45], v[6:7], v[72:73] op_sel:[1,1] op_sel_hi:[0,1] neg_lo:[1,0]
	v_pk_fma_f32 v[6:7], v[6:7], v[72:73], v[44:45] op_sel_hi:[1,0,1]
	ds_write2_b64 v12, v[42:43], v[6:7] offset0:204 offset1:221
	v_pk_mul_f32 v[6:7], v[2:3], v[58:59] op_sel:[1,1] op_sel_hi:[0,1] neg_lo:[1,0]
	v_pk_fma_f32 v[2:3], v[2:3], v[58:59], v[6:7] op_sel_hi:[1,0,1]
	v_pk_mul_f32 v[6:7], v[0:1], v[46:47] op_sel:[1,1] op_sel_hi:[0,1] neg_lo:[1,0]
	v_pk_fma_f32 v[0:1], v[0:1], v[46:47], v[6:7] op_sel_hi:[1,0,1]
	ds_write2_b64 v12, v[2:3], v[0:1] offset0:238 offset1:255
	s_waitcnt lgkmcnt(0)
	s_barrier
	v_mul_f32_e32 v12, 0x4b800000, v5
	v_and_b32_e32 v0, 0xff, v206
	v_mad_u32_u24 v6, v0, s19, v207
	ds_read2_b64 v[0:3], v6 offset1:1
	ds_read2_b64 v[42:45], v6 offset0:2 offset1:3
	ds_read2_b64 v[46:49], v6 offset0:8 offset1:9
	ds_read2_b64 v[50:53], v6 offset0:4 offset1:5
	ds_read2_b64 v[54:57], v6 offset0:6 offset1:7
	ds_read2_b64 v[58:61], v6 offset0:12 offset1:13
	ds_read2_b64 v[62:65], v6 offset0:10 offset1:11
	ds_read2_b64 v[66:69], v6 offset0:14 offset1:15
	s_waitcnt lgkmcnt(5)
	v_pk_add_f32 v[6:7], v[0:1], v[46:47]
	v_pk_add_f32 v[0:1], v[0:1], v[46:47] neg_lo:[0,1] neg_hi:[0,1]
	s_waitcnt lgkmcnt(2)
	v_pk_add_f32 v[46:47], v[50:51], v[58:59]
	v_pk_add_f32 v[50:51], v[50:51], v[58:59] neg_lo:[0,1] neg_hi:[0,1]
	v_cndmask_b32_e32 v5, v5, v12, vcc
	v_xor_b32_e32 v59, 0x80000000, v50
	v_mov_b32_e32 v58, v51
	v_pk_add_f32 v[50:51], v[6:7], v[46:47]
	v_pk_add_f32 v[6:7], v[6:7], v[46:47] neg_lo:[0,1] neg_hi:[0,1]
	v_pk_add_f32 v[46:47], v[2:3], v[48:49]
	v_pk_add_f32 v[2:3], v[2:3], v[48:49] neg_lo:[0,1] neg_hi:[0,1]
	v_pk_add_f32 v[48:49], v[52:53], v[60:61]
	v_pk_add_f32 v[52:53], v[52:53], v[60:61] neg_lo:[0,1] neg_hi:[0,1]
	v_pk_add_f32 v[70:71], v[0:1], v[58:59]
	v_pk_add_f32 v[0:1], v[0:1], v[58:59] neg_lo:[0,1] neg_hi:[0,1]
	v_pk_add_f32 v[60:61], v[2:3], v[52:53] op_sel:[0,1] op_sel_hi:[1,0] neg_hi:[0,1]
	v_pk_add_f32 v[2:3], v[2:3], v[52:53] op_sel:[0,1] op_sel_hi:[1,0] neg_lo:[0,1]
	s_waitcnt lgkmcnt(0)
	v_pk_add_f32 v[58:59], v[54:55], v[66:67]
	v_pk_add_f32 v[54:55], v[54:55], v[66:67] neg_lo:[0,1] neg_hi:[0,1]
	v_pk_add_f32 v[52:53], v[46:47], v[48:49]
	v_pk_add_f32 v[46:47], v[46:47], v[48:49] neg_lo:[0,1] neg_hi:[0,1]
	v_pk_add_f32 v[48:49], v[42:43], v[62:63]
	v_pk_add_f32 v[42:43], v[42:43], v[62:63] neg_lo:[0,1] neg_hi:[0,1]
	v_xor_b32_e32 v63, 0x80000000, v54
	v_mov_b32_e32 v62, v55
	v_pk_add_f32 v[54:55], v[48:49], v[58:59]
	v_pk_add_f32 v[66:67], v[42:43], v[62:63]
	v_pk_add_f32 v[48:49], v[48:49], v[58:59] neg_lo:[0,1] neg_hi:[0,1]
	v_pk_add_f32 v[42:43], v[42:43], v[62:63] neg_lo:[0,1] neg_hi:[0,1]
	v_pk_add_f32 v[58:59], v[44:45], v[64:65]
	v_pk_add_f32 v[62:63], v[56:57], v[68:69]
	v_pk_add_f32 v[56:57], v[56:57], v[68:69] neg_lo:[0,1] neg_hi:[0,1]
	v_pk_add_f32 v[44:45], v[44:45], v[64:65] neg_lo:[0,1] neg_hi:[0,1]
	v_xor_b32_e32 v65, 0x80000000, v56
	v_mov_b32_e32 v64, v57
	v_pk_add_f32 v[56:57], v[58:59], v[62:63]
	v_pk_add_f32 v[58:59], v[58:59], v[62:63] neg_lo:[0,1] neg_hi:[0,1]
	v_pk_mul_f32 v[62:63], v[60:61], s[22:23] op_sel:[1,0] op_sel_hi:[0,0] neg_lo:[1,0]
	v_pk_add_f32 v[68:69], v[44:45], v[64:65]
	v_pk_fma_f32 v[60:61], v[60:61], s[36:37], v[62:63] op_sel_hi:[1,0,1] neg_lo:[0,0,1] neg_hi:[0,0,1]
	v_pk_mul_f32 v[62:63], v[46:47], s[12:13] op_sel:[1,0] op_sel_hi:[0,0] neg_lo:[1,0]
	v_pk_add_f32 v[44:45], v[44:45], v[64:65] neg_lo:[0,1] neg_hi:[0,1]
	v_pk_fma_f32 v[46:47], v[46:47], s[12:13], v[62:63] op_sel_hi:[1,0,1] neg_lo:[0,0,1] neg_hi:[0,0,1]
	v_pk_mul_f32 v[62:63], v[2:3], s[36:37] op_sel:[1,0] op_sel_hi:[0,0] neg_lo:[1,0]
	v_pk_fma_f32 v[2:3], v[2:3], s[22:23], v[62:63] op_sel_hi:[1,0,1] neg_lo:[0,0,1] neg_hi:[0,0,1]
	v_pk_mul_f32 v[62:63], v[66:67], s[12:13] op_sel:[1,0] op_sel_hi:[0,0] neg_lo:[1,0]
	v_pk_fma_f32 v[48:49], v[48:49], 0, v[48:49] op_sel:[0,0,1] op_sel_hi:[1,0,0] neg_hi:[0,0,1]
	v_pk_fma_f32 v[62:63], v[66:67], s[12:13], v[62:63] op_sel_hi:[1,0,1] neg_lo:[0,0,1] neg_hi:[0,0,1]
	v_pk_mul_f32 v[64:65], v[42:43], s[12:13] op_sel:[1,0] op_sel_hi:[0,0] neg_lo:[1,0]
	v_pk_fma_f32 v[42:43], v[42:43], s[18:19], v[64:65] op_sel_hi:[1,0,1] neg_lo:[0,0,1] neg_hi:[0,0,1]
	v_pk_mul_f32 v[66:67], v[58:59], s[12:13] op_sel:[1,0] op_sel_hi:[0,0] neg_lo:[1,0]
	v_pk_mul_f32 v[64:65], v[68:69], s[36:37] op_sel:[1,0] op_sel_hi:[0,0] neg_lo:[1,0]
	v_pk_fma_f32 v[58:59], v[58:59], s[18:19], v[66:67] op_sel_hi:[1,0,1] neg_lo:[0,0,1] neg_hi:[0,0,1]
	v_xor_b32_e32 v66, 0x80000000, v45
	v_mov_b32_e32 v67, v44
	v_pk_mul_f32 v[44:45], v[44:45], s[36:37] op_sel_hi:[1,0]
	v_pk_fma_f32 v[64:65], v[68:69], s[22:23], v[64:65] op_sel_hi:[1,0,1] neg_lo:[0,0,1] neg_hi:[0,0,1]
	v_pk_fma_f32 v[44:45], v[66:67], s[22:23], v[44:45] op_sel_hi:[1,0,1] neg_lo:[0,0,1] neg_hi:[0,0,1]
	v_pk_add_f32 v[66:67], v[50:51], v[54:55]
	v_pk_add_f32 v[50:51], v[50:51], v[54:55] neg_lo:[0,1] neg_hi:[0,1]
	v_pk_add_f32 v[54:55], v[52:53], v[56:57]
	v_pk_add_f32 v[52:53], v[52:53], v[56:57] neg_lo:[0,1] neg_hi:[0,1]
	v_rsq_f32_e32 v5, v5
	v_xor_b32_e32 v57, 0x80000000, v52
	v_mov_b32_e32 v56, v53
	v_pk_add_f32 v[52:53], v[66:67], v[54:55]
	v_pk_add_f32 v[54:55], v[66:67], v[54:55] neg_lo:[0,1] neg_hi:[0,1]
	v_pk_add_f32 v[66:67], v[60:61], v[64:65]
	v_pk_add_f32 v[60:61], v[60:61], v[64:65] neg_lo:[0,1] neg_hi:[0,1]
	v_pk_add_f32 v[68:69], v[50:51], v[56:57]
	v_pk_add_f32 v[50:51], v[50:51], v[56:57] neg_lo:[0,1] neg_hi:[0,1]
	v_pk_add_f32 v[56:57], v[70:71], v[62:63]
	v_pk_add_f32 v[62:63], v[70:71], v[62:63] neg_lo:[0,1] neg_hi:[0,1]
	s_nop 0
	v_pk_add_f32 v[70:71], v[62:63], v[60:61] op_sel:[0,1] op_sel_hi:[1,0] neg_hi:[0,1]
	v_pk_add_f32 v[62:63], v[62:63], v[60:61] op_sel:[0,1] op_sel_hi:[1,0] neg_lo:[0,1]
	v_pk_add_f32 v[64:65], v[6:7], v[48:49]
	v_pk_add_f32 v[6:7], v[6:7], v[48:49] neg_lo:[0,1] neg_hi:[0,1]
	v_pk_add_f32 v[48:49], v[46:47], v[58:59]
	v_pk_add_f32 v[46:47], v[46:47], v[58:59] neg_lo:[0,1] neg_hi:[0,1]
	v_mul_f32_e32 v12, 0x45800000, v5
	v_pk_add_f32 v[60:61], v[56:57], v[66:67]
	v_pk_add_f32 v[56:57], v[56:57], v[66:67] neg_lo:[0,1] neg_hi:[0,1]
	v_pk_add_f32 v[66:67], v[6:7], v[46:47] op_sel:[0,1] op_sel_hi:[1,0] neg_hi:[0,1]
	v_pk_add_f32 v[6:7], v[6:7], v[46:47] op_sel:[0,1] op_sel_hi:[1,0] neg_lo:[0,1]
	v_pk_add_f32 v[58:59], v[0:1], v[42:43]
	v_pk_add_f32 v[0:1], v[0:1], v[42:43] neg_lo:[0,1] neg_hi:[0,1]
	v_pk_add_f32 v[42:43], v[2:3], v[44:45]
	v_pk_add_f32 v[2:3], v[2:3], v[44:45] neg_lo:[0,1] neg_hi:[0,1]
	v_cndmask_b32_e32 v5, v5, v12, vcc
	v_pk_mul_f32 v[4:5], v[4:5], s[2:3] op_sel_hi:[1,0]
	v_pk_add_f32 v[46:47], v[64:65], v[48:49]
	v_pk_add_f32 v[48:49], v[64:65], v[48:49] neg_lo:[0,1] neg_hi:[0,1]
	v_pk_add_f32 v[64:65], v[0:1], v[2:3] op_sel:[0,1] op_sel_hi:[1,0] neg_hi:[0,1]
	v_pk_add_f32 v[0:1], v[0:1], v[2:3] op_sel:[0,1] op_sel_hi:[1,0] neg_lo:[0,1]
	v_pk_fma_f32 v[44:45], v[4:5], v[52:53], v[4:5] op_sel:[1,0,0] op_sel_hi:[0,1,1]
	v_pk_mul_f32 v[52:53], v[4:5], v[52:53]
	v_pk_add_f32 v[2:3], v[58:59], v[42:43]
	v_pk_add_f32 v[42:43], v[58:59], v[42:43] neg_lo:[0,1] neg_hi:[0,1]
	v_mov_b32_e32 v45, v53
	v_pk_fma_f32 v[52:53], v[4:5], v[68:69], v[4:5] op_sel:[1,0,0] op_sel_hi:[0,1,1]
	v_pk_mul_f32 v[58:59], v[4:5], v[68:69]
	v_pk_mul_f32 v[68:69], v[4:5], v[70:71]
	v_mov_b32_e32 v53, v59
	v_pk_fma_f32 v[58:59], v[4:5], v[54:55], v[4:5] op_sel:[1,0,0] op_sel_hi:[0,1,1]
	v_pk_mul_f32 v[54:55], v[4:5], v[54:55]
	s_nop 0
	v_mov_b32_e32 v59, v55
	v_pk_fma_f32 v[54:55], v[4:5], v[50:51], v[4:5] op_sel:[1,0,0] op_sel_hi:[0,1,1]
	v_pk_mul_f32 v[50:51], v[4:5], v[50:51]
	s_barrier
	v_mov_b32_e32 v55, v51
	v_pk_fma_f32 v[50:51], v[4:5], v[60:61], v[4:5] op_sel:[1,0,0] op_sel_hi:[0,1,1]
	v_pk_mul_f32 v[60:61], v[4:5], v[60:61]
	s_nop 0
	v_mov_b32_e32 v51, v61
	v_pk_fma_f32 v[60:61], v[4:5], v[70:71], v[4:5] op_sel:[1,0,0] op_sel_hi:[0,1,1]
	v_mov_b32_e32 v61, v69
	v_pk_fma_f32 v[68:69], v[4:5], v[56:57], v[4:5] op_sel:[1,0,0] op_sel_hi:[0,1,1]
	v_pk_mul_f32 v[56:57], v[4:5], v[56:57]
	s_nop 0
	v_mov_b32_e32 v69, v57
	v_pk_fma_f32 v[56:57], v[4:5], v[62:63], v[4:5] op_sel:[1,0,0] op_sel_hi:[0,1,1]
	v_pk_mul_f32 v[62:63], v[4:5], v[62:63]
	s_nop 0
	v_mov_b32_e32 v57, v63
	v_pk_fma_f32 v[62:63], v[4:5], v[46:47], v[4:5] op_sel:[1,0,0] op_sel_hi:[0,1,1]
	v_pk_mul_f32 v[46:47], v[4:5], v[46:47]
	s_nop 0
	v_mov_b32_e32 v63, v47
	v_pk_fma_f32 v[46:47], v[4:5], v[66:67], v[4:5] op_sel:[1,0,0] op_sel_hi:[0,1,1]
	v_pk_mul_f32 v[66:67], v[4:5], v[66:67]
	s_nop 0
	v_mov_b32_e32 v47, v67
	v_pk_fma_f32 v[66:67], v[4:5], v[48:49], v[4:5] op_sel:[1,0,0] op_sel_hi:[0,1,1]
	v_pk_mul_f32 v[48:49], v[4:5], v[48:49]
	s_nop 0
	v_mov_b32_e32 v67, v49
	v_pk_fma_f32 v[48:49], v[4:5], v[6:7], v[4:5] op_sel:[1,0,0] op_sel_hi:[0,1,1]
	v_pk_mul_f32 v[6:7], v[4:5], v[6:7]
	s_nop 0
	v_mov_b32_e32 v49, v7
	v_pk_fma_f32 v[6:7], v[4:5], v[2:3], v[4:5] op_sel:[1,0,0] op_sel_hi:[0,1,1]
	v_pk_mul_f32 v[2:3], v[4:5], v[2:3]
	s_nop 0
	v_mov_b32_e32 v7, v3
	v_pk_fma_f32 v[2:3], v[4:5], v[64:65], v[4:5] op_sel:[1,0,0] op_sel_hi:[0,1,1]
	v_pk_mul_f32 v[64:65], v[4:5], v[64:65]
	s_nop 0
	v_mov_b32_e32 v3, v65
	v_pk_fma_f32 v[64:65], v[4:5], v[42:43], v[4:5] op_sel:[1,0,0] op_sel_hi:[0,1,1]
	v_pk_mul_f32 v[42:43], v[4:5], v[42:43]
	s_nop 0
	v_mov_b32_e32 v65, v43
	v_pk_fma_f32 v[42:43], v[4:5], v[0:1], v[4:5] op_sel:[1,0,0] op_sel_hi:[0,1,1]
	v_pk_mul_f32 v[0:1], v[4:5], v[0:1]
	s_nop 0
	v_mov_b32_e32 v43, v1
	v_and_b32_e32 v0, 0x1ff, v212
	v_lshl_add_u32 v0, v0, 3, 0
	v_add_u32_e32 v0, 0x11040, v0
	ds_write2st64_b64 v0, v[44:45], v[52:53] offset1:8
	ds_write2st64_b64 v0, v[58:59], v[54:55] offset0:16 offset1:24
	ds_write2st64_b64 v0, v[50:51], v[60:61] offset0:32 offset1:40
	ds_write2st64_b64 v0, v[68:69], v[56:57] offset0:48 offset1:56
	ds_write2st64_b64 v0, v[62:63], v[46:47] offset0:64 offset1:72
	ds_write2st64_b64 v0, v[66:67], v[48:49] offset0:80 offset1:88
	ds_write2st64_b64 v0, v[6:7], v[2:3] offset0:96 offset1:104
	ds_write2st64_b64 v0, v[64:65], v[42:43] offset0:112 offset1:120
	v_add_f32_e32 v47, v20, v20
	v_and_b32_e32 v0, 0x1ff, v212
	v_lshlrev_b32_e32 v1, 3, v0
	v_add_u32_e32 v2, -1, v1
	v_cmp_ne_u32_e32 vcc, 0, v0
	v_add_u32_e32 v1, 8, v1
	s_waitcnt vmcnt(0)
	v_mul_f32_e32 v47, v47, v25
	v_cndmask_b32_e32 v176, 0, v2, vcc
	v_cmp_ne_u32_e32 vcc, s37, v0
	v_lshlrev_b64 v[42:43], 1, v[176:177]
	v_lshlrev_b32_e32 v0, 4, v0
	v_cndmask_b32_e32 v12, v229, v1, vcc
	v_lshl_add_u64 v[44:45], s[40:41], 0, v[42:43]
	v_lshlrev_b32_e32 v12, 1, v12
	global_load_dwordx4 v[4:7], v0, s[40:41]
	s_nop 0
	global_load_dwordx4 v[0:3], v0, s[6:7]
	v_lshl_add_u64 v[42:43], s[6:7], 0, v[42:43]
	global_load_ushort v143, v[44:45], off
	global_load_ushort v142, v12, s[40:41]
	global_load_ushort v141, v[42:43], off
	global_load_ushort v140, v12, s[6:7]
	s_nop 0
	global_load_dword v12, v177, s[44:45]
	v_mov_b32_e32 v43, v212
	v_add_f32_e32 v176, v20, v25
	v_and_b32_e32 v42, 0x1ff, v212
	v_bfe_u32 v44, v212, 1, 8
	v_cmp_eq_u32_e32 vcc, 0, v42
	v_sub_f32_e32 v48, v20, v25
	v_mul_f32_e32 v25, v25, v25
	v_lshl_add_u32 v46, v42, 3, v44
	v_mov_b32_e32 v44, v213
	v_mov_b32_e32 v45, v214
	v_cndmask_b32_e32 v47, 0, v47, vcc
	v_fmac_f32_e32 v25, v20, v20
	v_cndmask_b32_e32 v20, v48, v176, vcc
	v_add_f32_e32 v25, v25, v47
	v_lshl_add_u32 v50, v46, 3, 0
	v_pk_mul_f32 v[46:47], v[44:45], v[20:21] op_sel_hi:[1,0]
	v_pk_mul_f32 v[48:49], v[214:215], s[8:9] op_sel_hi:[0,1]
	v_pk_fma_f32 v[44:45], v[212:213], s[30:31], v[48:49] op_sel:[1,0,0]
	v_add_f32_e32 v20, v21, v19
	v_sub_f32_e32 v48, v21, v19
	v_mul_f32_e32 v19, v19, v19
	v_fmac_f32_e32 v19, v21, v21
	v_mov_b32_e32 v21, v177
	v_add_u32_e32 v51, 0x8800, v50
	ds_write2_b64 v50, v[176:177], v[20:21] offset1:1
	v_pk_mul_f32 v[20:21], v[48:49], v[44:45] op_sel_hi:[0,1]
	ds_write2_b64 v51, v[46:47], v[20:21] offset1:1
	v_pk_mul_f32 v[20:21], v[44:45], s[8:9] op_sel:[1,0]
	v_add_f32_e32 v176, v22, v18
	v_pk_fma_f32 v[20:21], v[44:45], s[30:31], v[20:21] op_sel_hi:[0,1,1]
	v_sub_f32_e32 v44, v22, v18
	v_mul_f32_e32 v18, v18, v18
	v_add_f32_e32 v19, v19, v25
	v_fmac_f32_e32 v18, v22, v22
	v_add_f32_e32 v25, v18, v19
	v_pk_mul_f32 v[18:19], v[44:45], v[20:21] op_sel_hi:[0,1]
	v_pk_mul_f32 v[44:45], v[20:21], s[8:9] op_sel:[1,0]
	v_add_f32_e32 v22, v23, v17
	v_pk_fma_f32 v[20:21], v[20:21], s[30:31], v[44:45] op_sel_hi:[0,1,1]
	v_sub_f32_e32 v44, v23, v17
	v_mul_f32_e32 v17, v17, v17
	v_fmac_f32_e32 v17, v23, v23
	v_mov_b32_e32 v23, v177
	v_add_u32_e32 v46, 0x8810, v50
	ds_write2_b64 v50, v[176:177], v[22:23] offset0:2 offset1:3
	v_pk_mul_f32 v[22:23], v[44:45], v[20:21] op_sel_hi:[0,1]
	ds_write2_b64 v46, v[18:19], v[22:23] offset1:1
	v_pk_mul_f32 v[18:19], v[20:21], s[8:9] op_sel:[1,0]
	v_add_f32_e32 v176, v8, v16
	v_pk_fma_f32 v[18:19], v[20:21], s[30:31], v[18:19] op_sel_hi:[0,1,1]
	v_sub_f32_e32 v20, v8, v16
	v_mul_f32_e32 v16, v16, v16
	v_add_f32_e32 v17, v17, v25
	v_fmac_f32_e32 v16, v8, v8
	v_add_f32_e32 v8, v16, v17
	v_pk_mul_f32 v[16:17], v[20:21], v[18:19] op_sel_hi:[0,1]
	v_mul_f32_e32 v20, v15, v15
	v_fmac_f32_e32 v20, v9, v9
	v_add_f32_e32 v8, v20, v8
	v_mul_f32_e32 v20, v14, v14
	v_fmac_f32_e32 v20, v10, v10
	v_add_f32_e32 v8, v20, v8
	v_mul_f32_e32 v20, v13, v13
	v_fmac_f32_e32 v20, v11, v11
	v_add_f32_e32 v23, v20, v8
	ds_bpermute_b32 v25, v27, v23
	v_pk_mul_f32 v[20:21], v[18:19], s[8:9] op_sel:[1,0]
	v_add_f32_e32 v8, v9, v15
	v_pk_fma_f32 v[18:19], v[18:19], s[30:31], v[20:21] op_sel_hi:[0,1,1]
	v_sub_f32_e32 v20, v9, v15
	s_waitcnt lgkmcnt(0)
	v_add_f32_e32 v15, v23, v25
	ds_bpermute_b32 v21, v29, v15
	v_mov_b32_e32 v9, v177
	v_add_u32_e32 v22, 0x8820, v50
	ds_write2_b64 v50, v[176:177], v[8:9] offset0:4 offset1:5
	v_add_f32_e32 v176, v10, v14
	s_waitcnt lgkmcnt(1)
	v_pk_mul_f32 v[8:9], v[20:21], v[18:19] op_sel_hi:[0,1]
	v_add_f32_e32 v15, v15, v21
	ds_write2_b64 v22, v[16:17], v[8:9] offset1:1
	ds_bpermute_b32 v16, v35, v15
	v_pk_mul_f32 v[8:9], v[18:19], s[8:9] op_sel:[1,0]
	v_sub_f32_e32 v10, v10, v14
	v_pk_fma_f32 v[8:9], v[18:19], s[30:31], v[8:9] op_sel_hi:[0,1,1]
	v_add_u32_e32 v20, 0x8830, v50
	s_waitcnt lgkmcnt(0)
	v_add_f32_e32 v18, v15, v16
	ds_bpermute_b32 v19, v37, v18
	v_pk_mul_f32 v[16:17], v[8:9], s[8:9] op_sel:[1,0]
	v_pk_mul_f32 v[14:15], v[10:11], v[8:9] op_sel_hi:[0,1]
	v_pk_fma_f32 v[16:17], v[8:9], s[30:31], v[16:17] op_sel_hi:[0,1,1]
	v_add_f32_e32 v8, v11, v13
	s_waitcnt lgkmcnt(0)
	v_add_f32_e32 v18, v18, v19
	ds_bpermute_b32 v19, v39, v18
	v_mov_b32_e32 v9, v177
	ds_write2_b64 v50, v[176:177], v[8:9] offset0:6 offset1:7
	v_sub_f32_e32 v10, v11, v13
	v_pk_mul_f32 v[10:11], v[10:11], v[16:17] op_sel_hi:[0,1]
	s_waitcnt lgkmcnt(1)
	v_add_f32_e32 v8, v18, v19
	ds_bpermute_b32 v9, v40, v8
	ds_write2_b64 v20, v[14:15], v[10:11] offset1:1
	v_and_b32_e32 v10, 63, v212
	v_cmp_eq_u32_e32 vcc, 0, v10
	s_and_saveexec_b64 s[28:29], vcc
	v_readlane_b32 s64, v255, 6
	v_readlane_b32 s65, v255, 7
	v_readlane_b32 s66, v255, 8
	v_readlane_b32 s67, v255, 9
	s_cbranch_execz .LBB0_208
	v_lshrrev_b32_e32 v10, 4, v42
	v_add_u32_e32 v10, 0, v10
	v_add_u32_e32 v10, 0x11000, v10
	s_waitcnt lgkmcnt(1)
	v_add_f32_e32 v8, v8, v9
	ds_write_b32 v10, v8
.LBB0_208:
	s_or_b64 exec, exec, s[28:29]
	s_waitcnt lgkmcnt(1)
	v_mov_b32_e32 v46, 1.0
	v_mov_b32_e32 v47, v177
	v_pk_mul_f32 v[10:11], v[208:209], v[208:209] op_sel:[1,1] op_sel_hi:[0,1] neg_lo:[1,0]
	v_mov_b32_e32 v13, s3
	v_pk_fma_f32 v[10:11], v[208:209], v[208:209], v[10:11] op_sel_hi:[0,1,1]
	v_pk_mul_f32 v[14:15], v[208:209], v[176:177] op_sel:[1,1] op_sel_hi:[0,1] neg_lo:[1,0]
	v_pk_mul_f32 v[18:19], v[10:11], v[10:11] op_sel:[1,1] op_sel_hi:[1,0] neg_lo:[0,1]
	v_pk_fma_f32 v[56:57], v[208:209], v[46:47], v[14:15] op_sel_hi:[1,0,1]
	v_pk_mul_f32 v[8:9], v[176:177], v[10:11] op_sel:[1,1] op_sel_hi:[1,0] neg_lo:[0,1]
	s_nop 0
	v_pk_fma_f32 v[58:59], v[46:47], v[10:11], v[8:9] op_sel_hi:[0,1,1]
	v_pk_mul_f32 v[8:9], v[56:57], v[10:11] op_sel:[1,1] op_sel_hi:[1,0] neg_lo:[0,1]
	s_waitcnt lgkmcnt(0)
	s_barrier
	ds_read_b128 v[14:17], v13
	v_pk_fma_f32 v[20:21], v[10:11], v[10:11], v[18:19] op_sel_hi:[1,0,1]
	v_readlane_b32 s2, v254, 61
	s_nop 1
	v_mov_b32_e32 v13, s2
	v_pk_fma_f32 v[60:61], v[10:11], v[56:57], v[8:9] op_sel_hi:[1,0,1]
	v_pk_mul_f32 v[8:9], v[176:177], v[20:21] op_sel:[1,1] op_sel_hi:[1,0] neg_lo:[0,1]
	ds_read_b128 v[52:55], v13
	v_pk_fma_f32 v[50:51], v[46:47], v[20:21], v[8:9] op_sel_hi:[0,1,1]
	v_pk_mul_f32 v[8:9], v[56:57], v[20:21] op_sel:[1,1] op_sel_hi:[1,0] neg_lo:[0,1]
	s_waitcnt lgkmcnt(1)
	v_add_f32_e32 v13, 0, v14
	v_pk_fma_f32 v[44:45], v[56:57], v[20:21], v[8:9] op_sel_hi:[0,1,1]
	v_pk_mul_f32 v[8:9], v[58:59], v[20:21] op_sel:[1,1] op_sel_hi:[1,0] neg_lo:[0,1]
	v_add_f32_e32 v13, v13, v15
	v_pk_mul_f32 v[42:43], v[20:21], v[20:21] op_sel:[1,1] op_sel_hi:[1,0] neg_lo:[0,1]
	v_pk_fma_f32 v[22:23], v[20:21], v[58:59], v[8:9] op_sel_hi:[1,0,1]
	v_pk_mul_f32 v[8:9], v[60:61], v[20:21] op_sel:[1,1] op_sel_hi:[1,0] neg_lo:[0,1]
	v_add_f32_e32 v13, v13, v16
	v_mov_b32_e32 v25, v206
	v_pk_fma_f32 v[18:19], v[20:21], v[60:61], v[8:9] op_sel_hi:[1,0,1]
	v_pk_fma_f32 v[8:9], v[20:21], v[20:21], v[42:43] op_sel_hi:[1,0,1]
	v_add_f32_e32 v13, v13, v17
	s_waitcnt lgkmcnt(0)
	v_add_f32_e32 v13, v13, v52
	v_lshlrev_b32_sdwa v27, v228, v25 dst_sel:DWORD dst_unused:UNUSED_PAD src0_sel:DWORD src1_sel:BYTE_0
	v_lshrrev_b32_e32 v25, 1, v206
	v_pk_mul_f32 v[10:11], v[176:177], v[8:9] op_sel:[1,1] op_sel_hi:[1,0] neg_lo:[0,1]
	v_add_f32_e32 v13, v13, v53
	v_and_b32_e32 v25, 0x78, v25
	v_pk_fma_f32 v[20:21], v[46:47], v[8:9], v[10:11] op_sel_hi:[0,1,1]
	v_pk_mul_f32 v[48:49], v[56:57], v[8:9] op_sel:[1,1] op_sel_hi:[1,0] neg_lo:[0,1]
	v_pk_mul_f32 v[10:11], v[58:59], v[8:9] op_sel:[1,1] op_sel_hi:[1,0] neg_lo:[0,1]
	v_pk_mul_f32 v[62:63], v[60:61], v[8:9] op_sel:[1,1] op_sel_hi:[1,0] neg_lo:[0,1]
	v_pk_mul_f32 v[64:65], v[50:51], v[8:9] op_sel:[1,1] op_sel_hi:[1,0] neg_lo:[0,1]
	v_pk_mul_f32 v[66:67], v[44:45], v[8:9] op_sel:[1,1] op_sel_hi:[1,0] neg_lo:[0,1]
	v_pk_mul_f32 v[68:69], v[22:23], v[8:9] op_sel:[1,1] op_sel_hi:[1,0] neg_lo:[0,1]
	v_pk_mul_f32 v[70:71], v[18:19], v[8:9] op_sel:[1,1] op_sel_hi:[1,0] neg_lo:[0,1]
	v_add_f32_e32 v13, v13, v54
	v_add3_u32 v25, v207, v27, v25
	v_pk_fma_f32 v[10:11], v[58:59], v[8:9], v[10:11] op_sel_hi:[0,1,1]
	v_add_f32_e32 v13, v13, v55
	v_pk_fma_f32 v[52:53], v[56:57], v[8:9], v[48:49] op_sel_hi:[0,1,1]
	v_pk_fma_f32 v[48:49], v[60:61], v[8:9], v[62:63] op_sel_hi:[0,1,1]
	v_pk_fma_f32 v[42:43], v[8:9], v[50:51], v[64:65] op_sel_hi:[1,0,1]
	v_pk_fma_f32 v[16:17], v[8:9], v[44:45], v[66:67] op_sel_hi:[1,0,1]
	v_pk_fma_f32 v[14:15], v[8:9], v[22:23], v[68:69] op_sel_hi:[1,0,1]
	v_pk_fma_f32 v[8:9], v[8:9], v[18:19], v[70:71] op_sel_hi:[1,0,1]
	ds_read_b64 v[54:55], v25
	ds_read_b64 v[62:63], v25 offset:2176
	ds_read_b64 v[64:65], v25 offset:4352
	ds_read_b64 v[66:67], v25 offset:6528
	ds_read_b64 v[68:69], v25 offset:8704
	ds_read_b64 v[70:71], v25 offset:10880
	ds_read_b64 v[72:73], v25 offset:13056
	ds_read_b64 v[74:75], v25 offset:15232
	ds_read_b64 v[76:77], v25 offset:17408
	ds_read_b64 v[78:79], v25 offset:19584
	ds_read_b64 v[80:81], v25 offset:21760
	ds_read_b64 v[82:83], v25 offset:23936
	ds_read_b64 v[84:85], v25 offset:26112
	ds_read_b64 v[86:87], v25 offset:28288
	ds_read_b64 v[88:89], v25 offset:30464
	ds_read_b64 v[90:91], v25 offset:32640
	s_waitcnt lgkmcnt(7)
	v_pk_add_f32 v[92:93], v[54:55], v[76:77]
	v_pk_add_f32 v[54:55], v[54:55], v[76:77] neg_lo:[0,1] neg_hi:[0,1]
	s_waitcnt lgkmcnt(3)
	v_pk_add_f32 v[76:77], v[68:69], v[84:85]
	v_pk_add_f32 v[68:69], v[68:69], v[84:85] neg_lo:[0,1] neg_hi:[0,1]
	s_lshl_b64 s[42:43], s[42:43], 16
	v_pk_add_f32 v[94:95], v[54:55], v[68:69] op_sel:[0,1] op_sel_hi:[1,0] neg_hi:[0,1]
	v_pk_add_f32 v[54:55], v[54:55], v[68:69] op_sel:[0,1] op_sel_hi:[1,0] neg_lo:[0,1]
	v_pk_add_f32 v[84:85], v[62:63], v[78:79]
	v_pk_add_f32 v[62:63], v[62:63], v[78:79] neg_lo:[0,1] neg_hi:[0,1]
	s_waitcnt lgkmcnt(2)
	v_pk_add_f32 v[78:79], v[70:71], v[86:87]
	v_pk_add_f32 v[70:71], v[70:71], v[86:87] neg_lo:[0,1] neg_hi:[0,1]
	v_pk_add_f32 v[68:69], v[92:93], v[76:77]
	v_xor_b32_e32 v87, 0x80000000, v70
	v_mov_b32_e32 v86, v71
	v_pk_add_f32 v[70:71], v[84:85], v[78:79]
	v_pk_add_f32 v[78:79], v[84:85], v[78:79] neg_lo:[0,1] neg_hi:[0,1]
	v_pk_add_f32 v[84:85], v[64:65], v[80:81]
	v_pk_add_f32 v[64:65], v[64:65], v[80:81] neg_lo:[0,1] neg_hi:[0,1]
	s_waitcnt lgkmcnt(1)
	v_pk_add_f32 v[80:81], v[72:73], v[88:89]
	v_pk_add_f32 v[72:73], v[72:73], v[88:89] neg_lo:[0,1] neg_hi:[0,1]
	v_pk_add_f32 v[76:77], v[92:93], v[76:77] neg_lo:[0,1] neg_hi:[0,1]
	v_pk_add_f32 v[92:93], v[62:63], v[86:87]
	v_pk_add_f32 v[62:63], v[62:63], v[86:87] neg_lo:[0,1] neg_hi:[0,1]
	v_xor_b32_e32 v87, 0x80000000, v72
	v_mov_b32_e32 v86, v73
	v_pk_add_f32 v[72:73], v[84:85], v[80:81]
	v_pk_add_f32 v[80:81], v[84:85], v[80:81] neg_lo:[0,1] neg_hi:[0,1]
	v_pk_add_f32 v[84:85], v[66:67], v[82:83]
	v_pk_add_f32 v[66:67], v[66:67], v[82:83] neg_lo:[0,1] neg_hi:[0,1]
	s_waitcnt lgkmcnt(0)
	v_pk_add_f32 v[82:83], v[74:75], v[90:91]
	v_pk_add_f32 v[74:75], v[74:75], v[90:91] neg_lo:[0,1] neg_hi:[0,1]
	v_pk_add_f32 v[88:89], v[64:65], v[86:87]
	v_pk_add_f32 v[64:65], v[64:65], v[86:87] neg_lo:[0,1] neg_hi:[0,1]
	v_pk_add_f32 v[90:91], v[66:67], v[74:75] op_sel:[0,1] op_sel_hi:[1,0] neg_hi:[0,1]
	v_pk_add_f32 v[66:67], v[66:67], v[74:75] op_sel:[0,1] op_sel_hi:[1,0] neg_lo:[0,1]
	v_pk_mul_f32 v[86:87], v[78:79], s[12:13] op_sel:[1,0] op_sel_hi:[0,0] neg_lo:[1,0]
	v_pk_add_f32 v[74:75], v[84:85], v[82:83]
	v_pk_fma_f32 v[78:79], v[78:79], s[12:13], v[86:87] op_sel_hi:[1,0,1] neg_lo:[0,0,1] neg_hi:[0,0,1]
	v_pk_mul_f32 v[86:87], v[62:63], s[36:37] op_sel:[1,0] op_sel_hi:[0,0] neg_lo:[1,0]
	v_pk_add_f32 v[82:83], v[84:85], v[82:83] neg_lo:[0,1] neg_hi:[0,1]
	v_pk_fma_f32 v[62:63], v[62:63], s[22:23], v[86:87] op_sel_hi:[1,0,1] neg_lo:[0,0,1] neg_hi:[0,0,1]
	v_pk_mul_f32 v[86:87], v[88:89], s[12:13] op_sel:[1,0] op_sel_hi:[0,0] neg_lo:[1,0]
	v_pk_fma_f32 v[86:87], v[88:89], s[12:13], v[86:87] op_sel_hi:[1,0,1] neg_lo:[0,0,1] neg_hi:[0,0,1]
	v_pk_fma_f32 v[80:81], v[80:81], 0, v[80:81] op_sel:[0,0,1] op_sel_hi:[1,0,0] neg_hi:[0,0,1]
	v_pk_mul_f32 v[88:89], v[64:65], s[12:13] op_sel:[1,0] op_sel_hi:[0,0] neg_lo:[1,0]
	v_pk_fma_f32 v[64:65], v[64:65], s[18:19], v[88:89] op_sel_hi:[1,0,1] neg_lo:[0,0,1] neg_hi:[0,0,1]
	v_pk_mul_f32 v[88:89], v[90:91], s[36:37] op_sel:[1,0] op_sel_hi:[0,0] neg_lo:[1,0]
	v_pk_mul_f32 v[84:85], v[92:93], s[22:23] op_sel:[1,0] op_sel_hi:[0,0] neg_lo:[1,0]
	v_pk_fma_f32 v[88:89], v[90:91], s[22:23], v[88:89] op_sel_hi:[1,0,1] neg_lo:[0,0,1] neg_hi:[0,0,1]
	v_pk_mul_f32 v[90:91], v[82:83], s[12:13] op_sel:[1,0] op_sel_hi:[0,0] neg_lo:[1,0]
	v_pk_fma_f32 v[84:85], v[92:93], s[36:37], v[84:85] op_sel_hi:[1,0,1] neg_lo:[0,0,1] neg_hi:[0,0,1]
	v_pk_fma_f32 v[82:83], v[82:83], s[18:19], v[90:91] op_sel_hi:[1,0,1] neg_lo:[0,0,1] neg_hi:[0,0,1]
	v_xor_b32_e32 v90, 0x80000000, v67
	v_mov_b32_e32 v91, v66
	v_pk_mul_f32 v[66:67], v[66:67], s[36:37] op_sel_hi:[1,0]
	s_nop 0
	v_pk_fma_f32 v[66:67], v[90:91], s[22:23], v[66:67] op_sel_hi:[1,0,1] neg_lo:[0,0,1] neg_hi:[0,0,1]
	v_pk_add_f32 v[90:91], v[68:69], v[72:73]
	v_pk_add_f32 v[68:69], v[68:69], v[72:73] neg_lo:[0,1] neg_hi:[0,1]
	v_pk_add_f32 v[72:73], v[70:71], v[74:75]
	v_pk_add_f32 v[70:71], v[70:71], v[74:75] neg_lo:[0,1] neg_hi:[0,1]
	s_nop 0
	v_xor_b32_e32 v75, 0x80000000, v70
	v_mov_b32_e32 v74, v71
	v_pk_add_f32 v[70:71], v[90:91], v[72:73]
	v_pk_add_f32 v[72:73], v[90:91], v[72:73] neg_lo:[0,1] neg_hi:[0,1]
	v_pk_add_f32 v[90:91], v[84:85], v[88:89]
	v_pk_add_f32 v[84:85], v[84:85], v[88:89] neg_lo:[0,1] neg_hi:[0,1]
	v_pk_add_f32 v[92:93], v[68:69], v[74:75]
	v_pk_add_f32 v[68:69], v[68:69], v[74:75] neg_lo:[0,1] neg_hi:[0,1]
	v_pk_add_f32 v[74:75], v[94:95], v[86:87]
	v_pk_add_f32 v[86:87], v[94:95], v[86:87] neg_lo:[0,1] neg_hi:[0,1]
	s_nop 0
	v_pk_add_f32 v[94:95], v[86:87], v[84:85] op_sel:[0,1] op_sel_hi:[1,0] neg_hi:[0,1]
	v_pk_add_f32 v[86:87], v[86:87], v[84:85] op_sel:[0,1] op_sel_hi:[1,0] neg_lo:[0,1]
	v_pk_add_f32 v[88:89], v[76:77], v[80:81]
	v_pk_add_f32 v[76:77], v[76:77], v[80:81] neg_lo:[0,1] neg_hi:[0,1]
	v_pk_add_f32 v[80:81], v[78:79], v[82:83]
	v_pk_add_f32 v[78:79], v[78:79], v[82:83] neg_lo:[0,1] neg_hi:[0,1]
	v_pk_add_f32 v[84:85], v[74:75], v[90:91]
	v_pk_add_f32 v[74:75], v[74:75], v[90:91] neg_lo:[0,1] neg_hi:[0,1]
	v_pk_add_f32 v[90:91], v[76:77], v[78:79] op_sel:[0,1] op_sel_hi:[1,0] neg_hi:[0,1]
	v_pk_add_f32 v[76:77], v[76:77], v[78:79] op_sel:[0,1] op_sel_hi:[1,0] neg_lo:[0,1]
	v_pk_add_f32 v[82:83], v[54:55], v[64:65]
	v_pk_add_f32 v[54:55], v[54:55], v[64:65] neg_lo:[0,1] neg_hi:[0,1]
	v_pk_add_f32 v[64:65], v[62:63], v[66:67]
	v_pk_add_f32 v[62:63], v[62:63], v[66:67] neg_lo:[0,1] neg_hi:[0,1]
	v_pk_add_f32 v[78:79], v[88:89], v[80:81]
	v_pk_add_f32 v[80:81], v[88:89], v[80:81] neg_lo:[0,1] neg_hi:[0,1]
	v_pk_add_f32 v[88:89], v[54:55], v[62:63] op_sel:[0,1] op_sel_hi:[1,0] neg_hi:[0,1]
	v_pk_add_f32 v[54:55], v[54:55], v[62:63] op_sel:[0,1] op_sel_hi:[1,0] neg_lo:[0,1]
	v_xor_b32_e32 v66, 0x80000000, v47
	v_mov_b32_e32 v67, v46
	v_pk_mul_f32 v[66:67], v[66:67], v[70:71] op_sel:[0,1]
	v_pk_add_f32 v[62:63], v[82:83], v[64:65]
	v_pk_fma_f32 v[46:47], v[46:47], v[70:71], v[66:67] op_sel_hi:[1,0,1]
	ds_write_b64 v25, v[46:47]
	v_pk_mul_f32 v[46:47], v[56:57], v[84:85] op_sel:[1,1] op_sel_hi:[0,1] neg_lo:[1,0]
	v_pk_add_f32 v[64:65], v[82:83], v[64:65] neg_lo:[0,1] neg_hi:[0,1]
	v_pk_fma_f32 v[46:47], v[56:57], v[84:85], v[46:47] op_sel_hi:[1,0,1]
	ds_write_b64 v25, v[46:47] offset:2176
	v_pk_mul_f32 v[46:47], v[58:59], v[78:79] op_sel:[1,1] op_sel_hi:[0,1] neg_lo:[1,0]
	v_pk_fma_f32 v[46:47], v[58:59], v[78:79], v[46:47] op_sel_hi:[1,0,1]
	ds_write_b64 v25, v[46:47] offset:4352
	v_pk_mul_f32 v[46:47], v[60:61], v[62:63] op_sel:[1,1] op_sel_hi:[0,1] neg_lo:[1,0]
	v_pk_fma_f32 v[46:47], v[60:61], v[62:63], v[46:47] op_sel_hi:[1,0,1]
	ds_write_b64 v25, v[46:47] offset:6528
	v_pk_mul_f32 v[46:47], v[50:51], v[92:93] op_sel:[1,1] op_sel_hi:[0,1] neg_lo:[1,0]
	v_pk_fma_f32 v[46:47], v[50:51], v[92:93], v[46:47] op_sel_hi:[1,0,1]
	ds_write_b64 v25, v[46:47] offset:8704
	v_pk_mul_f32 v[46:47], v[44:45], v[94:95] op_sel:[1,1] op_sel_hi:[0,1] neg_lo:[1,0]
	v_pk_fma_f32 v[44:45], v[44:45], v[94:95], v[46:47] op_sel_hi:[1,0,1]
	ds_write_b64 v25, v[44:45] offset:10880
	v_pk_mul_f32 v[44:45], v[22:23], v[90:91] op_sel:[1,1] op_sel_hi:[0,1] neg_lo:[1,0]
	v_pk_fma_f32 v[22:23], v[22:23], v[90:91], v[44:45] op_sel_hi:[1,0,1]
	ds_write_b64 v25, v[22:23] offset:13056
	v_pk_mul_f32 v[22:23], v[18:19], v[88:89] op_sel:[1,1] op_sel_hi:[0,1] neg_lo:[1,0]
	v_pk_fma_f32 v[18:19], v[18:19], v[88:89], v[22:23] op_sel_hi:[1,0,1]
	ds_write_b64 v25, v[18:19] offset:15232
	v_pk_mul_f32 v[18:19], v[20:21], v[72:73] op_sel:[1,1] op_sel_hi:[0,1] neg_lo:[1,0]
	v_pk_fma_f32 v[18:19], v[20:21], v[72:73], v[18:19] op_sel_hi:[1,0,1]
	ds_write_b64 v25, v[18:19] offset:17408
	v_pk_mul_f32 v[18:19], v[52:53], v[74:75] op_sel:[1,1] op_sel_hi:[0,1] neg_lo:[1,0]
	v_pk_fma_f32 v[18:19], v[52:53], v[74:75], v[18:19] op_sel_hi:[1,0,1]
	ds_write_b64 v25, v[18:19] offset:19584
	v_pk_mul_f32 v[18:19], v[10:11], v[80:81] op_sel:[1,1] op_sel_hi:[0,1] neg_lo:[1,0]
	v_pk_fma_f32 v[10:11], v[10:11], v[80:81], v[18:19] op_sel_hi:[1,0,1]
	ds_write_b64 v25, v[10:11] offset:21760
	v_pk_mul_f32 v[10:11], v[48:49], v[64:65] op_sel:[1,1] op_sel_hi:[0,1] neg_lo:[1,0]
	v_pk_fma_f32 v[10:11], v[48:49], v[64:65], v[10:11] op_sel_hi:[1,0,1]
	ds_write_b64 v25, v[10:11] offset:23936
	v_pk_mul_f32 v[10:11], v[42:43], v[68:69] op_sel:[1,1] op_sel_hi:[0,1] neg_lo:[1,0]
	v_pk_fma_f32 v[10:11], v[42:43], v[68:69], v[10:11] op_sel_hi:[1,0,1]
	ds_write_b64 v25, v[10:11] offset:26112
	v_pk_mul_f32 v[10:11], v[16:17], v[86:87] op_sel:[1,1] op_sel_hi:[0,1] neg_lo:[1,0]
	v_pk_fma_f32 v[10:11], v[16:17], v[86:87], v[10:11] op_sel_hi:[1,0,1]
	ds_write_b64 v25, v[10:11] offset:28288
	v_pk_mul_f32 v[10:11], v[14:15], v[76:77] op_sel:[1,1] op_sel_hi:[0,1] neg_lo:[1,0]
	v_pk_fma_f32 v[10:11], v[14:15], v[76:77], v[10:11] op_sel_hi:[1,0,1]
	ds_write_b64 v25, v[10:11] offset:30464
	v_pk_mul_f32 v[10:11], v[8:9], v[54:55] op_sel:[1,1] op_sel_hi:[0,1] neg_lo:[1,0]
	v_pk_fma_f32 v[8:9], v[8:9], v[54:55], v[10:11] op_sel_hi:[1,0,1]
	ds_write_b64 v25, v[8:9] offset:32640
	v_mov_b32_e32 v70, 1.0
	v_pk_mul_f32 v[10:11], v[210:211], v[210:211] op_sel:[1,1] op_sel_hi:[0,1] neg_lo:[1,0]
	v_mov_b32_e32 v71, v177
	v_pk_fma_f32 v[10:11], v[210:211], v[210:211], v[10:11] op_sel_hi:[0,1,1]
	v_pk_mul_f32 v[18:19], v[10:11], v[10:11] op_sel:[1,1] op_sel_hi:[1,0] neg_lo:[0,1]
	v_pk_mul_f32 v[14:15], v[210:211], v[176:177] op_sel:[1,1] op_sel_hi:[0,1] neg_lo:[1,0]
	v_pk_fma_f32 v[18:19], v[10:11], v[10:11], v[18:19] op_sel_hi:[1,0,1]
	v_pk_fma_f32 v[72:73], v[210:211], v[70:71], v[14:15] op_sel_hi:[1,0,1]
	v_pk_mul_f32 v[8:9], v[176:177], v[10:11] op_sel:[1,1] op_sel_hi:[1,0] neg_lo:[0,1]
	s_nop 0
	v_pk_fma_f32 v[74:75], v[70:71], v[10:11], v[8:9] op_sel_hi:[0,1,1]
	v_pk_mul_f32 v[8:9], v[72:73], v[10:11] op_sel:[1,1] op_sel_hi:[1,0] neg_lo:[0,1]
	v_pk_mul_f32 v[22:23], v[18:19], v[18:19] op_sel:[1,1] op_sel_hi:[1,0] neg_lo:[0,1]
	v_pk_fma_f32 v[76:77], v[10:11], v[72:73], v[8:9] op_sel_hi:[1,0,1]
	v_pk_mul_f32 v[8:9], v[176:177], v[18:19] op_sel:[1,1] op_sel_hi:[1,0] neg_lo:[0,1]
	s_nop 0
	v_pk_fma_f32 v[78:79], v[70:71], v[18:19], v[8:9] op_sel_hi:[0,1,1]
	v_pk_mul_f32 v[8:9], v[72:73], v[18:19] op_sel:[1,1] op_sel_hi:[1,0] neg_lo:[0,1]
	s_waitcnt lgkmcnt(0)
	v_pk_fma_f32 v[80:81], v[72:73], v[18:19], v[8:9] op_sel_hi:[0,1,1]
	v_pk_mul_f32 v[8:9], v[74:75], v[18:19] op_sel:[1,1] op_sel_hi:[1,0] neg_lo:[0,1]
	s_barrier
	v_pk_fma_f32 v[82:83], v[18:19], v[74:75], v[8:9] op_sel_hi:[1,0,1]
	v_pk_mul_f32 v[8:9], v[76:77], v[18:19] op_sel:[1,1] op_sel_hi:[1,0] neg_lo:[0,1]
	s_nop 0
	v_pk_fma_f32 v[84:85], v[18:19], v[76:77], v[8:9] op_sel_hi:[1,0,1]
	v_pk_fma_f32 v[8:9], v[18:19], v[18:19], v[22:23] op_sel_hi:[1,0,1]
	v_add_f32_e32 v13, 0x3727c5ac, v13
	v_pk_mul_f32 v[10:11], v[176:177], v[8:9] op_sel:[1,1] op_sel_hi:[1,0] neg_lo:[0,1]
	s_nop 0
	v_pk_fma_f32 v[86:87], v[70:71], v[8:9], v[10:11] op_sel_hi:[0,1,1]
	v_pk_mul_f32 v[10:11], v[72:73], v[8:9] op_sel:[1,1] op_sel_hi:[1,0] neg_lo:[0,1]
	v_cmp_gt_f32_e32 vcc, s23, v13
	v_pk_fma_f32 v[88:89], v[72:73], v[8:9], v[10:11] op_sel_hi:[0,1,1]
	v_pk_mul_f32 v[10:11], v[74:75], v[8:9] op_sel:[1,1] op_sel_hi:[1,0] neg_lo:[0,1]
	s_lshl_b64 s[0:1], s[0:1], 16
	v_pk_fma_f32 v[90:91], v[74:75], v[8:9], v[10:11] op_sel_hi:[0,1,1]
	v_pk_mul_f32 v[10:11], v[76:77], v[8:9] op_sel:[1,1] op_sel_hi:[1,0] neg_lo:[0,1]
	s_mov_b32 s2, 0x39000000
	v_pk_fma_f32 v[18:19], v[76:77], v[8:9], v[10:11] op_sel_hi:[0,1,1]
	v_pk_mul_f32 v[10:11], v[78:79], v[8:9] op_sel:[1,1] op_sel_hi:[1,0] neg_lo:[0,1]
	s_add_u32 s28, s64, s0
	v_pk_fma_f32 v[16:17], v[8:9], v[78:79], v[10:11] op_sel_hi:[1,0,1]
	v_pk_mul_f32 v[10:11], v[80:81], v[8:9] op_sel:[1,1] op_sel_hi:[1,0] neg_lo:[0,1]
	s_addc_u32 s29, s65, s1
	v_pk_fma_f32 v[14:15], v[8:9], v[80:81], v[10:11] op_sel_hi:[1,0,1]
	v_pk_mul_f32 v[10:11], v[82:83], v[8:9] op_sel:[1,1] op_sel_hi:[1,0] neg_lo:[0,1]
	v_pk_mul_f32 v[20:21], v[84:85], v[8:9] op_sel:[1,1] op_sel_hi:[1,0] neg_lo:[0,1]
	v_pk_fma_f32 v[10:11], v[8:9], v[82:83], v[10:11] op_sel_hi:[1,0,1]
	v_pk_fma_f32 v[8:9], v[8:9], v[84:85], v[20:21] op_sel_hi:[1,0,1]
	s_add_u32 s39, s64, s42
	v_bfe_u32 v21, v206, 4, 4
	v_and_b32_e32 v20, 15, v206
	v_mul_u32_u24_e32 v21, 0x880, v21
	v_lshlrev_b32_e32 v20, 3, v20
	v_add3_u32 v25, v207, v21, v20
	ds_read2_b64 v[20:23], v25 offset1:17
	ds_read2_b64 v[42:45], v25 offset0:34 offset1:51
	ds_read2_b64 v[46:49], v25 offset0:68 offset1:85
	ds_read2_b64 v[50:53], v25 offset0:136 offset1:153
	ds_read2_b64 v[54:57], v25 offset0:102 offset1:119
	ds_read2_b64 v[58:61], v25 offset0:204 offset1:221
	ds_read2_b64 v[62:65], v25 offset0:170 offset1:187
	ds_read2_b64 v[66:69], v25 offset0:238 offset1:255
	s_waitcnt lgkmcnt(4)
	v_pk_add_f32 v[92:93], v[20:21], v[50:51]
	v_pk_add_f32 v[20:21], v[20:21], v[50:51] neg_lo:[0,1] neg_hi:[0,1]
	s_waitcnt lgkmcnt(2)
	v_pk_add_f32 v[50:51], v[46:47], v[58:59]
	v_pk_add_f32 v[46:47], v[46:47], v[58:59] neg_lo:[0,1] neg_hi:[0,1]
	v_mov_b32_e32 v40, v32
	v_pk_add_f32 v[94:95], v[20:21], v[46:47] op_sel:[0,1] op_sel_hi:[1,0] neg_hi:[0,1]
	v_pk_add_f32 v[20:21], v[20:21], v[46:47] op_sel:[0,1] op_sel_hi:[1,0] neg_lo:[0,1]
	v_pk_add_f32 v[58:59], v[22:23], v[52:53]
	v_pk_add_f32 v[22:23], v[22:23], v[52:53] neg_lo:[0,1] neg_hi:[0,1]
	v_pk_add_f32 v[52:53], v[48:49], v[60:61]
	v_pk_add_f32 v[48:49], v[48:49], v[60:61] neg_lo:[0,1] neg_hi:[0,1]
	v_pk_add_f32 v[46:47], v[92:93], v[50:51]
	v_pk_add_f32 v[50:51], v[92:93], v[50:51] neg_lo:[0,1] neg_hi:[0,1]
	v_pk_add_f32 v[92:93], v[22:23], v[48:49] op_sel:[0,1] op_sel_hi:[1,0] neg_hi:[0,1]
	v_pk_add_f32 v[22:23], v[22:23], v[48:49] op_sel:[0,1] op_sel_hi:[1,0] neg_lo:[0,1]
	s_waitcnt lgkmcnt(0)
	v_pk_add_f32 v[60:61], v[54:55], v[66:67]
	v_pk_add_f32 v[54:55], v[54:55], v[66:67] neg_lo:[0,1] neg_hi:[0,1]
	v_pk_add_f32 v[48:49], v[58:59], v[52:53]
	v_pk_add_f32 v[52:53], v[58:59], v[52:53] neg_lo:[0,1] neg_hi:[0,1]
	v_pk_add_f32 v[58:59], v[42:43], v[62:63]
	v_pk_add_f32 v[42:43], v[42:43], v[62:63] neg_lo:[0,1] neg_hi:[0,1]
	s_nop 0
	v_pk_add_f32 v[66:67], v[42:43], v[54:55] op_sel:[0,1] op_sel_hi:[1,0] neg_hi:[0,1]
	v_pk_add_f32 v[42:43], v[42:43], v[54:55] op_sel:[0,1] op_sel_hi:[1,0] neg_lo:[0,1]
	v_pk_add_f32 v[62:63], v[56:57], v[68:69]
	v_pk_add_f32 v[56:57], v[56:57], v[68:69] neg_lo:[0,1] neg_hi:[0,1]
	v_pk_add_f32 v[54:55], v[58:59], v[60:61]
	v_pk_add_f32 v[58:59], v[58:59], v[60:61] neg_lo:[0,1] neg_hi:[0,1]
	v_pk_add_f32 v[60:61], v[44:45], v[64:65]
	v_pk_add_f32 v[44:45], v[44:45], v[64:65] neg_lo:[0,1] neg_hi:[0,1]
	s_nop 0
	v_pk_add_f32 v[68:69], v[44:45], v[56:57] op_sel:[0,1] op_sel_hi:[1,0] neg_hi:[0,1]
	v_pk_add_f32 v[44:45], v[44:45], v[56:57] op_sel:[0,1] op_sel_hi:[1,0] neg_lo:[0,1]
	v_pk_mul_f32 v[64:65], v[52:53], s[12:13] op_sel:[1,0] op_sel_hi:[0,0] neg_lo:[1,0]
	v_pk_add_f32 v[56:57], v[60:61], v[62:63]
	v_pk_fma_f32 v[52:53], v[52:53], s[12:13], v[64:65] op_sel_hi:[1,0,1] neg_lo:[0,0,1] neg_hi:[0,0,1]
	v_pk_mul_f32 v[64:65], v[22:23], s[36:37] op_sel:[1,0] op_sel_hi:[0,0] neg_lo:[1,0]
	v_pk_add_f32 v[60:61], v[60:61], v[62:63] neg_lo:[0,1] neg_hi:[0,1]
	v_pk_fma_f32 v[22:23], v[22:23], s[22:23], v[64:65] op_sel_hi:[1,0,1] neg_lo:[0,0,1] neg_hi:[0,0,1]
	v_pk_mul_f32 v[64:65], v[66:67], s[12:13] op_sel:[1,0] op_sel_hi:[0,0] neg_lo:[1,0]
	v_pk_fma_f32 v[64:65], v[66:67], s[12:13], v[64:65] op_sel_hi:[1,0,1] neg_lo:[0,0,1] neg_hi:[0,0,1]
	v_pk_fma_f32 v[58:59], v[58:59], 0, v[58:59] op_sel:[0,0,1] op_sel_hi:[1,0,0] neg_hi:[0,0,1]
	v_pk_mul_f32 v[66:67], v[42:43], s[12:13] op_sel:[1,0] op_sel_hi:[0,0] neg_lo:[1,0]
	v_pk_fma_f32 v[42:43], v[42:43], s[18:19], v[66:67] op_sel_hi:[1,0,1] neg_lo:[0,0,1] neg_hi:[0,0,1]
	v_pk_mul_f32 v[66:67], v[68:69], s[36:37] op_sel:[1,0] op_sel_hi:[0,0] neg_lo:[1,0]
	v_pk_mul_f32 v[62:63], v[92:93], s[22:23] op_sel:[1,0] op_sel_hi:[0,0] neg_lo:[1,0]
	v_pk_fma_f32 v[66:67], v[68:69], s[22:23], v[66:67] op_sel_hi:[1,0,1] neg_lo:[0,0,1] neg_hi:[0,0,1]
	v_pk_mul_f32 v[68:69], v[60:61], s[12:13] op_sel:[1,0] op_sel_hi:[0,0] neg_lo:[1,0]
	v_pk_fma_f32 v[62:63], v[92:93], s[36:37], v[62:63] op_sel_hi:[1,0,1] neg_lo:[0,0,1] neg_hi:[0,0,1]
	v_pk_fma_f32 v[60:61], v[60:61], s[18:19], v[68:69] op_sel_hi:[1,0,1] neg_lo:[0,0,1] neg_hi:[0,0,1]
	v_xor_b32_e32 v68, 0x80000000, v45
	v_mov_b32_e32 v69, v44
	v_pk_mul_f32 v[44:45], v[44:45], s[36:37] op_sel_hi:[1,0]
	v_mov_b32_e32 v98, v41
	v_pk_fma_f32 v[44:45], v[68:69], s[22:23], v[44:45] op_sel_hi:[1,0,1] neg_lo:[0,0,1] neg_hi:[0,0,1]
	v_pk_add_f32 v[68:69], v[46:47], v[54:55]
	v_pk_add_f32 v[46:47], v[46:47], v[54:55] neg_lo:[0,1] neg_hi:[0,1]
	v_pk_add_f32 v[54:55], v[48:49], v[56:57]
	v_pk_add_f32 v[48:49], v[48:49], v[56:57] neg_lo:[0,1] neg_hi:[0,1]
	v_mov_b32_e32 v99, v32
	v_xor_b32_e32 v57, 0x80000000, v48
	v_mov_b32_e32 v56, v49
	v_pk_add_f32 v[48:49], v[68:69], v[54:55]
	v_pk_add_f32 v[54:55], v[68:69], v[54:55] neg_lo:[0,1] neg_hi:[0,1]
	v_pk_add_f32 v[68:69], v[62:63], v[66:67]
	v_pk_add_f32 v[62:63], v[62:63], v[66:67] neg_lo:[0,1] neg_hi:[0,1]
	v_pk_add_f32 v[92:93], v[46:47], v[56:57]
	v_pk_add_f32 v[46:47], v[46:47], v[56:57] neg_lo:[0,1] neg_hi:[0,1]
	v_pk_add_f32 v[56:57], v[94:95], v[64:65]
	v_pk_add_f32 v[64:65], v[94:95], v[64:65] neg_lo:[0,1] neg_hi:[0,1]
	s_nop 0
	v_pk_add_f32 v[94:95], v[64:65], v[62:63] op_sel:[0,1] op_sel_hi:[1,0] neg_hi:[0,1]
	v_pk_add_f32 v[64:65], v[64:65], v[62:63] op_sel:[0,1] op_sel_hi:[1,0] neg_lo:[0,1]
	v_pk_add_f32 v[66:67], v[50:51], v[58:59]
	v_pk_add_f32 v[50:51], v[50:51], v[58:59] neg_lo:[0,1] neg_hi:[0,1]
	v_pk_add_f32 v[58:59], v[52:53], v[60:61]
	v_pk_add_f32 v[52:53], v[52:53], v[60:61] neg_lo:[0,1] neg_hi:[0,1]
	v_pk_add_f32 v[62:63], v[56:57], v[68:69]
	v_pk_add_f32 v[56:57], v[56:57], v[68:69] neg_lo:[0,1] neg_hi:[0,1]
	v_pk_add_f32 v[68:69], v[50:51], v[52:53] op_sel:[0,1] op_sel_hi:[1,0] neg_hi:[0,1]
	v_pk_add_f32 v[50:51], v[50:51], v[52:53] op_sel:[0,1] op_sel_hi:[1,0] neg_lo:[0,1]
	v_pk_add_f32 v[60:61], v[20:21], v[42:43]
	v_pk_add_f32 v[20:21], v[20:21], v[42:43] neg_lo:[0,1] neg_hi:[0,1]
	v_pk_add_f32 v[42:43], v[22:23], v[44:45]
	v_pk_add_f32 v[22:23], v[22:23], v[44:45] neg_lo:[0,1] neg_hi:[0,1]
	v_pk_add_f32 v[52:53], v[66:67], v[58:59]
	v_pk_add_f32 v[58:59], v[66:67], v[58:59] neg_lo:[0,1] neg_hi:[0,1]
	v_pk_add_f32 v[66:67], v[20:21], v[22:23] op_sel:[0,1] op_sel_hi:[1,0] neg_hi:[0,1]
	v_pk_add_f32 v[20:21], v[20:21], v[22:23] op_sel:[0,1] op_sel_hi:[1,0] neg_lo:[0,1]
	v_xor_b32_e32 v44, 0x80000000, v71
	v_mov_b32_e32 v45, v70
	v_pk_mul_f32 v[44:45], v[44:45], v[48:49] op_sel:[0,1]
	v_pk_add_f32 v[22:23], v[60:61], v[42:43]
	v_pk_fma_f32 v[44:45], v[70:71], v[48:49], v[44:45] op_sel_hi:[1,0,1]
	v_pk_mul_f32 v[48:49], v[72:73], v[62:63] op_sel:[1,1] op_sel_hi:[0,1] neg_lo:[1,0]
	v_pk_add_f32 v[42:43], v[60:61], v[42:43] neg_lo:[0,1] neg_hi:[0,1]
	v_pk_fma_f32 v[48:49], v[72:73], v[62:63], v[48:49] op_sel_hi:[1,0,1]
	ds_write2_b64 v25, v[44:45], v[48:49] offset1:17
	v_pk_mul_f32 v[44:45], v[74:75], v[52:53] op_sel:[1,1] op_sel_hi:[0,1] neg_lo:[1,0]
	v_pk_mul_f32 v[48:49], v[76:77], v[22:23] op_sel:[1,1] op_sel_hi:[0,1] neg_lo:[1,0]
	v_pk_fma_f32 v[44:45], v[74:75], v[52:53], v[44:45] op_sel_hi:[1,0,1]
	v_pk_fma_f32 v[22:23], v[76:77], v[22:23], v[48:49] op_sel_hi:[1,0,1]
	ds_write2_b64 v25, v[44:45], v[22:23] offset0:34 offset1:51
	v_pk_mul_f32 v[22:23], v[78:79], v[92:93] op_sel:[1,1] op_sel_hi:[0,1] neg_lo:[1,0]
	v_pk_mul_f32 v[44:45], v[80:81], v[94:95] op_sel:[1,1] op_sel_hi:[0,1] neg_lo:[1,0]
	v_pk_fma_f32 v[22:23], v[78:79], v[92:93], v[22:23] op_sel_hi:[1,0,1]
	v_pk_fma_f32 v[44:45], v[80:81], v[94:95], v[44:45] op_sel_hi:[1,0,1]
	ds_write2_b64 v25, v[22:23], v[44:45] offset0:68 offset1:85
	v_pk_mul_f32 v[22:23], v[82:83], v[68:69] op_sel:[1,1] op_sel_hi:[0,1] neg_lo:[1,0]
	v_pk_mul_f32 v[44:45], v[84:85], v[66:67] op_sel:[1,1] op_sel_hi:[0,1] neg_lo:[1,0]
	v_pk_fma_f32 v[22:23], v[82:83], v[68:69], v[22:23] op_sel_hi:[1,0,1]
	v_pk_fma_f32 v[44:45], v[84:85], v[66:67], v[44:45] op_sel_hi:[1,0,1]
	ds_write2_b64 v25, v[22:23], v[44:45] offset0:102 offset1:119
	v_pk_mul_f32 v[22:23], v[86:87], v[54:55] op_sel:[1,1] op_sel_hi:[0,1] neg_lo:[1,0]
	v_pk_mul_f32 v[44:45], v[88:89], v[56:57] op_sel:[1,1] op_sel_hi:[0,1] neg_lo:[1,0]
	v_pk_fma_f32 v[22:23], v[86:87], v[54:55], v[22:23] op_sel_hi:[1,0,1]
	v_pk_fma_f32 v[44:45], v[88:89], v[56:57], v[44:45] op_sel_hi:[1,0,1]
	ds_write2_b64 v25, v[22:23], v[44:45] offset0:136 offset1:153
	v_pk_mul_f32 v[22:23], v[90:91], v[58:59] op_sel:[1,1] op_sel_hi:[0,1] neg_lo:[1,0]
	v_pk_mul_f32 v[44:45], v[18:19], v[42:43] op_sel:[1,1] op_sel_hi:[0,1] neg_lo:[1,0]
	v_pk_fma_f32 v[22:23], v[90:91], v[58:59], v[22:23] op_sel_hi:[1,0,1]
	v_pk_fma_f32 v[18:19], v[18:19], v[42:43], v[44:45] op_sel_hi:[1,0,1]
	ds_write2_b64 v25, v[22:23], v[18:19] offset0:170 offset1:187
	v_pk_mul_f32 v[18:19], v[16:17], v[46:47] op_sel:[1,1] op_sel_hi:[0,1] neg_lo:[1,0]
	v_mov_b32_e32 v29, v28
	v_pk_fma_f32 v[16:17], v[16:17], v[46:47], v[18:19] op_sel_hi:[1,0,1]
	v_pk_mul_f32 v[18:19], v[14:15], v[64:65] op_sel:[1,1] op_sel_hi:[0,1] neg_lo:[1,0]
	v_mov_b32_e32 v27, v26
	v_pk_fma_f32 v[14:15], v[14:15], v[64:65], v[18:19] op_sel_hi:[1,0,1]
	ds_write2_b64 v25, v[16:17], v[14:15] offset0:204 offset1:221
	v_pk_mul_f32 v[14:15], v[10:11], v[50:51] op_sel:[1,1] op_sel_hi:[0,1] neg_lo:[1,0]
	v_mov_b32_e32 v39, v38
	v_pk_fma_f32 v[10:11], v[10:11], v[50:51], v[14:15] op_sel_hi:[1,0,1]
	v_pk_mul_f32 v[14:15], v[8:9], v[20:21] op_sel:[1,1] op_sel_hi:[0,1] neg_lo:[1,0]
	v_mov_b32_e32 v37, v36
	v_pk_fma_f32 v[8:9], v[8:9], v[20:21], v[14:15] op_sel_hi:[1,0,1]
	ds_write2_b64 v25, v[10:11], v[8:9] offset0:238 offset1:255
	s_waitcnt lgkmcnt(0)
	s_barrier
	v_mov_b32_e32 v25, v24
	v_and_b32_e32 v8, 0xff, v206
	v_mad_u32_u24 v22, v8, s19, v207
	ds_read2_b64 v[8:11], v22 offset1:1
	ds_read2_b64 v[14:17], v22 offset0:2 offset1:3
	ds_read2_b64 v[18:21], v22 offset0:8 offset1:9
	ds_read2_b64 v[42:45], v22 offset0:4 offset1:5
	ds_read2_b64 v[46:49], v22 offset0:6 offset1:7
	ds_read2_b64 v[50:53], v22 offset0:12 offset1:13
	ds_read2_b64 v[54:57], v22 offset0:10 offset1:11
	ds_read2_b64 v[58:61], v22 offset0:14 offset1:15
	s_waitcnt lgkmcnt(5)
	v_pk_add_f32 v[22:23], v[8:9], v[18:19]
	v_pk_add_f32 v[8:9], v[8:9], v[18:19] neg_lo:[0,1] neg_hi:[0,1]
	s_waitcnt lgkmcnt(2)
	v_pk_add_f32 v[18:19], v[42:43], v[50:51]
	v_pk_add_f32 v[42:43], v[42:43], v[50:51] neg_lo:[0,1] neg_hi:[0,1]
	v_mov_b32_e32 v35, v34
	v_xor_b32_e32 v51, 0x80000000, v42
	v_mov_b32_e32 v50, v43
	v_pk_add_f32 v[42:43], v[22:23], v[18:19]
	v_pk_add_f32 v[18:19], v[22:23], v[18:19] neg_lo:[0,1] neg_hi:[0,1]
	v_pk_add_f32 v[22:23], v[10:11], v[20:21]
	v_pk_add_f32 v[10:11], v[10:11], v[20:21] neg_lo:[0,1] neg_hi:[0,1]
	v_pk_add_f32 v[20:21], v[44:45], v[52:53]
	v_pk_add_f32 v[44:45], v[44:45], v[52:53] neg_lo:[0,1] neg_hi:[0,1]
	v_pk_add_f32 v[62:63], v[8:9], v[50:51]
	v_pk_add_f32 v[8:9], v[8:9], v[50:51] neg_lo:[0,1] neg_hi:[0,1]
	v_pk_add_f32 v[52:53], v[10:11], v[44:45] op_sel:[0,1] op_sel_hi:[1,0] neg_hi:[0,1]
	v_pk_add_f32 v[10:11], v[10:11], v[44:45] op_sel:[0,1] op_sel_hi:[1,0] neg_lo:[0,1]
	s_waitcnt lgkmcnt(0)
	v_pk_add_f32 v[50:51], v[46:47], v[58:59]
	v_pk_add_f32 v[46:47], v[46:47], v[58:59] neg_lo:[0,1] neg_hi:[0,1]
	v_pk_add_f32 v[44:45], v[22:23], v[20:21]
	v_pk_add_f32 v[20:21], v[22:23], v[20:21] neg_lo:[0,1] neg_hi:[0,1]
	v_pk_add_f32 v[22:23], v[14:15], v[54:55]
	v_pk_add_f32 v[14:15], v[14:15], v[54:55] neg_lo:[0,1] neg_hi:[0,1]
	v_xor_b32_e32 v55, 0x80000000, v46
	v_mov_b32_e32 v54, v47
	v_pk_add_f32 v[46:47], v[22:23], v[50:51]
	v_pk_add_f32 v[58:59], v[14:15], v[54:55]
	v_pk_add_f32 v[22:23], v[22:23], v[50:51] neg_lo:[0,1] neg_hi:[0,1]
	v_pk_add_f32 v[14:15], v[14:15], v[54:55] neg_lo:[0,1] neg_hi:[0,1]
	v_pk_add_f32 v[50:51], v[16:17], v[56:57]
	v_pk_add_f32 v[54:55], v[48:49], v[60:61]
	v_pk_add_f32 v[48:49], v[48:49], v[60:61] neg_lo:[0,1] neg_hi:[0,1]
	v_pk_add_f32 v[16:17], v[16:17], v[56:57] neg_lo:[0,1] neg_hi:[0,1]
	v_xor_b32_e32 v57, 0x80000000, v48
	v_mov_b32_e32 v56, v49
	v_pk_add_f32 v[48:49], v[50:51], v[54:55]
	v_pk_add_f32 v[50:51], v[50:51], v[54:55] neg_lo:[0,1] neg_hi:[0,1]
	v_pk_mul_f32 v[54:55], v[52:53], s[22:23] op_sel:[1,0] op_sel_hi:[0,0] neg_lo:[1,0]
	v_pk_add_f32 v[60:61], v[16:17], v[56:57]
	v_pk_fma_f32 v[52:53], v[52:53], s[36:37], v[54:55] op_sel_hi:[1,0,1] neg_lo:[0,0,1] neg_hi:[0,0,1]
	v_pk_mul_f32 v[54:55], v[20:21], s[12:13] op_sel:[1,0] op_sel_hi:[0,0] neg_lo:[1,0]
	v_pk_add_f32 v[16:17], v[16:17], v[56:57] neg_lo:[0,1] neg_hi:[0,1]
	v_pk_fma_f32 v[20:21], v[20:21], s[12:13], v[54:55] op_sel_hi:[1,0,1] neg_lo:[0,0,1] neg_hi:[0,0,1]
	v_pk_mul_f32 v[54:55], v[10:11], s[36:37] op_sel:[1,0] op_sel_hi:[0,0] neg_lo:[1,0]
	v_pk_fma_f32 v[10:11], v[10:11], s[22:23], v[54:55] op_sel_hi:[1,0,1] neg_lo:[0,0,1] neg_hi:[0,0,1]
	v_pk_mul_f32 v[54:55], v[58:59], s[12:13] op_sel:[1,0] op_sel_hi:[0,0] neg_lo:[1,0]
	v_pk_fma_f32 v[22:23], v[22:23], 0, v[22:23] op_sel:[0,0,1] op_sel_hi:[1,0,0] neg_hi:[0,0,1]
	v_pk_fma_f32 v[54:55], v[58:59], s[12:13], v[54:55] op_sel_hi:[1,0,1] neg_lo:[0,0,1] neg_hi:[0,0,1]
	v_pk_mul_f32 v[56:57], v[14:15], s[12:13] op_sel:[1,0] op_sel_hi:[0,0] neg_lo:[1,0]
	v_pk_fma_f32 v[14:15], v[14:15], s[18:19], v[56:57] op_sel_hi:[1,0,1] neg_lo:[0,0,1] neg_hi:[0,0,1]
	v_pk_mul_f32 v[58:59], v[50:51], s[12:13] op_sel:[1,0] op_sel_hi:[0,0] neg_lo:[1,0]
	v_pk_mul_f32 v[56:57], v[60:61], s[36:37] op_sel:[1,0] op_sel_hi:[0,0] neg_lo:[1,0]
	v_pk_fma_f32 v[50:51], v[50:51], s[18:19], v[58:59] op_sel_hi:[1,0,1] neg_lo:[0,0,1] neg_hi:[0,0,1]
	v_xor_b32_e32 v58, 0x80000000, v17
	v_mov_b32_e32 v59, v16
	v_pk_mul_f32 v[16:17], v[16:17], s[36:37] op_sel_hi:[1,0]
	v_pk_fma_f32 v[56:57], v[60:61], s[22:23], v[56:57] op_sel_hi:[1,0,1] neg_lo:[0,0,1] neg_hi:[0,0,1]
	v_pk_fma_f32 v[16:17], v[58:59], s[22:23], v[16:17] op_sel_hi:[1,0,1] neg_lo:[0,0,1] neg_hi:[0,0,1]
	v_pk_add_f32 v[58:59], v[42:43], v[46:47]
	v_pk_add_f32 v[42:43], v[42:43], v[46:47] neg_lo:[0,1] neg_hi:[0,1]
	v_pk_add_f32 v[46:47], v[44:45], v[48:49]
	v_pk_add_f32 v[44:45], v[44:45], v[48:49] neg_lo:[0,1] neg_hi:[0,1]
	v_mov_b32_e32 v100, v31
	v_xor_b32_e32 v49, 0x80000000, v44
	v_mov_b32_e32 v48, v45
	v_pk_add_f32 v[44:45], v[58:59], v[46:47]
	v_pk_add_f32 v[46:47], v[58:59], v[46:47] neg_lo:[0,1] neg_hi:[0,1]
	v_pk_add_f32 v[58:59], v[52:53], v[56:57]
	v_pk_add_f32 v[52:53], v[52:53], v[56:57] neg_lo:[0,1] neg_hi:[0,1]
	v_pk_add_f32 v[60:61], v[42:43], v[48:49]
	v_pk_add_f32 v[42:43], v[42:43], v[48:49] neg_lo:[0,1] neg_hi:[0,1]
	v_pk_add_f32 v[48:49], v[62:63], v[54:55]
	v_pk_add_f32 v[54:55], v[62:63], v[54:55] neg_lo:[0,1] neg_hi:[0,1]
	s_nop 0
	v_pk_add_f32 v[62:63], v[54:55], v[52:53] op_sel:[0,1] op_sel_hi:[1,0] neg_hi:[0,1]
	v_pk_add_f32 v[54:55], v[54:55], v[52:53] op_sel:[0,1] op_sel_hi:[1,0] neg_lo:[0,1]
	v_pk_add_f32 v[56:57], v[18:19], v[22:23]
	v_pk_add_f32 v[18:19], v[18:19], v[22:23] neg_lo:[0,1] neg_hi:[0,1]
	v_pk_add_f32 v[22:23], v[20:21], v[50:51]
	v_pk_add_f32 v[20:21], v[20:21], v[50:51] neg_lo:[0,1] neg_hi:[0,1]
	v_pk_add_f32 v[52:53], v[48:49], v[58:59]
	v_xor_b32_e32 v51, 0x80000000, v20
	v_mul_f32_e32 v20, 0x4b800000, v13
	v_cndmask_b32_e32 v13, v13, v20, vcc
	v_rsq_f32_e32 v13, v13
	v_mov_b32_e32 v50, v21
	v_pk_add_f32 v[64:65], v[18:19], v[50:51]
	v_pk_add_f32 v[66:67], v[18:19], v[50:51] neg_lo:[0,1] neg_hi:[0,1]
	v_pk_add_f32 v[18:19], v[8:9], v[14:15]
	v_pk_add_f32 v[8:9], v[8:9], v[14:15] neg_lo:[0,1] neg_hi:[0,1]
	v_pk_add_f32 v[14:15], v[10:11], v[16:17]
	v_pk_add_f32 v[10:11], v[10:11], v[16:17] neg_lo:[0,1] neg_hi:[0,1]
	v_pk_add_f32 v[48:49], v[48:49], v[58:59] neg_lo:[0,1] neg_hi:[0,1]
	v_pk_add_f32 v[68:69], v[8:9], v[10:11] op_sel:[0,1] op_sel_hi:[1,0] neg_hi:[0,1]
	v_pk_add_f32 v[8:9], v[8:9], v[10:11] op_sel:[0,1] op_sel_hi:[1,0] neg_lo:[0,1]
	v_mul_f32_e32 v16, 0x45800000, v13
	v_cndmask_b32_e32 v13, v13, v16, vcc
	v_pk_add_f32 v[58:59], v[56:57], v[22:23]
	v_pk_add_f32 v[56:57], v[56:57], v[22:23] neg_lo:[0,1] neg_hi:[0,1]
	v_pk_add_f32 v[10:11], v[18:19], v[14:15]
	v_pk_add_f32 v[14:15], v[18:19], v[14:15] neg_lo:[0,1] neg_hi:[0,1]
	s_waitcnt vmcnt(0)
	v_pk_mul_f32 v[12:13], v[12:13], s[2:3] op_sel_hi:[1,0]
	v_mov_b32_e32 v101, v31
	v_pk_fma_f32 v[16:17], v[12:13], v[44:45], v[12:13] op_sel:[1,0,0] op_sel_hi:[0,1,1]
	v_pk_mul_f32 v[70:71], v[12:13], v[44:45]
	v_pk_fma_f32 v[18:19], v[12:13], v[60:61], v[12:13] op_sel:[1,0,0] op_sel_hi:[0,1,1]
	v_pk_mul_f32 v[72:73], v[12:13], v[60:61]
	v_pk_fma_f32 v[20:21], v[12:13], v[46:47], v[12:13] op_sel:[1,0,0] op_sel_hi:[0,1,1]
	v_pk_mul_f32 v[74:75], v[12:13], v[46:47]
	v_pk_fma_f32 v[22:23], v[12:13], v[42:43], v[12:13] op_sel:[1,0,0] op_sel_hi:[0,1,1]
	v_pk_mul_f32 v[76:77], v[12:13], v[42:43]
	v_pk_fma_f32 v[42:43], v[12:13], v[52:53], v[12:13] op_sel:[1,0,0] op_sel_hi:[0,1,1]
	v_pk_mul_f32 v[78:79], v[12:13], v[52:53]
	v_pk_fma_f32 v[44:45], v[12:13], v[62:63], v[12:13] op_sel:[1,0,0] op_sel_hi:[0,1,1]
	v_pk_mul_f32 v[80:81], v[12:13], v[62:63]
	v_pk_fma_f32 v[46:47], v[12:13], v[48:49], v[12:13] op_sel:[1,0,0] op_sel_hi:[0,1,1]
	v_pk_mul_f32 v[82:83], v[12:13], v[48:49]
	v_pk_fma_f32 v[48:49], v[12:13], v[54:55], v[12:13] op_sel:[1,0,0] op_sel_hi:[0,1,1]
	v_pk_mul_f32 v[84:85], v[12:13], v[54:55]
	v_pk_fma_f32 v[50:51], v[12:13], v[58:59], v[12:13] op_sel:[1,0,0] op_sel_hi:[0,1,1]
	v_pk_mul_f32 v[86:87], v[12:13], v[58:59]
	v_pk_fma_f32 v[52:53], v[12:13], v[64:65], v[12:13] op_sel:[1,0,0] op_sel_hi:[0,1,1]
	v_pk_mul_f32 v[88:89], v[12:13], v[64:65]
	v_pk_fma_f32 v[54:55], v[12:13], v[56:57], v[12:13] op_sel:[1,0,0] op_sel_hi:[0,1,1]
	v_pk_mul_f32 v[90:91], v[12:13], v[56:57]
	v_pk_fma_f32 v[56:57], v[12:13], v[66:67], v[12:13] op_sel:[1,0,0] op_sel_hi:[0,1,1]
	v_pk_mul_f32 v[92:93], v[12:13], v[66:67]
	v_pk_fma_f32 v[58:59], v[12:13], v[10:11], v[12:13] op_sel:[1,0,0] op_sel_hi:[0,1,1]
	v_pk_mul_f32 v[10:11], v[12:13], v[10:11]
	v_pk_fma_f32 v[60:61], v[12:13], v[68:69], v[12:13] op_sel:[1,0,0] op_sel_hi:[0,1,1]
	v_pk_mul_f32 v[94:95], v[12:13], v[68:69]
	v_pk_fma_f32 v[62:63], v[12:13], v[14:15], v[12:13] op_sel:[1,0,0] op_sel_hi:[0,1,1]
	v_pk_mul_f32 v[14:15], v[12:13], v[14:15]
	v_pk_fma_f32 v[64:65], v[12:13], v[8:9], v[12:13] op_sel:[1,0,0] op_sel_hi:[0,1,1]
	v_pk_mul_f32 v[8:9], v[12:13], v[8:9]
	v_mov_b32_e32 v17, v71
	v_mov_b32_e32 v19, v73
	v_mov_b32_e32 v21, v75
	v_mov_b32_e32 v23, v77
	v_mov_b32_e32 v43, v79
	v_mov_b32_e32 v45, v81
	v_mov_b32_e32 v47, v83
	v_mov_b32_e32 v49, v85
	v_mov_b32_e32 v51, v87
	v_mov_b32_e32 v53, v89
	v_mov_b32_e32 v55, v91
	v_mov_b32_e32 v57, v93
	v_mov_b32_e32 v59, v11
	v_mov_b32_e32 v61, v95
	v_mov_b32_e32 v63, v15
	v_mov_b32_e32 v65, v9
	v_xor_b32_e32 v66, 0x80000000, v71
	v_mov_b32_e32 v67, v16
	v_xor_b32_e32 v68, 0x80000000, v73
	v_mov_b32_e32 v69, v18
	v_xor_b32_e32 v70, 0x80000000, v75
	v_mov_b32_e32 v71, v20
	v_xor_b32_e32 v72, 0x80000000, v77
	v_mov_b32_e32 v73, v22
	v_xor_b32_e32 v74, 0x80000000, v79
	v_mov_b32_e32 v75, v42
	v_xor_b32_e32 v76, 0x80000000, v81
	v_mov_b32_e32 v77, v44
	v_xor_b32_e32 v78, 0x80000000, v83
	v_mov_b32_e32 v79, v46
	v_xor_b32_e32 v80, 0x80000000, v85
	v_mov_b32_e32 v81, v48
	v_xor_b32_e32 v82, 0x80000000, v87
	v_mov_b32_e32 v83, v50
	v_xor_b32_e32 v84, 0x80000000, v89
	v_mov_b32_e32 v85, v52
	v_xor_b32_e32 v86, 0x80000000, v91
	v_mov_b32_e32 v87, v54
	v_xor_b32_e32 v88, 0x80000000, v93
	v_mov_b32_e32 v89, v56
	v_xor_b32_e32 v90, 0x80000000, v11
	v_mov_b32_e32 v91, v58
	v_xor_b32_e32 v92, 0x80000000, v95
	v_mov_b32_e32 v93, v60
	v_xor_b32_e32 v94, 0x80000000, v15
	v_mov_b32_e32 v95, v62
	v_xor_b32_e32 v96, 0x80000000, v9
	v_mov_b32_e32 v97, v64
	v_mov_b32_e32 v102, v30
	v_mov_b32_e32 v103, v30
	s_addc_u32 s46, s65, s43
	s_mov_b64 s[42:43], 0
	s_movk_i32 s47, 0x2000
	s_barrier
.LBB0_209:
	s_waitcnt vmcnt(5)
	v_lshlrev_b32_e32 v10, 16, v143
	v_and_b32_e32 v121, 0x1ff, v212
	v_cmp_eq_u32_e32 vcc, 0, v121
	v_and_b32_e32 v12, 0xffff0000, v4
	v_lshlrev_b32_e32 v13, 16, v4
	v_cndmask_b32_e64 v10, v10, 0, vcc
	v_pk_mul_f32 v[14:15], v[32:33], v[12:13]
	v_mov_b32_e32 v105, v13
	v_fma_f32 v4, v41, v10, v15
	v_add_f32_e32 v4, v14, v4
	v_add_f32_e32 v14, v219, v4
	v_and_b32_e32 v4, 0xffff0000, v5
	v_lshlrev_b32_e32 v5, 16, v5
	v_mov_b32_e32 v104, v5
	v_pk_mul_f32 v[104:105], v[40:41], v[104:105]
	v_pk_mul_f32 v[106:107], v[32:33], v[4:5]
	v_fma_f32 v10, v33, v12, v105
	v_add_f32_e32 v10, v104, v10
	v_add_f32_e32 v104, v219, v10
	v_fma_f32 v10, v41, v12, v107
	v_lshlrev_b32_e32 v107, 16, v6
	v_mov_b32_e32 v108, v107
	v_mov_b32_e32 v109, v5
	v_add_f32_e32 v10, v106, v10
	v_and_b32_e32 v106, 0xffff0000, v6
	v_pk_mul_f32 v[108:109], v[40:41], v[108:109]
	v_pk_mul_f32 v[110:111], v[32:33], v[106:107]
	v_fma_f32 v5, v33, v4, v109
	v_add_f32_e32 v5, v108, v5
	v_fma_f32 v4, v41, v4, v111
	v_add_f32_e32 v108, v219, v5
	v_add_f32_e32 v4, v110, v4
	v_lshlrev_b32_e32 v5, 16, v7
	v_add_f32_e32 v110, v219, v4
	v_and_b32_e32 v4, 0xffff0000, v7
	v_mov_b32_e32 v6, v5
	v_mov_b32_e32 v7, v107
	v_pk_mul_f32 v[6:7], v[40:41], v[6:7]
	s_waitcnt vmcnt(4)
	v_lshlrev_b32_e32 v11, 16, v142
	v_fma_f32 v7, v33, v106, v7
	v_add_f32_e32 v6, v6, v7
	v_add_f32_e32 v112, v219, v6
	v_pk_mul_f32 v[6:7], v[32:33], v[4:5]
	v_cmp_eq_u32_e64 s[0:1], s37, v121
	v_fma_f32 v7, v41, v106, v7
	v_add_f32_e32 v12, v219, v10
	v_cndmask_b32_e64 v11, v11, 0, s[0:1]
	v_add_f32_e32 v6, v6, v7
	v_mov_b32_e32 v10, v5
	v_add_f32_e32 v106, v219, v6
	v_pk_mul_f32 v[6:7], v[98:99], v[10:11]
	s_waitcnt vmcnt(2)
	v_lshlrev_b32_e32 v5, 16, v140
	v_fma_f32 v4, v33, v4, v6
	v_add_f32_e32 v4, v4, v7
	v_add_f32_e32 v10, v219, v4
	v_lshlrev_b32_e32 v4, 16, v141
	v_and_b32_e32 v6, 0xffff0000, v0
	v_lshlrev_b32_e32 v7, 16, v0
	v_cndmask_b32_e64 v4, v4, 0, vcc
	v_pk_mul_f32 v[114:115], v[32:33], v[6:7]
	v_mov_b32_e32 v117, v7
	v_fma_f32 v0, v41, v4, v115
	v_add_f32_e32 v0, v114, v0
	v_add_f32_e32 v114, v219, v0
	v_and_b32_e32 v0, 0xffff0000, v1
	v_lshlrev_b32_e32 v1, 16, v1
	v_mov_b32_e32 v116, v1
	v_pk_mul_f32 v[116:117], v[40:41], v[116:117]
	v_lshlrev_b32_e32 v7, 16, v2
	v_fma_f32 v4, v33, v6, v117
	v_mov_b32_e32 v118, v7
	v_mov_b32_e32 v119, v1
	v_add_f32_e32 v4, v116, v4
	v_pk_mul_f32 v[116:117], v[32:33], v[0:1]
	v_pk_mul_f32 v[118:119], v[40:41], v[118:119]
	v_add_f32_e32 v105, v219, v4
	v_fma_f32 v4, v41, v6, v117
	v_and_b32_e32 v6, 0xffff0000, v2
	v_fma_f32 v1, v33, v0, v119
	v_add_f32_e32 v1, v118, v1
	v_pk_mul_f32 v[118:119], v[32:33], v[6:7]
	v_add_f32_e32 v109, v219, v1
	v_fma_f32 v0, v41, v0, v119
	v_add_f32_e32 v0, v118, v0
	v_lshlrev_b32_e32 v1, 16, v3
	v_add_f32_e32 v118, v219, v0
	v_and_b32_e32 v0, 0xffff0000, v3
	v_mov_b32_e32 v2, v1
	v_mov_b32_e32 v3, v7
	v_pk_mul_f32 v[2:3], v[40:41], v[2:3]
	v_add_f32_e32 v4, v116, v4
	v_fma_f32 v3, v33, v6, v3
	v_add_f32_e32 v2, v2, v3
	v_add_f32_e32 v113, v219, v2
	v_pk_mul_f32 v[2:3], v[32:33], v[0:1]
	v_cndmask_b32_e64 v5, v5, 0, s[0:1]
	v_fma_f32 v3, v41, v6, v3
	v_add_f32_e32 v116, v219, v4
	v_add_f32_e32 v2, v2, v3
	v_mov_b32_e32 v4, v1
	v_add_f32_e32 v120, v219, v2
	v_pk_mul_f32 v[2:3], v[98:99], v[4:5]
	v_lshlrev_b32_e32 v122, 3, v121
	v_fma_f32 v0, v33, v0, v2
	v_add_f32_e32 v0, v0, v3
	v_add_f32_e32 v11, v219, v0
	v_add_u32_e32 v0, -1, v122
	v_cndmask_b32_e64 v176, v0, 0, vcc
	v_add_u32_e32 v0, 8, v122
	s_add_u32 s44, s28, s42
	v_cndmask_b32_e64 v13, v0, v229, s[0:1]
	v_lshlrev_b32_e32 v0, 4, v121
	v_mov_b32_e32 v1, v177
	s_addc_u32 s45, s29, s43
	v_bfe_u32 v8, v212, 1, 8
	v_lshl_add_u64 v[0:1], s[44:45], 0, v[0:1]
	v_add_u32_e32 v126, v122, v8
	v_mov_b32_e32 v9, v214
	v_mov_b32_e32 v8, v213
	v_add_co_u32_e32 v2, vcc, s5, v0
	v_lshl_add_u32 v117, v126, 3, 0
	s_nop 0
	v_addc_co_u32_e32 v3, vcc, 0, v1, vcc
	v_xor_b32_e32 v126, 0x80000000, v9
	v_mov_b32_e32 v127, v8
	s_mov_b32 s9, s30
	v_add_co_u32_e32 v4, vcc, s27, v0
	v_pk_mul_f32 v[126:127], v[126:127], v[114:115] op_sel_hi:[1,0]
	v_pk_mul_f32 v[128:129], v[214:215], s[8:9] op_sel_hi:[0,1]
	v_addc_co_u32_e32 v5, vcc, 0, v1, vcc
	v_pk_fma_f32 v[126:127], v[8:9], v[14:15], v[126:127] op_sel_hi:[1,0,1]
	v_pk_fma_f32 v[8:9], v[212:213], s[30:31], v[128:129] op_sel:[1,0,0]
	v_mov_b32_e32 v15, v114
	global_load_dwordx4 v[0:3], v[2:3], off
	s_nop 0
	global_load_dwordx4 v[4:7], v[4:5], off
	ds_write2_b64 v117, v[14:15], v[104:105] offset1:1
	v_pk_mul_f32 v[14:15], v[104:105], v[8:9] op_sel:[1,1] op_sel_hi:[1,0] neg_lo:[0,1]
	v_lshl_add_u64 v[122:123], v[176:177], 1, s[44:45]
	v_lshlrev_b32_e32 v176, 1, v13
	v_add_u32_e32 v13, 0x8800, v117
	v_pk_fma_f32 v[14:15], v[8:9], v[104:105], v[14:15] op_sel_hi:[1,0,1]
	ds_write2_b64 v13, v[126:127], v[14:15] offset1:1
	v_pk_mul_f32 v[14:15], v[8:9], s[8:9] op_sel:[1,0]
	v_add_u32_e32 v107, 0x8810, v117
	v_pk_fma_f32 v[8:9], v[8:9], s[30:31], v[14:15] op_sel_hi:[0,1,1]
	v_pk_mul_f32 v[14:15], v[116:117], v[8:9] op_sel:[0,1] op_sel_hi:[0,0] neg_lo:[0,1]
	v_pk_mul_f32 v[104:105], v[8:9], s[8:9] op_sel:[1,0]
	v_pk_fma_f32 v[14:15], v[12:13], v[8:9], v[14:15] op_sel_hi:[0,1,1]
	v_pk_fma_f32 v[8:9], v[8:9], s[30:31], v[104:105] op_sel_hi:[0,1,1]
	v_mov_b32_e32 v13, v116
	ds_write2_b64 v117, v[12:13], v[108:109] offset0:2 offset1:3
	v_pk_mul_f32 v[12:13], v[108:109], v[8:9] op_sel:[1,1] op_sel_hi:[1,0] neg_lo:[0,1]
	s_nop 0
	v_pk_fma_f32 v[12:13], v[108:109], v[8:9], v[12:13] op_sel_hi:[0,1,1]
	ds_write2_b64 v107, v[14:15], v[12:13] offset1:1
	v_pk_mul_f32 v[12:13], v[8:9], s[8:9] op_sel:[1,0]
	v_add_u32_e32 v107, 0x8820, v117
	v_pk_fma_f32 v[8:9], v[8:9], s[30:31], v[12:13] op_sel_hi:[0,1,1]
	v_pk_mul_f32 v[12:13], v[118:119], v[8:9] op_sel:[0,1] op_sel_hi:[0,0] neg_lo:[0,1]
	v_pk_mul_f32 v[14:15], v[8:9], s[8:9] op_sel:[1,0]
	v_pk_fma_f32 v[12:13], v[110:111], v[8:9], v[12:13] op_sel_hi:[0,1,1]
	v_pk_fma_f32 v[8:9], v[8:9], s[30:31], v[14:15] op_sel_hi:[0,1,1]
	v_pk_mul_f32 v[14:15], v[112:113], v[8:9] op_sel:[1,1] op_sel_hi:[1,0] neg_lo:[0,1]
	s_nop 0
	v_pk_fma_f32 v[14:15], v[112:113], v[8:9], v[14:15] op_sel_hi:[0,1,1]
	ds_write2_b64 v107, v[12:13], v[14:15] offset1:1
	v_pk_mul_f32 v[12:13], v[8:9], s[8:9] op_sel:[1,0]
	v_add_u32_e32 v108, 0x8830, v117
	v_pk_fma_f32 v[8:9], v[8:9], s[30:31], v[12:13] op_sel_hi:[0,1,1]
	v_pk_mul_f32 v[12:13], v[120:121], v[8:9] op_sel:[0,1] op_sel_hi:[0,0] neg_lo:[0,1]
	v_pk_mul_f32 v[14:15], v[8:9], s[8:9] op_sel:[1,0]
	v_pk_fma_f32 v[12:13], v[106:107], v[8:9], v[12:13] op_sel_hi:[0,1,1]
	v_pk_fma_f32 v[8:9], v[8:9], s[30:31], v[14:15] op_sel_hi:[0,1,1]
	v_pk_mul_f32 v[14:15], v[10:11], v[8:9] op_sel:[1,1] op_sel_hi:[1,0] neg_lo:[0,1]
	s_nop 0
	v_pk_fma_f32 v[8:9], v[10:11], v[8:9], v[14:15] op_sel_hi:[0,1,1]
	ds_write2_b64 v108, v[12:13], v[8:9] offset1:1
	v_add_co_u32_e32 v8, vcc, s27, v122
	v_mov_b32_e32 v107, v120
	s_nop 0
	v_addc_co_u32_e32 v9, vcc, 0, v123, vcc
	ds_write2_b64 v117, v[106:107], v[10:11] offset0:6 offset1:7
	v_add_co_u32_e32 v10, vcc, s5, v122
	v_lshl_add_u64 v[124:125], s[44:45], 0, v[176:177]
	s_nop 0
	v_addc_co_u32_e32 v11, vcc, 0, v123, vcc
	v_add_co_u32_e32 v12, vcc, s27, v124
	v_mov_b32_e32 v111, v118
	s_nop 0
	v_addc_co_u32_e32 v13, vcc, 0, v125, vcc
	ds_write2_b64 v117, v[110:111], v[112:113] offset0:4 offset1:5
	v_add_co_u32_e32 v14, vcc, s5, v124
	v_mov_b32_e32 v110, 1.0
	s_nop 0
	v_addc_co_u32_e32 v15, vcc, 0, v125, vcc
	global_load_ushort v162, v[8:9], off
	global_load_ushort v163, v[10:11], off
	global_load_ushort v160, v[12:13], off
	global_load_ushort v161, v[14:15], off
	v_mov_b32_e32 v111, v177
	v_pk_mul_f32 v[10:11], v[208:209], v[208:209] op_sel:[1,1] op_sel_hi:[0,1] neg_lo:[1,0]
	s_waitcnt lgkmcnt(0)
	v_pk_fma_f32 v[10:11], v[208:209], v[208:209], v[10:11] op_sel_hi:[0,1,1]
	v_pk_mul_f32 v[104:105], v[10:11], v[10:11] op_sel:[1,1] op_sel_hi:[1,0] neg_lo:[0,1]
	v_pk_mul_f32 v[12:13], v[208:209], v[176:177] op_sel:[1,1] op_sel_hi:[0,1] neg_lo:[1,0]
	v_pk_fma_f32 v[104:105], v[10:11], v[10:11], v[104:105] op_sel_hi:[1,0,1]
	v_pk_fma_f32 v[114:115], v[208:209], v[110:111], v[12:13] op_sel_hi:[1,0,1]
	v_pk_mul_f32 v[8:9], v[176:177], v[10:11] op_sel:[1,1] op_sel_hi:[1,0] neg_lo:[0,1]
	s_nop 0
	v_pk_fma_f32 v[116:117], v[110:111], v[10:11], v[8:9] op_sel_hi:[0,1,1]
	v_pk_mul_f32 v[8:9], v[114:115], v[10:11] op_sel:[1,1] op_sel_hi:[1,0] neg_lo:[0,1]
	v_pk_mul_f32 v[108:109], v[104:105], v[104:105] op_sel:[1,1] op_sel_hi:[1,0] neg_lo:[0,1]
	v_pk_fma_f32 v[118:119], v[10:11], v[114:115], v[8:9] op_sel_hi:[1,0,1]
	v_pk_mul_f32 v[8:9], v[176:177], v[104:105] op_sel:[1,1] op_sel_hi:[1,0] neg_lo:[0,1]
	s_nop 0
	v_pk_fma_f32 v[120:121], v[110:111], v[104:105], v[8:9] op_sel_hi:[0,1,1]
	v_pk_mul_f32 v[8:9], v[114:115], v[104:105] op_sel:[1,1] op_sel_hi:[1,0] neg_lo:[0,1]
	s_barrier
	v_pk_fma_f32 v[122:123], v[114:115], v[104:105], v[8:9] op_sel_hi:[0,1,1]
	v_pk_mul_f32 v[8:9], v[116:117], v[104:105] op_sel:[1,1] op_sel_hi:[1,0] neg_lo:[0,1]
	s_nop 0
	v_pk_fma_f32 v[124:125], v[104:105], v[116:117], v[8:9] op_sel_hi:[1,0,1]
	v_pk_mul_f32 v[8:9], v[118:119], v[104:105] op_sel:[1,1] op_sel_hi:[1,0] neg_lo:[0,1]
	s_nop 0
	v_pk_fma_f32 v[126:127], v[104:105], v[118:119], v[8:9] op_sel_hi:[1,0,1]
	v_pk_fma_f32 v[8:9], v[104:105], v[104:105], v[108:109] op_sel_hi:[1,0,1]
	s_nop 0
	v_pk_mul_f32 v[10:11], v[176:177], v[8:9] op_sel:[1,1] op_sel_hi:[1,0] neg_lo:[0,1]
	s_nop 0
	v_pk_fma_f32 v[112:113], v[110:111], v[8:9], v[10:11] op_sel_hi:[0,1,1]
	v_pk_mul_f32 v[10:11], v[114:115], v[8:9] op_sel:[1,1] op_sel_hi:[1,0] neg_lo:[0,1]
	s_nop 0
	v_pk_fma_f32 v[108:109], v[114:115], v[8:9], v[10:11] op_sel_hi:[0,1,1]
	v_pk_mul_f32 v[10:11], v[116:117], v[8:9] op_sel:[1,1] op_sel_hi:[1,0] neg_lo:[0,1]
	s_nop 0
	v_pk_fma_f32 v[106:107], v[116:117], v[8:9], v[10:11] op_sel_hi:[0,1,1]
	v_pk_mul_f32 v[10:11], v[118:119], v[8:9] op_sel:[1,1] op_sel_hi:[1,0] neg_lo:[0,1]
	s_nop 0
	v_pk_fma_f32 v[104:105], v[118:119], v[8:9], v[10:11] op_sel_hi:[0,1,1]
	v_pk_mul_f32 v[10:11], v[120:121], v[8:9] op_sel:[1,1] op_sel_hi:[1,0] neg_lo:[0,1]
	s_nop 0
	v_pk_fma_f32 v[14:15], v[8:9], v[120:121], v[10:11] op_sel_hi:[1,0,1]
	v_pk_mul_f32 v[10:11], v[122:123], v[8:9] op_sel:[1,1] op_sel_hi:[1,0] neg_lo:[0,1]
	s_nop 0
	v_pk_fma_f32 v[12:13], v[8:9], v[122:123], v[10:11] op_sel_hi:[1,0,1]
	v_pk_mul_f32 v[10:11], v[124:125], v[8:9] op_sel:[1,1] op_sel_hi:[1,0] neg_lo:[0,1]
	v_pk_mul_f32 v[128:129], v[126:127], v[8:9] op_sel:[1,1] op_sel_hi:[1,0] neg_lo:[0,1]
	v_pk_fma_f32 v[10:11], v[8:9], v[124:125], v[10:11] op_sel_hi:[1,0,1]
	v_pk_fma_f32 v[8:9], v[8:9], v[126:127], v[128:129] op_sel_hi:[1,0,1]
	v_mov_b32_e32 v128, v206
	s_nop 0
	v_lshlrev_b32_sdwa v129, v228, v128 dst_sel:DWORD dst_unused:UNUSED_PAD src0_sel:DWORD src1_sel:BYTE_0
	v_lshrrev_b32_e32 v128, 1, v206
	v_and_b32_e32 v128, 0x78, v128
	v_add3_u32 v168, v207, v129, v128
	ds_read_b64 v[128:129], v168
	ds_read_b64 v[130:131], v168 offset:2176
	ds_read_b64 v[132:133], v168 offset:4352
	ds_read_b64 v[134:135], v168 offset:6528
	ds_read_b64 v[136:137], v168 offset:8704
	ds_read_b64 v[138:139], v168 offset:10880
	ds_read_b64 v[140:141], v168 offset:13056
	ds_read_b64 v[142:143], v168 offset:15232
	ds_read_b64 v[144:145], v168 offset:17408
	ds_read_b64 v[146:147], v168 offset:19584
	ds_read_b64 v[148:149], v168 offset:21760
	ds_read_b64 v[150:151], v168 offset:23936
	ds_read_b64 v[152:153], v168 offset:26112
	ds_read_b64 v[154:155], v168 offset:28288
	ds_read_b64 v[156:157], v168 offset:30464
	ds_read_b64 v[158:159], v168 offset:32640
	s_waitcnt lgkmcnt(7)
	v_pk_add_f32 v[164:165], v[128:129], v[144:145]
	v_pk_add_f32 v[128:129], v[128:129], v[144:145] neg_lo:[0,1] neg_hi:[0,1]
	s_waitcnt lgkmcnt(3)
	v_pk_add_f32 v[144:145], v[136:137], v[152:153]
	v_pk_add_f32 v[136:137], v[136:137], v[152:153] neg_lo:[0,1] neg_hi:[0,1]
	s_nop 0
	v_pk_add_f32 v[166:167], v[128:129], v[136:137] op_sel:[0,1] op_sel_hi:[1,0] neg_hi:[0,1]
	v_pk_add_f32 v[128:129], v[128:129], v[136:137] op_sel:[0,1] op_sel_hi:[1,0] neg_lo:[0,1]
	v_pk_add_f32 v[152:153], v[130:131], v[146:147]
	v_pk_add_f32 v[130:131], v[130:131], v[146:147] neg_lo:[0,1] neg_hi:[0,1]
	s_waitcnt lgkmcnt(2)
	v_pk_add_f32 v[146:147], v[138:139], v[154:155]
	v_pk_add_f32 v[138:139], v[138:139], v[154:155] neg_lo:[0,1] neg_hi:[0,1]
	v_pk_add_f32 v[136:137], v[164:165], v[144:145]
	v_xor_b32_e32 v155, 0x80000000, v138
	v_mov_b32_e32 v154, v139
	v_pk_add_f32 v[138:139], v[152:153], v[146:147]
	v_pk_add_f32 v[146:147], v[152:153], v[146:147] neg_lo:[0,1] neg_hi:[0,1]
	v_pk_add_f32 v[152:153], v[132:133], v[148:149]
	v_pk_add_f32 v[132:133], v[132:133], v[148:149] neg_lo:[0,1] neg_hi:[0,1]
	s_waitcnt lgkmcnt(1)
	v_pk_add_f32 v[148:149], v[140:141], v[156:157]
	v_pk_add_f32 v[140:141], v[140:141], v[156:157] neg_lo:[0,1] neg_hi:[0,1]
	v_pk_add_f32 v[144:145], v[164:165], v[144:145] neg_lo:[0,1] neg_hi:[0,1]
	v_pk_add_f32 v[164:165], v[130:131], v[154:155]
	v_pk_add_f32 v[130:131], v[130:131], v[154:155] neg_lo:[0,1] neg_hi:[0,1]
	v_xor_b32_e32 v155, 0x80000000, v140
	v_mov_b32_e32 v154, v141
	v_pk_add_f32 v[140:141], v[152:153], v[148:149]
	v_pk_add_f32 v[148:149], v[152:153], v[148:149] neg_lo:[0,1] neg_hi:[0,1]
	v_pk_add_f32 v[152:153], v[134:135], v[150:151]
	v_pk_add_f32 v[134:135], v[134:135], v[150:151] neg_lo:[0,1] neg_hi:[0,1]
	s_waitcnt lgkmcnt(0)
	v_pk_add_f32 v[150:151], v[142:143], v[158:159]
	v_pk_add_f32 v[142:143], v[142:143], v[158:159] neg_lo:[0,1] neg_hi:[0,1]
	v_pk_add_f32 v[156:157], v[132:133], v[154:155]
	v_pk_add_f32 v[132:133], v[132:133], v[154:155] neg_lo:[0,1] neg_hi:[0,1]
	v_pk_add_f32 v[158:159], v[134:135], v[142:143] op_sel:[0,1] op_sel_hi:[1,0] neg_hi:[0,1]
	v_pk_add_f32 v[134:135], v[134:135], v[142:143] op_sel:[0,1] op_sel_hi:[1,0] neg_lo:[0,1]
	v_pk_mul_f32 v[154:155], v[146:147], s[12:13] op_sel:[1,0] op_sel_hi:[0,0] neg_lo:[1,0]
	v_pk_add_f32 v[142:143], v[152:153], v[150:151]
	v_pk_fma_f32 v[146:147], v[146:147], s[12:13], v[154:155] op_sel_hi:[1,0,1] neg_lo:[0,0,1] neg_hi:[0,0,1]
	v_pk_mul_f32 v[154:155], v[130:131], s[36:37] op_sel:[1,0] op_sel_hi:[0,0] neg_lo:[1,0]
	v_pk_add_f32 v[150:151], v[152:153], v[150:151] neg_lo:[0,1] neg_hi:[0,1]
	v_pk_fma_f32 v[130:131], v[130:131], s[22:23], v[154:155] op_sel_hi:[1,0,1] neg_lo:[0,0,1] neg_hi:[0,0,1]
	v_pk_mul_f32 v[154:155], v[156:157], s[12:13] op_sel:[1,0] op_sel_hi:[0,0] neg_lo:[1,0]
	v_pk_fma_f32 v[154:155], v[156:157], s[12:13], v[154:155] op_sel_hi:[1,0,1] neg_lo:[0,0,1] neg_hi:[0,0,1]
	v_pk_fma_f32 v[148:149], v[148:149], 0, v[148:149] op_sel:[0,0,1] op_sel_hi:[1,0,0] neg_hi:[0,0,1]
	v_pk_mul_f32 v[156:157], v[132:133], s[12:13] op_sel:[1,0] op_sel_hi:[0,0] neg_lo:[1,0]
	v_pk_fma_f32 v[132:133], v[132:133], s[18:19], v[156:157] op_sel_hi:[1,0,1] neg_lo:[0,0,1] neg_hi:[0,0,1]
	v_pk_mul_f32 v[156:157], v[158:159], s[36:37] op_sel:[1,0] op_sel_hi:[0,0] neg_lo:[1,0]
	v_pk_mul_f32 v[152:153], v[164:165], s[22:23] op_sel:[1,0] op_sel_hi:[0,0] neg_lo:[1,0]
	v_pk_fma_f32 v[156:157], v[158:159], s[22:23], v[156:157] op_sel_hi:[1,0,1] neg_lo:[0,0,1] neg_hi:[0,0,1]
	v_pk_mul_f32 v[158:159], v[150:151], s[12:13] op_sel:[1,0] op_sel_hi:[0,0] neg_lo:[1,0]
	v_pk_fma_f32 v[152:153], v[164:165], s[36:37], v[152:153] op_sel_hi:[1,0,1] neg_lo:[0,0,1] neg_hi:[0,0,1]
	v_pk_fma_f32 v[150:151], v[150:151], s[18:19], v[158:159] op_sel_hi:[1,0,1] neg_lo:[0,0,1] neg_hi:[0,0,1]
	v_xor_b32_e32 v158, 0x80000000, v135
	v_mov_b32_e32 v159, v134
	v_pk_mul_f32 v[134:135], v[134:135], s[36:37] op_sel_hi:[1,0]
	s_nop 0
	v_pk_fma_f32 v[134:135], v[158:159], s[22:23], v[134:135] op_sel_hi:[1,0,1] neg_lo:[0,0,1] neg_hi:[0,0,1]
	v_pk_add_f32 v[158:159], v[136:137], v[140:141]
	v_pk_add_f32 v[136:137], v[136:137], v[140:141] neg_lo:[0,1] neg_hi:[0,1]
	v_pk_add_f32 v[140:141], v[138:139], v[142:143]
	v_pk_add_f32 v[138:139], v[138:139], v[142:143] neg_lo:[0,1] neg_hi:[0,1]
	s_nop 0
	v_xor_b32_e32 v143, 0x80000000, v138
	v_mov_b32_e32 v142, v139
	v_pk_add_f32 v[138:139], v[158:159], v[140:141]
	v_pk_add_f32 v[140:141], v[158:159], v[140:141] neg_lo:[0,1] neg_hi:[0,1]
	v_pk_add_f32 v[158:159], v[152:153], v[156:157]
	v_pk_add_f32 v[152:153], v[152:153], v[156:157] neg_lo:[0,1] neg_hi:[0,1]
	v_pk_add_f32 v[164:165], v[136:137], v[142:143]
	v_pk_add_f32 v[136:137], v[136:137], v[142:143] neg_lo:[0,1] neg_hi:[0,1]
	v_pk_add_f32 v[142:143], v[166:167], v[154:155]
	v_pk_add_f32 v[154:155], v[166:167], v[154:155] neg_lo:[0,1] neg_hi:[0,1]
	s_nop 0
	v_pk_add_f32 v[166:167], v[154:155], v[152:153] op_sel:[0,1] op_sel_hi:[1,0] neg_hi:[0,1]
	v_pk_add_f32 v[154:155], v[154:155], v[152:153] op_sel:[0,1] op_sel_hi:[1,0] neg_lo:[0,1]
	v_pk_add_f32 v[156:157], v[144:145], v[148:149]
	v_pk_add_f32 v[144:145], v[144:145], v[148:149] neg_lo:[0,1] neg_hi:[0,1]
	v_pk_add_f32 v[148:149], v[146:147], v[150:151]
	v_pk_add_f32 v[146:147], v[146:147], v[150:151] neg_lo:[0,1] neg_hi:[0,1]
	v_pk_add_f32 v[152:153], v[142:143], v[158:159]
	v_pk_add_f32 v[142:143], v[142:143], v[158:159] neg_lo:[0,1] neg_hi:[0,1]
	v_pk_add_f32 v[158:159], v[144:145], v[146:147] op_sel:[0,1] op_sel_hi:[1,0] neg_hi:[0,1]
	v_pk_add_f32 v[144:145], v[144:145], v[146:147] op_sel:[0,1] op_sel_hi:[1,0] neg_lo:[0,1]
	v_pk_add_f32 v[150:151], v[128:129], v[132:133]
	v_pk_add_f32 v[128:129], v[128:129], v[132:133] neg_lo:[0,1] neg_hi:[0,1]
	v_pk_add_f32 v[132:133], v[130:131], v[134:135]
	v_pk_add_f32 v[130:131], v[130:131], v[134:135] neg_lo:[0,1] neg_hi:[0,1]
	v_pk_add_f32 v[146:147], v[156:157], v[148:149]
	v_pk_add_f32 v[148:149], v[156:157], v[148:149] neg_lo:[0,1] neg_hi:[0,1]
	v_pk_add_f32 v[156:157], v[128:129], v[130:131] op_sel:[0,1] op_sel_hi:[1,0] neg_hi:[0,1]
	v_pk_add_f32 v[128:129], v[128:129], v[130:131] op_sel:[0,1] op_sel_hi:[1,0] neg_lo:[0,1]
	v_xor_b32_e32 v134, 0x80000000, v111
	v_mov_b32_e32 v135, v110
	v_pk_mul_f32 v[134:135], v[134:135], v[138:139] op_sel:[0,1]
	v_pk_add_f32 v[130:131], v[150:151], v[132:133]
	v_pk_fma_f32 v[110:111], v[110:111], v[138:139], v[134:135] op_sel_hi:[1,0,1]
	ds_write_b64 v168, v[110:111]
	v_pk_mul_f32 v[110:111], v[114:115], v[152:153] op_sel:[1,1] op_sel_hi:[0,1] neg_lo:[1,0]
	v_pk_add_f32 v[132:133], v[150:151], v[132:133] neg_lo:[0,1] neg_hi:[0,1]
	v_pk_fma_f32 v[110:111], v[114:115], v[152:153], v[110:111] op_sel_hi:[1,0,1]
	ds_write_b64 v168, v[110:111] offset:2176
	v_pk_mul_f32 v[110:111], v[116:117], v[146:147] op_sel:[1,1] op_sel_hi:[0,1] neg_lo:[1,0]
	v_pk_fma_f32 v[110:111], v[116:117], v[146:147], v[110:111] op_sel_hi:[1,0,1]
	ds_write_b64 v168, v[110:111] offset:4352
	v_pk_mul_f32 v[110:111], v[118:119], v[130:131] op_sel:[1,1] op_sel_hi:[0,1] neg_lo:[1,0]
	v_pk_fma_f32 v[110:111], v[118:119], v[130:131], v[110:111] op_sel_hi:[1,0,1]
	ds_write_b64 v168, v[110:111] offset:6528
	v_pk_mul_f32 v[110:111], v[120:121], v[164:165] op_sel:[1,1] op_sel_hi:[0,1] neg_lo:[1,0]
	v_pk_fma_f32 v[110:111], v[120:121], v[164:165], v[110:111] op_sel_hi:[1,0,1]
	ds_write_b64 v168, v[110:111] offset:8704
	v_pk_mul_f32 v[110:111], v[122:123], v[166:167] op_sel:[1,1] op_sel_hi:[0,1] neg_lo:[1,0]
	v_pk_fma_f32 v[110:111], v[122:123], v[166:167], v[110:111] op_sel_hi:[1,0,1]
	ds_write_b64 v168, v[110:111] offset:10880
	v_pk_mul_f32 v[110:111], v[124:125], v[158:159] op_sel:[1,1] op_sel_hi:[0,1] neg_lo:[1,0]
	v_pk_fma_f32 v[110:111], v[124:125], v[158:159], v[110:111] op_sel_hi:[1,0,1]
	ds_write_b64 v168, v[110:111] offset:13056
	v_pk_mul_f32 v[110:111], v[126:127], v[156:157] op_sel:[1,1] op_sel_hi:[0,1] neg_lo:[1,0]
	v_pk_fma_f32 v[110:111], v[126:127], v[156:157], v[110:111] op_sel_hi:[1,0,1]
	ds_write_b64 v168, v[110:111] offset:15232
	v_pk_mul_f32 v[110:111], v[112:113], v[140:141] op_sel:[1,1] op_sel_hi:[0,1] neg_lo:[1,0]
	v_pk_fma_f32 v[110:111], v[112:113], v[140:141], v[110:111] op_sel_hi:[1,0,1]
	ds_write_b64 v168, v[110:111] offset:17408
	v_pk_mul_f32 v[110:111], v[108:109], v[142:143] op_sel:[1,1] op_sel_hi:[0,1] neg_lo:[1,0]
	v_pk_fma_f32 v[108:109], v[108:109], v[142:143], v[110:111] op_sel_hi:[1,0,1]
	ds_write_b64 v168, v[108:109] offset:19584
	v_pk_mul_f32 v[108:109], v[106:107], v[148:149] op_sel:[1,1] op_sel_hi:[0,1] neg_lo:[1,0]
	v_pk_fma_f32 v[106:107], v[106:107], v[148:149], v[108:109] op_sel_hi:[1,0,1]
	ds_write_b64 v168, v[106:107] offset:21760
	v_pk_mul_f32 v[106:107], v[104:105], v[132:133] op_sel:[1,1] op_sel_hi:[0,1] neg_lo:[1,0]
	v_pk_fma_f32 v[104:105], v[104:105], v[132:133], v[106:107] op_sel_hi:[1,0,1]
	ds_write_b64 v168, v[104:105] offset:23936
	v_pk_mul_f32 v[104:105], v[14:15], v[136:137] op_sel:[1,1] op_sel_hi:[0,1] neg_lo:[1,0]
	v_pk_fma_f32 v[14:15], v[14:15], v[136:137], v[104:105] op_sel_hi:[1,0,1]
	ds_write_b64 v168, v[14:15] offset:26112
	v_pk_mul_f32 v[14:15], v[12:13], v[154:155] op_sel:[1,1] op_sel_hi:[0,1] neg_lo:[1,0]
	v_pk_fma_f32 v[12:13], v[12:13], v[154:155], v[14:15] op_sel_hi:[1,0,1]
	ds_write_b64 v168, v[12:13] offset:28288
	v_pk_mul_f32 v[12:13], v[10:11], v[144:145] op_sel:[1,1] op_sel_hi:[0,1] neg_lo:[1,0]
	v_pk_fma_f32 v[10:11], v[10:11], v[144:145], v[12:13] op_sel_hi:[1,0,1]
	ds_write_b64 v168, v[10:11] offset:30464
	v_pk_mul_f32 v[10:11], v[8:9], v[128:129] op_sel:[1,1] op_sel_hi:[0,1] neg_lo:[1,0]
	v_pk_fma_f32 v[8:9], v[8:9], v[128:129], v[10:11] op_sel_hi:[1,0,1]
	ds_write_b64 v168, v[8:9] offset:32640
	v_mov_b32_e32 v116, 1.0
	v_pk_mul_f32 v[10:11], v[210:211], v[210:211] op_sel:[1,1] op_sel_hi:[0,1] neg_lo:[1,0]
	v_mov_b32_e32 v117, v177
	v_pk_fma_f32 v[10:11], v[210:211], v[210:211], v[10:11] op_sel_hi:[0,1,1]
	v_pk_mul_f32 v[104:105], v[10:11], v[10:11] op_sel:[1,1] op_sel_hi:[1,0] neg_lo:[0,1]
	v_pk_mul_f32 v[12:13], v[210:211], v[176:177] op_sel:[1,1] op_sel_hi:[0,1] neg_lo:[1,0]
	v_pk_fma_f32 v[104:105], v[10:11], v[10:11], v[104:105] op_sel_hi:[1,0,1]
	v_pk_fma_f32 v[126:127], v[210:211], v[116:117], v[12:13] op_sel_hi:[1,0,1]
	v_pk_mul_f32 v[8:9], v[176:177], v[10:11] op_sel:[1,1] op_sel_hi:[1,0] neg_lo:[0,1]
	s_nop 0
	v_pk_fma_f32 v[124:125], v[116:117], v[10:11], v[8:9] op_sel_hi:[0,1,1]
	v_pk_mul_f32 v[8:9], v[126:127], v[10:11] op_sel:[1,1] op_sel_hi:[1,0] neg_lo:[0,1]
	v_pk_mul_f32 v[108:109], v[104:105], v[104:105] op_sel:[1,1] op_sel_hi:[1,0] neg_lo:[0,1]
	v_pk_fma_f32 v[122:123], v[10:11], v[126:127], v[8:9] op_sel_hi:[1,0,1]
	v_pk_mul_f32 v[8:9], v[176:177], v[104:105] op_sel:[1,1] op_sel_hi:[1,0] neg_lo:[0,1]
	s_nop 0
	v_pk_fma_f32 v[120:121], v[116:117], v[104:105], v[8:9] op_sel_hi:[0,1,1]
	v_pk_mul_f32 v[8:9], v[126:127], v[104:105] op_sel:[1,1] op_sel_hi:[1,0] neg_lo:[0,1]
	s_waitcnt lgkmcnt(0)
	v_pk_fma_f32 v[118:119], v[126:127], v[104:105], v[8:9] op_sel_hi:[0,1,1]
	v_pk_mul_f32 v[8:9], v[124:125], v[104:105] op_sel:[1,1] op_sel_hi:[1,0] neg_lo:[0,1]
	s_barrier
	v_pk_fma_f32 v[114:115], v[104:105], v[124:125], v[8:9] op_sel_hi:[1,0,1]
	v_pk_mul_f32 v[8:9], v[122:123], v[104:105] op_sel:[1,1] op_sel_hi:[1,0] neg_lo:[0,1]
	s_nop 0
	v_pk_fma_f32 v[112:113], v[104:105], v[122:123], v[8:9] op_sel_hi:[1,0,1]
	v_pk_fma_f32 v[8:9], v[104:105], v[104:105], v[108:109] op_sel_hi:[1,0,1]
	s_nop 0
	v_pk_mul_f32 v[10:11], v[176:177], v[8:9] op_sel:[1,1] op_sel_hi:[1,0] neg_lo:[0,1]
	s_nop 0
	v_pk_fma_f32 v[110:111], v[116:117], v[8:9], v[10:11] op_sel_hi:[0,1,1]
	v_pk_mul_f32 v[10:11], v[126:127], v[8:9] op_sel:[1,1] op_sel_hi:[1,0] neg_lo:[0,1]
	s_nop 0
	v_pk_fma_f32 v[108:109], v[126:127], v[8:9], v[10:11] op_sel_hi:[0,1,1]
	v_pk_mul_f32 v[10:11], v[124:125], v[8:9] op_sel:[1,1] op_sel_hi:[1,0] neg_lo:[0,1]
	s_nop 0
	v_pk_fma_f32 v[106:107], v[124:125], v[8:9], v[10:11] op_sel_hi:[0,1,1]
	v_pk_mul_f32 v[10:11], v[122:123], v[8:9] op_sel:[1,1] op_sel_hi:[1,0] neg_lo:[0,1]
	s_nop 0
	v_pk_fma_f32 v[104:105], v[122:123], v[8:9], v[10:11] op_sel_hi:[0,1,1]
	v_pk_mul_f32 v[10:11], v[120:121], v[8:9] op_sel:[1,1] op_sel_hi:[1,0] neg_lo:[0,1]
	s_nop 0
	v_pk_fma_f32 v[14:15], v[8:9], v[120:121], v[10:11] op_sel_hi:[1,0,1]
	v_pk_mul_f32 v[10:11], v[118:119], v[8:9] op_sel:[1,1] op_sel_hi:[1,0] neg_lo:[0,1]
	s_nop 0
	v_pk_fma_f32 v[12:13], v[8:9], v[118:119], v[10:11] op_sel_hi:[1,0,1]
	v_pk_mul_f32 v[10:11], v[114:115], v[8:9] op_sel:[1,1] op_sel_hi:[1,0] neg_lo:[0,1]
	v_pk_mul_f32 v[128:129], v[112:113], v[8:9] op_sel:[1,1] op_sel_hi:[1,0] neg_lo:[0,1]
	v_pk_fma_f32 v[10:11], v[8:9], v[114:115], v[10:11] op_sel_hi:[1,0,1]
	v_pk_fma_f32 v[8:9], v[8:9], v[112:113], v[128:129] op_sel_hi:[1,0,1]
	s_nop 0
	v_bfe_u32 v129, v206, 4, 4
	v_and_b32_e32 v128, 15, v206
	v_mul_u32_u24_e32 v129, 0x880, v129
	v_lshlrev_b32_e32 v128, 3, v128
	v_add3_u32 v176, v207, v129, v128
	ds_read2_b64 v[128:131], v176 offset1:17
	ds_read2_b64 v[132:135], v176 offset0:34 offset1:51
	ds_read2_b64 v[136:139], v176 offset0:68 offset1:85
	ds_read2_b64 v[140:143], v176 offset0:136 offset1:153
	ds_read2_b64 v[144:147], v176 offset0:102 offset1:119
	ds_read2_b64 v[148:151], v176 offset0:204 offset1:221
	ds_read2_b64 v[152:155], v176 offset0:170 offset1:187
	ds_read2_b64 v[156:159], v176 offset0:238 offset1:255
	s_waitcnt lgkmcnt(4)
	v_pk_add_f32 v[164:165], v[128:129], v[140:141]
	v_pk_add_f32 v[128:129], v[128:129], v[140:141] neg_lo:[0,1] neg_hi:[0,1]
	s_waitcnt lgkmcnt(2)
	v_pk_add_f32 v[140:141], v[136:137], v[148:149]
	v_pk_add_f32 v[136:137], v[136:137], v[148:149] neg_lo:[0,1] neg_hi:[0,1]
	s_nop 0
	v_pk_add_f32 v[166:167], v[128:129], v[136:137] op_sel:[0,1] op_sel_hi:[1,0] neg_hi:[0,1]
	v_pk_add_f32 v[128:129], v[128:129], v[136:137] op_sel:[0,1] op_sel_hi:[1,0] neg_lo:[0,1]
	v_pk_add_f32 v[148:149], v[130:131], v[142:143]
	v_pk_add_f32 v[130:131], v[130:131], v[142:143] neg_lo:[0,1] neg_hi:[0,1]
	v_pk_add_f32 v[142:143], v[138:139], v[150:151]
	v_pk_add_f32 v[138:139], v[138:139], v[150:151] neg_lo:[0,1] neg_hi:[0,1]
	v_pk_add_f32 v[136:137], v[164:165], v[140:141]
	v_pk_add_f32 v[140:141], v[164:165], v[140:141] neg_lo:[0,1] neg_hi:[0,1]
	v_pk_add_f32 v[164:165], v[130:131], v[138:139] op_sel:[0,1] op_sel_hi:[1,0] neg_hi:[0,1]
	v_pk_add_f32 v[130:131], v[130:131], v[138:139] op_sel:[0,1] op_sel_hi:[1,0] neg_lo:[0,1]
	s_waitcnt lgkmcnt(0)
	v_pk_add_f32 v[150:151], v[144:145], v[156:157]
	v_pk_add_f32 v[144:145], v[144:145], v[156:157] neg_lo:[0,1] neg_hi:[0,1]
	v_pk_add_f32 v[138:139], v[148:149], v[142:143]
	v_pk_add_f32 v[142:143], v[148:149], v[142:143] neg_lo:[0,1] neg_hi:[0,1]
	v_pk_add_f32 v[148:149], v[132:133], v[152:153]
	v_pk_add_f32 v[132:133], v[132:133], v[152:153] neg_lo:[0,1] neg_hi:[0,1]
	s_nop 0
	v_pk_add_f32 v[156:157], v[132:133], v[144:145] op_sel:[0,1] op_sel_hi:[1,0] neg_hi:[0,1]
	v_pk_add_f32 v[132:133], v[132:133], v[144:145] op_sel:[0,1] op_sel_hi:[1,0] neg_lo:[0,1]
	v_pk_add_f32 v[152:153], v[146:147], v[158:159]
	v_pk_add_f32 v[146:147], v[146:147], v[158:159] neg_lo:[0,1] neg_hi:[0,1]
	v_pk_add_f32 v[144:145], v[148:149], v[150:151]
	v_pk_add_f32 v[148:149], v[148:149], v[150:151] neg_lo:[0,1] neg_hi:[0,1]
	v_pk_add_f32 v[150:151], v[134:135], v[154:155]
	v_pk_add_f32 v[134:135], v[134:135], v[154:155] neg_lo:[0,1] neg_hi:[0,1]
	s_nop 0
	v_pk_add_f32 v[158:159], v[134:135], v[146:147] op_sel:[0,1] op_sel_hi:[1,0] neg_hi:[0,1]
	v_pk_add_f32 v[134:135], v[134:135], v[146:147] op_sel:[0,1] op_sel_hi:[1,0] neg_lo:[0,1]
	v_pk_mul_f32 v[154:155], v[142:143], s[12:13] op_sel:[1,0] op_sel_hi:[0,0] neg_lo:[1,0]
	v_pk_add_f32 v[146:147], v[150:151], v[152:153]
	v_pk_fma_f32 v[142:143], v[142:143], s[12:13], v[154:155] op_sel_hi:[1,0,1] neg_lo:[0,0,1] neg_hi:[0,0,1]
	v_pk_mul_f32 v[154:155], v[130:131], s[36:37] op_sel:[1,0] op_sel_hi:[0,0] neg_lo:[1,0]
	v_pk_add_f32 v[150:151], v[150:151], v[152:153] neg_lo:[0,1] neg_hi:[0,1]
	v_pk_fma_f32 v[130:131], v[130:131], s[22:23], v[154:155] op_sel_hi:[1,0,1] neg_lo:[0,0,1] neg_hi:[0,0,1]
	v_pk_mul_f32 v[154:155], v[156:157], s[12:13] op_sel:[1,0] op_sel_hi:[0,0] neg_lo:[1,0]
	v_pk_fma_f32 v[154:155], v[156:157], s[12:13], v[154:155] op_sel_hi:[1,0,1] neg_lo:[0,0,1] neg_hi:[0,0,1]
	v_pk_fma_f32 v[148:149], v[148:149], 0, v[148:149] op_sel:[0,0,1] op_sel_hi:[1,0,0] neg_hi:[0,0,1]
	v_pk_mul_f32 v[156:157], v[132:133], s[12:13] op_sel:[1,0] op_sel_hi:[0,0] neg_lo:[1,0]
	v_pk_fma_f32 v[132:133], v[132:133], s[18:19], v[156:157] op_sel_hi:[1,0,1] neg_lo:[0,0,1] neg_hi:[0,0,1]
	v_pk_mul_f32 v[156:157], v[158:159], s[36:37] op_sel:[1,0] op_sel_hi:[0,0] neg_lo:[1,0]
	v_pk_mul_f32 v[152:153], v[164:165], s[22:23] op_sel:[1,0] op_sel_hi:[0,0] neg_lo:[1,0]
	v_pk_fma_f32 v[156:157], v[158:159], s[22:23], v[156:157] op_sel_hi:[1,0,1] neg_lo:[0,0,1] neg_hi:[0,0,1]
	v_pk_mul_f32 v[158:159], v[150:151], s[12:13] op_sel:[1,0] op_sel_hi:[0,0] neg_lo:[1,0]
	v_pk_fma_f32 v[152:153], v[164:165], s[36:37], v[152:153] op_sel_hi:[1,0,1] neg_lo:[0,0,1] neg_hi:[0,0,1]
	v_pk_fma_f32 v[150:151], v[150:151], s[18:19], v[158:159] op_sel_hi:[1,0,1] neg_lo:[0,0,1] neg_hi:[0,0,1]
	v_xor_b32_e32 v158, 0x80000000, v135
	v_mov_b32_e32 v159, v134
	v_pk_mul_f32 v[134:135], v[134:135], s[36:37] op_sel_hi:[1,0]
	s_nop 0
	v_pk_fma_f32 v[134:135], v[158:159], s[22:23], v[134:135] op_sel_hi:[1,0,1] neg_lo:[0,0,1] neg_hi:[0,0,1]
	v_pk_add_f32 v[158:159], v[136:137], v[144:145]
	v_pk_add_f32 v[136:137], v[136:137], v[144:145] neg_lo:[0,1] neg_hi:[0,1]
	v_pk_add_f32 v[144:145], v[138:139], v[146:147]
	v_pk_add_f32 v[138:139], v[138:139], v[146:147] neg_lo:[0,1] neg_hi:[0,1]
	s_nop 0
	v_xor_b32_e32 v147, 0x80000000, v138
	v_mov_b32_e32 v146, v139
	v_pk_add_f32 v[138:139], v[158:159], v[144:145]
	v_pk_add_f32 v[164:165], v[136:137], v[146:147]
	v_pk_add_f32 v[144:145], v[158:159], v[144:145] neg_lo:[0,1] neg_hi:[0,1]
	v_pk_add_f32 v[146:147], v[136:137], v[146:147] neg_lo:[0,1] neg_hi:[0,1]
	v_pk_add_f32 v[136:137], v[166:167], v[154:155]
	v_pk_add_f32 v[158:159], v[152:153], v[156:157]
	v_pk_add_f32 v[152:153], v[152:153], v[156:157] neg_lo:[0,1] neg_hi:[0,1]
	v_pk_add_f32 v[154:155], v[166:167], v[154:155] neg_lo:[0,1] neg_hi:[0,1]
	v_xor_b32_e32 v157, 0x80000000, v152
	v_mov_b32_e32 v156, v153
	v_pk_add_f32 v[152:153], v[136:137], v[158:159]
	v_pk_add_f32 v[168:169], v[136:137], v[158:159] neg_lo:[0,1] neg_hi:[0,1]
	v_pk_add_f32 v[136:137], v[140:141], v[148:149]
	v_pk_add_f32 v[140:141], v[140:141], v[148:149] neg_lo:[0,1] neg_hi:[0,1]
	v_pk_add_f32 v[148:149], v[142:143], v[150:151]
	v_pk_add_f32 v[166:167], v[154:155], v[156:157]
	v_pk_add_f32 v[170:171], v[154:155], v[156:157] neg_lo:[0,1] neg_hi:[0,1]
	v_pk_add_f32 v[142:143], v[142:143], v[150:151] neg_lo:[0,1] neg_hi:[0,1]
	v_pk_add_f32 v[154:155], v[136:137], v[148:149]
	v_pk_add_f32 v[148:149], v[136:137], v[148:149] neg_lo:[0,1] neg_hi:[0,1]
	v_pk_add_f32 v[136:137], v[128:129], v[132:133]
	v_pk_add_f32 v[128:129], v[128:129], v[132:133] neg_lo:[0,1] neg_hi:[0,1]
	v_pk_add_f32 v[132:133], v[130:131], v[134:135]
	v_pk_add_f32 v[130:131], v[130:131], v[134:135] neg_lo:[0,1] neg_hi:[0,1]
	v_xor_b32_e32 v151, 0x80000000, v142
	v_mov_b32_e32 v150, v143
	v_xor_b32_e32 v135, 0x80000000, v130
	v_mov_b32_e32 v134, v131
	v_xor_b32_e32 v142, 0x80000000, v117
	v_mov_b32_e32 v143, v116
	v_pk_add_f32 v[172:173], v[140:141], v[150:151]
	v_pk_add_f32 v[174:175], v[140:141], v[150:151] neg_lo:[0,1] neg_hi:[0,1]
	v_pk_add_f32 v[130:131], v[136:137], v[132:133]
	v_pk_add_f32 v[150:151], v[128:129], v[134:135]
	v_pk_add_f32 v[198:199], v[136:137], v[132:133] neg_lo:[0,1] neg_hi:[0,1]
	v_pk_add_f32 v[200:201], v[128:129], v[134:135] neg_lo:[0,1] neg_hi:[0,1]
	v_pk_mul_f32 v[128:129], v[142:143], v[138:139] op_sel:[0,1]
	v_pk_mul_f32 v[132:133], v[126:127], v[152:153] op_sel:[1,1] op_sel_hi:[0,1] neg_lo:[1,0]
	v_pk_fma_f32 v[128:129], v[116:117], v[138:139], v[128:129] op_sel_hi:[1,0,1]
	v_pk_fma_f32 v[132:133], v[126:127], v[152:153], v[132:133] op_sel_hi:[1,0,1]
	ds_write2_b64 v176, v[128:129], v[132:133] offset1:17
	v_pk_mul_f32 v[128:129], v[124:125], v[154:155] op_sel:[1,1] op_sel_hi:[0,1] neg_lo:[1,0]
	v_pk_mul_f32 v[132:133], v[122:123], v[130:131] op_sel:[1,1] op_sel_hi:[0,1] neg_lo:[1,0]
	v_pk_fma_f32 v[128:129], v[124:125], v[154:155], v[128:129] op_sel_hi:[1,0,1]
	v_pk_fma_f32 v[130:131], v[122:123], v[130:131], v[132:133] op_sel_hi:[1,0,1]
	ds_write2_b64 v176, v[128:129], v[130:131] offset0:34 offset1:51
	v_pk_mul_f32 v[128:129], v[120:121], v[164:165] op_sel:[1,1] op_sel_hi:[0,1] neg_lo:[1,0]
	v_pk_mul_f32 v[130:131], v[118:119], v[166:167] op_sel:[1,1] op_sel_hi:[0,1] neg_lo:[1,0]
	v_pk_fma_f32 v[128:129], v[120:121], v[164:165], v[128:129] op_sel_hi:[1,0,1]
	v_pk_fma_f32 v[130:131], v[118:119], v[166:167], v[130:131] op_sel_hi:[1,0,1]
	ds_write2_b64 v176, v[128:129], v[130:131] offset0:68 offset1:85
	v_pk_mul_f32 v[128:129], v[114:115], v[172:173] op_sel:[1,1] op_sel_hi:[0,1] neg_lo:[1,0]
	v_pk_mul_f32 v[130:131], v[112:113], v[150:151] op_sel:[1,1] op_sel_hi:[0,1] neg_lo:[1,0]
	v_pk_fma_f32 v[128:129], v[114:115], v[172:173], v[128:129] op_sel_hi:[1,0,1]
	v_pk_fma_f32 v[130:131], v[112:113], v[150:151], v[130:131] op_sel_hi:[1,0,1]
	ds_write2_b64 v176, v[128:129], v[130:131] offset0:102 offset1:119
	v_pk_mul_f32 v[128:129], v[110:111], v[144:145] op_sel:[1,1] op_sel_hi:[0,1] neg_lo:[1,0]
	v_pk_mul_f32 v[130:131], v[108:109], v[168:169] op_sel:[1,1] op_sel_hi:[0,1] neg_lo:[1,0]
	v_pk_fma_f32 v[128:129], v[110:111], v[144:145], v[128:129] op_sel_hi:[1,0,1]
	v_pk_fma_f32 v[130:131], v[108:109], v[168:169], v[130:131] op_sel_hi:[1,0,1]
	ds_write2_b64 v176, v[128:129], v[130:131] offset0:136 offset1:153
	v_pk_mul_f32 v[128:129], v[106:107], v[148:149] op_sel:[1,1] op_sel_hi:[0,1] neg_lo:[1,0]
	v_pk_fma_f32 v[128:129], v[106:107], v[148:149], v[128:129] op_sel_hi:[1,0,1]
	v_pk_mul_f32 v[130:131], v[104:105], v[198:199] op_sel:[1,1] op_sel_hi:[0,1] neg_lo:[1,0]
	v_pk_fma_f32 v[130:131], v[104:105], v[198:199], v[130:131] op_sel_hi:[1,0,1]
	ds_write2_b64 v176, v[128:129], v[130:131] offset0:170 offset1:187
	v_pk_mul_f32 v[128:129], v[14:15], v[146:147] op_sel:[1,1] op_sel_hi:[0,1] neg_lo:[1,0]
	v_pk_fma_f32 v[128:129], v[14:15], v[146:147], v[128:129] op_sel_hi:[1,0,1]
	v_pk_mul_f32 v[144:145], v[12:13], v[170:171] op_sel:[1,1] op_sel_hi:[0,1] neg_lo:[1,0]
	v_pk_fma_f32 v[144:145], v[12:13], v[170:171], v[144:145] op_sel_hi:[1,0,1]
	ds_write2_b64 v176, v[128:129], v[144:145] offset0:204 offset1:221
	v_pk_mul_f32 v[144:145], v[10:11], v[174:175] op_sel:[1,1] op_sel_hi:[0,1] neg_lo:[1,0]
	v_pk_fma_f32 v[164:165], v[10:11], v[174:175], v[144:145] op_sel_hi:[1,0,1]
	v_pk_mul_f32 v[166:167], v[8:9], v[200:201] op_sel:[1,1] op_sel_hi:[0,1] neg_lo:[1,0]
	v_pk_fma_f32 v[166:167], v[8:9], v[200:201], v[166:167] op_sel_hi:[1,0,1]
	ds_write2_b64 v176, v[164:165], v[166:167] offset0:238 offset1:255
	s_waitcnt lgkmcnt(0)
	s_barrier
	s_nop 0
	v_and_b32_e32 v129, 0xff, v206
	v_mad_u32_u24 v129, v129, s19, v207
	ds_read2_b64 v[164:167], v129 offset1:1
	ds_read2_b64 v[168:171], v129 offset0:2 offset1:3
	ds_read2_b64 v[172:175], v129 offset0:8 offset1:9
	ds_read2_b64 v[198:201], v129 offset0:4 offset1:5
	ds_read2_b64 v[202:205], v129 offset0:6 offset1:7
	ds_read2_b64 v[232:235], v129 offset0:12 offset1:13
	ds_read2_b64 v[236:239], v129 offset0:10 offset1:11
	ds_read2_b64 v[240:243], v129 offset0:14 offset1:15
	s_waitcnt lgkmcnt(5)
	v_pk_add_f32 v[244:245], v[164:165], v[172:173]
	v_pk_add_f32 v[164:165], v[164:165], v[172:173] neg_lo:[0,1] neg_hi:[0,1]
	s_waitcnt lgkmcnt(2)
	v_pk_add_f32 v[172:173], v[198:199], v[232:233]
	v_pk_add_f32 v[198:199], v[198:199], v[232:233] neg_lo:[0,1] neg_hi:[0,1]
	s_nop 0
	v_pk_add_f32 v[246:247], v[164:165], v[198:199] op_sel:[0,1] op_sel_hi:[1,0] neg_hi:[0,1]
	v_pk_add_f32 v[164:165], v[164:165], v[198:199] op_sel:[0,1] op_sel_hi:[1,0] neg_lo:[0,1]
	v_pk_add_f32 v[232:233], v[166:167], v[174:175]
	v_pk_add_f32 v[166:167], v[166:167], v[174:175] neg_lo:[0,1] neg_hi:[0,1]
	v_pk_add_f32 v[174:175], v[200:201], v[234:235]
	v_pk_add_f32 v[200:201], v[200:201], v[234:235] neg_lo:[0,1] neg_hi:[0,1]
	v_pk_add_f32 v[198:199], v[244:245], v[172:173]
	v_pk_add_f32 v[172:173], v[244:245], v[172:173] neg_lo:[0,1] neg_hi:[0,1]
	v_pk_add_f32 v[244:245], v[166:167], v[200:201] op_sel:[0,1] op_sel_hi:[1,0] neg_hi:[0,1]
	v_pk_add_f32 v[166:167], v[166:167], v[200:201] op_sel:[0,1] op_sel_hi:[1,0] neg_lo:[0,1]
	s_waitcnt lgkmcnt(0)
	v_pk_add_f32 v[234:235], v[202:203], v[240:241]
	v_pk_add_f32 v[202:203], v[202:203], v[240:241] neg_lo:[0,1] neg_hi:[0,1]
	v_pk_add_f32 v[200:201], v[232:233], v[174:175]
	v_pk_add_f32 v[174:175], v[232:233], v[174:175] neg_lo:[0,1] neg_hi:[0,1]
	v_pk_add_f32 v[232:233], v[168:169], v[236:237]
	v_pk_add_f32 v[168:169], v[168:169], v[236:237] neg_lo:[0,1] neg_hi:[0,1]
	s_nop 0
	v_pk_add_f32 v[240:241], v[168:169], v[202:203] op_sel:[0,1] op_sel_hi:[1,0] neg_hi:[0,1]
	v_pk_add_f32 v[168:169], v[168:169], v[202:203] op_sel:[0,1] op_sel_hi:[1,0] neg_lo:[0,1]
	v_pk_add_f32 v[236:237], v[204:205], v[242:243]
	v_pk_add_f32 v[204:205], v[204:205], v[242:243] neg_lo:[0,1] neg_hi:[0,1]
	v_pk_add_f32 v[202:203], v[232:233], v[234:235]
	v_pk_add_f32 v[232:233], v[232:233], v[234:235] neg_lo:[0,1] neg_hi:[0,1]
	v_pk_add_f32 v[234:235], v[170:171], v[238:239]
	v_pk_add_f32 v[170:171], v[170:171], v[238:239] neg_lo:[0,1] neg_hi:[0,1]
	s_nop 0
	v_pk_add_f32 v[242:243], v[170:171], v[204:205] op_sel:[0,1] op_sel_hi:[1,0] neg_hi:[0,1]
	v_pk_add_f32 v[170:171], v[170:171], v[204:205] op_sel:[0,1] op_sel_hi:[1,0] neg_lo:[0,1]
	v_pk_mul_f32 v[238:239], v[174:175], s[12:13] op_sel:[1,0] op_sel_hi:[0,0] neg_lo:[1,0]
	v_pk_add_f32 v[204:205], v[234:235], v[236:237]
	v_pk_fma_f32 v[174:175], v[174:175], s[12:13], v[238:239] op_sel_hi:[1,0,1] neg_lo:[0,0,1] neg_hi:[0,0,1]
	v_pk_mul_f32 v[238:239], v[166:167], s[36:37] op_sel:[1,0] op_sel_hi:[0,0] neg_lo:[1,0]
	v_pk_add_f32 v[234:235], v[234:235], v[236:237] neg_lo:[0,1] neg_hi:[0,1]
	v_pk_fma_f32 v[166:167], v[166:167], s[22:23], v[238:239] op_sel_hi:[1,0,1] neg_lo:[0,0,1] neg_hi:[0,0,1]
	v_pk_mul_f32 v[238:239], v[240:241], s[12:13] op_sel:[1,0] op_sel_hi:[0,0] neg_lo:[1,0]
	v_pk_fma_f32 v[238:239], v[240:241], s[12:13], v[238:239] op_sel_hi:[1,0,1] neg_lo:[0,0,1] neg_hi:[0,0,1]
	v_pk_fma_f32 v[232:233], v[232:233], 0, v[232:233] op_sel:[0,0,1] op_sel_hi:[1,0,0] neg_hi:[0,0,1]
	v_pk_mul_f32 v[240:241], v[168:169], s[12:13] op_sel:[1,0] op_sel_hi:[0,0] neg_lo:[1,0]
	v_pk_fma_f32 v[168:169], v[168:169], s[18:19], v[240:241] op_sel_hi:[1,0,1] neg_lo:[0,0,1] neg_hi:[0,0,1]
	v_pk_mul_f32 v[240:241], v[242:243], s[36:37] op_sel:[1,0] op_sel_hi:[0,0] neg_lo:[1,0]
	v_pk_mul_f32 v[236:237], v[244:245], s[22:23] op_sel:[1,0] op_sel_hi:[0,0] neg_lo:[1,0]
	v_pk_fma_f32 v[240:241], v[242:243], s[22:23], v[240:241] op_sel_hi:[1,0,1] neg_lo:[0,0,1] neg_hi:[0,0,1]
	v_pk_mul_f32 v[242:243], v[234:235], s[12:13] op_sel:[1,0] op_sel_hi:[0,0] neg_lo:[1,0]
	v_pk_fma_f32 v[236:237], v[244:245], s[36:37], v[236:237] op_sel_hi:[1,0,1] neg_lo:[0,0,1] neg_hi:[0,0,1]
	v_pk_fma_f32 v[234:235], v[234:235], s[18:19], v[242:243] op_sel_hi:[1,0,1] neg_lo:[0,0,1] neg_hi:[0,0,1]
	v_xor_b32_e32 v242, 0x80000000, v171
	v_mov_b32_e32 v243, v170
	v_pk_mul_f32 v[170:171], v[170:171], s[36:37] op_sel_hi:[1,0]
	s_nop 0
	v_pk_fma_f32 v[170:171], v[242:243], s[22:23], v[170:171] op_sel_hi:[1,0,1] neg_lo:[0,0,1] neg_hi:[0,0,1]
	v_pk_add_f32 v[242:243], v[198:199], v[202:203]
	v_pk_add_f32 v[198:199], v[198:199], v[202:203] neg_lo:[0,1] neg_hi:[0,1]
	v_pk_add_f32 v[202:203], v[200:201], v[204:205]
	v_pk_add_f32 v[200:201], v[200:201], v[204:205] neg_lo:[0,1] neg_hi:[0,1]
	s_nop 0
	v_xor_b32_e32 v205, 0x80000000, v200
	v_mov_b32_e32 v204, v201
	v_pk_add_f32 v[200:201], v[242:243], v[202:203]
	v_pk_add_f32 v[202:203], v[242:243], v[202:203] neg_lo:[0,1] neg_hi:[0,1]
	v_pk_add_f32 v[242:243], v[236:237], v[240:241]
	v_pk_add_f32 v[236:237], v[236:237], v[240:241] neg_lo:[0,1] neg_hi:[0,1]
	v_pk_add_f32 v[244:245], v[198:199], v[204:205]
	v_pk_add_f32 v[198:199], v[198:199], v[204:205] neg_lo:[0,1] neg_hi:[0,1]
	v_pk_add_f32 v[204:205], v[246:247], v[238:239]
	v_pk_add_f32 v[238:239], v[246:247], v[238:239] neg_lo:[0,1] neg_hi:[0,1]
	s_nop 0
	v_pk_add_f32 v[246:247], v[238:239], v[236:237] op_sel:[0,1] op_sel_hi:[1,0] neg_hi:[0,1]
	v_pk_add_f32 v[238:239], v[238:239], v[236:237] op_sel:[0,1] op_sel_hi:[1,0] neg_lo:[0,1]
	v_pk_add_f32 v[240:241], v[172:173], v[232:233]
	v_pk_add_f32 v[172:173], v[172:173], v[232:233] neg_lo:[0,1] neg_hi:[0,1]
	v_pk_add_f32 v[232:233], v[174:175], v[234:235]
	v_pk_add_f32 v[174:175], v[174:175], v[234:235] neg_lo:[0,1] neg_hi:[0,1]
	v_pk_add_f32 v[236:237], v[204:205], v[242:243]
	v_pk_add_f32 v[204:205], v[204:205], v[242:243] neg_lo:[0,1] neg_hi:[0,1]
	v_pk_add_f32 v[242:243], v[172:173], v[174:175] op_sel:[0,1] op_sel_hi:[1,0] neg_hi:[0,1]
	v_pk_add_f32 v[172:173], v[172:173], v[174:175] op_sel:[0,1] op_sel_hi:[1,0] neg_lo:[0,1]
	v_pk_add_f32 v[234:235], v[164:165], v[168:169]
	v_pk_add_f32 v[164:165], v[164:165], v[168:169] neg_lo:[0,1] neg_hi:[0,1]
	v_pk_add_f32 v[168:169], v[166:167], v[170:171]
	v_pk_add_f32 v[166:167], v[166:167], v[170:171] neg_lo:[0,1] neg_hi:[0,1]
	v_pk_add_f32 v[174:175], v[240:241], v[232:233]
	v_pk_add_f32 v[232:233], v[240:241], v[232:233] neg_lo:[0,1] neg_hi:[0,1]
	v_pk_add_f32 v[240:241], v[164:165], v[166:167] op_sel:[0,1] op_sel_hi:[1,0] neg_hi:[0,1]
	v_pk_add_f32 v[164:165], v[164:165], v[166:167] op_sel:[0,1] op_sel_hi:[1,0] neg_lo:[0,1]
	v_pk_mul_f32 v[170:171], v[66:67], v[200:201] op_sel:[0,1]
	v_pk_add_f32 v[166:167], v[234:235], v[168:169]
	v_pk_fma_f32 v[170:171], v[16:17], v[200:201], v[170:171] op_sel_hi:[1,0,1]
	v_pk_mul_f32 v[200:201], v[68:69], v[244:245] op_sel:[0,1]
	v_pk_add_f32 v[168:169], v[234:235], v[168:169] neg_lo:[0,1] neg_hi:[0,1]
	v_pk_fma_f32 v[200:201], v[18:19], v[244:245], v[200:201] op_sel_hi:[1,0,1]
	v_pk_mul_f32 v[244:245], v[78:79], v[204:205] op_sel:[0,1]
	v_pk_mul_f32 v[234:235], v[70:71], v[202:203] op_sel:[0,1]
	v_pk_fma_f32 v[204:205], v[46:47], v[204:205], v[244:245] op_sel_hi:[1,0,1]
	v_pk_mul_f32 v[244:245], v[80:81], v[238:239] op_sel:[0,1]
	v_pk_fma_f32 v[202:203], v[20:21], v[202:203], v[234:235] op_sel_hi:[1,0,1]
	v_pk_fma_f32 v[238:239], v[48:49], v[238:239], v[244:245] op_sel_hi:[1,0,1]
	v_pk_mul_f32 v[244:245], v[82:83], v[174:175] op_sel:[0,1]
	v_pk_mul_f32 v[234:235], v[72:73], v[198:199] op_sel:[0,1]
	v_pk_fma_f32 v[174:175], v[50:51], v[174:175], v[244:245] op_sel_hi:[1,0,1]
	v_pk_mul_f32 v[244:245], v[84:85], v[242:243] op_sel:[0,1]
	v_pk_fma_f32 v[198:199], v[22:23], v[198:199], v[234:235] op_sel_hi:[1,0,1]
	v_pk_fma_f32 v[242:243], v[52:53], v[242:243], v[244:245] op_sel_hi:[1,0,1]
	v_pk_mul_f32 v[244:245], v[86:87], v[232:233] op_sel:[0,1]
	v_pk_mul_f32 v[234:235], v[74:75], v[236:237] op_sel:[0,1]
	v_pk_fma_f32 v[232:233], v[54:55], v[232:233], v[244:245] op_sel_hi:[1,0,1]
	v_pk_mul_f32 v[244:245], v[88:89], v[172:173] op_sel:[0,1]
	v_pk_fma_f32 v[234:235], v[42:43], v[236:237], v[234:235] op_sel_hi:[1,0,1]
	v_pk_fma_f32 v[172:173], v[56:57], v[172:173], v[244:245] op_sel_hi:[1,0,1]
	v_pk_mul_f32 v[244:245], v[90:91], v[166:167] op_sel:[0,1]
	v_pk_mul_f32 v[236:237], v[76:77], v[246:247] op_sel:[0,1]
	v_pk_fma_f32 v[166:167], v[58:59], v[166:167], v[244:245] op_sel_hi:[1,0,1]
	v_pk_mul_f32 v[244:245], v[92:93], v[240:241] op_sel:[0,1]
	v_pk_fma_f32 v[236:237], v[44:45], v[246:247], v[236:237] op_sel_hi:[1,0,1]
	v_pk_fma_f32 v[240:241], v[60:61], v[240:241], v[244:245] op_sel_hi:[1,0,1]
	v_pk_mul_f32 v[244:245], v[94:95], v[168:169] op_sel:[0,1]
	s_nop 0
	v_pk_fma_f32 v[168:169], v[62:63], v[168:169], v[244:245] op_sel_hi:[1,0,1]
	v_pk_mul_f32 v[244:245], v[96:97], v[164:165] op_sel:[0,1]
	s_nop 0
	v_pk_fma_f32 v[164:165], v[64:65], v[164:165], v[244:245] op_sel_hi:[1,0,1]
	v_pk_add_f32 v[244:245], v[170:171], v[202:203]
	v_pk_add_f32 v[170:171], v[170:171], v[202:203] neg_lo:[0,1] neg_hi:[0,1]
	v_pk_add_f32 v[202:203], v[200:201], v[198:199]
	v_pk_add_f32 v[198:199], v[200:201], v[198:199] neg_lo:[0,1] neg_hi:[0,1]
	s_nop 0
	v_pk_add_f32 v[246:247], v[170:171], v[198:199] op_sel:[0,1] op_sel_hi:[1,0] neg_lo:[0,1]
	v_pk_add_f32 v[170:171], v[170:171], v[198:199] op_sel:[0,1] op_sel_hi:[1,0] neg_hi:[0,1]
	v_pk_add_f32 v[200:201], v[234:235], v[204:205]
	v_pk_add_f32 v[204:205], v[234:235], v[204:205] neg_lo:[0,1] neg_hi:[0,1]
	v_pk_add_f32 v[234:235], v[236:237], v[238:239]
	v_pk_add_f32 v[236:237], v[236:237], v[238:239] neg_lo:[0,1] neg_hi:[0,1]
	v_pk_add_f32 v[198:199], v[244:245], v[202:203]
	v_xor_b32_e32 v238, 0x80000000, v237
	v_mov_b32_e32 v239, v236
	v_pk_add_f32 v[236:237], v[200:201], v[234:235]
	v_pk_add_f32 v[200:201], v[200:201], v[234:235] neg_lo:[0,1] neg_hi:[0,1]
	v_pk_add_f32 v[234:235], v[174:175], v[232:233]
	v_pk_add_f32 v[174:175], v[174:175], v[232:233] neg_lo:[0,1] neg_hi:[0,1]
	v_pk_add_f32 v[232:233], v[242:243], v[172:173]
	v_pk_add_f32 v[172:173], v[242:243], v[172:173] neg_lo:[0,1] neg_hi:[0,1]
	v_pk_add_f32 v[202:203], v[244:245], v[202:203] neg_lo:[0,1] neg_hi:[0,1]
	v_pk_add_f32 v[244:245], v[204:205], v[238:239]
	v_pk_add_f32 v[204:205], v[204:205], v[238:239] neg_lo:[0,1] neg_hi:[0,1]
	v_xor_b32_e32 v238, 0x80000000, v173
	v_mov_b32_e32 v239, v172
	v_pk_add_f32 v[172:173], v[234:235], v[232:233]
	v_pk_add_f32 v[232:233], v[234:235], v[232:233] neg_lo:[0,1] neg_hi:[0,1]
	v_pk_add_f32 v[234:235], v[166:167], v[168:169]
	v_pk_add_f32 v[166:167], v[166:167], v[168:169] neg_lo:[0,1] neg_hi:[0,1]
	v_pk_add_f32 v[168:169], v[240:241], v[164:165]
	v_pk_add_f32 v[164:165], v[240:241], v[164:165] neg_lo:[0,1] neg_hi:[0,1]
	v_pk_add_f32 v[242:243], v[174:175], v[238:239]
	v_pk_add_f32 v[174:175], v[174:175], v[238:239] neg_lo:[0,1] neg_hi:[0,1]
	v_pk_add_f32 v[240:241], v[166:167], v[164:165] op_sel:[0,1] op_sel_hi:[1,0] neg_lo:[0,1]
	v_pk_add_f32 v[166:167], v[166:167], v[164:165] op_sel:[0,1] op_sel_hi:[1,0] neg_hi:[0,1]
	v_pk_mul_f32 v[238:239], v[200:201], s[12:13] op_sel:[1,0] op_sel_hi:[0,0] neg_lo:[1,0]
	v_pk_add_f32 v[164:165], v[234:235], v[168:169]
	v_pk_fma_f32 v[200:201], v[200:201], s[12:13], v[238:239] op_sel_hi:[1,0,1]
	v_pk_mul_f32 v[238:239], v[204:205], s[36:37] op_sel:[1,0] op_sel_hi:[0,0] neg_lo:[1,0]
	v_pk_add_f32 v[168:169], v[234:235], v[168:169] neg_lo:[0,1] neg_hi:[0,1]
	v_pk_fma_f32 v[204:205], v[204:205], s[22:23], v[238:239] op_sel_hi:[1,0,1]
	v_pk_mul_f32 v[238:239], v[242:243], s[12:13] op_sel:[1,0] op_sel_hi:[0,0] neg_lo:[1,0]
	v_pk_fma_f32 v[238:239], v[242:243], s[12:13], v[238:239] op_sel_hi:[1,0,1]
	v_pk_fma_f32 v[232:233], v[232:233], 0, v[232:233] op_sel:[0,0,1] op_sel_hi:[1,0,0] neg_lo:[0,0,1]
	v_xor_b32_e32 v242, 0x80000000, v175
	v_mov_b32_e32 v243, v174
	v_pk_mul_f32 v[174:175], v[174:175], s[12:13] op_sel_hi:[1,0]
	s_nop 0
	v_pk_fma_f32 v[174:175], v[242:243], s[12:13], v[174:175] op_sel_hi:[1,0,1] neg_lo:[0,0,1] neg_hi:[0,0,1]
	v_pk_mul_f32 v[242:243], v[240:241], s[36:37] op_sel:[1,0] op_sel_hi:[0,0] neg_lo:[1,0]
	v_pk_mul_f32 v[234:235], v[244:245], s[22:23] op_sel:[1,0] op_sel_hi:[0,0] neg_lo:[1,0]
	v_pk_fma_f32 v[240:241], v[240:241], s[22:23], v[242:243] op_sel_hi:[1,0,1]
	v_xor_b32_e32 v242, 0x80000000, v169
	v_mov_b32_e32 v243, v168
	v_pk_mul_f32 v[168:169], v[168:169], s[12:13] op_sel_hi:[1,0]
	v_pk_fma_f32 v[234:235], v[244:245], s[36:37], v[234:235] op_sel_hi:[1,0,1]
	v_pk_fma_f32 v[168:169], v[242:243], s[12:13], v[168:169] op_sel_hi:[1,0,1] neg_lo:[0,0,1] neg_hi:[0,0,1]
	v_pk_mul_f32 v[242:243], v[166:167], s[22:23] op_sel:[1,0] op_sel_hi:[0,0] neg_lo:[1,0]
	v_pk_fma_f32 v[166:167], v[166:167], s[26:27], v[242:243] op_sel_hi:[1,0,1] neg_lo:[0,0,1] neg_hi:[0,0,1]
	v_pk_add_f32 v[242:243], v[198:199], v[172:173]
	v_pk_add_f32 v[172:173], v[198:199], v[172:173] neg_lo:[0,1] neg_hi:[0,1]
	v_pk_add_f32 v[198:199], v[236:237], v[164:165]
	v_pk_add_f32 v[164:165], v[236:237], v[164:165] neg_lo:[0,1] neg_hi:[0,1]
	s_nop 0
	v_xor_b32_e32 v236, 0x80000000, v165
	v_mov_b32_e32 v237, v164
	v_pk_add_f32 v[164:165], v[242:243], v[198:199]
	v_pk_add_f32 v[198:199], v[242:243], v[198:199] neg_lo:[0,1] neg_hi:[0,1]
	v_pk_add_f32 v[242:243], v[234:235], v[240:241]
	v_pk_add_f32 v[234:235], v[234:235], v[240:241] neg_lo:[0,1] neg_hi:[0,1]
	v_pk_add_f32 v[244:245], v[172:173], v[236:237]
	v_pk_add_f32 v[172:173], v[172:173], v[236:237] neg_lo:[0,1] neg_hi:[0,1]
	v_pk_add_f32 v[236:237], v[246:247], v[238:239]
	v_pk_add_f32 v[238:239], v[246:247], v[238:239] neg_lo:[0,1] neg_hi:[0,1]
	s_nop 0
	v_pk_add_f32 v[246:247], v[238:239], v[234:235] op_sel:[0,1] op_sel_hi:[1,0] neg_lo:[0,1]
	v_pk_add_f32 v[238:239], v[238:239], v[234:235] op_sel:[0,1] op_sel_hi:[1,0] neg_hi:[0,1]
	v_pk_add_f32 v[240:241], v[202:203], v[232:233]
	v_pk_add_f32 v[202:203], v[202:203], v[232:233] neg_lo:[0,1] neg_hi:[0,1]
	v_pk_add_f32 v[232:233], v[200:201], v[168:169]
	v_pk_add_f32 v[168:169], v[200:201], v[168:169] neg_lo:[0,1] neg_hi:[0,1]
	v_pk_add_f32 v[234:235], v[236:237], v[242:243]
	v_pk_add_f32 v[236:237], v[236:237], v[242:243] neg_lo:[0,1] neg_hi:[0,1]
	v_pk_add_f32 v[242:243], v[202:203], v[168:169] op_sel:[0,1] op_sel_hi:[1,0] neg_lo:[0,1]
	v_pk_add_f32 v[200:201], v[202:203], v[168:169] op_sel:[0,1] op_sel_hi:[1,0] neg_hi:[0,1]
	v_pk_add_f32 v[202:203], v[170:171], v[174:175]
	v_pk_add_f32 v[170:171], v[170:171], v[174:175] neg_lo:[0,1] neg_hi:[0,1]
	v_pk_add_f32 v[174:175], v[204:205], v[166:167]
	v_pk_add_f32 v[166:167], v[204:205], v[166:167] neg_lo:[0,1] neg_hi:[0,1]
	v_pk_add_f32 v[168:169], v[240:241], v[232:233]
	v_xor_b32_e32 v204, 0x80000000, v167
	v_mov_b32_e32 v205, v166
	v_pk_add_f32 v[166:167], v[202:203], v[174:175]
	v_pk_add_f32 v[174:175], v[202:203], v[174:175] neg_lo:[0,1] neg_hi:[0,1]
	v_mov_b32_e32 v202, v116
	v_mov_b32_e32 v203, v142
	v_pk_mul_f32 v[142:143], v[202:203], v[164:165] op_sel_hi:[1,0]
	v_pk_add_f32 v[232:233], v[240:241], v[232:233] neg_lo:[0,1] neg_hi:[0,1]
	v_pk_fma_f32 v[116:117], v[116:117], v[164:165], v[142:143] op_sel:[1,1,0] op_sel_hi:[0,1,1]
	v_pk_mul_f32 v[142:143], v[126:127], v[234:235] op_sel_hi:[1,0] neg_hi:[1,0]
	v_pk_add_f32 v[240:241], v[170:171], v[204:205]
	v_pk_fma_f32 v[126:127], v[126:127], v[234:235], v[142:143] op_sel:[1,1,0] op_sel_hi:[0,1,1]
	ds_write2_b64 v129, v[116:117], v[126:127] offset1:1
	v_pk_mul_f32 v[116:117], v[124:125], v[168:169] op_sel_hi:[1,0] neg_hi:[1,0]
	v_pk_add_f32 v[170:171], v[170:171], v[204:205] neg_lo:[0,1] neg_hi:[0,1]
	v_pk_fma_f32 v[116:117], v[124:125], v[168:169], v[116:117] op_sel:[1,1,0] op_sel_hi:[0,1,1]
	v_pk_mul_f32 v[124:125], v[122:123], v[166:167] op_sel_hi:[1,0] neg_hi:[1,0]
	s_nop 0
	v_pk_fma_f32 v[122:123], v[122:123], v[166:167], v[124:125] op_sel:[1,1,0] op_sel_hi:[0,1,1]
	ds_write2_b64 v129, v[116:117], v[122:123] offset0:2 offset1:3
	v_pk_mul_f32 v[116:117], v[120:121], v[244:245] op_sel_hi:[1,0] neg_hi:[1,0]
	s_nop 0
	v_pk_fma_f32 v[116:117], v[120:121], v[244:245], v[116:117] op_sel:[1,1,0] op_sel_hi:[0,1,1]
	v_pk_mul_f32 v[120:121], v[118:119], v[246:247] op_sel_hi:[1,0] neg_hi:[1,0]
	s_nop 0
	v_pk_fma_f32 v[118:119], v[118:119], v[246:247], v[120:121] op_sel:[1,1,0] op_sel_hi:[0,1,1]
	ds_write2_b64 v129, v[116:117], v[118:119] offset0:4 offset1:5
	v_pk_mul_f32 v[116:117], v[114:115], v[242:243] op_sel_hi:[1,0] neg_hi:[1,0]
	s_nop 0
	v_pk_fma_f32 v[114:115], v[114:115], v[242:243], v[116:117] op_sel:[1,1,0] op_sel_hi:[0,1,1]
	v_pk_mul_f32 v[116:117], v[112:113], v[240:241] op_sel_hi:[1,0] neg_hi:[1,0]
	s_nop 0
	v_pk_fma_f32 v[112:113], v[112:113], v[240:241], v[116:117] op_sel:[1,1,0] op_sel_hi:[0,1,1]
	ds_write2_b64 v129, v[114:115], v[112:113] offset0:6 offset1:7
	v_pk_mul_f32 v[112:113], v[110:111], v[198:199] op_sel_hi:[1,0] neg_hi:[1,0]
	s_nop 0
	v_pk_fma_f32 v[110:111], v[110:111], v[198:199], v[112:113] op_sel:[1,1,0] op_sel_hi:[0,1,1]
	v_pk_mul_f32 v[112:113], v[108:109], v[236:237] op_sel_hi:[1,0] neg_hi:[1,0]
	s_nop 0
	v_pk_fma_f32 v[108:109], v[108:109], v[236:237], v[112:113] op_sel:[1,1,0] op_sel_hi:[0,1,1]
	ds_write2_b64 v129, v[110:111], v[108:109] offset0:8 offset1:9
	v_pk_mul_f32 v[108:109], v[106:107], v[232:233] op_sel_hi:[1,0] neg_hi:[1,0]
	s_nop 0
	v_pk_fma_f32 v[106:107], v[106:107], v[232:233], v[108:109] op_sel:[1,1,0] op_sel_hi:[0,1,1]
	v_pk_mul_f32 v[108:109], v[104:105], v[174:175] op_sel_hi:[1,0] neg_hi:[1,0]
	s_nop 0
	v_pk_fma_f32 v[104:105], v[104:105], v[174:175], v[108:109] op_sel:[1,1,0] op_sel_hi:[0,1,1]
	ds_write2_b64 v129, v[106:107], v[104:105] offset0:10 offset1:11
	v_pk_mul_f32 v[104:105], v[14:15], v[172:173] op_sel_hi:[1,0] neg_hi:[1,0]
	s_nop 0
	v_pk_fma_f32 v[14:15], v[14:15], v[172:173], v[104:105] op_sel:[1,1,0] op_sel_hi:[0,1,1]
	v_pk_mul_f32 v[104:105], v[12:13], v[238:239] op_sel_hi:[1,0] neg_hi:[1,0]
	s_nop 0
	v_pk_fma_f32 v[12:13], v[12:13], v[238:239], v[104:105] op_sel:[1,1,0] op_sel_hi:[0,1,1]
	ds_write2_b64 v129, v[14:15], v[12:13] offset0:12 offset1:13
	v_pk_mul_f32 v[12:13], v[10:11], v[200:201] op_sel_hi:[1,0] neg_hi:[1,0]
	s_nop 0
	v_pk_fma_f32 v[10:11], v[10:11], v[200:201], v[12:13] op_sel:[1,1,0] op_sel_hi:[0,1,1]
	v_pk_mul_f32 v[12:13], v[8:9], v[170:171] op_sel_hi:[1,0] neg_hi:[1,0]
	s_nop 0
	v_pk_fma_f32 v[8:9], v[8:9], v[170:171], v[12:13] op_sel:[1,1,0] op_sel_hi:[0,1,1]
	ds_write2_b64 v129, v[10:11], v[8:9] offset0:14 offset1:15
	v_mov_b32_e32 v8, v217
	v_mov_b32_e32 v9, v218
	v_mov_b32_e32 v138, v215
	v_xor_b32_e32 v12, 0x80000000, v9
	v_mov_b32_e32 v13, v8
	v_pk_mul_f32 v[10:11], v[12:13], v[218:219] op_sel_hi:[1,0]
	v_mov_b32_e32 v139, v216
	v_pk_fma_f32 v[10:11], v[216:217], v[8:9], v[10:11] op_sel:[1,0,0]
	s_nop 0
	v_pk_mul_f32 v[104:105], v[10:11], v[10:11] op_sel:[1,1] op_sel_hi:[1,0] neg_lo:[0,1]
	v_pk_mul_f32 v[12:13], v[12:13], v[216:217] op_sel_hi:[1,0]
	v_pk_fma_f32 v[104:105], v[10:11], v[10:11], v[104:105] op_sel_hi:[1,0,1]
	v_pk_fma_f32 v[140:141], v[8:9], v[214:215], v[12:13] op_sel:[0,1,0]
	v_pk_mul_f32 v[8:9], v[216:217], v[10:11] op_sel:[0,1] op_sel_hi:[0,0] neg_lo:[0,1]
	v_pk_fma_f32 v[142:143], v[214:215], v[10:11], v[8:9] op_sel:[1,0,0]
	v_pk_mul_f32 v[8:9], v[140:141], v[10:11] op_sel:[1,1] op_sel_hi:[1,0] neg_lo:[0,1]
	v_pk_mul_f32 v[108:109], v[104:105], v[104:105] op_sel:[1,1] op_sel_hi:[1,0] neg_lo:[0,1]
	v_pk_fma_f32 v[144:145], v[10:11], v[140:141], v[8:9] op_sel_hi:[1,0,1]
	v_pk_mul_f32 v[8:9], v[216:217], v[104:105] op_sel:[0,1] op_sel_hi:[0,0] neg_lo:[0,1]
	v_pk_fma_f32 v[146:147], v[214:215], v[104:105], v[8:9] op_sel:[1,0,0]
	v_pk_mul_f32 v[8:9], v[140:141], v[104:105] op_sel:[1,1] op_sel_hi:[1,0] neg_lo:[0,1]
	s_waitcnt lgkmcnt(0)
	v_pk_fma_f32 v[148:149], v[140:141], v[104:105], v[8:9] op_sel_hi:[0,1,1]
	v_pk_mul_f32 v[8:9], v[142:143], v[104:105] op_sel:[1,1] op_sel_hi:[1,0] neg_lo:[0,1]
	s_barrier
	v_pk_fma_f32 v[150:151], v[104:105], v[142:143], v[8:9] op_sel_hi:[1,0,1]
	v_pk_mul_f32 v[8:9], v[144:145], v[104:105] op_sel:[1,1] op_sel_hi:[1,0] neg_lo:[0,1]
	s_nop 0
	v_pk_fma_f32 v[152:153], v[104:105], v[144:145], v[8:9] op_sel_hi:[1,0,1]
	v_pk_fma_f32 v[8:9], v[104:105], v[104:105], v[108:109] op_sel_hi:[1,0,1]
	s_nop 0
	v_pk_mul_f32 v[10:11], v[216:217], v[8:9] op_sel:[0,1] op_sel_hi:[0,0] neg_lo:[0,1]
	v_pk_fma_f32 v[154:155], v[214:215], v[8:9], v[10:11] op_sel:[1,0,0]
	v_pk_mul_f32 v[10:11], v[140:141], v[8:9] op_sel:[1,1] op_sel_hi:[1,0] neg_lo:[0,1]
	s_nop 0
	v_pk_fma_f32 v[156:157], v[140:141], v[8:9], v[10:11] op_sel_hi:[0,1,1]
	v_pk_mul_f32 v[10:11], v[142:143], v[8:9] op_sel:[1,1] op_sel_hi:[1,0] neg_lo:[0,1]
	s_nop 0
	v_pk_fma_f32 v[158:159], v[142:143], v[8:9], v[10:11] op_sel_hi:[0,1,1]
	v_pk_mul_f32 v[10:11], v[144:145], v[8:9] op_sel:[1,1] op_sel_hi:[1,0] neg_lo:[0,1]
	s_nop 0
	v_pk_fma_f32 v[104:105], v[144:145], v[8:9], v[10:11] op_sel_hi:[0,1,1]
	v_pk_mul_f32 v[10:11], v[146:147], v[8:9] op_sel:[1,1] op_sel_hi:[1,0] neg_lo:[0,1]
	s_nop 0
	v_pk_fma_f32 v[14:15], v[8:9], v[146:147], v[10:11] op_sel_hi:[1,0,1]
	v_pk_mul_f32 v[10:11], v[148:149], v[8:9] op_sel:[1,1] op_sel_hi:[1,0] neg_lo:[0,1]
	s_nop 0
	v_pk_fma_f32 v[12:13], v[8:9], v[148:149], v[10:11] op_sel_hi:[1,0,1]
	v_pk_mul_f32 v[10:11], v[150:151], v[8:9] op_sel:[1,1] op_sel_hi:[1,0] neg_lo:[0,1]
	v_pk_mul_f32 v[106:107], v[152:153], v[8:9] op_sel:[1,1] op_sel_hi:[1,0] neg_lo:[0,1]
	v_pk_fma_f32 v[10:11], v[8:9], v[150:151], v[10:11] op_sel_hi:[1,0,1]
	v_pk_fma_f32 v[8:9], v[8:9], v[152:153], v[106:107] op_sel_hi:[1,0,1]
	s_nop 0
	v_bfe_u32 v107, v206, 4, 4
	v_and_b32_e32 v106, 15, v206
	v_mul_u32_u24_e32 v107, 0x880, v107
	v_lshlrev_b32_e32 v106, 3, v106
	v_add3_u32 v168, v207, v107, v106
	ds_read2_b64 v[106:109], v168 offset1:17
	ds_read2_b64 v[110:113], v168 offset0:34 offset1:51
	ds_read2_b64 v[114:117], v168 offset0:68 offset1:85
	ds_read2_b64 v[118:121], v168 offset0:136 offset1:153
	ds_read2_b64 v[122:125], v168 offset0:102 offset1:119
	ds_read2_b64 v[126:129], v168 offset0:204 offset1:221
	ds_read2_b64 v[130:133], v168 offset0:170 offset1:187
	ds_read2_b64 v[134:137], v168 offset0:238 offset1:255
	s_waitcnt lgkmcnt(4)
	v_pk_add_f32 v[164:165], v[106:107], v[118:119]
	v_pk_add_f32 v[106:107], v[106:107], v[118:119] neg_lo:[0,1] neg_hi:[0,1]
	s_waitcnt lgkmcnt(2)
	v_pk_add_f32 v[118:119], v[114:115], v[126:127]
	v_pk_add_f32 v[114:115], v[114:115], v[126:127] neg_lo:[0,1] neg_hi:[0,1]
	s_nop 0
	v_pk_add_f32 v[166:167], v[106:107], v[114:115] op_sel:[0,1] op_sel_hi:[1,0] neg_lo:[0,1]
	v_pk_add_f32 v[106:107], v[106:107], v[114:115] op_sel:[0,1] op_sel_hi:[1,0] neg_hi:[0,1]
	v_pk_add_f32 v[126:127], v[108:109], v[120:121]
	v_pk_add_f32 v[108:109], v[108:109], v[120:121] neg_lo:[0,1] neg_hi:[0,1]
	v_pk_add_f32 v[120:121], v[116:117], v[128:129]
	v_pk_add_f32 v[116:117], v[116:117], v[128:129] neg_lo:[0,1] neg_hi:[0,1]
	v_pk_add_f32 v[114:115], v[164:165], v[118:119]
	v_pk_add_f32 v[118:119], v[164:165], v[118:119] neg_lo:[0,1] neg_hi:[0,1]
	v_pk_add_f32 v[164:165], v[108:109], v[116:117] op_sel:[0,1] op_sel_hi:[1,0] neg_lo:[0,1]
	v_pk_add_f32 v[108:109], v[108:109], v[116:117] op_sel:[0,1] op_sel_hi:[1,0] neg_hi:[0,1]
	s_waitcnt lgkmcnt(0)
	v_pk_add_f32 v[128:129], v[122:123], v[134:135]
	v_pk_add_f32 v[122:123], v[122:123], v[134:135] neg_lo:[0,1] neg_hi:[0,1]
	v_pk_add_f32 v[116:117], v[126:127], v[120:121]
	v_pk_add_f32 v[120:121], v[126:127], v[120:121] neg_lo:[0,1] neg_hi:[0,1]
	v_pk_add_f32 v[126:127], v[110:111], v[130:131]
	v_pk_add_f32 v[110:111], v[110:111], v[130:131] neg_lo:[0,1] neg_hi:[0,1]
	s_nop 0
	v_pk_add_f32 v[134:135], v[110:111], v[122:123] op_sel:[0,1] op_sel_hi:[1,0] neg_lo:[0,1]
	v_pk_add_f32 v[110:111], v[110:111], v[122:123] op_sel:[0,1] op_sel_hi:[1,0] neg_hi:[0,1]
	v_pk_add_f32 v[130:131], v[124:125], v[136:137]
	v_pk_add_f32 v[124:125], v[124:125], v[136:137] neg_lo:[0,1] neg_hi:[0,1]
	v_pk_add_f32 v[122:123], v[126:127], v[128:129]
	v_pk_add_f32 v[126:127], v[126:127], v[128:129] neg_lo:[0,1] neg_hi:[0,1]
	v_pk_add_f32 v[128:129], v[112:113], v[132:133]
	v_pk_add_f32 v[112:113], v[112:113], v[132:133] neg_lo:[0,1] neg_hi:[0,1]
	s_nop 0
	v_pk_add_f32 v[136:137], v[112:113], v[124:125] op_sel:[0,1] op_sel_hi:[1,0] neg_lo:[0,1]
	v_pk_add_f32 v[112:113], v[112:113], v[124:125] op_sel:[0,1] op_sel_hi:[1,0] neg_hi:[0,1]
	v_pk_mul_f32 v[132:133], v[120:121], s[12:13] op_sel:[1,0] op_sel_hi:[0,0] neg_lo:[1,0]
	v_pk_add_f32 v[124:125], v[128:129], v[130:131]
	v_pk_fma_f32 v[120:121], v[120:121], s[12:13], v[132:133] op_sel_hi:[1,0,1]
	v_pk_mul_f32 v[132:133], v[108:109], s[36:37] op_sel:[1,0] op_sel_hi:[0,0] neg_lo:[1,0]
	v_pk_add_f32 v[128:129], v[128:129], v[130:131] neg_lo:[0,1] neg_hi:[0,1]
	v_pk_fma_f32 v[108:109], v[108:109], s[22:23], v[132:133] op_sel_hi:[1,0,1]
	v_pk_mul_f32 v[132:133], v[134:135], s[12:13] op_sel:[1,0] op_sel_hi:[0,0] neg_lo:[1,0]
	v_pk_fma_f32 v[132:133], v[134:135], s[12:13], v[132:133] op_sel_hi:[1,0,1]
	v_pk_fma_f32 v[126:127], v[126:127], 0, v[126:127] op_sel:[0,0,1] op_sel_hi:[1,0,0] neg_lo:[0,0,1]
	v_xor_b32_e32 v134, 0x80000000, v111
	v_mov_b32_e32 v135, v110
	v_pk_mul_f32 v[110:111], v[110:111], s[12:13] op_sel_hi:[1,0]
	s_nop 0
	v_pk_fma_f32 v[110:111], v[134:135], s[12:13], v[110:111] op_sel_hi:[1,0,1] neg_lo:[0,0,1] neg_hi:[0,0,1]
	v_pk_mul_f32 v[134:135], v[136:137], s[36:37] op_sel:[1,0] op_sel_hi:[0,0] neg_lo:[1,0]
	v_pk_mul_f32 v[130:131], v[164:165], s[22:23] op_sel:[1,0] op_sel_hi:[0,0] neg_lo:[1,0]
	v_pk_fma_f32 v[134:135], v[136:137], s[22:23], v[134:135] op_sel_hi:[1,0,1]
	v_xor_b32_e32 v136, 0x80000000, v129
	v_mov_b32_e32 v137, v128
	v_pk_mul_f32 v[128:129], v[128:129], s[12:13] op_sel_hi:[1,0]
	v_pk_fma_f32 v[130:131], v[164:165], s[36:37], v[130:131] op_sel_hi:[1,0,1]
	v_pk_fma_f32 v[128:129], v[136:137], s[12:13], v[128:129] op_sel_hi:[1,0,1] neg_lo:[0,0,1] neg_hi:[0,0,1]
	v_pk_mul_f32 v[136:137], v[112:113], s[22:23] op_sel:[1,0] op_sel_hi:[0,0] neg_lo:[1,0]
	v_pk_fma_f32 v[112:113], v[112:113], s[26:27], v[136:137] op_sel_hi:[1,0,1] neg_lo:[0,0,1] neg_hi:[0,0,1]
	v_pk_add_f32 v[136:137], v[114:115], v[122:123]
	v_pk_add_f32 v[114:115], v[114:115], v[122:123] neg_lo:[0,1] neg_hi:[0,1]
	v_pk_add_f32 v[122:123], v[116:117], v[124:125]
	v_pk_add_f32 v[116:117], v[116:117], v[124:125] neg_lo:[0,1] neg_hi:[0,1]
	s_nop 0
	v_xor_b32_e32 v124, 0x80000000, v117
	v_mov_b32_e32 v125, v116
	v_pk_add_f32 v[116:117], v[136:137], v[122:123]
	v_pk_add_f32 v[122:123], v[136:137], v[122:123] neg_lo:[0,1] neg_hi:[0,1]
	v_pk_add_f32 v[136:137], v[130:131], v[134:135]
	v_pk_add_f32 v[130:131], v[130:131], v[134:135] neg_lo:[0,1] neg_hi:[0,1]
	v_pk_add_f32 v[164:165], v[114:115], v[124:125]
	v_pk_add_f32 v[114:115], v[114:115], v[124:125] neg_lo:[0,1] neg_hi:[0,1]
	v_pk_add_f32 v[124:125], v[166:167], v[132:133]
	v_pk_add_f32 v[132:133], v[166:167], v[132:133] neg_lo:[0,1] neg_hi:[0,1]
	s_nop 0
	v_pk_add_f32 v[166:167], v[132:133], v[130:131] op_sel:[0,1] op_sel_hi:[1,0] neg_lo:[0,1]
	v_pk_add_f32 v[132:133], v[132:133], v[130:131] op_sel:[0,1] op_sel_hi:[1,0] neg_hi:[0,1]
	v_pk_add_f32 v[134:135], v[118:119], v[126:127]
	v_pk_add_f32 v[118:119], v[118:119], v[126:127] neg_lo:[0,1] neg_hi:[0,1]
	v_pk_add_f32 v[126:127], v[120:121], v[128:129]
	v_pk_add_f32 v[120:121], v[120:121], v[128:129] neg_lo:[0,1] neg_hi:[0,1]
	v_pk_add_f32 v[130:131], v[124:125], v[136:137]
	v_pk_add_f32 v[124:125], v[124:125], v[136:137] neg_lo:[0,1] neg_hi:[0,1]
	v_pk_add_f32 v[136:137], v[118:119], v[120:121] op_sel:[0,1] op_sel_hi:[1,0] neg_lo:[0,1]
	v_pk_add_f32 v[118:119], v[118:119], v[120:121] op_sel:[0,1] op_sel_hi:[1,0] neg_hi:[0,1]
	v_pk_add_f32 v[128:129], v[106:107], v[110:111]
	v_pk_add_f32 v[106:107], v[106:107], v[110:111] neg_lo:[0,1] neg_hi:[0,1]
	v_pk_add_f32 v[110:111], v[108:109], v[112:113]
	v_pk_add_f32 v[108:109], v[108:109], v[112:113] neg_lo:[0,1] neg_hi:[0,1]
	v_pk_add_f32 v[120:121], v[134:135], v[126:127]
	v_pk_add_f32 v[126:127], v[134:135], v[126:127] neg_lo:[0,1] neg_hi:[0,1]
	v_pk_add_f32 v[134:135], v[106:107], v[108:109] op_sel:[0,1] op_sel_hi:[1,0] neg_lo:[0,1]
	v_pk_add_f32 v[106:107], v[106:107], v[108:109] op_sel:[0,1] op_sel_hi:[1,0] neg_hi:[0,1]
	v_xor_b32_e32 v112, 0x80000000, v139
	v_mov_b32_e32 v113, v138
	v_pk_mul_f32 v[112:113], v[112:113], v[116:117] op_sel:[0,1]
	v_pk_add_f32 v[108:109], v[128:129], v[110:111]
	v_pk_fma_f32 v[112:113], v[138:139], v[116:117], v[112:113] op_sel_hi:[1,0,1]
	v_pk_mul_f32 v[116:117], v[140:141], v[130:131] op_sel:[1,1] op_sel_hi:[0,1] neg_lo:[1,0]
	v_pk_add_f32 v[110:111], v[128:129], v[110:111] neg_lo:[0,1] neg_hi:[0,1]
	v_pk_fma_f32 v[116:117], v[140:141], v[130:131], v[116:117] op_sel_hi:[1,0,1]
	ds_write2_b64 v168, v[112:113], v[116:117] offset1:17
	v_pk_mul_f32 v[112:113], v[142:143], v[120:121] op_sel:[1,1] op_sel_hi:[0,1] neg_lo:[1,0]
	v_pk_mul_f32 v[116:117], v[144:145], v[108:109] op_sel:[1,1] op_sel_hi:[0,1] neg_lo:[1,0]
	v_pk_fma_f32 v[112:113], v[142:143], v[120:121], v[112:113] op_sel_hi:[1,0,1]
	v_pk_fma_f32 v[108:109], v[144:145], v[108:109], v[116:117] op_sel_hi:[1,0,1]
	ds_write2_b64 v168, v[112:113], v[108:109] offset0:34 offset1:51
	v_pk_mul_f32 v[108:109], v[146:147], v[164:165] op_sel:[1,1] op_sel_hi:[0,1] neg_lo:[1,0]
	v_pk_mul_f32 v[112:113], v[148:149], v[166:167] op_sel:[1,1] op_sel_hi:[0,1] neg_lo:[1,0]
	v_pk_fma_f32 v[108:109], v[146:147], v[164:165], v[108:109] op_sel_hi:[1,0,1]
	v_pk_fma_f32 v[112:113], v[148:149], v[166:167], v[112:113] op_sel_hi:[1,0,1]
	ds_write2_b64 v168, v[108:109], v[112:113] offset0:68 offset1:85
	v_pk_mul_f32 v[108:109], v[150:151], v[136:137] op_sel:[1,1] op_sel_hi:[0,1] neg_lo:[1,0]
	v_pk_mul_f32 v[112:113], v[152:153], v[134:135] op_sel:[1,1] op_sel_hi:[0,1] neg_lo:[1,0]
	v_pk_fma_f32 v[108:109], v[150:151], v[136:137], v[108:109] op_sel_hi:[1,0,1]
	v_pk_fma_f32 v[112:113], v[152:153], v[134:135], v[112:113] op_sel_hi:[1,0,1]
	ds_write2_b64 v168, v[108:109], v[112:113] offset0:102 offset1:119
	v_pk_mul_f32 v[108:109], v[154:155], v[122:123] op_sel:[1,1] op_sel_hi:[0,1] neg_lo:[1,0]
	v_pk_mul_f32 v[112:113], v[156:157], v[124:125] op_sel:[1,1] op_sel_hi:[0,1] neg_lo:[1,0]
	v_pk_fma_f32 v[108:109], v[154:155], v[122:123], v[108:109] op_sel_hi:[1,0,1]
	v_pk_fma_f32 v[112:113], v[156:157], v[124:125], v[112:113] op_sel_hi:[1,0,1]
	ds_write2_b64 v168, v[108:109], v[112:113] offset0:136 offset1:153
	v_pk_mul_f32 v[108:109], v[158:159], v[126:127] op_sel:[1,1] op_sel_hi:[0,1] neg_lo:[1,0]
	v_pk_mul_f32 v[112:113], v[104:105], v[110:111] op_sel:[1,1] op_sel_hi:[0,1] neg_lo:[1,0]
	v_pk_fma_f32 v[108:109], v[158:159], v[126:127], v[108:109] op_sel_hi:[1,0,1]
	v_pk_fma_f32 v[104:105], v[104:105], v[110:111], v[112:113] op_sel_hi:[1,0,1]
	ds_write2_b64 v168, v[108:109], v[104:105] offset0:170 offset1:187
	v_pk_mul_f32 v[104:105], v[14:15], v[114:115] op_sel:[1,1] op_sel_hi:[0,1] neg_lo:[1,0]
	v_pk_fma_f32 v[14:15], v[14:15], v[114:115], v[104:105] op_sel_hi:[1,0,1]
	v_pk_mul_f32 v[104:105], v[12:13], v[132:133] op_sel:[1,1] op_sel_hi:[0,1] neg_lo:[1,0]
	v_pk_fma_f32 v[12:13], v[12:13], v[132:133], v[104:105] op_sel_hi:[1,0,1]
	ds_write2_b64 v168, v[14:15], v[12:13] offset0:204 offset1:221
	v_pk_mul_f32 v[12:13], v[10:11], v[118:119] op_sel:[1,1] op_sel_hi:[0,1] neg_lo:[1,0]
	v_pk_fma_f32 v[10:11], v[10:11], v[118:119], v[12:13] op_sel_hi:[1,0,1]
	v_pk_mul_f32 v[12:13], v[8:9], v[106:107] op_sel:[1,1] op_sel_hi:[0,1] neg_lo:[1,0]
	v_pk_fma_f32 v[8:9], v[8:9], v[106:107], v[12:13] op_sel_hi:[1,0,1]
	ds_write2_b64 v168, v[10:11], v[8:9] offset0:238 offset1:255
	v_mov_b32_e32 v8, v206
	s_waitcnt lgkmcnt(0)
	s_barrier
	s_nop 0
	v_lshlrev_b32_sdwa v9, v228, v8 dst_sel:DWORD dst_unused:UNUSED_PAD src0_sel:DWORD src1_sel:BYTE_0
	v_lshrrev_b32_e32 v8, 1, v206
	v_and_b32_e32 v8, 0x78, v8
	v_add3_u32 v132, v207, v9, v8
	ds_read_b64 v[8:9], v132
	ds_read_b64 v[10:11], v132 offset:2176
	ds_read_b64 v[12:13], v132 offset:4352
	ds_read_b64 v[14:15], v132 offset:6528
	ds_read_b64 v[104:105], v132 offset:8704
	ds_read_b64 v[106:107], v132 offset:10880
	ds_read_b64 v[108:109], v132 offset:13056
	ds_read_b64 v[110:111], v132 offset:15232
	ds_read_b64 v[112:113], v132 offset:17408
	ds_read_b64 v[114:115], v132 offset:19584
	ds_read_b64 v[116:117], v132 offset:21760
	ds_read_b64 v[118:119], v132 offset:23936
	ds_read_b64 v[120:121], v132 offset:26112
	ds_read_b64 v[122:123], v132 offset:28288
	ds_read_b64 v[124:125], v132 offset:30464
	ds_read_b64 v[126:127], v132 offset:32640
	s_waitcnt lgkmcnt(7)
	v_pk_add_f32 v[128:129], v[8:9], v[112:113]
	v_pk_add_f32 v[8:9], v[8:9], v[112:113] neg_lo:[0,1] neg_hi:[0,1]
	s_waitcnt lgkmcnt(3)
	v_pk_add_f32 v[112:113], v[104:105], v[120:121]
	v_pk_add_f32 v[104:105], v[104:105], v[120:121] neg_lo:[0,1] neg_hi:[0,1]
	s_nop 0
	v_pk_add_f32 v[130:131], v[8:9], v[104:105] op_sel:[0,1] op_sel_hi:[1,0] neg_lo:[0,1]
	v_pk_add_f32 v[8:9], v[8:9], v[104:105] op_sel:[0,1] op_sel_hi:[1,0] neg_hi:[0,1]
	v_pk_add_f32 v[120:121], v[10:11], v[114:115]
	v_pk_add_f32 v[10:11], v[10:11], v[114:115] neg_lo:[0,1] neg_hi:[0,1]
	s_waitcnt lgkmcnt(2)
	v_pk_add_f32 v[114:115], v[106:107], v[122:123]
	v_pk_add_f32 v[106:107], v[106:107], v[122:123] neg_lo:[0,1] neg_hi:[0,1]
	v_pk_add_f32 v[104:105], v[128:129], v[112:113]
	v_xor_b32_e32 v122, 0x80000000, v107
	v_mov_b32_e32 v123, v106
	v_pk_add_f32 v[106:107], v[120:121], v[114:115]
	v_pk_add_f32 v[114:115], v[120:121], v[114:115] neg_lo:[0,1] neg_hi:[0,1]
	v_pk_add_f32 v[120:121], v[12:13], v[116:117]
	v_pk_add_f32 v[12:13], v[12:13], v[116:117] neg_lo:[0,1] neg_hi:[0,1]
	s_waitcnt lgkmcnt(1)
	v_pk_add_f32 v[116:117], v[108:109], v[124:125]
	v_pk_add_f32 v[108:109], v[108:109], v[124:125] neg_lo:[0,1] neg_hi:[0,1]
	v_pk_add_f32 v[112:113], v[128:129], v[112:113] neg_lo:[0,1] neg_hi:[0,1]
	v_pk_add_f32 v[128:129], v[10:11], v[122:123]
	v_pk_add_f32 v[10:11], v[10:11], v[122:123] neg_lo:[0,1] neg_hi:[0,1]
	v_xor_b32_e32 v122, 0x80000000, v109
	v_mov_b32_e32 v123, v108
	v_pk_add_f32 v[108:109], v[120:121], v[116:117]
	v_pk_add_f32 v[116:117], v[120:121], v[116:117] neg_lo:[0,1] neg_hi:[0,1]
	v_pk_add_f32 v[120:121], v[14:15], v[118:119]
	v_pk_add_f32 v[14:15], v[14:15], v[118:119] neg_lo:[0,1] neg_hi:[0,1]
	s_waitcnt lgkmcnt(0)
	v_pk_add_f32 v[118:119], v[110:111], v[126:127]
	v_pk_add_f32 v[110:111], v[110:111], v[126:127] neg_lo:[0,1] neg_hi:[0,1]
	v_pk_add_f32 v[124:125], v[12:13], v[122:123]
	v_pk_add_f32 v[12:13], v[12:13], v[122:123] neg_lo:[0,1] neg_hi:[0,1]
	v_pk_add_f32 v[126:127], v[14:15], v[110:111] op_sel:[0,1] op_sel_hi:[1,0] neg_lo:[0,1]
	v_pk_add_f32 v[14:15], v[14:15], v[110:111] op_sel:[0,1] op_sel_hi:[1,0] neg_hi:[0,1]
	v_pk_mul_f32 v[122:123], v[114:115], s[12:13] op_sel:[1,0] op_sel_hi:[0,0] neg_lo:[1,0]
	v_pk_add_f32 v[110:111], v[120:121], v[118:119]
	v_pk_fma_f32 v[114:115], v[114:115], s[12:13], v[122:123] op_sel_hi:[1,0,1]
	v_pk_mul_f32 v[122:123], v[10:11], s[36:37] op_sel:[1,0] op_sel_hi:[0,0] neg_lo:[1,0]
	v_pk_add_f32 v[118:119], v[120:121], v[118:119] neg_lo:[0,1] neg_hi:[0,1]
	v_pk_fma_f32 v[10:11], v[10:11], s[22:23], v[122:123] op_sel_hi:[1,0,1]
	v_pk_mul_f32 v[122:123], v[124:125], s[12:13] op_sel:[1,0] op_sel_hi:[0,0] neg_lo:[1,0]
	v_pk_fma_f32 v[122:123], v[124:125], s[12:13], v[122:123] op_sel_hi:[1,0,1]
	v_pk_fma_f32 v[116:117], v[116:117], 0, v[116:117] op_sel:[0,0,1] op_sel_hi:[1,0,0] neg_lo:[0,0,1]
	v_xor_b32_e32 v124, 0x80000000, v13
	v_mov_b32_e32 v125, v12
	v_pk_mul_f32 v[12:13], v[12:13], s[12:13] op_sel_hi:[1,0]
	s_nop 0
	v_pk_fma_f32 v[12:13], v[124:125], s[12:13], v[12:13] op_sel_hi:[1,0,1] neg_lo:[0,0,1] neg_hi:[0,0,1]
	v_pk_mul_f32 v[124:125], v[126:127], s[36:37] op_sel:[1,0] op_sel_hi:[0,0] neg_lo:[1,0]
	v_pk_mul_f32 v[120:121], v[128:129], s[22:23] op_sel:[1,0] op_sel_hi:[0,0] neg_lo:[1,0]
	v_pk_fma_f32 v[124:125], v[126:127], s[22:23], v[124:125] op_sel_hi:[1,0,1]
	v_xor_b32_e32 v126, 0x80000000, v119
	v_mov_b32_e32 v127, v118
	v_pk_mul_f32 v[118:119], v[118:119], s[12:13] op_sel_hi:[1,0]
	v_pk_fma_f32 v[120:121], v[128:129], s[36:37], v[120:121] op_sel_hi:[1,0,1]
	v_pk_fma_f32 v[118:119], v[126:127], s[12:13], v[118:119] op_sel_hi:[1,0,1] neg_lo:[0,0,1] neg_hi:[0,0,1]
	v_pk_mul_f32 v[126:127], v[14:15], s[22:23] op_sel:[1,0] op_sel_hi:[0,0] neg_lo:[1,0]
	v_pk_fma_f32 v[14:15], v[14:15], s[26:27], v[126:127] op_sel_hi:[1,0,1] neg_lo:[0,0,1] neg_hi:[0,0,1]
	v_pk_add_f32 v[126:127], v[104:105], v[108:109]
	v_pk_add_f32 v[104:105], v[104:105], v[108:109] neg_lo:[0,1] neg_hi:[0,1]
	v_pk_add_f32 v[108:109], v[106:107], v[110:111]
	v_pk_add_f32 v[106:107], v[106:107], v[110:111] neg_lo:[0,1] neg_hi:[0,1]
	s_nop 0
	v_xor_b32_e32 v110, 0x80000000, v107
	v_mov_b32_e32 v111, v106
	v_pk_add_f32 v[106:107], v[126:127], v[108:109]
	v_pk_add_f32 v[108:109], v[126:127], v[108:109] neg_lo:[0,1] neg_hi:[0,1]
	v_pk_add_f32 v[126:127], v[120:121], v[124:125]
	v_pk_add_f32 v[120:121], v[120:121], v[124:125] neg_lo:[0,1] neg_hi:[0,1]
	v_pk_add_f32 v[128:129], v[104:105], v[110:111]
	v_pk_add_f32 v[104:105], v[104:105], v[110:111] neg_lo:[0,1] neg_hi:[0,1]
	v_pk_add_f32 v[110:111], v[130:131], v[122:123]
	v_pk_add_f32 v[122:123], v[130:131], v[122:123] neg_lo:[0,1] neg_hi:[0,1]
	s_nop 0
	v_pk_add_f32 v[130:131], v[122:123], v[120:121] op_sel:[0,1] op_sel_hi:[1,0] neg_lo:[0,1]
	v_pk_add_f32 v[122:123], v[122:123], v[120:121] op_sel:[0,1] op_sel_hi:[1,0] neg_hi:[0,1]
	v_pk_add_f32 v[124:125], v[112:113], v[116:117]
	v_pk_add_f32 v[112:113], v[112:113], v[116:117] neg_lo:[0,1] neg_hi:[0,1]
	v_pk_add_f32 v[116:117], v[114:115], v[118:119]
	v_pk_add_f32 v[114:115], v[114:115], v[118:119] neg_lo:[0,1] neg_hi:[0,1]
	v_pk_add_f32 v[120:121], v[110:111], v[126:127]
	v_pk_add_f32 v[110:111], v[110:111], v[126:127] neg_lo:[0,1] neg_hi:[0,1]
	v_pk_add_f32 v[126:127], v[112:113], v[114:115] op_sel:[0,1] op_sel_hi:[1,0] neg_lo:[0,1]
	v_pk_add_f32 v[112:113], v[112:113], v[114:115] op_sel:[0,1] op_sel_hi:[1,0] neg_hi:[0,1]
	v_pk_add_f32 v[118:119], v[8:9], v[12:13]
	v_pk_add_f32 v[8:9], v[8:9], v[12:13] neg_lo:[0,1] neg_hi:[0,1]
	v_pk_add_f32 v[12:13], v[10:11], v[14:15]
	v_pk_add_f32 v[10:11], v[10:11], v[14:15] neg_lo:[0,1] neg_hi:[0,1]
	v_pk_add_f32 v[114:115], v[124:125], v[116:117]
	v_pk_add_f32 v[116:117], v[124:125], v[116:117] neg_lo:[0,1] neg_hi:[0,1]
	v_pk_add_f32 v[124:125], v[8:9], v[10:11] op_sel:[0,1] op_sel_hi:[1,0] neg_lo:[0,1]
	v_pk_add_f32 v[8:9], v[8:9], v[10:11] op_sel:[0,1] op_sel_hi:[1,0] neg_hi:[0,1]
	v_pk_add_f32 v[10:11], v[118:119], v[12:13]
	v_pk_add_f32 v[12:13], v[118:119], v[12:13] neg_lo:[0,1] neg_hi:[0,1]
	ds_write_b64 v132, v[106:107]
	ds_write_b64 v132, v[128:129] offset:8704
	ds_write_b64 v132, v[108:109] offset:17408
	ds_write_b64 v132, v[104:105] offset:26112
	ds_write_b64 v132, v[120:121] offset:2176
	ds_write_b64 v132, v[130:131] offset:10880
	ds_write_b64 v132, v[110:111] offset:19584
	ds_write_b64 v132, v[122:123] offset:28288
	ds_write_b64 v132, v[114:115] offset:4352
	ds_write_b64 v132, v[126:127] offset:13056
	ds_write_b64 v132, v[116:117] offset:21760
	ds_write_b64 v132, v[112:113] offset:30464
	ds_write_b64 v132, v[10:11] offset:6528
	ds_write_b64 v132, v[124:125] offset:15232
	ds_write_b64 v132, v[12:13] offset:23936
	ds_write_b64 v132, v[8:9] offset:32640
	s_waitcnt lgkmcnt(0)
	s_barrier
	s_waitcnt vmcnt(4)
	v_lshlrev_b32_e32 v9, 16, v4
	v_and_b32_e32 v104, 0x1ff, v212
	v_lshlrev_b32_e32 v105, 3, v104
	v_bfe_u32 v8, v212, 1, 8
	v_add_u32_e32 v106, v105, v8
	v_lshlrev_b32_e32 v8, 16, v0
	v_and_b32_e32 v11, 0xffff0000, v4
	v_and_b32_e32 v10, 0xffff0000, v0
	s_waitcnt vmcnt(2)
	v_lshlrev_b32_e32 v0, 16, v163
	v_lshlrev_b32_e32 v4, 16, v162
	v_cmp_eq_u32_e32 vcc, 0, v104
	v_pk_mul_f32 v[14:15], v[38:39], v[10:11]
	v_cmp_eq_u32_e64 s[0:1], s37, v104
	v_cndmask_b32_e64 v13, v4, 0, vcc
	v_cndmask_b32_e64 v12, v0, 0, vcc
	v_pk_mul_f32 v[12:13], v[24:25], v[12:13]
	v_and_b32_e32 v4, 0xffff0000, v1
	v_pk_fma_f32 v[12:13], v[38:39], v[8:9], v[12:13]
	v_pk_fma_f32 v[8:9], v[24:25], v[8:9], v[14:15]
	v_pk_fma_f32 v[12:13], v[26:27], v[10:11], v[12:13]
	v_lshl_add_u32 v136, v106, 3, 0
	v_pk_add_f32 v[122:123], v[28:29], v[12:13]
	v_lshlrev_b32_e32 v13, 16, v5
	v_lshlrev_b32_e32 v12, 16, v1
	v_pk_mul_f32 v[0:1], v[38:39], v[12:13]
	v_pk_fma_f32 v[8:9], v[26:27], v[12:13], v[8:9]
	v_and_b32_e32 v5, 0xffff0000, v5
	v_pk_fma_f32 v[0:1], v[24:25], v[10:11], v[0:1]
	v_pk_add_f32 v[124:125], v[28:29], v[8:9]
	v_pk_fma_f32 v[0:1], v[26:27], v[4:5], v[0:1]
	v_pk_mul_f32 v[8:9], v[38:39], v[4:5]
	v_pk_add_f32 v[126:127], v[28:29], v[0:1]
	v_lshlrev_b32_e32 v1, 16, v6
	v_lshlrev_b32_e32 v0, 16, v2
	v_pk_fma_f32 v[8:9], v[24:25], v[12:13], v[8:9]
	v_pk_mul_f32 v[10:11], v[38:39], v[0:1]
	v_pk_fma_f32 v[8:9], v[26:27], v[0:1], v[8:9]
	v_pk_fma_f32 v[4:5], v[24:25], v[4:5], v[10:11]
	v_pk_add_f32 v[128:129], v[28:29], v[8:9]
	v_and_b32_e32 v9, 0xffff0000, v6
	v_and_b32_e32 v8, 0xffff0000, v2
	v_pk_fma_f32 v[4:5], v[26:27], v[8:9], v[4:5]
	v_lshlrev_b32_e32 v11, 16, v7
	v_pk_add_f32 v[130:131], v[28:29], v[4:5]
	v_pk_mul_f32 v[4:5], v[38:39], v[8:9]
	v_lshlrev_b32_e32 v10, 16, v3
	v_pk_fma_f32 v[0:1], v[24:25], v[0:1], v[4:5]
	s_waitcnt vmcnt(0)
	v_lshlrev_b32_e32 v6, 16, v161
	v_pk_fma_f32 v[0:1], v[26:27], v[10:11], v[0:1]
	v_cndmask_b32_e64 v6, v6, 0, s[0:1]
	v_pk_add_f32 v[4:5], v[28:29], v[0:1]
	v_and_b32_e32 v0, 0xffff0000, v3
	v_pk_mul_f32 v[2:3], v[38:39], v[10:11]
	v_and_b32_e32 v1, 0xffff0000, v7
	v_pk_fma_f32 v[2:3], v[24:25], v[8:9], v[2:3]
	v_lshlrev_b32_e32 v7, 16, v160
	v_pk_fma_f32 v[2:3], v[26:27], v[0:1], v[2:3]
	v_pk_mul_f32 v[0:1], v[38:39], v[0:1]
	v_cndmask_b32_e64 v7, v7, 0, s[0:1]
	v_pk_fma_f32 v[0:1], v[24:25], v[10:11], v[0:1]
	v_mov_b32_e32 v121, v214
	v_pk_fma_f32 v[0:1], v[26:27], v[6:7], v[0:1]
	v_add_u32_e32 v6, -1, v105
	v_cndmask_b32_e64 v176, v6, 0, vcc
	v_add_u32_e32 v6, 8, v105
	v_cndmask_b32_e64 v105, v6, v229, s[0:1]
	s_add_u32 s0, s39, s42
	v_lshlrev_b32_e32 v6, 4, v104
	v_mov_b32_e32 v7, v177
	s_addc_u32 s1, s46, s43
	v_lshl_add_u64 v[6:7], s[0:1], 0, v[6:7]
	v_add_co_u32_e32 v8, vcc, s5, v6
	v_mov_b32_e32 v120, v213
	s_nop 0
	v_addc_co_u32_e32 v9, vcc, 0, v7, vcc
	v_add_co_u32_e32 v6, vcc, s27, v6
	v_add_u32_e32 v137, 0x8800, v136
	s_nop 0
	v_addc_co_u32_e32 v7, vcc, 0, v7, vcc
	global_load_dwordx4 v[12:15], v[8:9], off
	s_nop 0
	global_load_dwordx4 v[8:11], v[6:7], off
	ds_read2_b64 v[108:111], v137 offset1:1
	v_lshl_add_u64 v[6:7], v[176:177], 1, s[0:1]
	v_lshlrev_b32_e32 v176, 1, v105
	ds_read2_b64 v[104:107], v136 offset1:1
	v_xor_b32_e32 v135, 0x80000000, v121
	v_mov_b32_e32 v134, v120
	v_add_u32_e32 v138, 0x8810, v136
	ds_read2_b64 v[112:115], v138 offset1:1
	s_waitcnt lgkmcnt(2)
	v_pk_mul_f32 v[116:117], v[134:135], v[108:109] op_sel_hi:[1,0]
	v_lshl_add_u64 v[132:133], s[0:1], 0, v[176:177]
	v_pk_fma_f32 v[108:109], v[120:121], v[108:109], v[116:117] op_sel:[1,1,0] op_sel_hi:[0,1,1]
	ds_read2_b64 v[116:119], v136 offset0:2 offset1:3
	s_waitcnt lgkmcnt(2)
	v_pk_add_f32 v[104:105], v[104:105], v[108:109]
	v_mov_b32_e32 v108, v135
	v_pk_mul_f32 v[104:105], v[122:123], v[104:105]
	v_mov_b32_e32 v109, v120
	v_pk_mul_f32 v[108:109], v[108:109], v[104:105] op_sel:[0,1]
	v_pk_mul_f32 v[122:123], v[214:215], s[8:9] op_sel_hi:[0,1]
	v_pk_fma_f32 v[108:109], v[120:121], v[104:105], v[108:109] op_sel_hi:[1,0,1]
	v_pk_fma_f32 v[120:121], v[212:213], s[30:31], v[122:123] op_sel:[1,0,0]
	s_nop 0
	v_pk_mul_f32 v[134:135], v[120:121], v[110:111] op_sel_hi:[1,0] neg_hi:[1,0]
	v_mov_b32_e32 v110, v111
	v_pk_fma_f32 v[110:111], v[120:121], v[110:111], v[134:135] op_sel:[1,1,0] op_sel_hi:[0,1,1]
	v_pk_add_f32 v[106:107], v[106:107], v[110:111]
	v_add_u32_e32 v122, 0x8820, v136
	v_pk_mul_f32 v[106:107], v[124:125], v[106:107]
	ds_write2_b64 v136, v[104:105], v[106:107] offset1:1
	v_pk_mul_f32 v[104:105], v[120:121], v[106:107] op_sel:[1,1] op_sel_hi:[0,1] neg_lo:[1,0]
	v_pk_add_f32 v[2:3], v[28:29], v[2:3]
	v_pk_fma_f32 v[104:105], v[120:121], v[106:107], v[104:105] op_sel_hi:[1,0,1]
	ds_write2_b64 v137, v[108:109], v[104:105] offset1:1
	v_pk_mul_f32 v[104:105], v[120:121], s[8:9] op_sel:[1,0]
	v_pk_add_f32 v[0:1], v[28:29], v[0:1]
	v_pk_fma_f32 v[104:105], v[120:121], s[30:31], v[104:105] op_sel_hi:[0,1,1]
	s_waitcnt lgkmcnt(3)
	v_pk_mul_f32 v[108:109], v[104:105], v[112:113] op_sel_hi:[1,0] neg_hi:[1,0]
	s_nop 0
	v_pk_fma_f32 v[108:109], v[104:105], v[112:113], v[108:109] op_sel:[1,1,0] op_sel_hi:[0,1,1]
	s_waitcnt lgkmcnt(2)
	v_pk_add_f32 v[108:109], v[116:117], v[108:109]
	s_nop 0
	v_pk_mul_f32 v[108:109], v[126:127], v[108:109]
	v_pk_mul_f32 v[110:111], v[104:105], s[8:9] op_sel:[1,0]
	v_pk_mul_f32 v[106:107], v[104:105], v[108:109] op_sel:[1,1] op_sel_hi:[0,1] neg_lo:[1,0]
	v_pk_fma_f32 v[110:111], v[104:105], s[30:31], v[110:111] op_sel_hi:[0,1,1]
	v_pk_fma_f32 v[106:107], v[104:105], v[108:109], v[106:107] op_sel_hi:[1,0,1]
	v_pk_mul_f32 v[112:113], v[110:111], v[114:115] op_sel_hi:[1,0] neg_hi:[1,0]
	s_nop 0
	v_pk_fma_f32 v[112:113], v[110:111], v[114:115], v[112:113] op_sel:[1,1,0] op_sel_hi:[0,1,1]
	v_pk_add_f32 v[112:113], v[118:119], v[112:113]
	s_nop 0
	v_pk_mul_f32 v[112:113], v[128:129], v[112:113]
	s_nop 0
	v_pk_mul_f32 v[104:105], v[110:111], v[112:113] op_sel:[1,1] op_sel_hi:[0,1] neg_lo:[1,0]
	ds_write2_b64 v136, v[108:109], v[112:113] offset0:2 offset1:3
	v_pk_fma_f32 v[104:105], v[110:111], v[112:113], v[104:105] op_sel_hi:[1,0,1]
	ds_write2_b64 v138, v[106:107], v[104:105] offset1:1
	ds_read2_b64 v[104:107], v122 offset1:1
	v_pk_mul_f32 v[108:109], v[110:111], s[8:9] op_sel:[1,0]
	s_nop 0
	v_pk_fma_f32 v[116:117], v[110:111], s[30:31], v[108:109] op_sel_hi:[0,1,1]
	ds_read2_b64 v[108:111], v136 offset0:4 offset1:5
	s_waitcnt lgkmcnt(1)
	v_pk_mul_f32 v[112:113], v[116:117], v[104:105] op_sel_hi:[1,0] neg_hi:[1,0]
	s_nop 0
	v_pk_fma_f32 v[104:105], v[116:117], v[104:105], v[112:113] op_sel:[1,1,0] op_sel_hi:[0,1,1]
	s_waitcnt lgkmcnt(0)
	v_pk_add_f32 v[104:105], v[108:109], v[104:105]
	s_nop 0
	v_pk_mul_f32 v[104:105], v[130:131], v[104:105]
	s_nop 0
	v_pk_mul_f32 v[108:109], v[116:117], v[104:105] op_sel:[1,1] op_sel_hi:[0,1] neg_lo:[1,0]
	v_pk_mul_f32 v[118:119], v[116:117], s[8:9] op_sel:[1,0]
	v_pk_fma_f32 v[108:109], v[116:117], v[104:105], v[108:109] op_sel_hi:[1,0,1]
	v_pk_fma_f32 v[116:117], v[116:117], s[30:31], v[118:119] op_sel_hi:[0,1,1]
	v_pk_mul_f32 v[120:121], v[116:117], v[106:107] op_sel_hi:[1,0] neg_hi:[1,0]
	v_mov_b32_e32 v106, v107
	v_pk_fma_f32 v[106:107], v[116:117], v[106:107], v[120:121] op_sel:[1,1,0] op_sel_hi:[0,1,1]
	v_pk_add_f32 v[106:107], v[110:111], v[106:107]
	ds_read2_b64 v[112:115], v136 offset0:6 offset1:7
	v_pk_mul_f32 v[4:5], v[4:5], v[106:107]
	v_add_co_u32_e32 v106, vcc, s5, v6
	s_nop 1
	v_addc_co_u32_e32 v107, vcc, 0, v7, vcc
	v_add_co_u32_e32 v110, vcc, s5, v132
	s_nop 1
	v_addc_co_u32_e32 v111, vcc, 0, v133, vcc
	v_add_co_u32_e32 v6, vcc, s27, v6
	s_nop 1
	v_addc_co_u32_e32 v7, vcc, 0, v7, vcc
	v_add_co_u32_e32 v120, vcc, s27, v132
	s_nop 1
	v_addc_co_u32_e32 v121, vcc, 0, v133, vcc
	global_load_ushort v233, v[106:107], off
	global_load_ushort v232, v[110:111], off
	global_load_ushort v231, v[6:7], off
	global_load_ushort v176, v[120:121], off
	v_pk_mul_f32 v[6:7], v[116:117], v[4:5] op_sel:[1,1] op_sel_hi:[0,1] neg_lo:[1,0]
	ds_write2_b64 v136, v[104:105], v[4:5] offset0:4 offset1:5
	v_pk_fma_f32 v[4:5], v[116:117], v[4:5], v[6:7] op_sel_hi:[1,0,1]
	v_add_u32_e32 v110, 0x8830, v136
	ds_write2_b64 v122, v[108:109], v[4:5] offset1:1
	ds_read2_b64 v[4:7], v110 offset1:1
	v_pk_mul_f32 v[104:105], v[116:117], s[8:9] op_sel:[1,0]
	v_mov_b32_e32 v111, v177
	v_pk_fma_f32 v[104:105], v[116:117], s[30:31], v[104:105] op_sel_hi:[0,1,1]
	s_waitcnt lgkmcnt(0)
	v_pk_mul_f32 v[108:109], v[104:105], v[4:5] op_sel_hi:[1,0] neg_hi:[1,0]
	s_nop 0
	v_pk_fma_f32 v[4:5], v[104:105], v[4:5], v[108:109] op_sel:[1,1,0] op_sel_hi:[0,1,1]
	v_pk_add_f32 v[4:5], v[112:113], v[4:5]
	s_nop 0
	v_pk_mul_f32 v[2:3], v[2:3], v[4:5]
	s_nop 0
	v_pk_mul_f32 v[4:5], v[104:105], v[2:3] op_sel:[1,1] op_sel_hi:[0,1] neg_lo:[1,0]
	v_pk_mul_f32 v[106:107], v[104:105], s[8:9] op_sel:[1,0]
	v_pk_fma_f32 v[4:5], v[104:105], v[2:3], v[4:5] op_sel_hi:[1,0,1]
	v_pk_fma_f32 v[104:105], v[104:105], s[30:31], v[106:107] op_sel_hi:[0,1,1]
	v_pk_mul_f32 v[108:109], v[104:105], v[6:7] op_sel_hi:[1,0] neg_hi:[1,0]
	v_mov_b32_e32 v6, v7
	v_pk_fma_f32 v[6:7], v[104:105], v[6:7], v[108:109] op_sel:[1,1,0] op_sel_hi:[0,1,1]
	v_pk_add_f32 v[6:7], v[114:115], v[6:7]
	s_nop 0
	v_pk_mul_f32 v[0:1], v[0:1], v[6:7]
	ds_write2_b64 v136, v[2:3], v[0:1] offset0:6 offset1:7
	v_pk_mul_f32 v[2:3], v[104:105], v[0:1] op_sel:[1,1] op_sel_hi:[0,1] neg_lo:[1,0]
	v_pk_fma_f32 v[0:1], v[104:105], v[0:1], v[2:3] op_sel_hi:[1,0,1]
	ds_write2_b64 v110, v[4:5], v[0:1] offset1:1
	v_and_b32_e32 v0, 0x1ff, v212
	v_lshl_add_u32 v0, v0, 3, 0
	v_add_u32_e32 v234, 0x11040, v0
	v_mov_b32_e32 v110, 1.0
	v_pk_mul_f32 v[2:3], v[208:209], v[208:209] op_sel:[1,1] op_sel_hi:[0,1] neg_lo:[1,0]
	s_waitcnt lgkmcnt(0)
	v_pk_fma_f32 v[2:3], v[208:209], v[208:209], v[2:3] op_sel_hi:[0,1,1]
	v_pk_mul_f32 v[104:105], v[2:3], v[2:3] op_sel:[1,1] op_sel_hi:[1,0] neg_lo:[0,1]
	v_pk_mul_f32 v[4:5], v[208:209], v[176:177] op_sel:[1,1] op_sel_hi:[0,1] neg_lo:[1,0]
	v_pk_fma_f32 v[104:105], v[2:3], v[2:3], v[104:105] op_sel_hi:[1,0,1]
	v_pk_fma_f32 v[114:115], v[208:209], v[110:111], v[4:5] op_sel_hi:[1,0,1]
	v_pk_mul_f32 v[0:1], v[176:177], v[2:3] op_sel:[1,1] op_sel_hi:[1,0] neg_lo:[0,1]
	s_nop 0
	v_pk_fma_f32 v[116:117], v[110:111], v[2:3], v[0:1] op_sel_hi:[0,1,1]
	v_pk_mul_f32 v[0:1], v[114:115], v[2:3] op_sel:[1,1] op_sel_hi:[1,0] neg_lo:[0,1]
	v_pk_mul_f32 v[108:109], v[104:105], v[104:105] op_sel:[1,1] op_sel_hi:[1,0] neg_lo:[0,1]
	v_pk_fma_f32 v[118:119], v[2:3], v[114:115], v[0:1] op_sel_hi:[1,0,1]
	v_pk_mul_f32 v[0:1], v[176:177], v[104:105] op_sel:[1,1] op_sel_hi:[1,0] neg_lo:[0,1]
	s_nop 0
	v_pk_fma_f32 v[120:121], v[110:111], v[104:105], v[0:1] op_sel_hi:[0,1,1]
	v_pk_mul_f32 v[0:1], v[114:115], v[104:105] op_sel:[1,1] op_sel_hi:[1,0] neg_lo:[0,1]
	s_barrier
	v_pk_fma_f32 v[122:123], v[114:115], v[104:105], v[0:1] op_sel_hi:[0,1,1]
	v_pk_mul_f32 v[0:1], v[116:117], v[104:105] op_sel:[1,1] op_sel_hi:[1,0] neg_lo:[0,1]
	s_nop 0
	v_pk_fma_f32 v[124:125], v[104:105], v[116:117], v[0:1] op_sel_hi:[1,0,1]
	v_pk_mul_f32 v[0:1], v[118:119], v[104:105] op_sel:[1,1] op_sel_hi:[1,0] neg_lo:[0,1]
	s_nop 0
	v_pk_fma_f32 v[126:127], v[104:105], v[118:119], v[0:1] op_sel_hi:[1,0,1]
	v_pk_fma_f32 v[0:1], v[104:105], v[104:105], v[108:109] op_sel_hi:[1,0,1]
	s_nop 0
	v_pk_mul_f32 v[2:3], v[176:177], v[0:1] op_sel:[1,1] op_sel_hi:[1,0] neg_lo:[0,1]
	s_nop 0
	v_pk_fma_f32 v[112:113], v[110:111], v[0:1], v[2:3] op_sel_hi:[0,1,1]
	v_pk_mul_f32 v[2:3], v[114:115], v[0:1] op_sel:[1,1] op_sel_hi:[1,0] neg_lo:[0,1]
	s_nop 0
	v_pk_fma_f32 v[108:109], v[114:115], v[0:1], v[2:3] op_sel_hi:[0,1,1]
	v_pk_mul_f32 v[2:3], v[116:117], v[0:1] op_sel:[1,1] op_sel_hi:[1,0] neg_lo:[0,1]
	s_nop 0
	v_pk_fma_f32 v[106:107], v[116:117], v[0:1], v[2:3] op_sel_hi:[0,1,1]
	v_pk_mul_f32 v[2:3], v[118:119], v[0:1] op_sel:[1,1] op_sel_hi:[1,0] neg_lo:[0,1]
	s_nop 0
	v_pk_fma_f32 v[104:105], v[118:119], v[0:1], v[2:3] op_sel_hi:[0,1,1]
	v_pk_mul_f32 v[2:3], v[120:121], v[0:1] op_sel:[1,1] op_sel_hi:[1,0] neg_lo:[0,1]
	s_nop 0
	v_pk_fma_f32 v[6:7], v[0:1], v[120:121], v[2:3] op_sel_hi:[1,0,1]
	v_pk_mul_f32 v[2:3], v[122:123], v[0:1] op_sel:[1,1] op_sel_hi:[1,0] neg_lo:[0,1]
	s_nop 0
	v_pk_fma_f32 v[4:5], v[0:1], v[122:123], v[2:3] op_sel_hi:[1,0,1]
	v_pk_mul_f32 v[2:3], v[124:125], v[0:1] op_sel:[1,1] op_sel_hi:[1,0] neg_lo:[0,1]
	v_pk_mul_f32 v[128:129], v[126:127], v[0:1] op_sel:[1,1] op_sel_hi:[1,0] neg_lo:[0,1]
	v_pk_fma_f32 v[2:3], v[0:1], v[124:125], v[2:3] op_sel_hi:[1,0,1]
	v_pk_fma_f32 v[0:1], v[0:1], v[126:127], v[128:129] op_sel_hi:[1,0,1]
	v_mov_b32_e32 v128, v206
	s_nop 0
	v_lshlrev_b32_sdwa v129, v228, v128 dst_sel:DWORD dst_unused:UNUSED_PAD src0_sel:DWORD src1_sel:BYTE_0
	v_lshrrev_b32_e32 v128, 1, v206
	v_and_b32_e32 v128, 0x78, v128
	v_add3_u32 v164, v207, v129, v128
	ds_read_b64 v[128:129], v164
	ds_read_b64 v[130:131], v164 offset:2176
	ds_read_b64 v[132:133], v164 offset:4352
	ds_read_b64 v[134:135], v164 offset:6528
	ds_read_b64 v[136:137], v164 offset:8704
	ds_read_b64 v[138:139], v164 offset:10880
	ds_read_b64 v[140:141], v164 offset:13056
	ds_read_b64 v[142:143], v164 offset:15232
	ds_read_b64 v[144:145], v164 offset:17408
	ds_read_b64 v[146:147], v164 offset:19584
	ds_read_b64 v[148:149], v164 offset:21760
	ds_read_b64 v[150:151], v164 offset:23936
	ds_read_b64 v[152:153], v164 offset:26112
	ds_read_b64 v[154:155], v164 offset:28288
	ds_read_b64 v[156:157], v164 offset:30464
	ds_read_b64 v[158:159], v164 offset:32640
	s_waitcnt lgkmcnt(7)
	v_pk_add_f32 v[160:161], v[128:129], v[144:145]
	v_pk_add_f32 v[128:129], v[128:129], v[144:145] neg_lo:[0,1] neg_hi:[0,1]
	s_waitcnt lgkmcnt(3)
	v_pk_add_f32 v[144:145], v[136:137], v[152:153]
	v_pk_add_f32 v[136:137], v[136:137], v[152:153] neg_lo:[0,1] neg_hi:[0,1]
	s_nop 0
	v_pk_add_f32 v[162:163], v[128:129], v[136:137] op_sel:[0,1] op_sel_hi:[1,0] neg_hi:[0,1]
	v_pk_add_f32 v[128:129], v[128:129], v[136:137] op_sel:[0,1] op_sel_hi:[1,0] neg_lo:[0,1]
	v_pk_add_f32 v[152:153], v[130:131], v[146:147]
	v_pk_add_f32 v[130:131], v[130:131], v[146:147] neg_lo:[0,1] neg_hi:[0,1]
	s_waitcnt lgkmcnt(2)
	v_pk_add_f32 v[146:147], v[138:139], v[154:155]
	v_pk_add_f32 v[138:139], v[138:139], v[154:155] neg_lo:[0,1] neg_hi:[0,1]
	v_pk_add_f32 v[136:137], v[160:161], v[144:145]
	v_xor_b32_e32 v155, 0x80000000, v138
	v_mov_b32_e32 v154, v139
	v_pk_add_f32 v[138:139], v[152:153], v[146:147]
	v_pk_add_f32 v[146:147], v[152:153], v[146:147] neg_lo:[0,1] neg_hi:[0,1]
	v_pk_add_f32 v[152:153], v[132:133], v[148:149]
	v_pk_add_f32 v[132:133], v[132:133], v[148:149] neg_lo:[0,1] neg_hi:[0,1]
	s_waitcnt lgkmcnt(1)
	v_pk_add_f32 v[148:149], v[140:141], v[156:157]
	v_pk_add_f32 v[140:141], v[140:141], v[156:157] neg_lo:[0,1] neg_hi:[0,1]
	v_pk_add_f32 v[144:145], v[160:161], v[144:145] neg_lo:[0,1] neg_hi:[0,1]
	v_pk_add_f32 v[160:161], v[130:131], v[154:155]
	v_pk_add_f32 v[130:131], v[130:131], v[154:155] neg_lo:[0,1] neg_hi:[0,1]
	v_xor_b32_e32 v155, 0x80000000, v140
	v_mov_b32_e32 v154, v141
	v_pk_add_f32 v[140:141], v[152:153], v[148:149]
	v_pk_add_f32 v[148:149], v[152:153], v[148:149] neg_lo:[0,1] neg_hi:[0,1]
	v_pk_add_f32 v[152:153], v[134:135], v[150:151]
	v_pk_add_f32 v[134:135], v[134:135], v[150:151] neg_lo:[0,1] neg_hi:[0,1]
	s_waitcnt lgkmcnt(0)
	v_pk_add_f32 v[150:151], v[142:143], v[158:159]
	v_pk_add_f32 v[142:143], v[142:143], v[158:159] neg_lo:[0,1] neg_hi:[0,1]
	v_pk_add_f32 v[156:157], v[132:133], v[154:155]
	v_pk_add_f32 v[132:133], v[132:133], v[154:155] neg_lo:[0,1] neg_hi:[0,1]
	v_pk_add_f32 v[158:159], v[134:135], v[142:143] op_sel:[0,1] op_sel_hi:[1,0] neg_hi:[0,1]
	v_pk_add_f32 v[134:135], v[134:135], v[142:143] op_sel:[0,1] op_sel_hi:[1,0] neg_lo:[0,1]
	v_pk_mul_f32 v[154:155], v[146:147], s[12:13] op_sel:[1,0] op_sel_hi:[0,0] neg_lo:[1,0]
	v_pk_add_f32 v[142:143], v[152:153], v[150:151]
	v_pk_fma_f32 v[146:147], v[146:147], s[12:13], v[154:155] op_sel_hi:[1,0,1] neg_lo:[0,0,1] neg_hi:[0,0,1]
	v_pk_mul_f32 v[154:155], v[130:131], s[36:37] op_sel:[1,0] op_sel_hi:[0,0] neg_lo:[1,0]
	v_pk_add_f32 v[150:151], v[152:153], v[150:151] neg_lo:[0,1] neg_hi:[0,1]
	v_pk_fma_f32 v[130:131], v[130:131], s[22:23], v[154:155] op_sel_hi:[1,0,1] neg_lo:[0,0,1] neg_hi:[0,0,1]
	v_pk_mul_f32 v[154:155], v[156:157], s[12:13] op_sel:[1,0] op_sel_hi:[0,0] neg_lo:[1,0]
	v_pk_fma_f32 v[154:155], v[156:157], s[12:13], v[154:155] op_sel_hi:[1,0,1] neg_lo:[0,0,1] neg_hi:[0,0,1]
	v_pk_fma_f32 v[148:149], v[148:149], 0, v[148:149] op_sel:[0,0,1] op_sel_hi:[1,0,0] neg_hi:[0,0,1]
	v_pk_mul_f32 v[156:157], v[132:133], s[12:13] op_sel:[1,0] op_sel_hi:[0,0] neg_lo:[1,0]
	v_pk_fma_f32 v[132:133], v[132:133], s[18:19], v[156:157] op_sel_hi:[1,0,1] neg_lo:[0,0,1] neg_hi:[0,0,1]
	v_pk_mul_f32 v[156:157], v[158:159], s[36:37] op_sel:[1,0] op_sel_hi:[0,0] neg_lo:[1,0]
	v_pk_mul_f32 v[152:153], v[160:161], s[22:23] op_sel:[1,0] op_sel_hi:[0,0] neg_lo:[1,0]
	v_pk_fma_f32 v[156:157], v[158:159], s[22:23], v[156:157] op_sel_hi:[1,0,1] neg_lo:[0,0,1] neg_hi:[0,0,1]
	v_pk_mul_f32 v[158:159], v[150:151], s[12:13] op_sel:[1,0] op_sel_hi:[0,0] neg_lo:[1,0]
	v_pk_fma_f32 v[152:153], v[160:161], s[36:37], v[152:153] op_sel_hi:[1,0,1] neg_lo:[0,0,1] neg_hi:[0,0,1]
	v_pk_fma_f32 v[150:151], v[150:151], s[18:19], v[158:159] op_sel_hi:[1,0,1] neg_lo:[0,0,1] neg_hi:[0,0,1]
	v_xor_b32_e32 v158, 0x80000000, v135
	v_mov_b32_e32 v159, v134
	v_pk_mul_f32 v[134:135], v[134:135], s[36:37] op_sel_hi:[1,0]
	s_nop 0
	v_pk_fma_f32 v[134:135], v[158:159], s[22:23], v[134:135] op_sel_hi:[1,0,1] neg_lo:[0,0,1] neg_hi:[0,0,1]
	v_pk_add_f32 v[158:159], v[136:137], v[140:141]
	v_pk_add_f32 v[136:137], v[136:137], v[140:141] neg_lo:[0,1] neg_hi:[0,1]
	v_pk_add_f32 v[140:141], v[138:139], v[142:143]
	v_pk_add_f32 v[138:139], v[138:139], v[142:143] neg_lo:[0,1] neg_hi:[0,1]
	s_nop 0
	v_xor_b32_e32 v143, 0x80000000, v138
	v_mov_b32_e32 v142, v139
	v_pk_add_f32 v[138:139], v[158:159], v[140:141]
	v_pk_add_f32 v[140:141], v[158:159], v[140:141] neg_lo:[0,1] neg_hi:[0,1]
	v_pk_add_f32 v[158:159], v[152:153], v[156:157]
	v_pk_add_f32 v[152:153], v[152:153], v[156:157] neg_lo:[0,1] neg_hi:[0,1]
	v_pk_add_f32 v[160:161], v[136:137], v[142:143]
	v_pk_add_f32 v[136:137], v[136:137], v[142:143] neg_lo:[0,1] neg_hi:[0,1]
	v_pk_add_f32 v[142:143], v[162:163], v[154:155]
	v_pk_add_f32 v[154:155], v[162:163], v[154:155] neg_lo:[0,1] neg_hi:[0,1]
	s_nop 0
	v_pk_add_f32 v[162:163], v[154:155], v[152:153] op_sel:[0,1] op_sel_hi:[1,0] neg_hi:[0,1]
	v_pk_add_f32 v[154:155], v[154:155], v[152:153] op_sel:[0,1] op_sel_hi:[1,0] neg_lo:[0,1]
	v_pk_add_f32 v[156:157], v[144:145], v[148:149]
	v_pk_add_f32 v[144:145], v[144:145], v[148:149] neg_lo:[0,1] neg_hi:[0,1]
	v_pk_add_f32 v[148:149], v[146:147], v[150:151]
	v_pk_add_f32 v[146:147], v[146:147], v[150:151] neg_lo:[0,1] neg_hi:[0,1]
	v_pk_add_f32 v[152:153], v[142:143], v[158:159]
	v_pk_add_f32 v[142:143], v[142:143], v[158:159] neg_lo:[0,1] neg_hi:[0,1]
	v_pk_add_f32 v[158:159], v[144:145], v[146:147] op_sel:[0,1] op_sel_hi:[1,0] neg_hi:[0,1]
	v_pk_add_f32 v[144:145], v[144:145], v[146:147] op_sel:[0,1] op_sel_hi:[1,0] neg_lo:[0,1]
	v_pk_add_f32 v[150:151], v[128:129], v[132:133]
	v_pk_add_f32 v[128:129], v[128:129], v[132:133] neg_lo:[0,1] neg_hi:[0,1]
	v_pk_add_f32 v[132:133], v[130:131], v[134:135]
	v_pk_add_f32 v[130:131], v[130:131], v[134:135] neg_lo:[0,1] neg_hi:[0,1]
	v_pk_add_f32 v[146:147], v[156:157], v[148:149]
	v_pk_add_f32 v[148:149], v[156:157], v[148:149] neg_lo:[0,1] neg_hi:[0,1]
	v_pk_add_f32 v[156:157], v[128:129], v[130:131] op_sel:[0,1] op_sel_hi:[1,0] neg_hi:[0,1]
	v_pk_add_f32 v[128:129], v[128:129], v[130:131] op_sel:[0,1] op_sel_hi:[1,0] neg_lo:[0,1]
	v_xor_b32_e32 v134, 0x80000000, v111
	v_mov_b32_e32 v135, v110
	v_pk_mul_f32 v[134:135], v[134:135], v[138:139] op_sel:[0,1]
	v_pk_add_f32 v[130:131], v[150:151], v[132:133]
	v_pk_fma_f32 v[110:111], v[110:111], v[138:139], v[134:135] op_sel_hi:[1,0,1]
	ds_write_b64 v164, v[110:111]
	v_pk_mul_f32 v[110:111], v[114:115], v[152:153] op_sel:[1,1] op_sel_hi:[0,1] neg_lo:[1,0]
	v_pk_add_f32 v[132:133], v[150:151], v[132:133] neg_lo:[0,1] neg_hi:[0,1]
	v_pk_fma_f32 v[110:111], v[114:115], v[152:153], v[110:111] op_sel_hi:[1,0,1]
	ds_write_b64 v164, v[110:111] offset:2176
	v_pk_mul_f32 v[110:111], v[116:117], v[146:147] op_sel:[1,1] op_sel_hi:[0,1] neg_lo:[1,0]
	v_pk_fma_f32 v[110:111], v[116:117], v[146:147], v[110:111] op_sel_hi:[1,0,1]
	ds_write_b64 v164, v[110:111] offset:4352
	v_pk_mul_f32 v[110:111], v[118:119], v[130:131] op_sel:[1,1] op_sel_hi:[0,1] neg_lo:[1,0]
	v_pk_fma_f32 v[110:111], v[118:119], v[130:131], v[110:111] op_sel_hi:[1,0,1]
	ds_write_b64 v164, v[110:111] offset:6528
	v_pk_mul_f32 v[110:111], v[120:121], v[160:161] op_sel:[1,1] op_sel_hi:[0,1] neg_lo:[1,0]
	v_pk_fma_f32 v[110:111], v[120:121], v[160:161], v[110:111] op_sel_hi:[1,0,1]
	ds_write_b64 v164, v[110:111] offset:8704
	v_pk_mul_f32 v[110:111], v[122:123], v[162:163] op_sel:[1,1] op_sel_hi:[0,1] neg_lo:[1,0]
	v_pk_fma_f32 v[110:111], v[122:123], v[162:163], v[110:111] op_sel_hi:[1,0,1]
	ds_write_b64 v164, v[110:111] offset:10880
	v_pk_mul_f32 v[110:111], v[124:125], v[158:159] op_sel:[1,1] op_sel_hi:[0,1] neg_lo:[1,0]
	v_pk_fma_f32 v[110:111], v[124:125], v[158:159], v[110:111] op_sel_hi:[1,0,1]
	ds_write_b64 v164, v[110:111] offset:13056
	v_pk_mul_f32 v[110:111], v[126:127], v[156:157] op_sel:[1,1] op_sel_hi:[0,1] neg_lo:[1,0]
	v_pk_fma_f32 v[110:111], v[126:127], v[156:157], v[110:111] op_sel_hi:[1,0,1]
	ds_write_b64 v164, v[110:111] offset:15232
	v_pk_mul_f32 v[110:111], v[112:113], v[140:141] op_sel:[1,1] op_sel_hi:[0,1] neg_lo:[1,0]
	v_pk_fma_f32 v[110:111], v[112:113], v[140:141], v[110:111] op_sel_hi:[1,0,1]
	ds_write_b64 v164, v[110:111] offset:17408
	v_pk_mul_f32 v[110:111], v[108:109], v[142:143] op_sel:[1,1] op_sel_hi:[0,1] neg_lo:[1,0]
	v_pk_fma_f32 v[108:109], v[108:109], v[142:143], v[110:111] op_sel_hi:[1,0,1]
	ds_write_b64 v164, v[108:109] offset:19584
	v_pk_mul_f32 v[108:109], v[106:107], v[148:149] op_sel:[1,1] op_sel_hi:[0,1] neg_lo:[1,0]
	v_pk_fma_f32 v[106:107], v[106:107], v[148:149], v[108:109] op_sel_hi:[1,0,1]
	ds_write_b64 v164, v[106:107] offset:21760
	v_pk_mul_f32 v[106:107], v[104:105], v[132:133] op_sel:[1,1] op_sel_hi:[0,1] neg_lo:[1,0]
	v_pk_fma_f32 v[104:105], v[104:105], v[132:133], v[106:107] op_sel_hi:[1,0,1]
	ds_write_b64 v164, v[104:105] offset:23936
	v_pk_mul_f32 v[104:105], v[6:7], v[136:137] op_sel:[1,1] op_sel_hi:[0,1] neg_lo:[1,0]
	v_pk_fma_f32 v[6:7], v[6:7], v[136:137], v[104:105] op_sel_hi:[1,0,1]
	ds_write_b64 v164, v[6:7] offset:26112
	v_pk_mul_f32 v[6:7], v[4:5], v[154:155] op_sel:[1,1] op_sel_hi:[0,1] neg_lo:[1,0]
	v_pk_fma_f32 v[4:5], v[4:5], v[154:155], v[6:7] op_sel_hi:[1,0,1]
	ds_write_b64 v164, v[4:5] offset:28288
	v_pk_mul_f32 v[4:5], v[2:3], v[144:145] op_sel:[1,1] op_sel_hi:[0,1] neg_lo:[1,0]
	v_pk_fma_f32 v[2:3], v[2:3], v[144:145], v[4:5] op_sel_hi:[1,0,1]
	ds_write_b64 v164, v[2:3] offset:30464
	v_pk_mul_f32 v[2:3], v[0:1], v[128:129] op_sel:[1,1] op_sel_hi:[0,1] neg_lo:[1,0]
	v_pk_fma_f32 v[0:1], v[0:1], v[128:129], v[2:3] op_sel_hi:[1,0,1]
	ds_write_b64 v164, v[0:1] offset:32640
	v_mov_b32_e32 v116, 1.0
	v_pk_mul_f32 v[2:3], v[210:211], v[210:211] op_sel:[1,1] op_sel_hi:[0,1] neg_lo:[1,0]
	v_mov_b32_e32 v117, v177
	v_pk_fma_f32 v[2:3], v[210:211], v[210:211], v[2:3] op_sel_hi:[0,1,1]
	v_pk_mul_f32 v[104:105], v[2:3], v[2:3] op_sel:[1,1] op_sel_hi:[1,0] neg_lo:[0,1]
	v_pk_mul_f32 v[4:5], v[210:211], v[176:177] op_sel:[1,1] op_sel_hi:[0,1] neg_lo:[1,0]
	v_pk_fma_f32 v[104:105], v[2:3], v[2:3], v[104:105] op_sel_hi:[1,0,1]
	v_pk_fma_f32 v[126:127], v[210:211], v[116:117], v[4:5] op_sel_hi:[1,0,1]
	v_pk_mul_f32 v[0:1], v[176:177], v[2:3] op_sel:[1,1] op_sel_hi:[1,0] neg_lo:[0,1]
	s_nop 0
	v_pk_fma_f32 v[124:125], v[116:117], v[2:3], v[0:1] op_sel_hi:[0,1,1]
	v_pk_mul_f32 v[0:1], v[126:127], v[2:3] op_sel:[1,1] op_sel_hi:[1,0] neg_lo:[0,1]
	v_pk_mul_f32 v[108:109], v[104:105], v[104:105] op_sel:[1,1] op_sel_hi:[1,0] neg_lo:[0,1]
	v_pk_fma_f32 v[122:123], v[2:3], v[126:127], v[0:1] op_sel_hi:[1,0,1]
	v_pk_mul_f32 v[0:1], v[176:177], v[104:105] op_sel:[1,1] op_sel_hi:[1,0] neg_lo:[0,1]
	s_nop 0
	v_pk_fma_f32 v[120:121], v[116:117], v[104:105], v[0:1] op_sel_hi:[0,1,1]
	v_pk_mul_f32 v[0:1], v[126:127], v[104:105] op_sel:[1,1] op_sel_hi:[1,0] neg_lo:[0,1]
	s_waitcnt lgkmcnt(0)
	v_pk_fma_f32 v[118:119], v[126:127], v[104:105], v[0:1] op_sel_hi:[0,1,1]
	v_pk_mul_f32 v[0:1], v[124:125], v[104:105] op_sel:[1,1] op_sel_hi:[1,0] neg_lo:[0,1]
	s_barrier
	v_pk_fma_f32 v[114:115], v[104:105], v[124:125], v[0:1] op_sel_hi:[1,0,1]
	v_pk_mul_f32 v[0:1], v[122:123], v[104:105] op_sel:[1,1] op_sel_hi:[1,0] neg_lo:[0,1]
	s_nop 0
	v_pk_fma_f32 v[112:113], v[104:105], v[122:123], v[0:1] op_sel_hi:[1,0,1]
	v_pk_fma_f32 v[0:1], v[104:105], v[104:105], v[108:109] op_sel_hi:[1,0,1]
	s_nop 0
	v_pk_mul_f32 v[2:3], v[176:177], v[0:1] op_sel:[1,1] op_sel_hi:[1,0] neg_lo:[0,1]
	s_nop 0
	v_pk_fma_f32 v[110:111], v[116:117], v[0:1], v[2:3] op_sel_hi:[0,1,1]
	v_pk_mul_f32 v[2:3], v[126:127], v[0:1] op_sel:[1,1] op_sel_hi:[1,0] neg_lo:[0,1]
	s_nop 0
	v_pk_fma_f32 v[108:109], v[126:127], v[0:1], v[2:3] op_sel_hi:[0,1,1]
	v_pk_mul_f32 v[2:3], v[124:125], v[0:1] op_sel:[1,1] op_sel_hi:[1,0] neg_lo:[0,1]
	s_nop 0
	v_pk_fma_f32 v[106:107], v[124:125], v[0:1], v[2:3] op_sel_hi:[0,1,1]
	v_pk_mul_f32 v[2:3], v[122:123], v[0:1] op_sel:[1,1] op_sel_hi:[1,0] neg_lo:[0,1]
	s_nop 0
	v_pk_fma_f32 v[104:105], v[122:123], v[0:1], v[2:3] op_sel_hi:[0,1,1]
	v_pk_mul_f32 v[2:3], v[120:121], v[0:1] op_sel:[1,1] op_sel_hi:[1,0] neg_lo:[0,1]
	s_nop 0
	v_pk_fma_f32 v[6:7], v[0:1], v[120:121], v[2:3] op_sel_hi:[1,0,1]
	v_pk_mul_f32 v[2:3], v[118:119], v[0:1] op_sel:[1,1] op_sel_hi:[1,0] neg_lo:[0,1]
	s_nop 0
	v_pk_fma_f32 v[4:5], v[0:1], v[118:119], v[2:3] op_sel_hi:[1,0,1]
	v_pk_mul_f32 v[2:3], v[114:115], v[0:1] op_sel:[1,1] op_sel_hi:[1,0] neg_lo:[0,1]
	v_pk_mul_f32 v[128:129], v[112:113], v[0:1] op_sel:[1,1] op_sel_hi:[1,0] neg_lo:[0,1]
	v_pk_fma_f32 v[2:3], v[0:1], v[114:115], v[2:3] op_sel_hi:[1,0,1]
	v_pk_fma_f32 v[0:1], v[0:1], v[112:113], v[128:129] op_sel_hi:[1,0,1]
	s_nop 0
	v_bfe_u32 v129, v206, 4, 4
	v_and_b32_e32 v128, 15, v206
	v_mul_u32_u24_e32 v129, 0x880, v129
	v_lshlrev_b32_e32 v128, 3, v128
	v_add3_u32 v184, v207, v129, v128
	ds_read2_b64 v[128:131], v184 offset1:17
	ds_read2_b64 v[132:135], v184 offset0:34 offset1:51
	ds_read2_b64 v[136:139], v184 offset0:68 offset1:85
	ds_read2_b64 v[140:143], v184 offset0:102 offset1:119
	ds_read2_b64 v[144:147], v184 offset0:136 offset1:153
	ds_read2_b64 v[148:151], v184 offset0:170 offset1:187
	ds_read2_b64 v[152:155], v184 offset0:204 offset1:221
	ds_read2_b64 v[156:159], v184 offset0:238 offset1:255
	s_waitcnt lgkmcnt(3)
	v_pk_add_f32 v[160:161], v[128:129], v[144:145]
	v_pk_add_f32 v[128:129], v[128:129], v[144:145] neg_lo:[0,1] neg_hi:[0,1]
	s_waitcnt lgkmcnt(1)
	v_pk_add_f32 v[144:145], v[136:137], v[152:153]
	v_pk_add_f32 v[136:137], v[136:137], v[152:153] neg_lo:[0,1] neg_hi:[0,1]
	s_nop 0
	v_pk_add_f32 v[162:163], v[128:129], v[136:137] op_sel:[0,1] op_sel_hi:[1,0] neg_hi:[0,1]
	v_pk_add_f32 v[128:129], v[128:129], v[136:137] op_sel:[0,1] op_sel_hi:[1,0] neg_lo:[0,1]
	v_pk_add_f32 v[152:153], v[130:131], v[146:147]
	v_pk_add_f32 v[130:131], v[130:131], v[146:147] neg_lo:[0,1] neg_hi:[0,1]
	v_pk_add_f32 v[146:147], v[138:139], v[154:155]
	v_pk_add_f32 v[138:139], v[138:139], v[154:155] neg_lo:[0,1] neg_hi:[0,1]
	v_pk_add_f32 v[136:137], v[160:161], v[144:145]
	v_xor_b32_e32 v155, 0x80000000, v138
	v_mov_b32_e32 v154, v139
	v_pk_add_f32 v[138:139], v[152:153], v[146:147]
	v_pk_add_f32 v[146:147], v[152:153], v[146:147] neg_lo:[0,1] neg_hi:[0,1]
	v_pk_add_f32 v[152:153], v[132:133], v[148:149]
	v_pk_add_f32 v[132:133], v[132:133], v[148:149] neg_lo:[0,1] neg_hi:[0,1]
	s_waitcnt lgkmcnt(0)
	v_pk_add_f32 v[148:149], v[140:141], v[156:157]
	v_pk_add_f32 v[140:141], v[140:141], v[156:157] neg_lo:[0,1] neg_hi:[0,1]
	v_pk_add_f32 v[144:145], v[160:161], v[144:145] neg_lo:[0,1] neg_hi:[0,1]
	v_pk_add_f32 v[160:161], v[130:131], v[154:155]
	v_pk_add_f32 v[130:131], v[130:131], v[154:155] neg_lo:[0,1] neg_hi:[0,1]
	v_xor_b32_e32 v155, 0x80000000, v140
	v_mov_b32_e32 v154, v141
	v_pk_add_f32 v[140:141], v[152:153], v[148:149]
	v_pk_add_f32 v[148:149], v[152:153], v[148:149] neg_lo:[0,1] neg_hi:[0,1]
	v_pk_add_f32 v[152:153], v[134:135], v[150:151]
	v_pk_add_f32 v[134:135], v[134:135], v[150:151] neg_lo:[0,1] neg_hi:[0,1]
	v_pk_add_f32 v[150:151], v[142:143], v[158:159]
	v_pk_add_f32 v[142:143], v[142:143], v[158:159] neg_lo:[0,1] neg_hi:[0,1]
	v_pk_add_f32 v[156:157], v[132:133], v[154:155]
	v_pk_add_f32 v[132:133], v[132:133], v[154:155] neg_lo:[0,1] neg_hi:[0,1]
	v_pk_add_f32 v[158:159], v[134:135], v[142:143] op_sel:[0,1] op_sel_hi:[1,0] neg_hi:[0,1]
	v_pk_add_f32 v[134:135], v[134:135], v[142:143] op_sel:[0,1] op_sel_hi:[1,0] neg_lo:[0,1]
	v_pk_mul_f32 v[154:155], v[146:147], s[12:13] op_sel:[1,0] op_sel_hi:[0,0] neg_lo:[1,0]
	v_pk_add_f32 v[142:143], v[152:153], v[150:151]
	v_pk_fma_f32 v[146:147], v[146:147], s[12:13], v[154:155] op_sel_hi:[1,0,1] neg_lo:[0,0,1] neg_hi:[0,0,1]
	v_pk_mul_f32 v[154:155], v[130:131], s[36:37] op_sel:[1,0] op_sel_hi:[0,0] neg_lo:[1,0]
	v_pk_add_f32 v[150:151], v[152:153], v[150:151] neg_lo:[0,1] neg_hi:[0,1]
	v_pk_fma_f32 v[130:131], v[130:131], s[22:23], v[154:155] op_sel_hi:[1,0,1] neg_lo:[0,0,1] neg_hi:[0,0,1]
	v_pk_mul_f32 v[154:155], v[156:157], s[12:13] op_sel:[1,0] op_sel_hi:[0,0] neg_lo:[1,0]
	v_pk_fma_f32 v[154:155], v[156:157], s[12:13], v[154:155] op_sel_hi:[1,0,1] neg_lo:[0,0,1] neg_hi:[0,0,1]
	v_pk_fma_f32 v[148:149], v[148:149], 0, v[148:149] op_sel:[0,0,1] op_sel_hi:[1,0,0] neg_hi:[0,0,1]
	v_pk_mul_f32 v[156:157], v[132:133], s[12:13] op_sel:[1,0] op_sel_hi:[0,0] neg_lo:[1,0]
	v_pk_fma_f32 v[132:133], v[132:133], s[18:19], v[156:157] op_sel_hi:[1,0,1] neg_lo:[0,0,1] neg_hi:[0,0,1]
	v_pk_mul_f32 v[156:157], v[158:159], s[36:37] op_sel:[1,0] op_sel_hi:[0,0] neg_lo:[1,0]
	v_pk_mul_f32 v[152:153], v[160:161], s[22:23] op_sel:[1,0] op_sel_hi:[0,0] neg_lo:[1,0]
	v_pk_fma_f32 v[156:157], v[158:159], s[22:23], v[156:157] op_sel_hi:[1,0,1] neg_lo:[0,0,1] neg_hi:[0,0,1]
	v_pk_mul_f32 v[158:159], v[150:151], s[12:13] op_sel:[1,0] op_sel_hi:[0,0] neg_lo:[1,0]
	v_pk_fma_f32 v[152:153], v[160:161], s[36:37], v[152:153] op_sel_hi:[1,0,1] neg_lo:[0,0,1] neg_hi:[0,0,1]
	v_pk_fma_f32 v[150:151], v[150:151], s[18:19], v[158:159] op_sel_hi:[1,0,1] neg_lo:[0,0,1] neg_hi:[0,0,1]
	v_xor_b32_e32 v158, 0x80000000, v135
	v_mov_b32_e32 v159, v134
	v_pk_mul_f32 v[134:135], v[134:135], s[36:37] op_sel_hi:[1,0]
	s_nop 0
	v_pk_fma_f32 v[134:135], v[158:159], s[22:23], v[134:135] op_sel_hi:[1,0,1] neg_lo:[0,0,1] neg_hi:[0,0,1]
	v_pk_add_f32 v[158:159], v[136:137], v[140:141]
	v_pk_add_f32 v[136:137], v[136:137], v[140:141] neg_lo:[0,1] neg_hi:[0,1]
	v_pk_add_f32 v[140:141], v[138:139], v[142:143]
	v_pk_add_f32 v[138:139], v[138:139], v[142:143] neg_lo:[0,1] neg_hi:[0,1]
	v_pk_add_f32 v[164:165], v[158:159], v[140:141] neg_lo:[0,1] neg_hi:[0,1]
	v_pk_add_f32 v[160:161], v[136:137], v[138:139] op_sel:[0,1] op_sel_hi:[1,0] neg_hi:[0,1]
	v_pk_add_f32 v[166:167], v[136:137], v[138:139] op_sel:[0,1] op_sel_hi:[1,0] neg_lo:[0,1]
	v_pk_add_f32 v[142:143], v[152:153], v[156:157]
	v_pk_add_f32 v[152:153], v[152:153], v[156:157] neg_lo:[0,1] neg_hi:[0,1]
	v_pk_add_f32 v[138:139], v[158:159], v[140:141]
	v_pk_add_f32 v[136:137], v[162:163], v[154:155]
	v_pk_add_f32 v[140:141], v[162:163], v[154:155] neg_lo:[0,1] neg_hi:[0,1]
	v_xor_b32_e32 v155, 0x80000000, v152
	v_mov_b32_e32 v154, v153
	v_pk_add_f32 v[152:153], v[136:137], v[142:143]
	v_pk_add_f32 v[162:163], v[140:141], v[154:155]
	v_pk_add_f32 v[168:169], v[136:137], v[142:143] neg_lo:[0,1] neg_hi:[0,1]
	v_pk_add_f32 v[170:171], v[140:141], v[154:155] neg_lo:[0,1] neg_hi:[0,1]
	v_pk_add_f32 v[136:137], v[144:145], v[148:149]
	v_pk_add_f32 v[140:141], v[144:145], v[148:149] neg_lo:[0,1] neg_hi:[0,1]
	v_pk_add_f32 v[142:143], v[146:147], v[150:151]
	v_pk_add_f32 v[144:145], v[146:147], v[150:151] neg_lo:[0,1] neg_hi:[0,1]
	v_pk_add_f32 v[172:173], v[136:137], v[142:143] neg_lo:[0,1] neg_hi:[0,1]
	v_xor_b32_e32 v147, 0x80000000, v144
	v_mov_b32_e32 v146, v145
	v_pk_add_f32 v[144:145], v[136:137], v[142:143]
	v_pk_add_f32 v[136:137], v[128:129], v[132:133]
	v_pk_add_f32 v[128:129], v[128:129], v[132:133] neg_lo:[0,1] neg_hi:[0,1]
	v_pk_add_f32 v[132:133], v[130:131], v[134:135]
	v_pk_add_f32 v[130:131], v[130:131], v[134:135] neg_lo:[0,1] neg_hi:[0,1]
	v_xor_b32_e32 v142, 0x80000000, v117
	v_xor_b32_e32 v135, 0x80000000, v130
	v_mov_b32_e32 v134, v131
	v_mov_b32_e32 v143, v116
	v_pk_add_f32 v[148:149], v[140:141], v[146:147]
	v_pk_add_f32 v[174:175], v[140:141], v[146:147] neg_lo:[0,1] neg_hi:[0,1]
	v_pk_add_f32 v[130:131], v[136:137], v[132:133]
	v_pk_add_f32 v[146:147], v[128:129], v[134:135]
	v_pk_add_f32 v[198:199], v[136:137], v[132:133] neg_lo:[0,1] neg_hi:[0,1]
	v_pk_add_f32 v[200:201], v[128:129], v[134:135] neg_lo:[0,1] neg_hi:[0,1]
	v_pk_mul_f32 v[128:129], v[142:143], v[138:139] op_sel:[0,1]
	v_pk_mul_f32 v[132:133], v[126:127], v[152:153] op_sel:[1,1] op_sel_hi:[0,1] neg_lo:[1,0]
	v_pk_fma_f32 v[128:129], v[116:117], v[138:139], v[128:129] op_sel_hi:[1,0,1]
	v_pk_fma_f32 v[132:133], v[126:127], v[152:153], v[132:133] op_sel_hi:[1,0,1]
	ds_write2_b64 v184, v[128:129], v[132:133] offset1:17
	v_pk_mul_f32 v[128:129], v[124:125], v[144:145] op_sel:[1,1] op_sel_hi:[0,1] neg_lo:[1,0]
	v_pk_mul_f32 v[132:133], v[122:123], v[130:131] op_sel:[1,1] op_sel_hi:[0,1] neg_lo:[1,0]
	v_pk_fma_f32 v[128:129], v[124:125], v[144:145], v[128:129] op_sel_hi:[1,0,1]
	v_pk_fma_f32 v[130:131], v[122:123], v[130:131], v[132:133] op_sel_hi:[1,0,1]
	ds_write2_b64 v184, v[128:129], v[130:131] offset0:34 offset1:51
	v_pk_mul_f32 v[128:129], v[120:121], v[160:161] op_sel:[1,1] op_sel_hi:[0,1] neg_lo:[1,0]
	v_pk_mul_f32 v[130:131], v[118:119], v[162:163] op_sel:[1,1] op_sel_hi:[0,1] neg_lo:[1,0]
	v_pk_fma_f32 v[128:129], v[120:121], v[160:161], v[128:129] op_sel_hi:[1,0,1]
	v_pk_fma_f32 v[130:131], v[118:119], v[162:163], v[130:131] op_sel_hi:[1,0,1]
	ds_write2_b64 v184, v[128:129], v[130:131] offset0:68 offset1:85
	v_pk_mul_f32 v[128:129], v[114:115], v[148:149] op_sel:[1,1] op_sel_hi:[0,1] neg_lo:[1,0]
	v_pk_mul_f32 v[130:131], v[112:113], v[146:147] op_sel:[1,1] op_sel_hi:[0,1] neg_lo:[1,0]
	v_pk_fma_f32 v[128:129], v[114:115], v[148:149], v[128:129] op_sel_hi:[1,0,1]
	v_pk_fma_f32 v[130:131], v[112:113], v[146:147], v[130:131] op_sel_hi:[1,0,1]
	ds_write2_b64 v184, v[128:129], v[130:131] offset0:102 offset1:119
	v_pk_mul_f32 v[128:129], v[110:111], v[164:165] op_sel:[1,1] op_sel_hi:[0,1] neg_lo:[1,0]
	v_pk_mul_f32 v[130:131], v[108:109], v[168:169] op_sel:[1,1] op_sel_hi:[0,1] neg_lo:[1,0]
	v_pk_fma_f32 v[128:129], v[110:111], v[164:165], v[128:129] op_sel_hi:[1,0,1]
	v_pk_fma_f32 v[130:131], v[108:109], v[168:169], v[130:131] op_sel_hi:[1,0,1]
	ds_write2_b64 v184, v[128:129], v[130:131] offset0:136 offset1:153
	v_pk_mul_f32 v[128:129], v[106:107], v[172:173] op_sel:[1,1] op_sel_hi:[0,1] neg_lo:[1,0]
	v_pk_mul_f32 v[130:131], v[104:105], v[198:199] op_sel:[1,1] op_sel_hi:[0,1] neg_lo:[1,0]
	v_pk_fma_f32 v[128:129], v[106:107], v[172:173], v[128:129] op_sel_hi:[1,0,1]
	v_pk_fma_f32 v[130:131], v[104:105], v[198:199], v[130:131] op_sel_hi:[1,0,1]
	ds_write2_b64 v184, v[128:129], v[130:131] offset0:170 offset1:187
	v_pk_mul_f32 v[128:129], v[6:7], v[166:167] op_sel:[1,1] op_sel_hi:[0,1] neg_lo:[1,0]
	v_pk_mul_f32 v[144:145], v[4:5], v[170:171] op_sel:[1,1] op_sel_hi:[0,1] neg_lo:[1,0]
	v_pk_fma_f32 v[128:129], v[6:7], v[166:167], v[128:129] op_sel_hi:[1,0,1]
	v_pk_fma_f32 v[144:145], v[4:5], v[170:171], v[144:145] op_sel_hi:[1,0,1]
	ds_write2_b64 v184, v[128:129], v[144:145] offset0:204 offset1:221
	v_pk_mul_f32 v[144:145], v[2:3], v[174:175] op_sel:[1,1] op_sel_hi:[0,1] neg_lo:[1,0]
	v_pk_fma_f32 v[160:161], v[2:3], v[174:175], v[144:145] op_sel_hi:[1,0,1]
	v_pk_mul_f32 v[162:163], v[0:1], v[200:201] op_sel:[1,1] op_sel_hi:[0,1] neg_lo:[1,0]
	v_pk_fma_f32 v[162:163], v[0:1], v[200:201], v[162:163] op_sel_hi:[1,0,1]
	ds_write2_b64 v184, v[160:161], v[162:163] offset0:238 offset1:255
	s_waitcnt lgkmcnt(0)
	s_barrier
	s_nop 0
	v_and_b32_e32 v129, 0xff, v206
	v_mad_u32_u24 v129, v129, s19, v207
	ds_read2_b64 v[160:163], v129 offset1:1
	ds_read2_b64 v[164:167], v129 offset0:2 offset1:3
	ds_read2_b64 v[168:171], v129 offset0:4 offset1:5
	ds_read2_b64 v[172:175], v129 offset0:6 offset1:7
	ds_read2_b64 v[198:201], v129 offset0:8 offset1:9
	ds_read2_b64 v[202:205], v129 offset0:10 offset1:11
	ds_read2_b64 v[236:239], v129 offset0:12 offset1:13
	ds_read2_b64 v[240:243], v129 offset0:14 offset1:15
	s_waitcnt lgkmcnt(3)
	v_pk_add_f32 v[244:245], v[160:161], v[198:199]
	v_pk_add_f32 v[160:161], v[160:161], v[198:199] neg_lo:[0,1] neg_hi:[0,1]
	s_waitcnt lgkmcnt(1)
	v_pk_add_f32 v[198:199], v[168:169], v[236:237]
	v_pk_add_f32 v[168:169], v[168:169], v[236:237] neg_lo:[0,1] neg_hi:[0,1]
	s_nop 0
	v_pk_add_f32 v[246:247], v[160:161], v[168:169] op_sel:[0,1] op_sel_hi:[1,0] neg_hi:[0,1]
	v_pk_add_f32 v[160:161], v[160:161], v[168:169] op_sel:[0,1] op_sel_hi:[1,0] neg_lo:[0,1]
	v_pk_add_f32 v[236:237], v[162:163], v[200:201]
	v_pk_add_f32 v[162:163], v[162:163], v[200:201] neg_lo:[0,1] neg_hi:[0,1]
	v_pk_add_f32 v[200:201], v[170:171], v[238:239]
	v_pk_add_f32 v[170:171], v[170:171], v[238:239] neg_lo:[0,1] neg_hi:[0,1]
	v_pk_add_f32 v[168:169], v[244:245], v[198:199]
	v_xor_b32_e32 v239, 0x80000000, v170
	v_mov_b32_e32 v238, v171
	v_pk_add_f32 v[170:171], v[236:237], v[200:201]
	v_pk_add_f32 v[200:201], v[236:237], v[200:201] neg_lo:[0,1] neg_hi:[0,1]
	v_pk_add_f32 v[236:237], v[164:165], v[202:203]
	v_pk_add_f32 v[164:165], v[164:165], v[202:203] neg_lo:[0,1] neg_hi:[0,1]
	s_waitcnt lgkmcnt(0)
	v_pk_add_f32 v[202:203], v[172:173], v[240:241]
	v_pk_add_f32 v[172:173], v[172:173], v[240:241] neg_lo:[0,1] neg_hi:[0,1]
	v_pk_add_f32 v[198:199], v[244:245], v[198:199] neg_lo:[0,1] neg_hi:[0,1]
	v_pk_add_f32 v[244:245], v[162:163], v[238:239]
	v_pk_add_f32 v[162:163], v[162:163], v[238:239] neg_lo:[0,1] neg_hi:[0,1]
	v_xor_b32_e32 v239, 0x80000000, v172
	v_mov_b32_e32 v238, v173
	v_pk_add_f32 v[172:173], v[236:237], v[202:203]
	v_pk_add_f32 v[202:203], v[236:237], v[202:203] neg_lo:[0,1] neg_hi:[0,1]
	v_pk_add_f32 v[236:237], v[166:167], v[204:205]
	v_pk_add_f32 v[166:167], v[166:167], v[204:205] neg_lo:[0,1] neg_hi:[0,1]
	v_pk_add_f32 v[204:205], v[174:175], v[242:243]
	v_pk_add_f32 v[174:175], v[174:175], v[242:243] neg_lo:[0,1] neg_hi:[0,1]
	v_pk_add_f32 v[240:241], v[164:165], v[238:239]
	v_pk_add_f32 v[164:165], v[164:165], v[238:239] neg_lo:[0,1] neg_hi:[0,1]
	v_pk_add_f32 v[242:243], v[166:167], v[174:175] op_sel:[0,1] op_sel_hi:[1,0] neg_hi:[0,1]
	v_pk_add_f32 v[166:167], v[166:167], v[174:175] op_sel:[0,1] op_sel_hi:[1,0] neg_lo:[0,1]
	v_pk_mul_f32 v[238:239], v[200:201], s[12:13] op_sel:[1,0] op_sel_hi:[0,0] neg_lo:[1,0]
	v_pk_add_f32 v[174:175], v[236:237], v[204:205]
	v_pk_fma_f32 v[200:201], v[200:201], s[12:13], v[238:239] op_sel_hi:[1,0,1] neg_lo:[0,0,1] neg_hi:[0,0,1]
	v_pk_mul_f32 v[238:239], v[162:163], s[36:37] op_sel:[1,0] op_sel_hi:[0,0] neg_lo:[1,0]
	v_pk_add_f32 v[204:205], v[236:237], v[204:205] neg_lo:[0,1] neg_hi:[0,1]
	v_pk_fma_f32 v[162:163], v[162:163], s[22:23], v[238:239] op_sel_hi:[1,0,1] neg_lo:[0,0,1] neg_hi:[0,0,1]
	v_pk_mul_f32 v[238:239], v[240:241], s[12:13] op_sel:[1,0] op_sel_hi:[0,0] neg_lo:[1,0]
	v_pk_fma_f32 v[238:239], v[240:241], s[12:13], v[238:239] op_sel_hi:[1,0,1] neg_lo:[0,0,1] neg_hi:[0,0,1]
	v_pk_fma_f32 v[202:203], v[202:203], 0, v[202:203] op_sel:[0,0,1] op_sel_hi:[1,0,0] neg_hi:[0,0,1]
	v_pk_mul_f32 v[240:241], v[164:165], s[12:13] op_sel:[1,0] op_sel_hi:[0,0] neg_lo:[1,0]
	v_pk_fma_f32 v[164:165], v[164:165], s[18:19], v[240:241] op_sel_hi:[1,0,1] neg_lo:[0,0,1] neg_hi:[0,0,1]
	v_pk_mul_f32 v[240:241], v[242:243], s[36:37] op_sel:[1,0] op_sel_hi:[0,0] neg_lo:[1,0]
	v_pk_mul_f32 v[236:237], v[244:245], s[22:23] op_sel:[1,0] op_sel_hi:[0,0] neg_lo:[1,0]
	v_pk_fma_f32 v[240:241], v[242:243], s[22:23], v[240:241] op_sel_hi:[1,0,1] neg_lo:[0,0,1] neg_hi:[0,0,1]
	v_pk_mul_f32 v[242:243], v[204:205], s[12:13] op_sel:[1,0] op_sel_hi:[0,0] neg_lo:[1,0]
	v_pk_fma_f32 v[236:237], v[244:245], s[36:37], v[236:237] op_sel_hi:[1,0,1] neg_lo:[0,0,1] neg_hi:[0,0,1]
	v_pk_fma_f32 v[204:205], v[204:205], s[18:19], v[242:243] op_sel_hi:[1,0,1] neg_lo:[0,0,1] neg_hi:[0,0,1]
	v_xor_b32_e32 v242, 0x80000000, v167
	v_mov_b32_e32 v243, v166
	v_pk_mul_f32 v[166:167], v[166:167], s[36:37] op_sel_hi:[1,0]
	s_nop 0
	v_pk_fma_f32 v[166:167], v[242:243], s[22:23], v[166:167] op_sel_hi:[1,0,1] neg_lo:[0,0,1] neg_hi:[0,0,1]
	v_pk_add_f32 v[242:243], v[168:169], v[172:173]
	v_pk_add_f32 v[168:169], v[168:169], v[172:173] neg_lo:[0,1] neg_hi:[0,1]
	v_pk_add_f32 v[172:173], v[170:171], v[174:175]
	v_pk_add_f32 v[170:171], v[170:171], v[174:175] neg_lo:[0,1] neg_hi:[0,1]
	v_pk_add_f32 v[244:245], v[242:243], v[172:173]
	v_pk_add_f32 v[248:249], v[168:169], v[170:171] op_sel:[0,1] op_sel_hi:[1,0] neg_hi:[0,1]
	v_pk_add_f32 v[250:251], v[168:169], v[170:171] op_sel:[0,1] op_sel_hi:[1,0] neg_lo:[0,1]
	v_pk_add_f32 v[174:175], v[236:237], v[240:241] neg_lo:[0,1] neg_hi:[0,1]
	v_pk_add_f32 v[242:243], v[242:243], v[172:173] neg_lo:[0,1] neg_hi:[0,1]
	v_pk_add_f32 v[168:169], v[246:247], v[238:239]
	v_pk_add_f32 v[172:173], v[236:237], v[240:241]
	v_xor_b32_e32 v237, 0x80000000, v174
	v_mov_b32_e32 v236, v175
	v_pk_add_f32 v[174:175], v[200:201], v[204:205] neg_lo:[0,1] neg_hi:[0,1]
	v_pk_add_f32 v[170:171], v[246:247], v[238:239] neg_lo:[0,1] neg_hi:[0,1]
	v_pk_add_f32 v[238:239], v[168:169], v[172:173]
	v_pk_add_f32 v[246:247], v[168:169], v[172:173] neg_lo:[0,1] neg_hi:[0,1]
	v_pk_add_f32 v[172:173], v[200:201], v[204:205]
	v_xor_b32_e32 v201, 0x80000000, v174
	v_mov_b32_e32 v200, v175
	v_pk_add_f32 v[174:175], v[160:161], v[164:165]
	v_pk_add_f32 v[160:161], v[160:161], v[164:165] neg_lo:[0,1] neg_hi:[0,1]
	v_pk_add_f32 v[164:165], v[162:163], v[166:167]
	v_pk_add_f32 v[162:163], v[162:163], v[166:167] neg_lo:[0,1] neg_hi:[0,1]
	v_pk_add_f32 v[240:241], v[170:171], v[236:237]
	v_pk_add_f32 v[192:193], v[170:171], v[236:237] neg_lo:[0,1] neg_hi:[0,1]
	v_pk_add_f32 v[168:169], v[198:199], v[202:203]
	v_pk_add_f32 v[170:171], v[198:199], v[202:203] neg_lo:[0,1] neg_hi:[0,1]
	v_xor_b32_e32 v167, 0x80000000, v162
	v_mov_b32_e32 v166, v163
	v_pk_add_f32 v[194:195], v[168:169], v[172:173]
	v_pk_add_f32 v[184:185], v[170:171], v[200:201]
	v_pk_add_f32 v[198:199], v[168:169], v[172:173] neg_lo:[0,1] neg_hi:[0,1]
	v_pk_add_f32 v[172:173], v[170:171], v[200:201] neg_lo:[0,1] neg_hi:[0,1]
	v_pk_add_f32 v[170:171], v[174:175], v[164:165]
	v_pk_add_f32 v[168:169], v[160:161], v[162:163] op_sel:[0,1] op_sel_hi:[1,0] neg_hi:[0,1]
	v_pk_add_f32 v[162:163], v[174:175], v[164:165] neg_lo:[0,1] neg_hi:[0,1]
	v_pk_add_f32 v[160:161], v[160:161], v[166:167] neg_lo:[0,1] neg_hi:[0,1]
	ds_read2st64_b64 v[164:167], v234 offset1:8
	ds_read2st64_b64 v[200:203], v234 offset0:16 offset1:24
	s_waitcnt lgkmcnt(1)
	v_pk_mul_f32 v[174:175], v[164:165], v[244:245] op_sel:[1,1] op_sel_hi:[0,1] neg_lo:[1,0]
	v_pk_fma_f32 v[164:165], v[164:165], v[244:245], v[174:175] op_sel_hi:[1,0,1]
	v_pk_mul_f32 v[174:175], v[166:167], v[248:249] op_sel:[1,1] op_sel_hi:[0,1] neg_lo:[1,0]
	v_pk_fma_f32 v[166:167], v[166:167], v[248:249], v[174:175] op_sel_hi:[1,0,1]
	s_waitcnt lgkmcnt(0)
	v_pk_mul_f32 v[174:175], v[242:243], v[200:201] op_sel:[1,1] op_sel_hi:[1,0] neg_lo:[0,1]
	s_nop 0
	v_pk_fma_f32 v[174:175], v[200:201], v[242:243], v[174:175] op_sel_hi:[1,0,1]
	v_pk_mul_f32 v[200:201], v[202:203], v[250:251] op_sel:[1,1] op_sel_hi:[0,1] neg_lo:[1,0]
	v_pk_fma_f32 v[200:201], v[202:203], v[250:251], v[200:201] op_sel_hi:[1,0,1]
	ds_read2st64_b64 v[202:205], v234 offset0:32 offset1:40
	s_waitcnt lgkmcnt(0)
	v_pk_mul_f32 v[236:237], v[202:203], v[238:239] op_sel:[1,1] op_sel_hi:[0,1] neg_lo:[1,0]
	v_pk_fma_f32 v[202:203], v[202:203], v[238:239], v[236:237] op_sel_hi:[1,0,1]
	v_pk_mul_f32 v[236:237], v[204:205], v[240:241] op_sel:[1,1] op_sel_hi:[0,1] neg_lo:[1,0]
	v_pk_fma_f32 v[204:205], v[204:205], v[240:241], v[236:237] op_sel_hi:[1,0,1]
	ds_read2st64_b64 v[236:239], v234 offset0:48 offset1:56
	s_waitcnt lgkmcnt(0)
	v_pk_mul_f32 v[240:241], v[236:237], v[246:247] op_sel:[1,1] op_sel_hi:[0,1] neg_lo:[1,0]
	v_pk_fma_f32 v[240:241], v[236:237], v[246:247], v[240:241] op_sel_hi:[1,0,1]
	v_pk_mul_f32 v[236:237], v[238:239], v[192:193] op_sel:[1,1] op_sel_hi:[0,1] neg_lo:[1,0]
	v_pk_fma_f32 v[192:193], v[238:239], v[192:193], v[236:237] op_sel_hi:[1,0,1]
	ds_read2st64_b64 v[236:239], v234 offset0:64 offset1:72
	s_waitcnt lgkmcnt(0)
	v_pk_mul_f32 v[242:243], v[194:195], v[236:237] op_sel:[1,1] op_sel_hi:[1,0] neg_lo:[0,1]
	s_nop 0
	v_pk_fma_f32 v[194:195], v[236:237], v[194:195], v[242:243] op_sel_hi:[1,0,1]
	v_pk_mul_f32 v[236:237], v[184:185], v[238:239] op_sel:[1,1] op_sel_hi:[1,0] neg_lo:[0,1]
	s_nop 0
	v_pk_fma_f32 v[184:185], v[238:239], v[184:185], v[236:237] op_sel_hi:[1,0,1]
	ds_read2st64_b64 v[236:239], v234 offset0:80 offset1:88
	s_waitcnt lgkmcnt(0)
	v_pk_mul_f32 v[242:243], v[198:199], v[236:237] op_sel:[1,1] op_sel_hi:[1,0] neg_lo:[0,1]
	s_nop 0
	v_pk_fma_f32 v[198:199], v[198:199], v[236:237], v[242:243] op_sel_hi:[0,1,1]
	v_pk_mul_f32 v[236:237], v[172:173], v[238:239] op_sel:[1,1] op_sel_hi:[1,0] neg_lo:[0,1]
	s_nop 0
	v_pk_fma_f32 v[172:173], v[238:239], v[172:173], v[236:237] op_sel_hi:[1,0,1]
	ds_read2st64_b64 v[236:239], v234 offset0:96 offset1:104
	s_waitcnt lgkmcnt(0)
	v_pk_mul_f32 v[242:243], v[170:171], v[236:237] op_sel:[1,1] op_sel_hi:[1,0] neg_lo:[0,1]
	s_nop 0
	v_pk_fma_f32 v[236:237], v[170:171], v[236:237], v[242:243] op_sel_hi:[0,1,1]
	v_pk_mul_f32 v[170:171], v[168:169], v[238:239] op_sel:[1,1] op_sel_hi:[1,0] neg_lo:[0,1]
	s_nop 0
	v_pk_fma_f32 v[238:239], v[238:239], v[168:169], v[170:171] op_sel_hi:[1,0,1]
	ds_read2st64_b64 v[168:171], v234 offset0:112 offset1:120
	s_waitcnt lgkmcnt(0)
	v_pk_mul_f32 v[234:235], v[162:163], v[168:169] op_sel:[1,1] op_sel_hi:[1,0] neg_lo:[0,1]
	s_nop 0
	v_pk_fma_f32 v[162:163], v[162:163], v[168:169], v[234:235] op_sel_hi:[0,1,1]
	v_pk_mul_f32 v[168:169], v[160:161], v[170:171] op_sel:[1,1] op_sel_hi:[1,0] neg_lo:[0,1]
	s_nop 0
	v_pk_fma_f32 v[160:161], v[160:161], v[170:171], v[168:169] op_sel_hi:[0,1,1]
	v_pk_add_f32 v[170:171], v[166:167], v[200:201]
	v_pk_add_f32 v[166:167], v[166:167], v[200:201] neg_lo:[0,1] neg_hi:[0,1]
	v_pk_add_f32 v[168:169], v[164:165], v[174:175]
	v_pk_add_f32 v[164:165], v[164:165], v[174:175] neg_lo:[0,1] neg_hi:[0,1]
	v_xor_b32_e32 v174, 0x80000000, v167
	v_mov_b32_e32 v175, v166
	v_pk_add_f32 v[166:167], v[168:169], v[170:171]
	v_pk_add_f32 v[200:201], v[164:165], v[174:175]
	v_pk_add_f32 v[168:169], v[168:169], v[170:171] neg_lo:[0,1] neg_hi:[0,1]
	v_pk_add_f32 v[164:165], v[164:165], v[174:175] neg_lo:[0,1] neg_hi:[0,1]
	v_pk_add_f32 v[170:171], v[202:203], v[240:241]
	v_pk_add_f32 v[174:175], v[202:203], v[240:241] neg_lo:[0,1] neg_hi:[0,1]
	v_pk_add_f32 v[202:203], v[204:205], v[192:193]
	v_pk_add_f32 v[192:193], v[204:205], v[192:193] neg_lo:[0,1] neg_hi:[0,1]
	s_nop 0
	v_xor_b32_e32 v204, 0x80000000, v193
	v_mov_b32_e32 v205, v192
	v_pk_add_f32 v[192:193], v[170:171], v[202:203]
	v_pk_add_f32 v[170:171], v[170:171], v[202:203] neg_lo:[0,1] neg_hi:[0,1]
	v_pk_add_f32 v[202:203], v[194:195], v[198:199]
	v_pk_add_f32 v[194:195], v[194:195], v[198:199] neg_lo:[0,1] neg_hi:[0,1]
	v_pk_add_f32 v[198:199], v[184:185], v[172:173]
	v_pk_add_f32 v[172:173], v[184:185], v[172:173] neg_lo:[0,1] neg_hi:[0,1]
	v_pk_add_f32 v[234:235], v[174:175], v[204:205]
	v_xor_b32_e32 v184, 0x80000000, v173
	v_mov_b32_e32 v185, v172
	v_pk_add_f32 v[174:175], v[174:175], v[204:205] neg_lo:[0,1] neg_hi:[0,1]
	v_pk_add_f32 v[172:173], v[202:203], v[198:199]
	v_pk_add_f32 v[204:205], v[194:195], v[184:185]
	v_pk_add_f32 v[198:199], v[202:203], v[198:199] neg_lo:[0,1] neg_hi:[0,1]
	v_pk_add_f32 v[184:185], v[194:195], v[184:185] neg_lo:[0,1] neg_hi:[0,1]
	v_pk_add_f32 v[194:195], v[236:237], v[162:163]
	v_pk_add_f32 v[202:203], v[238:239], v[160:161]
	v_pk_add_f32 v[160:161], v[238:239], v[160:161] neg_lo:[0,1] neg_hi:[0,1]
	v_pk_add_f32 v[162:163], v[236:237], v[162:163] neg_lo:[0,1] neg_hi:[0,1]
	v_xor_b32_e32 v236, 0x80000000, v161
	v_mov_b32_e32 v237, v160
	v_pk_add_f32 v[160:161], v[194:195], v[202:203]
	v_pk_add_f32 v[194:195], v[194:195], v[202:203] neg_lo:[0,1] neg_hi:[0,1]
	v_pk_mul_f32 v[202:203], v[234:235], s[22:23] op_sel:[1,0] op_sel_hi:[0,0] neg_lo:[1,0]
	v_pk_add_f32 v[238:239], v[162:163], v[236:237]
	v_pk_fma_f32 v[202:203], v[234:235], s[36:37], v[202:203] op_sel_hi:[1,0,1]
	v_pk_mul_f32 v[234:235], v[170:171], s[12:13] op_sel:[1,0] op_sel_hi:[0,0] neg_lo:[1,0]
	v_pk_add_f32 v[162:163], v[162:163], v[236:237] neg_lo:[0,1] neg_hi:[0,1]
	v_pk_fma_f32 v[170:171], v[170:171], s[12:13], v[234:235] op_sel_hi:[1,0,1]
	v_pk_mul_f32 v[234:235], v[174:175], s[36:37] op_sel:[1,0] op_sel_hi:[0,0] neg_lo:[1,0]
	v_xor_b32_e32 v236, 0x80000000, v195
	v_pk_fma_f32 v[174:175], v[174:175], s[22:23], v[234:235] op_sel_hi:[1,0,1]
	v_pk_mul_f32 v[234:235], v[204:205], s[12:13] op_sel:[1,0] op_sel_hi:[0,0] neg_lo:[1,0]
	v_mov_b32_e32 v237, v194
	v_pk_fma_f32 v[204:205], v[204:205], s[12:13], v[234:235] op_sel_hi:[1,0,1]
	v_pk_mul_f32 v[194:195], v[194:195], s[12:13] op_sel_hi:[1,0]
	v_pk_fma_f32 v[198:199], v[198:199], 0, v[198:199] op_sel:[0,0,1] op_sel_hi:[1,0,0] neg_lo:[0,0,1]
	v_xor_b32_e32 v234, 0x80000000, v185
	v_mov_b32_e32 v235, v184
	v_pk_mul_f32 v[184:185], v[184:185], s[12:13] op_sel_hi:[1,0]
	v_pk_fma_f32 v[194:195], v[236:237], s[12:13], v[194:195] op_sel_hi:[1,0,1] neg_lo:[0,0,1] neg_hi:[0,0,1]
	v_pk_fma_f32 v[184:185], v[234:235], s[12:13], v[184:185] op_sel_hi:[1,0,1] neg_lo:[0,0,1] neg_hi:[0,0,1]
	v_pk_mul_f32 v[236:237], v[162:163], s[22:23] op_sel:[1,0] op_sel_hi:[0,0] neg_lo:[1,0]
	v_pk_mul_f32 v[234:235], v[238:239], s[36:37] op_sel:[1,0] op_sel_hi:[0,0] neg_lo:[1,0]
	v_pk_fma_f32 v[162:163], v[162:163], s[26:27], v[236:237] op_sel_hi:[1,0,1] neg_lo:[0,0,1] neg_hi:[0,0,1]
	v_pk_add_f32 v[236:237], v[166:167], v[172:173]
	v_pk_add_f32 v[166:167], v[166:167], v[172:173] neg_lo:[0,1] neg_hi:[0,1]
	v_pk_add_f32 v[172:173], v[192:193], v[160:161]
	v_pk_add_f32 v[160:161], v[192:193], v[160:161] neg_lo:[0,1] neg_hi:[0,1]
	v_pk_fma_f32 v[234:235], v[238:239], s[22:23], v[234:235] op_sel_hi:[1,0,1]
	v_pk_add_f32 v[238:239], v[166:167], v[160:161] op_sel:[0,1] op_sel_hi:[1,0] neg_lo:[0,1]
	v_pk_add_f32 v[166:167], v[166:167], v[160:161] op_sel:[0,1] op_sel_hi:[1,0] neg_hi:[0,1]
	v_pk_add_f32 v[192:193], v[200:201], v[204:205]
	v_pk_add_f32 v[200:201], v[200:201], v[204:205] neg_lo:[0,1] neg_hi:[0,1]
	v_pk_add_f32 v[204:205], v[202:203], v[234:235]
	v_pk_add_f32 v[202:203], v[202:203], v[234:235] neg_lo:[0,1] neg_hi:[0,1]
	v_pk_add_f32 v[160:161], v[236:237], v[172:173]
	v_xor_b32_e32 v234, 0x80000000, v203
	v_mov_b32_e32 v235, v202
	v_pk_add_f32 v[202:203], v[192:193], v[204:205]
	v_pk_add_f32 v[192:193], v[192:193], v[204:205] neg_lo:[0,1] neg_hi:[0,1]
	v_pk_add_f32 v[204:205], v[168:169], v[198:199]
	v_pk_add_f32 v[168:169], v[168:169], v[198:199] neg_lo:[0,1] neg_hi:[0,1]
	v_pk_add_f32 v[198:199], v[170:171], v[194:195]
	v_pk_add_f32 v[170:171], v[170:171], v[194:195] neg_lo:[0,1] neg_hi:[0,1]
	v_pk_add_f32 v[172:173], v[236:237], v[172:173] neg_lo:[0,1] neg_hi:[0,1]
	v_pk_add_f32 v[236:237], v[200:201], v[234:235]
	v_pk_add_f32 v[200:201], v[200:201], v[234:235] neg_lo:[0,1] neg_hi:[0,1]
	v_pk_add_f32 v[234:235], v[168:169], v[170:171] op_sel:[0,1] op_sel_hi:[1,0] neg_lo:[0,1]
	v_pk_add_f32 v[168:169], v[168:169], v[170:171] op_sel:[0,1] op_sel_hi:[1,0] neg_hi:[0,1]
	v_pk_add_f32 v[194:195], v[164:165], v[184:185]
	v_pk_add_f32 v[164:165], v[164:165], v[184:185] neg_lo:[0,1] neg_hi:[0,1]
	v_pk_add_f32 v[184:185], v[174:175], v[162:163]
	v_pk_add_f32 v[162:163], v[174:175], v[162:163] neg_lo:[0,1] neg_hi:[0,1]
	v_pk_add_f32 v[170:171], v[204:205], v[198:199]
	v_pk_add_f32 v[198:199], v[204:205], v[198:199] neg_lo:[0,1] neg_hi:[0,1]
	v_pk_add_f32 v[204:205], v[164:165], v[162:163] op_sel:[0,1] op_sel_hi:[1,0] neg_lo:[0,1]
	v_pk_add_f32 v[164:165], v[164:165], v[162:163] op_sel:[0,1] op_sel_hi:[1,0] neg_hi:[0,1]
	v_mov_b32_e32 v174, v116
	v_mov_b32_e32 v175, v142
	v_pk_mul_f32 v[142:143], v[174:175], v[160:161] op_sel_hi:[1,0]
	v_pk_add_f32 v[162:163], v[194:195], v[184:185]
	v_pk_fma_f32 v[116:117], v[116:117], v[160:161], v[142:143] op_sel:[1,1,0] op_sel_hi:[0,1,1]
	v_pk_mul_f32 v[142:143], v[126:127], v[202:203] op_sel_hi:[1,0] neg_hi:[1,0]
	v_pk_add_f32 v[184:185], v[194:195], v[184:185] neg_lo:[0,1] neg_hi:[0,1]
	v_pk_fma_f32 v[126:127], v[126:127], v[202:203], v[142:143] op_sel:[1,1,0] op_sel_hi:[0,1,1]
	ds_write2_b64 v129, v[116:117], v[126:127] offset1:1
	v_pk_mul_f32 v[116:117], v[124:125], v[170:171] op_sel_hi:[1,0] neg_hi:[1,0]
	s_nop 0
	v_pk_fma_f32 v[116:117], v[124:125], v[170:171], v[116:117] op_sel:[1,1,0] op_sel_hi:[0,1,1]
	v_pk_mul_f32 v[124:125], v[122:123], v[162:163] op_sel_hi:[1,0] neg_hi:[1,0]
	s_nop 0
	v_pk_fma_f32 v[122:123], v[122:123], v[162:163], v[124:125] op_sel:[1,1,0] op_sel_hi:[0,1,1]
	ds_write2_b64 v129, v[116:117], v[122:123] offset0:2 offset1:3
	v_pk_mul_f32 v[116:117], v[120:121], v[238:239] op_sel_hi:[1,0] neg_hi:[1,0]
	s_nop 0
	v_pk_fma_f32 v[116:117], v[120:121], v[238:239], v[116:117] op_sel:[1,1,0] op_sel_hi:[0,1,1]
	v_pk_mul_f32 v[120:121], v[118:119], v[236:237] op_sel_hi:[1,0] neg_hi:[1,0]
	s_nop 0
	v_pk_fma_f32 v[118:119], v[118:119], v[236:237], v[120:121] op_sel:[1,1,0] op_sel_hi:[0,1,1]
	ds_write2_b64 v129, v[116:117], v[118:119] offset0:4 offset1:5
	v_pk_mul_f32 v[116:117], v[114:115], v[234:235] op_sel_hi:[1,0] neg_hi:[1,0]
	s_nop 0
	v_pk_fma_f32 v[114:115], v[114:115], v[234:235], v[116:117] op_sel:[1,1,0] op_sel_hi:[0,1,1]
	v_pk_mul_f32 v[116:117], v[112:113], v[204:205] op_sel_hi:[1,0] neg_hi:[1,0]
	s_nop 0
	v_pk_fma_f32 v[112:113], v[112:113], v[204:205], v[116:117] op_sel:[1,1,0] op_sel_hi:[0,1,1]
	ds_write2_b64 v129, v[114:115], v[112:113] offset0:6 offset1:7
	v_pk_mul_f32 v[112:113], v[110:111], v[172:173] op_sel_hi:[1,0] neg_hi:[1,0]
	s_nop 0
	v_pk_fma_f32 v[110:111], v[110:111], v[172:173], v[112:113] op_sel:[1,1,0] op_sel_hi:[0,1,1]
	v_pk_mul_f32 v[112:113], v[108:109], v[192:193] op_sel_hi:[1,0] neg_hi:[1,0]
	s_nop 0
	v_pk_fma_f32 v[108:109], v[108:109], v[192:193], v[112:113] op_sel:[1,1,0] op_sel_hi:[0,1,1]
	ds_write2_b64 v129, v[110:111], v[108:109] offset0:8 offset1:9
	v_pk_mul_f32 v[108:109], v[106:107], v[198:199] op_sel_hi:[1,0] neg_hi:[1,0]
	s_nop 0
	v_pk_fma_f32 v[106:107], v[106:107], v[198:199], v[108:109] op_sel:[1,1,0] op_sel_hi:[0,1,1]
	v_pk_mul_f32 v[108:109], v[104:105], v[184:185] op_sel_hi:[1,0] neg_hi:[1,0]
	s_nop 0
	v_pk_fma_f32 v[104:105], v[104:105], v[184:185], v[108:109] op_sel:[1,1,0] op_sel_hi:[0,1,1]
	ds_write2_b64 v129, v[106:107], v[104:105] offset0:10 offset1:11
	v_pk_mul_f32 v[104:105], v[6:7], v[166:167] op_sel_hi:[1,0] neg_hi:[1,0]
	s_nop 0
	v_pk_fma_f32 v[6:7], v[6:7], v[166:167], v[104:105] op_sel:[1,1,0] op_sel_hi:[0,1,1]
	v_pk_mul_f32 v[104:105], v[4:5], v[200:201] op_sel_hi:[1,0] neg_hi:[1,0]
	s_nop 0
	v_pk_fma_f32 v[4:5], v[4:5], v[200:201], v[104:105] op_sel:[1,1,0] op_sel_hi:[0,1,1]
	ds_write2_b64 v129, v[6:7], v[4:5] offset0:12 offset1:13
	v_pk_mul_f32 v[4:5], v[2:3], v[168:169] op_sel_hi:[1,0] neg_hi:[1,0]
	s_nop 0
	v_pk_fma_f32 v[2:3], v[2:3], v[168:169], v[4:5] op_sel:[1,1,0] op_sel_hi:[0,1,1]
	v_pk_mul_f32 v[4:5], v[0:1], v[164:165] op_sel_hi:[1,0] neg_hi:[1,0]
	s_nop 0
	v_pk_fma_f32 v[0:1], v[0:1], v[164:165], v[4:5] op_sel:[1,1,0] op_sel_hi:[0,1,1]
	ds_write2_b64 v129, v[2:3], v[0:1] offset0:14 offset1:15
	v_mov_b32_e32 v0, v217
	v_mov_b32_e32 v1, v218
	v_mov_b32_e32 v114, v215
	v_xor_b32_e32 v4, 0x80000000, v1
	v_mov_b32_e32 v5, v0
	v_pk_mul_f32 v[2:3], v[4:5], v[218:219] op_sel_hi:[1,0]
	v_mov_b32_e32 v115, v216
	v_pk_fma_f32 v[2:3], v[216:217], v[0:1], v[2:3] op_sel:[1,0,0]
	s_nop 0
	v_pk_mul_f32 v[104:105], v[2:3], v[2:3] op_sel:[1,1] op_sel_hi:[1,0] neg_lo:[0,1]
	v_pk_mul_f32 v[4:5], v[4:5], v[216:217] op_sel_hi:[1,0]
	v_pk_fma_f32 v[104:105], v[2:3], v[2:3], v[104:105] op_sel_hi:[1,0,1]
	v_pk_fma_f32 v[126:127], v[0:1], v[214:215], v[4:5] op_sel:[0,1,0]
	v_pk_mul_f32 v[0:1], v[216:217], v[2:3] op_sel:[0,1] op_sel_hi:[0,0] neg_lo:[0,1]
	v_pk_fma_f32 v[124:125], v[214:215], v[2:3], v[0:1] op_sel:[1,0,0]
	v_pk_mul_f32 v[0:1], v[126:127], v[2:3] op_sel:[1,1] op_sel_hi:[1,0] neg_lo:[0,1]
	v_pk_mul_f32 v[108:109], v[104:105], v[104:105] op_sel:[1,1] op_sel_hi:[1,0] neg_lo:[0,1]
	v_pk_fma_f32 v[122:123], v[2:3], v[126:127], v[0:1] op_sel_hi:[1,0,1]
	v_pk_mul_f32 v[0:1], v[216:217], v[104:105] op_sel:[0,1] op_sel_hi:[0,0] neg_lo:[0,1]
	v_pk_fma_f32 v[120:121], v[214:215], v[104:105], v[0:1] op_sel:[1,0,0]
	v_pk_mul_f32 v[0:1], v[126:127], v[104:105] op_sel:[1,1] op_sel_hi:[1,0] neg_lo:[0,1]
	s_waitcnt lgkmcnt(0)
	v_pk_fma_f32 v[118:119], v[126:127], v[104:105], v[0:1] op_sel_hi:[0,1,1]
	v_pk_mul_f32 v[0:1], v[124:125], v[104:105] op_sel:[1,1] op_sel_hi:[1,0] neg_lo:[0,1]
	s_barrier
	v_pk_fma_f32 v[116:117], v[104:105], v[124:125], v[0:1] op_sel_hi:[1,0,1]
	v_pk_mul_f32 v[0:1], v[122:123], v[104:105] op_sel:[1,1] op_sel_hi:[1,0] neg_lo:[0,1]
	s_nop 0
	v_pk_fma_f32 v[110:111], v[104:105], v[122:123], v[0:1] op_sel_hi:[1,0,1]
	v_pk_fma_f32 v[0:1], v[104:105], v[104:105], v[108:109] op_sel_hi:[1,0,1]
	s_cmpk_lg_u32 s42, 0xc000
	v_pk_mul_f32 v[2:3], v[216:217], v[0:1] op_sel:[0,1] op_sel_hi:[0,0] neg_lo:[0,1]
	v_pk_fma_f32 v[112:113], v[214:215], v[0:1], v[2:3] op_sel:[1,0,0]
	v_pk_mul_f32 v[2:3], v[126:127], v[0:1] op_sel:[1,1] op_sel_hi:[1,0] neg_lo:[0,1]
	s_cselect_b32 s34, s47, 0
	v_pk_fma_f32 v[108:109], v[126:127], v[0:1], v[2:3] op_sel_hi:[0,1,1]
	v_pk_mul_f32 v[2:3], v[124:125], v[0:1] op_sel:[1,1] op_sel_hi:[1,0] neg_lo:[0,1]
	s_lshl_b64 s[2:3], s[34:35], 1
	v_pk_fma_f32 v[106:107], v[124:125], v[0:1], v[2:3] op_sel_hi:[0,1,1]
	v_pk_mul_f32 v[2:3], v[122:123], v[0:1] op_sel:[1,1] op_sel_hi:[1,0] neg_lo:[0,1]
	s_add_u32 s2, s40, s2
	v_pk_fma_f32 v[104:105], v[122:123], v[0:1], v[2:3] op_sel_hi:[0,1,1]
	v_pk_mul_f32 v[2:3], v[120:121], v[0:1] op_sel:[1,1] op_sel_hi:[1,0] neg_lo:[0,1]
	s_addc_u32 s3, s41, s3
	v_pk_fma_f32 v[6:7], v[0:1], v[120:121], v[2:3] op_sel_hi:[1,0,1]
	v_pk_mul_f32 v[2:3], v[118:119], v[0:1] op_sel:[1,1] op_sel_hi:[1,0] neg_lo:[0,1]
	s_add_u32 s6, s2, 0x2000
	v_pk_fma_f32 v[4:5], v[0:1], v[118:119], v[2:3] op_sel_hi:[1,0,1]
	v_pk_mul_f32 v[2:3], v[116:117], v[0:1] op_sel:[1,1] op_sel_hi:[1,0] neg_lo:[0,1]
	v_pk_mul_f32 v[128:129], v[110:111], v[0:1] op_sel:[1,1] op_sel_hi:[1,0] neg_lo:[0,1]
	v_pk_fma_f32 v[2:3], v[0:1], v[116:117], v[2:3] op_sel_hi:[1,0,1]
	v_pk_fma_f32 v[0:1], v[0:1], v[110:111], v[128:129] op_sel_hi:[1,0,1]
	s_addc_u32 s7, s3, 0
	v_bfe_u32 v129, v206, 4, 4
	v_and_b32_e32 v128, 15, v206
	v_mul_u32_u24_e32 v129, 0x880, v129
	v_lshlrev_b32_e32 v128, 3, v128
	v_add3_u32 v164, v207, v129, v128
	ds_read2_b64 v[128:131], v164 offset1:17
	ds_read2_b64 v[132:135], v164 offset0:34 offset1:51
	ds_read2_b64 v[136:139], v164 offset0:68 offset1:85
	ds_read2_b64 v[140:143], v164 offset0:102 offset1:119
	ds_read2_b64 v[144:147], v164 offset0:136 offset1:153
	ds_read2_b64 v[148:151], v164 offset0:170 offset1:187
	ds_read2_b64 v[152:155], v164 offset0:204 offset1:221
	ds_read2_b64 v[156:159], v164 offset0:238 offset1:255
	s_add_u32 s42, s42, 0x4000
	s_waitcnt lgkmcnt(3)
	v_pk_add_f32 v[160:161], v[128:129], v[144:145]
	v_pk_add_f32 v[128:129], v[128:129], v[144:145] neg_lo:[0,1] neg_hi:[0,1]
	s_waitcnt lgkmcnt(1)
	v_pk_add_f32 v[144:145], v[136:137], v[152:153]
	v_pk_add_f32 v[136:137], v[136:137], v[152:153] neg_lo:[0,1] neg_hi:[0,1]
	s_addc_u32 s43, s43, 0
	v_pk_add_f32 v[162:163], v[128:129], v[136:137] op_sel:[0,1] op_sel_hi:[1,0] neg_lo:[0,1]
	v_pk_add_f32 v[128:129], v[128:129], v[136:137] op_sel:[0,1] op_sel_hi:[1,0] neg_hi:[0,1]
	v_pk_add_f32 v[152:153], v[130:131], v[146:147]
	v_pk_add_f32 v[130:131], v[130:131], v[146:147] neg_lo:[0,1] neg_hi:[0,1]
	v_pk_add_f32 v[146:147], v[138:139], v[154:155]
	v_pk_add_f32 v[138:139], v[138:139], v[154:155] neg_lo:[0,1] neg_hi:[0,1]
	v_pk_add_f32 v[136:137], v[160:161], v[144:145]
	v_xor_b32_e32 v154, 0x80000000, v139
	v_mov_b32_e32 v155, v138
	v_pk_add_f32 v[138:139], v[152:153], v[146:147]
	v_pk_add_f32 v[146:147], v[152:153], v[146:147] neg_lo:[0,1] neg_hi:[0,1]
	v_pk_add_f32 v[152:153], v[132:133], v[148:149]
	v_pk_add_f32 v[132:133], v[132:133], v[148:149] neg_lo:[0,1] neg_hi:[0,1]
	s_waitcnt lgkmcnt(0)
	v_pk_add_f32 v[148:149], v[140:141], v[156:157]
	v_pk_add_f32 v[140:141], v[140:141], v[156:157] neg_lo:[0,1] neg_hi:[0,1]
	v_pk_add_f32 v[144:145], v[160:161], v[144:145] neg_lo:[0,1] neg_hi:[0,1]
	v_pk_add_f32 v[160:161], v[130:131], v[154:155]
	v_pk_add_f32 v[130:131], v[130:131], v[154:155] neg_lo:[0,1] neg_hi:[0,1]
	v_xor_b32_e32 v154, 0x80000000, v141
	v_mov_b32_e32 v155, v140
	v_pk_add_f32 v[140:141], v[152:153], v[148:149]
	v_pk_add_f32 v[148:149], v[152:153], v[148:149] neg_lo:[0,1] neg_hi:[0,1]
	v_pk_add_f32 v[152:153], v[134:135], v[150:151]
	v_pk_add_f32 v[134:135], v[134:135], v[150:151] neg_lo:[0,1] neg_hi:[0,1]
	v_pk_add_f32 v[150:151], v[142:143], v[158:159]
	v_pk_add_f32 v[142:143], v[142:143], v[158:159] neg_lo:[0,1] neg_hi:[0,1]
	v_pk_add_f32 v[156:157], v[132:133], v[154:155]
	v_pk_add_f32 v[132:133], v[132:133], v[154:155] neg_lo:[0,1] neg_hi:[0,1]
	v_pk_add_f32 v[158:159], v[134:135], v[142:143] op_sel:[0,1] op_sel_hi:[1,0] neg_lo:[0,1]
	v_pk_add_f32 v[134:135], v[134:135], v[142:143] op_sel:[0,1] op_sel_hi:[1,0] neg_hi:[0,1]
	v_pk_mul_f32 v[154:155], v[146:147], s[12:13] op_sel:[1,0] op_sel_hi:[0,0] neg_lo:[1,0]
	v_pk_add_f32 v[142:143], v[152:153], v[150:151]
	v_pk_fma_f32 v[146:147], v[146:147], s[12:13], v[154:155] op_sel_hi:[1,0,1]
	v_pk_mul_f32 v[154:155], v[130:131], s[36:37] op_sel:[1,0] op_sel_hi:[0,0] neg_lo:[1,0]
	v_pk_add_f32 v[150:151], v[152:153], v[150:151] neg_lo:[0,1] neg_hi:[0,1]
	v_pk_fma_f32 v[130:131], v[130:131], s[22:23], v[154:155] op_sel_hi:[1,0,1]
	v_pk_mul_f32 v[154:155], v[156:157], s[12:13] op_sel:[1,0] op_sel_hi:[0,0] neg_lo:[1,0]
	v_pk_fma_f32 v[154:155], v[156:157], s[12:13], v[154:155] op_sel_hi:[1,0,1]
	v_pk_fma_f32 v[148:149], v[148:149], 0, v[148:149] op_sel:[0,0,1] op_sel_hi:[1,0,0] neg_lo:[0,0,1]
	v_xor_b32_e32 v156, 0x80000000, v133
	v_mov_b32_e32 v157, v132
	v_pk_mul_f32 v[132:133], v[132:133], s[12:13] op_sel_hi:[1,0]
	s_nop 0
	v_pk_fma_f32 v[132:133], v[156:157], s[12:13], v[132:133] op_sel_hi:[1,0,1] neg_lo:[0,0,1] neg_hi:[0,0,1]
	v_pk_mul_f32 v[156:157], v[158:159], s[36:37] op_sel:[1,0] op_sel_hi:[0,0] neg_lo:[1,0]
	v_pk_mul_f32 v[152:153], v[160:161], s[22:23] op_sel:[1,0] op_sel_hi:[0,0] neg_lo:[1,0]
	v_pk_fma_f32 v[156:157], v[158:159], s[22:23], v[156:157] op_sel_hi:[1,0,1]
	v_xor_b32_e32 v158, 0x80000000, v151
	v_mov_b32_e32 v159, v150
	v_pk_mul_f32 v[150:151], v[150:151], s[12:13] op_sel_hi:[1,0]
	v_pk_fma_f32 v[152:153], v[160:161], s[36:37], v[152:153] op_sel_hi:[1,0,1]
	v_pk_fma_f32 v[150:151], v[158:159], s[12:13], v[150:151] op_sel_hi:[1,0,1] neg_lo:[0,0,1] neg_hi:[0,0,1]
	v_pk_mul_f32 v[158:159], v[134:135], s[22:23] op_sel:[1,0] op_sel_hi:[0,0] neg_lo:[1,0]
	s_addk_i32 s47, 0x2000
	v_pk_fma_f32 v[134:135], v[134:135], s[26:27], v[158:159] op_sel_hi:[1,0,1] neg_lo:[0,0,1] neg_hi:[0,0,1]
	v_pk_add_f32 v[158:159], v[136:137], v[140:141]
	v_pk_add_f32 v[136:137], v[136:137], v[140:141] neg_lo:[0,1] neg_hi:[0,1]
	v_pk_add_f32 v[140:141], v[138:139], v[142:143]
	v_pk_add_f32 v[138:139], v[138:139], v[142:143] neg_lo:[0,1] neg_hi:[0,1]
	s_cmp_eq_u32 s42, 0x10000
	v_xor_b32_e32 v142, 0x80000000, v139
	v_mov_b32_e32 v143, v138
	v_pk_add_f32 v[138:139], v[158:159], v[140:141]
	v_pk_add_f32 v[140:141], v[158:159], v[140:141] neg_lo:[0,1] neg_hi:[0,1]
	v_pk_add_f32 v[158:159], v[152:153], v[156:157]
	v_pk_add_f32 v[152:153], v[152:153], v[156:157] neg_lo:[0,1] neg_hi:[0,1]
	v_pk_add_f32 v[160:161], v[136:137], v[142:143]
	v_pk_add_f32 v[136:137], v[136:137], v[142:143] neg_lo:[0,1] neg_hi:[0,1]
	v_pk_add_f32 v[142:143], v[162:163], v[154:155]
	v_pk_add_f32 v[154:155], v[162:163], v[154:155] neg_lo:[0,1] neg_hi:[0,1]
	s_nop 0
	v_pk_add_f32 v[162:163], v[154:155], v[152:153] op_sel:[0,1] op_sel_hi:[1,0] neg_lo:[0,1]
	v_pk_add_f32 v[154:155], v[154:155], v[152:153] op_sel:[0,1] op_sel_hi:[1,0] neg_hi:[0,1]
	v_pk_add_f32 v[156:157], v[144:145], v[148:149]
	v_pk_add_f32 v[144:145], v[144:145], v[148:149] neg_lo:[0,1] neg_hi:[0,1]
	v_pk_add_f32 v[148:149], v[146:147], v[150:151]
	v_pk_add_f32 v[146:147], v[146:147], v[150:151] neg_lo:[0,1] neg_hi:[0,1]
	v_pk_add_f32 v[152:153], v[142:143], v[158:159]
	v_pk_add_f32 v[142:143], v[142:143], v[158:159] neg_lo:[0,1] neg_hi:[0,1]
	v_pk_add_f32 v[158:159], v[144:145], v[146:147] op_sel:[0,1] op_sel_hi:[1,0] neg_lo:[0,1]
	v_pk_add_f32 v[144:145], v[144:145], v[146:147] op_sel:[0,1] op_sel_hi:[1,0] neg_hi:[0,1]
	v_pk_add_f32 v[150:151], v[128:129], v[132:133]
	v_pk_add_f32 v[128:129], v[128:129], v[132:133] neg_lo:[0,1] neg_hi:[0,1]
	v_pk_add_f32 v[132:133], v[130:131], v[134:135]
	v_pk_add_f32 v[130:131], v[130:131], v[134:135] neg_lo:[0,1] neg_hi:[0,1]
	v_pk_add_f32 v[146:147], v[156:157], v[148:149]
	v_pk_add_f32 v[148:149], v[156:157], v[148:149] neg_lo:[0,1] neg_hi:[0,1]
	v_pk_add_f32 v[156:157], v[128:129], v[130:131] op_sel:[0,1] op_sel_hi:[1,0] neg_lo:[0,1]
	v_pk_add_f32 v[128:129], v[128:129], v[130:131] op_sel:[0,1] op_sel_hi:[1,0] neg_hi:[0,1]
	v_xor_b32_e32 v134, 0x80000000, v115
	v_mov_b32_e32 v135, v114
	v_pk_mul_f32 v[134:135], v[134:135], v[138:139] op_sel:[0,1]
	v_pk_add_f32 v[130:131], v[150:151], v[132:133]
	v_pk_fma_f32 v[114:115], v[114:115], v[138:139], v[134:135] op_sel_hi:[1,0,1]
	v_pk_mul_f32 v[134:135], v[126:127], v[152:153] op_sel:[1,1] op_sel_hi:[0,1] neg_lo:[1,0]
	v_pk_add_f32 v[132:133], v[150:151], v[132:133] neg_lo:[0,1] neg_hi:[0,1]
	v_pk_fma_f32 v[126:127], v[126:127], v[152:153], v[134:135] op_sel_hi:[1,0,1]
	ds_write2_b64 v164, v[114:115], v[126:127] offset1:17
	v_pk_mul_f32 v[114:115], v[124:125], v[146:147] op_sel:[1,1] op_sel_hi:[0,1] neg_lo:[1,0]
	v_pk_fma_f32 v[114:115], v[124:125], v[146:147], v[114:115] op_sel_hi:[1,0,1]
	v_pk_mul_f32 v[124:125], v[122:123], v[130:131] op_sel:[1,1] op_sel_hi:[0,1] neg_lo:[1,0]
	v_pk_fma_f32 v[122:123], v[122:123], v[130:131], v[124:125] op_sel_hi:[1,0,1]
	ds_write2_b64 v164, v[114:115], v[122:123] offset0:34 offset1:51
	v_pk_mul_f32 v[114:115], v[120:121], v[160:161] op_sel:[1,1] op_sel_hi:[0,1] neg_lo:[1,0]
	v_pk_fma_f32 v[114:115], v[120:121], v[160:161], v[114:115] op_sel_hi:[1,0,1]
	v_pk_mul_f32 v[120:121], v[118:119], v[162:163] op_sel:[1,1] op_sel_hi:[0,1] neg_lo:[1,0]
	v_pk_fma_f32 v[118:119], v[118:119], v[162:163], v[120:121] op_sel_hi:[1,0,1]
	ds_write2_b64 v164, v[114:115], v[118:119] offset0:68 offset1:85
	v_pk_mul_f32 v[114:115], v[116:117], v[158:159] op_sel:[1,1] op_sel_hi:[0,1] neg_lo:[1,0]
	v_pk_fma_f32 v[114:115], v[116:117], v[158:159], v[114:115] op_sel_hi:[1,0,1]
	v_pk_mul_f32 v[116:117], v[110:111], v[156:157] op_sel:[1,1] op_sel_hi:[0,1] neg_lo:[1,0]
	v_pk_fma_f32 v[110:111], v[110:111], v[156:157], v[116:117] op_sel_hi:[1,0,1]
	ds_write2_b64 v164, v[114:115], v[110:111] offset0:102 offset1:119
	v_pk_mul_f32 v[110:111], v[112:113], v[140:141] op_sel:[1,1] op_sel_hi:[0,1] neg_lo:[1,0]
	v_pk_fma_f32 v[110:111], v[112:113], v[140:141], v[110:111] op_sel_hi:[1,0,1]
	v_pk_mul_f32 v[112:113], v[108:109], v[142:143] op_sel:[1,1] op_sel_hi:[0,1] neg_lo:[1,0]
	v_pk_fma_f32 v[108:109], v[108:109], v[142:143], v[112:113] op_sel_hi:[1,0,1]
	ds_write2_b64 v164, v[110:111], v[108:109] offset0:136 offset1:153
	v_pk_mul_f32 v[108:109], v[106:107], v[148:149] op_sel:[1,1] op_sel_hi:[0,1] neg_lo:[1,0]
	v_pk_fma_f32 v[106:107], v[106:107], v[148:149], v[108:109] op_sel_hi:[1,0,1]
	v_pk_mul_f32 v[108:109], v[104:105], v[132:133] op_sel:[1,1] op_sel_hi:[0,1] neg_lo:[1,0]
	v_pk_fma_f32 v[104:105], v[104:105], v[132:133], v[108:109] op_sel_hi:[1,0,1]
	ds_write2_b64 v164, v[106:107], v[104:105] offset0:170 offset1:187
	v_pk_mul_f32 v[104:105], v[6:7], v[136:137] op_sel:[1,1] op_sel_hi:[0,1] neg_lo:[1,0]
	s_waitcnt vmcnt(5)
	v_and_b32_e32 v133, 0xffff0000, v13
	v_pk_fma_f32 v[6:7], v[6:7], v[136:137], v[104:105] op_sel_hi:[1,0,1]
	v_pk_mul_f32 v[104:105], v[4:5], v[154:155] op_sel:[1,1] op_sel_hi:[0,1] neg_lo:[1,0]
	v_lshlrev_b32_e32 v136, 16, v12
	v_pk_fma_f32 v[4:5], v[4:5], v[154:155], v[104:105] op_sel_hi:[1,0,1]
	ds_write2_b64 v164, v[6:7], v[4:5] offset0:204 offset1:221
	v_pk_mul_f32 v[4:5], v[2:3], v[144:145] op_sel:[1,1] op_sel_hi:[0,1] neg_lo:[1,0]
	v_and_b32_e32 v137, 0xffff0000, v12
	v_pk_fma_f32 v[2:3], v[2:3], v[144:145], v[4:5] op_sel_hi:[1,0,1]
	v_pk_mul_f32 v[4:5], v[0:1], v[128:129] op_sel:[1,1] op_sel_hi:[0,1] neg_lo:[1,0]
	v_pk_fma_f32 v[0:1], v[0:1], v[128:129], v[4:5] op_sel_hi:[1,0,1]
	ds_write2_b64 v164, v[2:3], v[0:1] offset0:238 offset1:255
	v_mov_b32_e32 v0, v206
	s_waitcnt lgkmcnt(0)
	s_barrier
	s_nop 0
	v_lshlrev_b32_sdwa v1, v228, v0 dst_sel:DWORD dst_unused:UNUSED_PAD src0_sel:DWORD src1_sel:BYTE_0
	v_lshrrev_b32_e32 v0, 1, v206
	v_and_b32_e32 v0, 0x78, v0
	v_add3_u32 v132, v207, v1, v0
	ds_read_b64 v[0:1], v132
	ds_read_b64 v[2:3], v132 offset:2176
	ds_read_b64 v[4:5], v132 offset:4352
	ds_read_b64 v[6:7], v132 offset:6528
	ds_read_b64 v[104:105], v132 offset:8704
	ds_read_b64 v[106:107], v132 offset:10880
	ds_read_b64 v[108:109], v132 offset:13056
	ds_read_b64 v[110:111], v132 offset:15232
	ds_read_b64 v[112:113], v132 offset:17408
	ds_read_b64 v[114:115], v132 offset:19584
	ds_read_b64 v[116:117], v132 offset:21760
	ds_read_b64 v[118:119], v132 offset:23936
	ds_read_b64 v[120:121], v132 offset:26112
	ds_read_b64 v[122:123], v132 offset:28288
	ds_read_b64 v[124:125], v132 offset:30464
	ds_read_b64 v[126:127], v132 offset:32640
	s_waitcnt lgkmcnt(7)
	v_pk_add_f32 v[128:129], v[0:1], v[112:113]
	v_pk_add_f32 v[0:1], v[0:1], v[112:113] neg_lo:[0,1] neg_hi:[0,1]
	s_waitcnt lgkmcnt(3)
	v_pk_add_f32 v[112:113], v[104:105], v[120:121]
	v_pk_add_f32 v[104:105], v[104:105], v[120:121] neg_lo:[0,1] neg_hi:[0,1]
	s_nop 0
	v_pk_add_f32 v[130:131], v[0:1], v[104:105] op_sel:[0,1] op_sel_hi:[1,0] neg_lo:[0,1]
	v_pk_add_f32 v[0:1], v[0:1], v[104:105] op_sel:[0,1] op_sel_hi:[1,0] neg_hi:[0,1]
	v_pk_add_f32 v[120:121], v[2:3], v[114:115]
	v_pk_add_f32 v[2:3], v[2:3], v[114:115] neg_lo:[0,1] neg_hi:[0,1]
	s_waitcnt lgkmcnt(2)
	v_pk_add_f32 v[114:115], v[106:107], v[122:123]
	v_pk_add_f32 v[106:107], v[106:107], v[122:123] neg_lo:[0,1] neg_hi:[0,1]
	v_pk_add_f32 v[104:105], v[128:129], v[112:113]
	v_xor_b32_e32 v122, 0x80000000, v107
	v_mov_b32_e32 v123, v106
	v_pk_add_f32 v[106:107], v[120:121], v[114:115]
	v_pk_add_f32 v[114:115], v[120:121], v[114:115] neg_lo:[0,1] neg_hi:[0,1]
	v_pk_add_f32 v[120:121], v[4:5], v[116:117]
	v_pk_add_f32 v[4:5], v[4:5], v[116:117] neg_lo:[0,1] neg_hi:[0,1]
	s_waitcnt lgkmcnt(1)
	v_pk_add_f32 v[116:117], v[108:109], v[124:125]
	v_pk_add_f32 v[108:109], v[108:109], v[124:125] neg_lo:[0,1] neg_hi:[0,1]
	v_pk_add_f32 v[112:113], v[128:129], v[112:113] neg_lo:[0,1] neg_hi:[0,1]
	v_pk_add_f32 v[128:129], v[2:3], v[122:123]
	v_pk_add_f32 v[2:3], v[2:3], v[122:123] neg_lo:[0,1] neg_hi:[0,1]
	v_xor_b32_e32 v122, 0x80000000, v109
	v_mov_b32_e32 v123, v108
	v_pk_add_f32 v[108:109], v[120:121], v[116:117]
	v_pk_add_f32 v[116:117], v[120:121], v[116:117] neg_lo:[0,1] neg_hi:[0,1]
	v_pk_add_f32 v[120:121], v[6:7], v[118:119]
	v_pk_add_f32 v[6:7], v[6:7], v[118:119] neg_lo:[0,1] neg_hi:[0,1]
	s_waitcnt lgkmcnt(0)
	v_pk_add_f32 v[118:119], v[110:111], v[126:127]
	v_pk_add_f32 v[110:111], v[110:111], v[126:127] neg_lo:[0,1] neg_hi:[0,1]
	v_pk_add_f32 v[124:125], v[4:5], v[122:123]
	v_pk_add_f32 v[4:5], v[4:5], v[122:123] neg_lo:[0,1] neg_hi:[0,1]
	v_pk_add_f32 v[126:127], v[6:7], v[110:111] op_sel:[0,1] op_sel_hi:[1,0] neg_lo:[0,1]
	v_pk_add_f32 v[6:7], v[6:7], v[110:111] op_sel:[0,1] op_sel_hi:[1,0] neg_hi:[0,1]
	v_pk_mul_f32 v[122:123], v[114:115], s[12:13] op_sel:[1,0] op_sel_hi:[0,0] neg_lo:[1,0]
	v_pk_add_f32 v[110:111], v[120:121], v[118:119]
	v_pk_fma_f32 v[114:115], v[114:115], s[12:13], v[122:123] op_sel_hi:[1,0,1]
	v_pk_mul_f32 v[122:123], v[2:3], s[36:37] op_sel:[1,0] op_sel_hi:[0,0] neg_lo:[1,0]
	v_pk_add_f32 v[118:119], v[120:121], v[118:119] neg_lo:[0,1] neg_hi:[0,1]
	v_pk_fma_f32 v[2:3], v[2:3], s[22:23], v[122:123] op_sel_hi:[1,0,1]
	v_pk_mul_f32 v[122:123], v[124:125], s[12:13] op_sel:[1,0] op_sel_hi:[0,0] neg_lo:[1,0]
	v_pk_fma_f32 v[122:123], v[124:125], s[12:13], v[122:123] op_sel_hi:[1,0,1]
	v_pk_fma_f32 v[116:117], v[116:117], 0, v[116:117] op_sel:[0,0,1] op_sel_hi:[1,0,0] neg_lo:[0,0,1]
	v_xor_b32_e32 v124, 0x80000000, v5
	v_mov_b32_e32 v125, v4
	v_pk_mul_f32 v[4:5], v[4:5], s[12:13] op_sel_hi:[1,0]
	s_nop 0
	v_pk_fma_f32 v[4:5], v[124:125], s[12:13], v[4:5] op_sel_hi:[1,0,1] neg_lo:[0,0,1] neg_hi:[0,0,1]
	v_pk_mul_f32 v[124:125], v[126:127], s[36:37] op_sel:[1,0] op_sel_hi:[0,0] neg_lo:[1,0]
	v_pk_mul_f32 v[120:121], v[128:129], s[22:23] op_sel:[1,0] op_sel_hi:[0,0] neg_lo:[1,0]
	v_pk_fma_f32 v[124:125], v[126:127], s[22:23], v[124:125] op_sel_hi:[1,0,1]
	v_xor_b32_e32 v126, 0x80000000, v119
	v_mov_b32_e32 v127, v118
	v_pk_mul_f32 v[118:119], v[118:119], s[12:13] op_sel_hi:[1,0]
	v_pk_fma_f32 v[120:121], v[128:129], s[36:37], v[120:121] op_sel_hi:[1,0,1]
	v_pk_fma_f32 v[118:119], v[126:127], s[12:13], v[118:119] op_sel_hi:[1,0,1] neg_lo:[0,0,1] neg_hi:[0,0,1]
	v_pk_mul_f32 v[126:127], v[6:7], s[22:23] op_sel:[1,0] op_sel_hi:[0,0] neg_lo:[1,0]
	v_pk_fma_f32 v[6:7], v[6:7], s[26:27], v[126:127] op_sel_hi:[1,0,1] neg_lo:[0,0,1] neg_hi:[0,0,1]
	v_pk_add_f32 v[126:127], v[104:105], v[108:109]
	v_pk_add_f32 v[104:105], v[104:105], v[108:109] neg_lo:[0,1] neg_hi:[0,1]
	v_pk_add_f32 v[108:109], v[106:107], v[110:111]
	v_pk_add_f32 v[106:107], v[106:107], v[110:111] neg_lo:[0,1] neg_hi:[0,1]
	s_nop 0
	v_xor_b32_e32 v110, 0x80000000, v107
	v_mov_b32_e32 v111, v106
	v_pk_add_f32 v[106:107], v[126:127], v[108:109]
	v_pk_add_f32 v[108:109], v[126:127], v[108:109] neg_lo:[0,1] neg_hi:[0,1]
	v_pk_add_f32 v[126:127], v[120:121], v[124:125]
	v_pk_add_f32 v[120:121], v[120:121], v[124:125] neg_lo:[0,1] neg_hi:[0,1]
	v_pk_add_f32 v[128:129], v[104:105], v[110:111]
	v_pk_add_f32 v[104:105], v[104:105], v[110:111] neg_lo:[0,1] neg_hi:[0,1]
	v_pk_add_f32 v[110:111], v[130:131], v[122:123]
	v_pk_add_f32 v[122:123], v[130:131], v[122:123] neg_lo:[0,1] neg_hi:[0,1]
	s_nop 0
	v_pk_add_f32 v[130:131], v[122:123], v[120:121] op_sel:[0,1] op_sel_hi:[1,0] neg_lo:[0,1]
	v_pk_add_f32 v[122:123], v[122:123], v[120:121] op_sel:[0,1] op_sel_hi:[1,0] neg_hi:[0,1]
	v_pk_add_f32 v[124:125], v[112:113], v[116:117]
	v_pk_add_f32 v[112:113], v[112:113], v[116:117] neg_lo:[0,1] neg_hi:[0,1]
	v_pk_add_f32 v[116:117], v[114:115], v[118:119]
	v_pk_add_f32 v[114:115], v[114:115], v[118:119] neg_lo:[0,1] neg_hi:[0,1]
	v_pk_add_f32 v[120:121], v[110:111], v[126:127]
	v_pk_add_f32 v[110:111], v[110:111], v[126:127] neg_lo:[0,1] neg_hi:[0,1]
	v_pk_add_f32 v[126:127], v[112:113], v[114:115] op_sel:[0,1] op_sel_hi:[1,0] neg_lo:[0,1]
	v_pk_add_f32 v[112:113], v[112:113], v[114:115] op_sel:[0,1] op_sel_hi:[1,0] neg_hi:[0,1]
	v_pk_add_f32 v[118:119], v[0:1], v[4:5]
	v_pk_add_f32 v[0:1], v[0:1], v[4:5] neg_lo:[0,1] neg_hi:[0,1]
	v_pk_add_f32 v[4:5], v[2:3], v[6:7]
	v_pk_add_f32 v[2:3], v[2:3], v[6:7] neg_lo:[0,1] neg_hi:[0,1]
	v_pk_add_f32 v[114:115], v[124:125], v[116:117]
	v_pk_add_f32 v[116:117], v[124:125], v[116:117] neg_lo:[0,1] neg_hi:[0,1]
	v_pk_add_f32 v[124:125], v[0:1], v[2:3] op_sel:[0,1] op_sel_hi:[1,0] neg_lo:[0,1]
	v_pk_add_f32 v[0:1], v[0:1], v[2:3] op_sel:[0,1] op_sel_hi:[1,0] neg_hi:[0,1]
	v_pk_add_f32 v[2:3], v[118:119], v[4:5]
	v_pk_add_f32 v[4:5], v[118:119], v[4:5] neg_lo:[0,1] neg_hi:[0,1]
	ds_write_b64 v132, v[106:107]
	ds_write_b64 v132, v[128:129] offset:8704
	ds_write_b64 v132, v[108:109] offset:17408
	ds_write_b64 v132, v[104:105] offset:26112
	ds_write_b64 v132, v[120:121] offset:2176
	ds_write_b64 v132, v[130:131] offset:10880
	ds_write_b64 v132, v[110:111] offset:19584
	ds_write_b64 v132, v[122:123] offset:28288
	ds_write_b64 v132, v[114:115] offset:4352
	ds_write_b64 v132, v[126:127] offset:13056
	ds_write_b64 v132, v[116:117] offset:21760
	ds_write_b64 v132, v[112:113] offset:30464
	ds_write_b64 v132, v[2:3] offset:6528
	ds_write_b64 v132, v[124:125] offset:15232
	ds_write_b64 v132, v[4:5] offset:23936
	ds_write_b64 v132, v[0:1] offset:32640
	s_waitcnt lgkmcnt(0)
	s_barrier
	v_mov_b32_e32 v115, v214
	v_and_b32_e32 v1, 0x1ff, v212
	v_lshlrev_b32_e32 v2, 3, v1
	v_bfe_u32 v0, v212, 1, 8
	v_add_u32_e32 v104, v2, v0
	v_cmp_eq_u32_e32 vcc, 0, v1
	s_waitcnt vmcnt(3)
	v_lshlrev_b32_e32 v0, 16, v233
	v_cmp_eq_u32_e64 s[0:1], s37, v1
	v_cndmask_b32_e64 v139, v0, 0, vcc
	s_waitcnt vmcnt(2)
	v_lshlrev_b32_e32 v0, 16, v232
	v_cndmask_b32_e64 v135, v0, 0, s[0:1]
	s_waitcnt vmcnt(1)
	v_lshlrev_b32_e32 v0, 16, v231
	v_cndmask_b32_e64 v121, v0, 0, vcc
	s_waitcnt vmcnt(0)
	v_lshlrev_b32_e32 v0, 16, v176
	v_cndmask_b32_e64 v107, v0, 0, s[0:1]
	v_add_u32_e32 v0, -1, v2
	v_cndmask_b32_e64 v176, v0, 0, vcc
	v_add_u32_e32 v0, 8, v2
	v_cndmask_b32_e64 v12, v0, v229, s[0:1]
	v_lshlrev_b64 v[110:111], 1, v[176:177]
	v_mov_b32_e32 v114, v213
	v_lshlrev_b32_e32 v116, 16, v8
	v_and_b32_e32 v117, 0xffff0000, v8
	v_lshlrev_b32_e32 v8, 4, v1
	v_lshl_add_u64 v[112:113], s[2:3], 0, v[110:111]
	v_lshlrev_b32_e32 v12, 1, v12
	v_lshl_add_u64 v[110:111], s[6:7], 0, v[110:111]
	v_lshl_add_u32 v104, v104, 3, 0
	global_load_dwordx4 v[4:7], v8, s[2:3]
	global_load_dwordx4 v[0:3], v8, s[6:7]
	global_load_ushort v143, v[112:113], off
	global_load_ushort v142, v12, s[2:3]
	global_load_ushort v141, v[110:111], off
	global_load_ushort v140, v12, s[6:7]
	v_add_u32_e32 v12, 0x8800, v104
	ds_read2_b64 v[110:113], v104 offset1:1
	ds_read2_b64 v[122:125], v12 offset1:1
	v_xor_b32_e32 v119, 0x80000000, v115
	v_mov_b32_e32 v118, v114
	v_mov_b32_e32 v132, v137
	s_waitcnt lgkmcnt(0)
	v_pk_mul_f32 v[118:119], v[118:119], v[122:123] op_sel_hi:[1,0]
	v_lshlrev_b32_e32 v131, 16, v15
	v_pk_fma_f32 v[118:119], v[114:115], v[122:123], v[118:119] op_sel:[1,1,0] op_sel_hi:[0,1,1]
	v_pk_add_f32 v[122:123], v[110:111], v[118:119]
	v_pk_mul_f32 v[110:111], v[214:215], s[8:9] op_sel_hi:[0,1]
	v_pk_fma_f32 v[110:111], v[212:213], s[30:31], v[110:111] op_sel:[1,0,0]
	s_nop 0
	v_pk_add_f32 v[114:115], v[110:111], 0 neg_lo:[1,1] neg_hi:[1,1]
	s_nop 0
	v_mov_b32_e32 v114, v110
	v_pk_mul_f32 v[114:115], v[114:115], v[124:125] op_sel_hi:[1,0]
	v_and_b32_e32 v15, 0xffff0000, v15
	v_pk_fma_f32 v[114:115], v[110:111], v[124:125], v[114:115] op_sel:[1,1,0] op_sel_hi:[0,1,1]
	v_pk_add_f32 v[124:125], v[112:113], v[114:115]
	v_pk_mul_f32 v[112:113], v[110:111], s[8:9] op_sel:[1,0]
	v_add_u32_e32 v12, 0x8810, v104
	v_pk_fma_f32 v[114:115], v[110:111], s[30:31], v[112:113] op_sel_hi:[0,1,1]
	ds_read2_b64 v[110:113], v104 offset0:2 offset1:3
	ds_read2_b64 v[126:129], v12 offset1:1
	v_pk_add_f32 v[118:119], v[114:115], 0 neg_lo:[1,1] neg_hi:[1,1]
	v_mov_b32_e32 v134, v131
	v_mov_b32_e32 v118, v114
	v_and_b32_e32 v109, 0xffff0000, v9
	s_waitcnt lgkmcnt(0)
	v_pk_mul_f32 v[118:119], v[118:119], v[126:127] op_sel_hi:[1,0]
	s_nop 0
	v_pk_fma_f32 v[118:119], v[114:115], v[126:127], v[118:119] op_sel:[1,1,0] op_sel_hi:[0,1,1]
	v_pk_add_f32 v[126:127], v[110:111], v[118:119]
	v_pk_mul_f32 v[110:111], v[114:115], s[8:9] op_sel:[1,0]
	v_lshlrev_b32_e32 v105, 16, v11
	v_pk_fma_f32 v[110:111], v[114:115], s[30:31], v[110:111] op_sel_hi:[0,1,1]
	v_pk_add_f32 v[114:115], v[110:111], 0 neg_lo:[1,1] neg_hi:[1,1]
	v_and_b32_e32 v11, 0xffff0000, v11
	v_mov_b32_e32 v114, v110
	v_pk_mul_f32 v[114:115], v[114:115], v[128:129] op_sel_hi:[1,0]
	s_brev_b32 s0, 48
	v_pk_fma_f32 v[114:115], v[110:111], v[128:129], v[114:115] op_sel:[1,1,0] op_sel_hi:[0,1,1]
	v_pk_add_f32 v[128:129], v[112:113], v[114:115]
	v_pk_mul_f32 v[112:113], v[110:111], s[8:9] op_sel:[1,0]
	v_add_u32_e32 v12, 0x8820, v104
	v_pk_fma_f32 v[114:115], v[110:111], s[30:31], v[112:113] op_sel_hi:[0,1,1]
	ds_read2_b64 v[110:113], v104 offset0:4 offset1:5
	ds_read2_b64 v[144:147], v12 offset1:1
	v_pk_add_f32 v[118:119], v[114:115], 0 neg_lo:[1,1] neg_hi:[1,1]
	s_waitcnt lgkmcnt(0)
	v_mov_b32_e32 v12, v147
	v_mov_b32_e32 v118, v114
	v_pk_mul_f32 v[118:119], v[118:119], v[144:145] op_sel_hi:[1,0]
	s_nop 0
	v_pk_fma_f32 v[118:119], v[114:115], v[144:145], v[118:119] op_sel:[1,1,0] op_sel_hi:[0,1,1]
	v_pk_add_f32 v[110:111], v[110:111], v[118:119]
	v_pk_mul_f32 v[118:119], v[114:115], s[8:9] op_sel:[1,0]
	s_nop 0
	v_pk_fma_f32 v[114:115], v[114:115], s[30:31], v[118:119] op_sel_hi:[0,1,1]
	v_pk_add_f32 v[118:119], v[114:115], 0 neg_lo:[1,1] neg_hi:[1,1]
	s_nop 0
	v_mov_b32_e32 v118, v114
	v_pk_mul_f32 v[118:119], v[118:119], v[146:147] op_sel_hi:[1,0]
	ds_read2_b64 v[144:147], v104 offset0:6 offset1:7
	v_pk_fma_f32 v[118:119], v[114:115], v[12:13], v[118:119] op_sel:[1,0,0] op_sel_hi:[0,0,1]
	v_add_u32_e32 v12, 0x8830, v104
	ds_read2_b64 v[148:151], v12 offset1:1
	v_pk_add_f32 v[112:113], v[112:113], v[118:119]
	v_pk_mul_f32 v[118:119], v[114:115], s[8:9] op_sel:[1,0]
	s_waitcnt lgkmcnt(0)
	v_pk_fma_f32 v[118:119], v[114:115], s[30:31], v[118:119] op_sel_hi:[0,1,1]
	v_pk_add_f32 v[114:115], v[118:119], 0 neg_lo:[1,1] neg_hi:[1,1]
	s_nop 0
	v_mov_b32_e32 v114, v118
	v_pk_mul_f32 v[114:115], v[114:115], v[148:149] op_sel_hi:[1,0]
	s_nop 0
	v_pk_fma_f32 v[114:115], v[118:119], v[148:149], v[114:115] op_sel:[1,1,0] op_sel_hi:[0,1,1]
	v_pk_add_f32 v[114:115], v[144:145], v[114:115]
	v_pk_mul_f32 v[144:145], v[118:119], s[8:9] op_sel:[1,0]
	s_nop 0
	v_pk_fma_f32 v[118:119], v[118:119], s[30:31], v[144:145] op_sel_hi:[0,1,1]
	v_pk_add_f32 v[144:145], v[118:119], 0 neg_lo:[1,1] neg_hi:[1,1]
	s_nop 0
	v_mov_b32_e32 v144, v118
	v_pk_mul_f32 v[144:145], v[150:151], v[144:145] op_sel_hi:[0,1]
	v_pk_fma_f32 v[118:119], v[118:119], v[150:151], v[144:145] op_sel:[1,1,0] op_sel_hi:[0,1,1]
	v_lshlrev_b32_e32 v144, 16, v13
	v_mov_b32_e32 v138, v144
	v_pk_mul_f32 v[138:139], v[30:31], v[138:139]
	v_mov_b32_e32 v12, v136
	v_mov_b32_e32 v13, v144
	v_pk_fma_f32 v[136:137], v[30:31], v[136:137], v[138:139] op_sel:[0,0,1] op_sel_hi:[1,1,0]
	v_pk_mul_f32 v[138:139], v[102:103], v[132:133]
	v_lshlrev_b32_e32 v145, 16, v14
	v_pk_fma_f32 v[136:137], v[34:35], v[132:133], v[136:137]
	v_pk_fma_f32 v[12:13], v[100:101], v[12:13], v[138:139]
	v_pk_add_f32 v[136:137], v[36:37], v[136:137]
	v_pk_fma_f32 v[12:13], v[34:35], v[144:145], v[12:13]
	v_mov_b32_e32 v138, v122
	v_mov_b32_e32 v139, v126
	v_pk_add_f32 v[12:13], v[36:37], v[12:13]
	v_pk_mul_f32 v[136:137], v[136:137], v[138:139]
	v_mov_b32_e32 v138, v124
	v_mov_b32_e32 v139, v128
	v_pk_mul_f32 v[12:13], v[12:13], v[138:139]
	v_and_b32_e32 v14, 0xffff0000, v14
	v_mov_b32_e32 v138, v145
	v_mov_b32_e32 v139, v131
	v_pk_mov_b32 v[132:133], v[132:133], v[14:15] op_sel:[1,0]
	v_pk_mul_f32 v[138:139], v[102:103], v[138:139]
	v_mov_b32_e32 v144, v15
	v_pk_fma_f32 v[132:133], v[100:101], v[132:133], v[138:139]
	v_mov_b32_e32 v130, v14
	v_pk_fma_f32 v[132:133], v[34:35], v[14:15], v[132:133]
	v_pk_mul_f32 v[14:15], v[30:31], v[144:145]
	v_pk_add_f32 v[118:119], v[146:147], v[118:119]
	v_pk_fma_f32 v[14:15], v[30:31], v[130:131], v[14:15] op_sel:[0,0,1] op_sel_hi:[1,1,0]
	v_pk_add_f32 v[132:133], v[36:37], v[132:133]
	v_pk_fma_f32 v[14:15], v[34:35], v[134:135], v[14:15]
	v_mov_b32_e32 v130, v110
	v_mov_b32_e32 v131, v114
	v_pk_add_f32 v[14:15], v[36:37], v[14:15]
	v_pk_mul_f32 v[130:131], v[132:133], v[130:131]
	v_mov_b32_e32 v132, v112
	v_mov_b32_e32 v133, v118
	v_pk_mul_f32 v[14:15], v[14:15], v[132:133]
	v_bfe_u32 v108, v13, 16, 1
	v_bfe_u32 v104, v15, 16, 1
	v_add3_u32 v15, v15, v104, s13
	v_add3_u32 v13, v13, v108, s13
	v_bfe_u32 v104, v130, 16, 1
	v_bfe_u32 v108, v136, 16, 1
	v_bfe_u32 v106, v14, 16, 1
	v_bfe_u32 v110, v12, 16, 1
	v_add3_u32 v104, v130, v104, s13
	v_add3_u32 v108, v136, v108, s13
	v_lshlrev_b32_e32 v130, 16, v9
	v_add3_u32 v14, v14, v106, s13
	v_add3_u32 v12, v12, v110, s13
	v_bfe_u32 v106, v131, 16, 1
	v_lshrrev_b32_e32 v108, 16, v108
	v_mov_b32_e32 v120, v130
	v_add3_u32 v106, v131, v106, s13
	v_and_or_b32 v12, v12, s33, v108
	v_lshlrev_b32_e32 v131, 16, v10
	v_mov_b32_e32 v108, v117
	v_pk_mul_f32 v[120:121], v[30:31], v[120:121]
	v_mov_b32_e32 v132, v116
	v_mov_b32_e32 v133, v130
	v_pk_fma_f32 v[116:117], v[30:31], v[116:117], v[120:121] op_sel:[0,0,1] op_sel_hi:[1,1,0]
	v_pk_mul_f32 v[120:121], v[102:103], v[108:109]
	v_mov_b32_e32 v126, v123
	v_and_b32_e32 v10, 0xffff0000, v10
	v_mov_b32_e32 v122, v131
	v_mov_b32_e32 v123, v105
	v_pk_fma_f32 v[116:117], v[34:35], v[108:109], v[116:117]
	v_pk_fma_f32 v[120:121], v[100:101], v[132:133], v[120:121]
	v_pk_mov_b32 v[108:109], v[108:109], v[10:11] op_sel:[1,0]
	v_pk_mul_f32 v[122:123], v[102:103], v[122:123]
	v_lshrrev_b32_e32 v104, 16, v104
	v_pk_fma_f32 v[120:121], v[34:35], v[130:131], v[120:121]
	v_pk_fma_f32 v[108:109], v[100:101], v[108:109], v[122:123]
	v_mov_b32_e32 v130, v11
	v_lshrrev_b32_e32 v106, 16, v106
	v_and_or_b32 v14, v14, s33, v104
	v_mov_b32_e32 v104, v10
	v_pk_fma_f32 v[108:109], v[34:35], v[10:11], v[108:109]
	v_pk_mul_f32 v[10:11], v[30:31], v[130:131]
	v_and_or_b32 v15, v15, s33, v106
	v_mov_b32_e32 v106, v105
	v_pk_fma_f32 v[10:11], v[30:31], v[104:105], v[10:11] op_sel:[0,0,1] op_sel_hi:[1,1,0]
	v_pk_add_f32 v[120:121], v[36:37], v[120:121]
	v_pk_fma_f32 v[10:11], v[34:35], v[106:107], v[10:11]
	v_mov_b32_e32 v128, v125
	v_pk_add_f32 v[10:11], v[36:37], v[10:11]
	v_mov_b32_e32 v118, v113
	v_pk_mul_f32 v[120:121], v[120:121], v[128:129]
	v_pk_add_f32 v[108:109], v[36:37], v[108:109]
	v_mov_b32_e32 v114, v111
	v_pk_mul_f32 v[10:11], v[10:11], v[118:119]
	v_pk_add_f32 v[116:117], v[36:37], v[116:117]
	v_pk_mul_f32 v[104:105], v[108:109], v[114:115]
	v_bfe_u32 v9, v11, 16, 1
	v_bfe_u32 v107, v121, 16, 1
	v_bfe_u32 v108, v120, 16, 1
	v_bfe_u32 v110, v137, 16, 1
	v_pk_mul_f32 v[116:117], v[116:117], v[126:127]
	v_add3_u32 v9, v11, v9, s13
	v_add3_u32 v11, v120, v108, s13
	v_add3_u32 v108, v121, v107, s13
	v_bfe_u32 v107, v105, 16, 1
	v_add3_u32 v110, v137, v110, s13
	v_bfe_u32 v106, v10, 16, 1
	v_bfe_u32 v109, v116, 16, 1
	v_add3_u32 v105, v105, v107, s13
	v_lshrrev_b32_e32 v110, 16, v110
	v_add3_u32 v10, v10, v106, s13
	v_bfe_u32 v106, v104, 16, 1
	v_add3_u32 v107, v116, v109, s13
	v_lshrrev_b32_e32 v105, 16, v105
	v_and_or_b32 v13, v13, s33, v110
	v_bfe_u32 v110, v117, 16, 1
	v_add3_u32 v104, v104, v106, s13
	v_lshrrev_b32_e32 v109, 16, v107
	v_and_or_b32 v107, v9, s33, v105
	v_mov_b32_e32 v9, v177
	v_add3_u32 v106, v117, v110, s13
	v_lshrrev_b32_e32 v104, 16, v104
	v_lshl_add_u64 v[8:9], s[44:45], 0, v[8:9]
	v_lshrrev_b32_e32 v110, 16, v106
	v_and_or_b32 v106, v10, s33, v104
	v_add_co_u32_e32 v10, vcc, s0, v8
	v_and_or_b32 v104, v11, s33, v109
	s_nop 0
	v_addc_co_u32_e32 v11, vcc, 0, v9, vcc
	v_add_co_u32_e32 v8, vcc, 0xc002000, v8
	v_and_or_b32 v105, v108, s33, v110
	s_nop 0
	v_addc_co_u32_e32 v9, vcc, 0, v9, vcc
	global_store_dwordx4 v[10:11], v[12:15], off
	global_store_dwordx4 v[8:9], v[104:107], off
	s_cbranch_scc0 .LBB0_209
	s_load_dword s0, s[74:75], 0x0
	s_waitcnt lgkmcnt(0)
	s_add_i32 s38, s0, s38
	s_cmpk_gt_i32 s38, 0x1ff
	s_cbranch_scc0 .LBB0_204

.LBB0_214:
	s_mov_b32 s0, s9
	s_add_i32 s9, s9, s3
	s_cmpk_gt_i32 s9, 0x7ff
	s_cselect_b64 s[40:41], -1, 0
	s_cmpk_lt_i32 s9, 0x800
	v_add_u32_e32 v69, s0, v34
	s_cselect_b32 s0, s9, s0
	v_add_u32_e32 v2, s0, v34
	v_and_b32_e32 v0, 31, v2
	v_lshlrev_b32_e32 v1, 1, v2
	s_movk_i32 s0, 0x1c0
	v_and_or_b32 v0, v1, s0, v0
	v_readlane_b32 s0, v254, 43
	v_lshlrev_b32_e32 v2, 4, v2
	v_lshlrev_b32_e32 v176, 16, v0
	v_readlane_b32 s1, v254, 44
	v_and_b32_e32 v2, 0xfffff000, v2
	v_ashrrev_i32_e32 v3, 31, v2
	v_lshl_add_u64 v[0:1], s[0:1], 0, v[176:177]
	v_lshlrev_b32_e32 v4, 1, v206
	v_lshl_add_u64 v[0:1], v[2:3], 1, v[0:1]
	s_mov_b64 s[0:1], 0x200000
	v_and_b32_e32 v176, 0x1fe, v4
	v_lshl_add_u64 v[2:3], v[0:1], 0, s[0:1]
	v_lshl_add_u64 v[4:5], v[0:1], 0, v[176:177]
	s_waitcnt vmcnt(0)
	v_lshlrev_b32_e32 v70, 16, v68
	v_lshlrev_b32_e32 v71, 16, v67
	v_lshlrev_b32_e32 v72, 16, v63
	v_lshlrev_b32_e32 v73, 16, v66
	v_lshlrev_b32_e32 v22, 16, v62
	v_lshlrev_b32_e32 v23, 16, v65
	v_lshlrev_b32_e32 v6, 16, v59
	v_lshlrev_b32_e32 v7, 16, v64
	v_lshlrev_b32_e32 v74, 16, v57
	v_lshlrev_b32_e32 v75, 16, v61
	v_lshlrev_b32_e32 v76, 16, v55
	v_lshlrev_b32_e32 v77, 16, v58
	v_lshlrev_b32_e32 v24, 16, v54
	v_lshlrev_b32_e32 v25, 16, v56
	v_lshlrev_b32_e32 v10, 16, v51
	v_lshlrev_b32_e32 v11, 16, v53
	v_lshl_add_u64 v[8:9], v[2:3], 0, v[176:177]
	global_load_ushort v68, v[4:5], off
	global_load_ushort v63, v[4:5], off offset:512
	global_load_ushort v62, v[4:5], off offset:1024
	global_load_ushort v59, v[4:5], off offset:1536
	global_load_ushort v57, v[4:5], off offset:2048
	global_load_ushort v55, v[4:5], off offset:2560
	global_load_ushort v54, v[4:5], off offset:3072
	global_load_ushort v51, v[4:5], off offset:3584
	global_load_ushort v67, v[8:9], off
	global_load_ushort v66, v[8:9], off offset:512
	global_load_ushort v65, v[8:9], off offset:1024
	global_load_ushort v64, v[8:9], off offset:1536
	global_load_ushort v61, v[8:9], off offset:2048
	global_load_ushort v58, v[8:9], off offset:2560
	global_load_ushort v56, v[8:9], off offset:3072
	global_load_ushort v53, v[8:9], off offset:3584
	v_or_b32_e32 v4, 0x1000, v176
	v_mov_b32_e32 v5, v177
	v_or_b32_e32 v12, 0x1200, v176
	v_mov_b32_e32 v13, v177
	v_or_b32_e32 v16, 0x1400, v176
	v_mov_b32_e32 v17, v177
	v_lshl_add_u64 v[8:9], v[0:1], 0, v[4:5]
	v_lshl_add_u64 v[4:5], v[2:3], 0, v[4:5]
	v_lshl_add_u64 v[14:15], v[0:1], 0, v[12:13]
	v_lshl_add_u64 v[12:13], v[2:3], 0, v[12:13]
	v_lshl_add_u64 v[26:27], v[0:1], 0, v[16:17]
	v_lshl_add_u64 v[16:17], v[2:3], 0, v[16:17]
	v_or_b32_e32 v28, 0x1600, v176
	v_mov_b32_e32 v29, v177
	v_lshlrev_b32_e32 v78, 16, v60
	v_lshlrev_b32_e32 v79, 16, v50
	v_lshlrev_b32_e32 v80, 16, v48
	v_lshlrev_b32_e32 v81, 16, v47
	v_lshlrev_b32_e32 v82, 16, v45
	v_lshlrev_b32_e32 v83, 16, v44
	v_lshlrev_b32_e32 v18, 16, v43
	v_lshlrev_b32_e32 v19, 16, v42
	v_lshl_add_u64 v[30:31], v[0:1], 0, v[28:29]
	v_lshl_add_u64 v[28:29], v[2:3], 0, v[28:29]
	global_load_ushort v60, v[8:9], off
	global_load_ushort v50, v[4:5], off
	global_load_ushort v48, v[14:15], off
	global_load_ushort v47, v[12:13], off
	global_load_ushort v45, v[26:27], off
	global_load_ushort v44, v[16:17], off
	global_load_ushort v43, v[30:31], off
	global_load_ushort v42, v[28:29], off
	v_or_b32_e32 v4, 0x1800, v176
	v_mov_b32_e32 v5, v177
	v_or_b32_e32 v12, 0x1a00, v176
	v_mov_b32_e32 v13, v177
	v_or_b32_e32 v16, 0x1c00, v176
	v_mov_b32_e32 v17, v177
	v_or_b32_e32 v176, 0x1e00, v176
	v_lshl_add_u64 v[8:9], v[0:1], 0, v[4:5]
	v_lshl_add_u64 v[14:15], v[0:1], 0, v[12:13]
	v_lshl_add_u64 v[26:27], v[0:1], 0, v[16:17]
	v_lshl_add_u64 v[0:1], v[0:1], 0, v[176:177]
	v_lshlrev_b32_e32 v84, 16, v46
	v_lshlrev_b32_e32 v85, 16, v41
	v_lshlrev_b32_e32 v86, 16, v40
	v_lshlrev_b32_e32 v87, 16, v39
	v_lshlrev_b32_e32 v88, 16, v38
	v_lshlrev_b32_e32 v89, 16, v37
	v_lshlrev_b32_e32 v20, 16, v36
	v_lshlrev_b32_e32 v21, 16, v35
	v_lshl_add_u64 v[4:5], v[2:3], 0, v[4:5]
	v_lshl_add_u64 v[12:13], v[2:3], 0, v[12:13]
	v_lshl_add_u64 v[16:17], v[2:3], 0, v[16:17]
	v_lshl_add_u64 v[2:3], v[2:3], 0, v[176:177]
	global_load_ushort v46, v[8:9], off
	global_load_ushort v41, v[4:5], off
	global_load_ushort v40, v[14:15], off
	global_load_ushort v39, v[12:13], off
	global_load_ushort v38, v[26:27], off
	global_load_ushort v37, v[16:17], off
	global_load_ushort v36, v[0:1], off
	global_load_ushort v35, v[2:3], off
	v_mov_b32_e32 v90, 1.0
	v_pk_mul_f32 v[2:3], v[208:209], v[208:209] op_sel:[1,1] op_sel_hi:[0,1] neg_lo:[1,0]
	v_mov_b32_e32 v91, v177
	v_pk_fma_f32 v[2:3], v[208:209], v[208:209], v[2:3] op_sel_hi:[0,1,1]
	v_pk_mul_f32 v[12:13], v[2:3], v[2:3] op_sel:[1,1] op_sel_hi:[1,0] neg_lo:[0,1]
	v_pk_mul_f32 v[4:5], v[208:209], v[176:177] op_sel:[1,1] op_sel_hi:[0,1] neg_lo:[1,0]
	v_pk_fma_f32 v[12:13], v[2:3], v[2:3], v[12:13] op_sel_hi:[1,0,1]
	v_pk_fma_f32 v[92:93], v[208:209], v[90:91], v[4:5] op_sel_hi:[1,0,1]
	v_pk_mul_f32 v[0:1], v[176:177], v[2:3] op_sel:[1,1] op_sel_hi:[1,0] neg_lo:[0,1]
	s_nop 0
	v_pk_fma_f32 v[94:95], v[90:91], v[2:3], v[0:1] op_sel_hi:[0,1,1]
	v_pk_mul_f32 v[0:1], v[92:93], v[2:3] op_sel:[1,1] op_sel_hi:[1,0] neg_lo:[0,1]
	v_pk_mul_f32 v[16:17], v[12:13], v[12:13] op_sel:[1,1] op_sel_hi:[1,0] neg_lo:[0,1]
	v_pk_fma_f32 v[96:97], v[2:3], v[92:93], v[0:1] op_sel_hi:[1,0,1]
	v_pk_mul_f32 v[0:1], v[176:177], v[12:13] op_sel:[1,1] op_sel_hi:[1,0] neg_lo:[0,1]
	s_nop 0
	v_pk_fma_f32 v[98:99], v[90:91], v[12:13], v[0:1] op_sel_hi:[0,1,1]
	v_pk_mul_f32 v[0:1], v[92:93], v[12:13] op_sel:[1,1] op_sel_hi:[1,0] neg_lo:[0,1]
	s_nop 0
	v_pk_fma_f32 v[32:33], v[92:93], v[12:13], v[0:1] op_sel_hi:[0,1,1]
	v_pk_mul_f32 v[0:1], v[94:95], v[12:13] op_sel:[1,1] op_sel_hi:[1,0] neg_lo:[0,1]
	s_nop 0
	v_pk_fma_f32 v[30:31], v[12:13], v[94:95], v[0:1] op_sel_hi:[1,0,1]
	v_pk_mul_f32 v[0:1], v[96:97], v[12:13] op_sel:[1,1] op_sel_hi:[1,0] neg_lo:[0,1]
	s_nop 0
	v_pk_fma_f32 v[26:27], v[12:13], v[96:97], v[0:1] op_sel_hi:[1,0,1]
	v_pk_fma_f32 v[0:1], v[12:13], v[12:13], v[16:17] op_sel_hi:[1,0,1]
	s_nop 0
	v_pk_mul_f32 v[2:3], v[176:177], v[0:1] op_sel:[1,1] op_sel_hi:[1,0] neg_lo:[0,1]
	s_nop 0
	v_pk_fma_f32 v[28:29], v[90:91], v[0:1], v[2:3] op_sel_hi:[0,1,1]
	v_pk_mul_f32 v[2:3], v[92:93], v[0:1] op_sel:[1,1] op_sel_hi:[1,0] neg_lo:[0,1]
	s_nop 0
	v_pk_fma_f32 v[16:17], v[92:93], v[0:1], v[2:3] op_sel_hi:[0,1,1]
	v_pk_mul_f32 v[2:3], v[94:95], v[0:1] op_sel:[1,1] op_sel_hi:[1,0] neg_lo:[0,1]
	s_nop 0
	v_pk_fma_f32 v[14:15], v[94:95], v[0:1], v[2:3] op_sel_hi:[0,1,1]
	v_pk_mul_f32 v[2:3], v[96:97], v[0:1] op_sel:[1,1] op_sel_hi:[1,0] neg_lo:[0,1]
	s_nop 0
	v_pk_fma_f32 v[12:13], v[96:97], v[0:1], v[2:3] op_sel_hi:[0,1,1]
	v_pk_mul_f32 v[2:3], v[98:99], v[0:1] op_sel:[1,1] op_sel_hi:[1,0] neg_lo:[0,1]
	s_nop 0
	v_pk_fma_f32 v[8:9], v[0:1], v[98:99], v[2:3] op_sel_hi:[1,0,1]
	v_pk_mul_f32 v[2:3], v[32:33], v[0:1] op_sel:[1,1] op_sel_hi:[1,0] neg_lo:[0,1]
	s_nop 0
	v_pk_fma_f32 v[4:5], v[0:1], v[32:33], v[2:3] op_sel_hi:[1,0,1]
	v_pk_mul_f32 v[2:3], v[30:31], v[0:1] op_sel:[1,1] op_sel_hi:[1,0] neg_lo:[0,1]
	v_pk_mul_f32 v[100:101], v[26:27], v[0:1] op_sel:[1,1] op_sel_hi:[1,0] neg_lo:[0,1]
	v_pk_fma_f32 v[2:3], v[0:1], v[30:31], v[2:3] op_sel_hi:[1,0,1]
	v_pk_fma_f32 v[0:1], v[0:1], v[26:27], v[100:101] op_sel_hi:[1,0,1]
	v_pk_add_f32 v[100:101], v[78:79], v[70:71]
	v_pk_add_f32 v[70:71], v[70:71], v[78:79] neg_lo:[0,1] neg_hi:[0,1]
	v_pk_add_f32 v[78:79], v[84:85], v[74:75]
	v_pk_add_f32 v[74:75], v[74:75], v[84:85] neg_lo:[0,1] neg_hi:[0,1]
	s_nop 0
	v_pk_add_f32 v[102:103], v[74:75], v[70:71] op_sel:[1,0] op_sel_hi:[0,1] neg_hi:[1,0]
	v_pk_add_f32 v[70:71], v[70:71], v[74:75] op_sel:[0,1] op_sel_hi:[1,0] neg_lo:[0,1]
	v_pk_add_f32 v[84:85], v[80:81], v[72:73]
	v_pk_add_f32 v[72:73], v[72:73], v[80:81] neg_lo:[0,1] neg_hi:[0,1]
	v_pk_add_f32 v[80:81], v[86:87], v[76:77]
	v_pk_add_f32 v[76:77], v[76:77], v[86:87] neg_lo:[0,1] neg_hi:[0,1]
	v_pk_add_f32 v[74:75], v[78:79], v[100:101]
	v_xor_b32_e32 v87, 0x80000000, v76
	v_mov_b32_e32 v86, v77
	v_pk_add_f32 v[76:77], v[80:81], v[84:85]
	v_pk_add_f32 v[80:81], v[84:85], v[80:81] neg_lo:[0,1] neg_hi:[0,1]
	v_pk_add_f32 v[84:85], v[82:83], v[22:23]
	v_pk_add_f32 v[22:23], v[22:23], v[82:83] neg_lo:[0,1] neg_hi:[0,1]
	v_pk_add_f32 v[82:83], v[88:89], v[24:25]
	v_pk_add_f32 v[24:25], v[24:25], v[88:89] neg_lo:[0,1] neg_hi:[0,1]
	v_pk_add_f32 v[78:79], v[100:101], v[78:79] neg_lo:[0,1] neg_hi:[0,1]
	v_pk_add_f32 v[100:101], v[86:87], v[72:73]
	v_pk_add_f32 v[72:73], v[72:73], v[86:87] neg_lo:[0,1] neg_hi:[0,1]
	v_xor_b32_e32 v87, 0x80000000, v24
	v_mov_b32_e32 v86, v25
	v_pk_add_f32 v[24:25], v[82:83], v[84:85]
	v_pk_add_f32 v[82:83], v[84:85], v[82:83] neg_lo:[0,1] neg_hi:[0,1]
	v_pk_add_f32 v[84:85], v[18:19], v[6:7]
	v_pk_add_f32 v[6:7], v[6:7], v[18:19] neg_lo:[0,1] neg_hi:[0,1]
	v_pk_add_f32 v[18:19], v[20:21], v[10:11]
	v_pk_add_f32 v[10:11], v[10:11], v[20:21] neg_lo:[0,1] neg_hi:[0,1]
	v_pk_add_f32 v[88:89], v[86:87], v[22:23]
	v_xor_b32_e32 v21, 0x80000000, v10
	v_mov_b32_e32 v20, v11
	v_pk_add_f32 v[10:11], v[18:19], v[84:85]
	v_pk_add_f32 v[18:19], v[84:85], v[18:19] neg_lo:[0,1] neg_hi:[0,1]
	v_pk_mul_f32 v[84:85], v[80:81], s[12:13] op_sel:[1,0] op_sel_hi:[0,0] neg_lo:[1,0]
	v_pk_add_f32 v[22:23], v[22:23], v[86:87] neg_lo:[0,1] neg_hi:[0,1]
	v_pk_fma_f32 v[80:81], v[80:81], s[12:13], v[84:85] op_sel_hi:[1,0,1] neg_lo:[0,0,1] neg_hi:[0,0,1]
	v_pk_mul_f32 v[84:85], v[72:73], s[36:37] op_sel:[1,0] op_sel_hi:[0,0] neg_lo:[1,0]
	v_pk_add_f32 v[86:87], v[20:21], v[6:7]
	v_pk_fma_f32 v[72:73], v[72:73], s[22:23], v[84:85] op_sel_hi:[1,0,1] neg_lo:[0,0,1] neg_hi:[0,0,1]
	v_pk_mul_f32 v[84:85], v[88:89], s[12:13] op_sel:[1,0] op_sel_hi:[0,0] neg_lo:[1,0]
	v_pk_add_f32 v[6:7], v[6:7], v[20:21] neg_lo:[0,1] neg_hi:[0,1]
	v_pk_fma_f32 v[84:85], v[88:89], s[12:13], v[84:85] op_sel_hi:[1,0,1] neg_lo:[0,0,1] neg_hi:[0,0,1]
	v_pk_fma_f32 v[82:83], v[82:83], 0, v[82:83] op_sel:[0,0,1] op_sel_hi:[1,0,0] neg_hi:[0,0,1]
	v_pk_mul_f32 v[88:89], v[22:23], s[12:13] op_sel:[1,0] op_sel_hi:[0,0] neg_lo:[1,0]
	v_pk_fma_f32 v[22:23], v[22:23], s[18:19], v[88:89] op_sel_hi:[1,0,1] neg_lo:[0,0,1] neg_hi:[0,0,1]
	v_pk_mul_f32 v[88:89], v[86:87], s[36:37] op_sel:[1,0] op_sel_hi:[0,0] neg_lo:[1,0]
	v_pk_fma_f32 v[86:87], v[86:87], s[22:23], v[88:89] op_sel_hi:[1,0,1] neg_lo:[0,0,1] neg_hi:[0,0,1]
	v_pk_mul_f32 v[88:89], v[18:19], s[12:13] op_sel:[1,0] op_sel_hi:[0,0] neg_lo:[1,0]
	v_pk_mul_f32 v[20:21], v[100:101], s[22:23] op_sel:[1,0] op_sel_hi:[0,0] neg_lo:[1,0]
	v_pk_fma_f32 v[18:19], v[18:19], s[18:19], v[88:89] op_sel_hi:[1,0,1] neg_lo:[0,0,1] neg_hi:[0,0,1]
	v_xor_b32_e32 v88, 0x80000000, v7
	v_mov_b32_e32 v89, v6
	v_pk_mul_f32 v[6:7], v[6:7], s[36:37] op_sel_hi:[1,0]
	v_pk_fma_f32 v[20:21], v[100:101], s[36:37], v[20:21] op_sel_hi:[1,0,1] neg_lo:[0,0,1] neg_hi:[0,0,1]
	v_pk_fma_f32 v[6:7], v[88:89], s[22:23], v[6:7] op_sel_hi:[1,0,1] neg_lo:[0,0,1] neg_hi:[0,0,1]
	v_pk_add_f32 v[88:89], v[24:25], v[74:75]
	v_pk_add_f32 v[24:25], v[74:75], v[24:25] neg_lo:[0,1] neg_hi:[0,1]
	v_pk_add_f32 v[74:75], v[10:11], v[76:77]
	v_pk_add_f32 v[10:11], v[76:77], v[10:11] neg_lo:[0,1] neg_hi:[0,1]
	s_nop 0
	v_xor_b32_e32 v77, 0x80000000, v10
	v_mov_b32_e32 v76, v11
	v_pk_add_f32 v[10:11], v[74:75], v[88:89]
	v_pk_add_f32 v[74:75], v[88:89], v[74:75] neg_lo:[0,1] neg_hi:[0,1]
	v_pk_add_f32 v[88:89], v[86:87], v[20:21]
	v_pk_add_f32 v[20:21], v[20:21], v[86:87] neg_lo:[0,1] neg_hi:[0,1]
	v_pk_add_f32 v[100:101], v[24:25], v[76:77]
	v_pk_add_f32 v[24:25], v[24:25], v[76:77] neg_lo:[0,1] neg_hi:[0,1]
	v_pk_add_f32 v[76:77], v[102:103], v[84:85]
	v_pk_add_f32 v[84:85], v[102:103], v[84:85] neg_lo:[0,1] neg_hi:[0,1]
	s_nop 0
	v_pk_add_f32 v[102:103], v[84:85], v[20:21] op_sel:[0,1] op_sel_hi:[1,0] neg_hi:[0,1]
	v_pk_add_f32 v[84:85], v[84:85], v[20:21] op_sel:[0,1] op_sel_hi:[1,0] neg_lo:[0,1]
	v_pk_add_f32 v[86:87], v[78:79], v[82:83]
	v_pk_add_f32 v[78:79], v[78:79], v[82:83] neg_lo:[0,1] neg_hi:[0,1]
	v_pk_add_f32 v[82:83], v[18:19], v[80:81]
	v_pk_add_f32 v[18:19], v[80:81], v[18:19] neg_lo:[0,1] neg_hi:[0,1]
	v_pk_add_f32 v[20:21], v[76:77], v[88:89]
	v_pk_add_f32 v[76:77], v[76:77], v[88:89] neg_lo:[0,1] neg_hi:[0,1]
	v_pk_add_f32 v[88:89], v[78:79], v[18:19] op_sel:[0,1] op_sel_hi:[1,0] neg_hi:[0,1]
	v_pk_add_f32 v[78:79], v[78:79], v[18:19] op_sel:[0,1] op_sel_hi:[1,0] neg_lo:[0,1]
	v_pk_add_f32 v[80:81], v[70:71], v[22:23]
	v_pk_add_f32 v[22:23], v[70:71], v[22:23] neg_lo:[0,1] neg_hi:[0,1]
	v_pk_add_f32 v[70:71], v[6:7], v[72:73]
	v_pk_add_f32 v[6:7], v[72:73], v[6:7] neg_lo:[0,1] neg_hi:[0,1]
	v_pk_add_f32 v[18:19], v[86:87], v[82:83]
	v_pk_add_f32 v[82:83], v[86:87], v[82:83] neg_lo:[0,1] neg_hi:[0,1]
	v_pk_add_f32 v[86:87], v[22:23], v[6:7] op_sel:[0,1] op_sel_hi:[1,0] neg_hi:[0,1]
	v_pk_add_f32 v[22:23], v[22:23], v[6:7] op_sel:[0,1] op_sel_hi:[1,0] neg_lo:[0,1]
	v_mov_b32_e32 v72, v206
	v_pk_add_f32 v[6:7], v[80:81], v[70:71]
	v_lshlrev_b32_sdwa v73, v228, v72 dst_sel:DWORD dst_unused:UNUSED_PAD src0_sel:DWORD src1_sel:BYTE_0
	v_lshrrev_b32_e32 v72, 1, v206
	v_and_b32_e32 v72, 0x78, v72
	v_pk_add_f32 v[70:71], v[80:81], v[70:71] neg_lo:[0,1] neg_hi:[0,1]
	v_add3_u32 v80, v207, v73, v72
	v_xor_b32_e32 v72, 0x80000000, v91
	v_mov_b32_e32 v73, v90
	v_pk_mul_f32 v[72:73], v[10:11], v[72:73] op_sel:[1,0]
	s_nop 0
	v_pk_fma_f32 v[10:11], v[10:11], v[90:91], v[72:73] op_sel_hi:[0,1,1]
	ds_write_b64 v80, v[10:11]
	v_pk_mul_f32 v[10:11], v[20:21], v[92:93] op_sel:[1,1] op_sel_hi:[1,0] neg_lo:[0,1]
	s_nop 0
	v_pk_fma_f32 v[10:11], v[20:21], v[92:93], v[10:11] op_sel_hi:[0,1,1]
	ds_write_b64 v80, v[10:11] offset:2176
	v_pk_mul_f32 v[10:11], v[18:19], v[94:95] op_sel:[1,1] op_sel_hi:[1,0] neg_lo:[0,1]
	s_nop 0
	v_pk_fma_f32 v[10:11], v[18:19], v[94:95], v[10:11] op_sel_hi:[0,1,1]
	ds_write_b64 v80, v[10:11] offset:4352
	v_pk_mul_f32 v[10:11], v[6:7], v[96:97] op_sel:[1,1] op_sel_hi:[1,0] neg_lo:[0,1]
	s_nop 0
	v_pk_fma_f32 v[6:7], v[6:7], v[96:97], v[10:11] op_sel_hi:[0,1,1]
	ds_write_b64 v80, v[6:7] offset:6528
	v_pk_mul_f32 v[6:7], v[100:101], v[98:99] op_sel:[1,1] op_sel_hi:[1,0] neg_lo:[0,1]
	s_nop 0
	v_pk_fma_f32 v[6:7], v[100:101], v[98:99], v[6:7] op_sel_hi:[0,1,1]
	ds_write_b64 v80, v[6:7] offset:8704
	v_pk_mul_f32 v[6:7], v[102:103], v[32:33] op_sel:[1,1] op_sel_hi:[1,0] neg_lo:[0,1]
	s_nop 0
	v_pk_fma_f32 v[6:7], v[102:103], v[32:33], v[6:7] op_sel_hi:[0,1,1]
	ds_write_b64 v80, v[6:7] offset:10880
	v_pk_mul_f32 v[6:7], v[88:89], v[30:31] op_sel:[1,1] op_sel_hi:[1,0] neg_lo:[0,1]
	s_nop 0
	v_pk_fma_f32 v[6:7], v[88:89], v[30:31], v[6:7] op_sel_hi:[0,1,1]
	ds_write_b64 v80, v[6:7] offset:13056
	v_pk_mul_f32 v[6:7], v[86:87], v[26:27] op_sel:[1,1] op_sel_hi:[1,0] neg_lo:[0,1]
	s_nop 0
	v_pk_fma_f32 v[6:7], v[86:87], v[26:27], v[6:7] op_sel_hi:[0,1,1]
	ds_write_b64 v80, v[6:7] offset:15232
	v_pk_mul_f32 v[6:7], v[74:75], v[28:29] op_sel:[1,1] op_sel_hi:[1,0] neg_lo:[0,1]
	s_nop 0
	v_pk_fma_f32 v[6:7], v[74:75], v[28:29], v[6:7] op_sel_hi:[0,1,1]
	ds_write_b64 v80, v[6:7] offset:17408
	v_pk_mul_f32 v[6:7], v[76:77], v[16:17] op_sel:[1,1] op_sel_hi:[1,0] neg_lo:[0,1]
	s_nop 0
	v_pk_fma_f32 v[6:7], v[76:77], v[16:17], v[6:7] op_sel_hi:[0,1,1]
	ds_write_b64 v80, v[6:7] offset:19584
	v_pk_mul_f32 v[6:7], v[82:83], v[14:15] op_sel:[1,1] op_sel_hi:[1,0] neg_lo:[0,1]
	s_nop 0
	v_pk_fma_f32 v[6:7], v[82:83], v[14:15], v[6:7] op_sel_hi:[0,1,1]
	ds_write_b64 v80, v[6:7] offset:21760
	v_pk_mul_f32 v[6:7], v[70:71], v[12:13] op_sel:[1,1] op_sel_hi:[1,0] neg_lo:[0,1]
	s_nop 0
	v_pk_fma_f32 v[6:7], v[70:71], v[12:13], v[6:7] op_sel_hi:[0,1,1]
	ds_write_b64 v80, v[6:7] offset:23936
	v_pk_mul_f32 v[6:7], v[24:25], v[8:9] op_sel:[1,1] op_sel_hi:[1,0] neg_lo:[0,1]
	s_nop 0
	v_pk_fma_f32 v[6:7], v[24:25], v[8:9], v[6:7] op_sel_hi:[0,1,1]
	ds_write_b64 v80, v[6:7] offset:26112
	v_pk_mul_f32 v[6:7], v[84:85], v[4:5] op_sel:[1,1] op_sel_hi:[1,0] neg_lo:[0,1]
	s_nop 0
	v_pk_fma_f32 v[4:5], v[84:85], v[4:5], v[6:7] op_sel_hi:[0,1,1]
	ds_write_b64 v80, v[4:5] offset:28288
	v_pk_mul_f32 v[4:5], v[78:79], v[2:3] op_sel:[1,1] op_sel_hi:[1,0] neg_lo:[0,1]
	s_nop 0
	v_pk_fma_f32 v[2:3], v[78:79], v[2:3], v[4:5] op_sel_hi:[0,1,1]
	ds_write_b64 v80, v[2:3] offset:30464
	v_pk_mul_f32 v[2:3], v[22:23], v[0:1] op_sel:[1,1] op_sel_hi:[1,0] neg_lo:[0,1]
	s_nop 0
	v_pk_fma_f32 v[0:1], v[22:23], v[0:1], v[2:3] op_sel_hi:[0,1,1]
	ds_write_b64 v80, v[0:1] offset:32640
	v_mov_b32_e32 v78, 1.0
	v_pk_mul_f32 v[2:3], v[210:211], v[210:211] op_sel:[1,1] op_sel_hi:[0,1] neg_lo:[1,0]
	v_mov_b32_e32 v79, v177
	v_pk_fma_f32 v[2:3], v[210:211], v[210:211], v[2:3] op_sel_hi:[0,1,1]
	v_pk_mul_f32 v[8:9], v[2:3], v[2:3] op_sel:[1,1] op_sel_hi:[1,0] neg_lo:[0,1]
	v_pk_mul_f32 v[4:5], v[210:211], v[176:177] op_sel:[1,1] op_sel_hi:[0,1] neg_lo:[1,0]
	v_pk_fma_f32 v[8:9], v[2:3], v[2:3], v[8:9] op_sel_hi:[1,0,1]
	v_pk_fma_f32 v[80:81], v[210:211], v[78:79], v[4:5] op_sel_hi:[1,0,1]
	v_pk_mul_f32 v[0:1], v[176:177], v[2:3] op_sel:[1,1] op_sel_hi:[1,0] neg_lo:[0,1]
	s_nop 0
	v_pk_fma_f32 v[82:83], v[78:79], v[2:3], v[0:1] op_sel_hi:[0,1,1]
	v_pk_mul_f32 v[0:1], v[80:81], v[2:3] op_sel:[1,1] op_sel_hi:[1,0] neg_lo:[0,1]
	v_pk_mul_f32 v[12:13], v[8:9], v[8:9] op_sel:[1,1] op_sel_hi:[1,0] neg_lo:[0,1]
	v_pk_fma_f32 v[84:85], v[2:3], v[80:81], v[0:1] op_sel_hi:[1,0,1]
	v_pk_mul_f32 v[0:1], v[176:177], v[8:9] op_sel:[1,1] op_sel_hi:[1,0] neg_lo:[0,1]
	s_nop 0
	v_pk_fma_f32 v[86:87], v[78:79], v[8:9], v[0:1] op_sel_hi:[0,1,1]
	v_pk_mul_f32 v[0:1], v[80:81], v[8:9] op_sel:[1,1] op_sel_hi:[1,0] neg_lo:[0,1]
	s_waitcnt lgkmcnt(0)
	v_pk_fma_f32 v[88:89], v[80:81], v[8:9], v[0:1] op_sel_hi:[0,1,1]
	v_pk_mul_f32 v[0:1], v[82:83], v[8:9] op_sel:[1,1] op_sel_hi:[1,0] neg_lo:[0,1]
	s_barrier
	v_pk_fma_f32 v[90:91], v[8:9], v[82:83], v[0:1] op_sel_hi:[1,0,1]
	v_pk_mul_f32 v[0:1], v[84:85], v[8:9] op_sel:[1,1] op_sel_hi:[1,0] neg_lo:[0,1]
	s_nop 0
	v_pk_fma_f32 v[92:93], v[8:9], v[84:85], v[0:1] op_sel_hi:[1,0,1]
	v_pk_fma_f32 v[0:1], v[8:9], v[8:9], v[12:13] op_sel_hi:[1,0,1]
	s_nop 0
	v_pk_mul_f32 v[2:3], v[176:177], v[0:1] op_sel:[1,1] op_sel_hi:[1,0] neg_lo:[0,1]
	s_nop 0
	v_pk_fma_f32 v[94:95], v[78:79], v[0:1], v[2:3] op_sel_hi:[0,1,1]
	v_pk_mul_f32 v[2:3], v[80:81], v[0:1] op_sel:[1,1] op_sel_hi:[1,0] neg_lo:[0,1]
	s_nop 0
	v_pk_fma_f32 v[96:97], v[80:81], v[0:1], v[2:3] op_sel_hi:[0,1,1]
	v_pk_mul_f32 v[2:3], v[82:83], v[0:1] op_sel:[1,1] op_sel_hi:[1,0] neg_lo:[0,1]
	s_nop 0
	v_pk_fma_f32 v[98:99], v[82:83], v[0:1], v[2:3] op_sel_hi:[0,1,1]
	v_pk_mul_f32 v[2:3], v[84:85], v[0:1] op_sel:[1,1] op_sel_hi:[1,0] neg_lo:[0,1]
	s_nop 0
	v_pk_fma_f32 v[8:9], v[84:85], v[0:1], v[2:3] op_sel_hi:[0,1,1]
	v_pk_mul_f32 v[2:3], v[86:87], v[0:1] op_sel:[1,1] op_sel_hi:[1,0] neg_lo:[0,1]
	s_nop 0
	v_pk_fma_f32 v[6:7], v[0:1], v[86:87], v[2:3] op_sel_hi:[1,0,1]
	v_pk_mul_f32 v[2:3], v[88:89], v[0:1] op_sel:[1,1] op_sel_hi:[1,0] neg_lo:[0,1]
	s_nop 0
	v_pk_fma_f32 v[4:5], v[0:1], v[88:89], v[2:3] op_sel_hi:[1,0,1]
	v_pk_mul_f32 v[2:3], v[90:91], v[0:1] op_sel:[1,1] op_sel_hi:[1,0] neg_lo:[0,1]
	v_pk_mul_f32 v[10:11], v[92:93], v[0:1] op_sel:[1,1] op_sel_hi:[1,0] neg_lo:[0,1]
	v_pk_fma_f32 v[2:3], v[0:1], v[90:91], v[2:3] op_sel_hi:[1,0,1]
	v_pk_fma_f32 v[0:1], v[0:1], v[92:93], v[10:11] op_sel_hi:[1,0,1]
	s_nop 0
	v_bfe_u32 v11, v206, 4, 4
	v_and_b32_e32 v10, 15, v206
	v_mul_u32_u24_e32 v11, 0x880, v11
	v_lshlrev_b32_e32 v10, 3, v10
	v_add3_u32 v104, v207, v11, v10
	ds_read2_b64 v[10:13], v104 offset1:17
	ds_read2_b64 v[14:17], v104 offset0:34 offset1:51
	ds_read2_b64 v[18:21], v104 offset0:68 offset1:85
	ds_read2_b64 v[22:25], v104 offset0:136 offset1:153
	ds_read2_b64 v[26:29], v104 offset0:102 offset1:119
	ds_read2_b64 v[30:33], v104 offset0:204 offset1:221
	ds_read2_b64 v[70:73], v104 offset0:170 offset1:187
	ds_read2_b64 v[74:77], v104 offset0:238 offset1:255
	s_waitcnt lgkmcnt(4)
	v_pk_add_f32 v[100:101], v[10:11], v[22:23]
	v_pk_add_f32 v[10:11], v[10:11], v[22:23] neg_lo:[0,1] neg_hi:[0,1]
	s_waitcnt lgkmcnt(2)
	v_pk_add_f32 v[22:23], v[18:19], v[30:31]
	v_pk_add_f32 v[18:19], v[18:19], v[30:31] neg_lo:[0,1] neg_hi:[0,1]
	s_nop 0
	v_pk_add_f32 v[102:103], v[10:11], v[18:19] op_sel:[0,1] op_sel_hi:[1,0] neg_hi:[0,1]
	v_pk_add_f32 v[10:11], v[10:11], v[18:19] op_sel:[0,1] op_sel_hi:[1,0] neg_lo:[0,1]
	v_pk_add_f32 v[30:31], v[12:13], v[24:25]
	v_pk_add_f32 v[12:13], v[12:13], v[24:25] neg_lo:[0,1] neg_hi:[0,1]
	v_pk_add_f32 v[24:25], v[20:21], v[32:33]
	v_pk_add_f32 v[20:21], v[20:21], v[32:33] neg_lo:[0,1] neg_hi:[0,1]
	v_pk_add_f32 v[18:19], v[100:101], v[22:23]
	v_pk_add_f32 v[22:23], v[100:101], v[22:23] neg_lo:[0,1] neg_hi:[0,1]
	v_pk_add_f32 v[100:101], v[12:13], v[20:21] op_sel:[0,1] op_sel_hi:[1,0] neg_hi:[0,1]
	v_pk_add_f32 v[12:13], v[12:13], v[20:21] op_sel:[0,1] op_sel_hi:[1,0] neg_lo:[0,1]
	s_waitcnt lgkmcnt(0)
	v_pk_add_f32 v[32:33], v[26:27], v[74:75]
	v_pk_add_f32 v[26:27], v[26:27], v[74:75] neg_lo:[0,1] neg_hi:[0,1]
	v_pk_add_f32 v[20:21], v[30:31], v[24:25]
	v_pk_add_f32 v[24:25], v[30:31], v[24:25] neg_lo:[0,1] neg_hi:[0,1]
	v_pk_add_f32 v[30:31], v[14:15], v[70:71]
	v_pk_add_f32 v[14:15], v[14:15], v[70:71] neg_lo:[0,1] neg_hi:[0,1]
	s_nop 0
	v_pk_add_f32 v[74:75], v[14:15], v[26:27] op_sel:[0,1] op_sel_hi:[1,0] neg_hi:[0,1]
	v_pk_add_f32 v[14:15], v[14:15], v[26:27] op_sel:[0,1] op_sel_hi:[1,0] neg_lo:[0,1]
	v_pk_add_f32 v[70:71], v[28:29], v[76:77]
	v_pk_add_f32 v[28:29], v[28:29], v[76:77] neg_lo:[0,1] neg_hi:[0,1]
	v_pk_add_f32 v[26:27], v[30:31], v[32:33]
	v_pk_add_f32 v[30:31], v[30:31], v[32:33] neg_lo:[0,1] neg_hi:[0,1]
	v_pk_add_f32 v[32:33], v[16:17], v[72:73]
	v_pk_add_f32 v[16:17], v[16:17], v[72:73] neg_lo:[0,1] neg_hi:[0,1]
	s_nop 0
	v_pk_add_f32 v[76:77], v[16:17], v[28:29] op_sel:[0,1] op_sel_hi:[1,0] neg_hi:[0,1]
	v_pk_add_f32 v[16:17], v[16:17], v[28:29] op_sel:[0,1] op_sel_hi:[1,0] neg_lo:[0,1]
	v_pk_mul_f32 v[72:73], v[24:25], s[12:13] op_sel:[1,0] op_sel_hi:[0,0] neg_lo:[1,0]
	v_pk_add_f32 v[28:29], v[32:33], v[70:71]
	v_pk_fma_f32 v[24:25], v[24:25], s[12:13], v[72:73] op_sel_hi:[1,0,1] neg_lo:[0,0,1] neg_hi:[0,0,1]
	v_pk_mul_f32 v[72:73], v[12:13], s[36:37] op_sel:[1,0] op_sel_hi:[0,0] neg_lo:[1,0]
	v_pk_add_f32 v[32:33], v[32:33], v[70:71] neg_lo:[0,1] neg_hi:[0,1]
	v_pk_fma_f32 v[12:13], v[12:13], s[22:23], v[72:73] op_sel_hi:[1,0,1] neg_lo:[0,0,1] neg_hi:[0,0,1]
	v_pk_mul_f32 v[72:73], v[74:75], s[12:13] op_sel:[1,0] op_sel_hi:[0,0] neg_lo:[1,0]
	v_pk_fma_f32 v[72:73], v[74:75], s[12:13], v[72:73] op_sel_hi:[1,0,1] neg_lo:[0,0,1] neg_hi:[0,0,1]
	v_pk_fma_f32 v[30:31], v[30:31], 0, v[30:31] op_sel:[0,0,1] op_sel_hi:[1,0,0] neg_hi:[0,0,1]
	v_pk_mul_f32 v[74:75], v[14:15], s[12:13] op_sel:[1,0] op_sel_hi:[0,0] neg_lo:[1,0]
	v_pk_fma_f32 v[14:15], v[14:15], s[18:19], v[74:75] op_sel_hi:[1,0,1] neg_lo:[0,0,1] neg_hi:[0,0,1]
	v_pk_mul_f32 v[74:75], v[76:77], s[36:37] op_sel:[1,0] op_sel_hi:[0,0] neg_lo:[1,0]
	v_pk_mul_f32 v[70:71], v[100:101], s[22:23] op_sel:[1,0] op_sel_hi:[0,0] neg_lo:[1,0]
	v_pk_fma_f32 v[74:75], v[76:77], s[22:23], v[74:75] op_sel_hi:[1,0,1] neg_lo:[0,0,1] neg_hi:[0,0,1]
	v_pk_mul_f32 v[76:77], v[32:33], s[12:13] op_sel:[1,0] op_sel_hi:[0,0] neg_lo:[1,0]
	v_pk_fma_f32 v[70:71], v[100:101], s[36:37], v[70:71] op_sel_hi:[1,0,1] neg_lo:[0,0,1] neg_hi:[0,0,1]
	v_pk_fma_f32 v[32:33], v[32:33], s[18:19], v[76:77] op_sel_hi:[1,0,1] neg_lo:[0,0,1] neg_hi:[0,0,1]
	v_xor_b32_e32 v76, 0x80000000, v17
	v_mov_b32_e32 v77, v16
	v_pk_mul_f32 v[16:17], v[16:17], s[36:37] op_sel_hi:[1,0]
	s_nop 0
	v_pk_fma_f32 v[16:17], v[76:77], s[22:23], v[16:17] op_sel_hi:[1,0,1] neg_lo:[0,0,1] neg_hi:[0,0,1]
	v_pk_add_f32 v[76:77], v[18:19], v[26:27]
	v_pk_add_f32 v[18:19], v[18:19], v[26:27] neg_lo:[0,1] neg_hi:[0,1]
	v_pk_add_f32 v[26:27], v[20:21], v[28:29]
	v_pk_add_f32 v[20:21], v[20:21], v[28:29] neg_lo:[0,1] neg_hi:[0,1]
	s_nop 0
	v_xor_b32_e32 v29, 0x80000000, v20
	v_mov_b32_e32 v28, v21
	v_pk_add_f32 v[20:21], v[76:77], v[26:27]
	v_pk_add_f32 v[26:27], v[76:77], v[26:27] neg_lo:[0,1] neg_hi:[0,1]
	v_pk_add_f32 v[76:77], v[70:71], v[74:75]
	v_pk_add_f32 v[70:71], v[70:71], v[74:75] neg_lo:[0,1] neg_hi:[0,1]
	v_pk_add_f32 v[100:101], v[18:19], v[28:29]
	v_pk_add_f32 v[18:19], v[18:19], v[28:29] neg_lo:[0,1] neg_hi:[0,1]
	v_pk_add_f32 v[28:29], v[102:103], v[72:73]
	v_pk_add_f32 v[72:73], v[102:103], v[72:73] neg_lo:[0,1] neg_hi:[0,1]
	s_nop 0
	v_pk_add_f32 v[102:103], v[72:73], v[70:71] op_sel:[0,1] op_sel_hi:[1,0] neg_hi:[0,1]
	v_pk_add_f32 v[72:73], v[72:73], v[70:71] op_sel:[0,1] op_sel_hi:[1,0] neg_lo:[0,1]
	v_pk_add_f32 v[74:75], v[22:23], v[30:31]
	v_pk_add_f32 v[22:23], v[22:23], v[30:31] neg_lo:[0,1] neg_hi:[0,1]
	v_pk_add_f32 v[30:31], v[24:25], v[32:33]
	v_pk_add_f32 v[24:25], v[24:25], v[32:33] neg_lo:[0,1] neg_hi:[0,1]
	v_pk_add_f32 v[70:71], v[28:29], v[76:77]
	v_pk_add_f32 v[28:29], v[28:29], v[76:77] neg_lo:[0,1] neg_hi:[0,1]
	v_pk_add_f32 v[76:77], v[22:23], v[24:25] op_sel:[0,1] op_sel_hi:[1,0] neg_hi:[0,1]
	v_pk_add_f32 v[22:23], v[22:23], v[24:25] op_sel:[0,1] op_sel_hi:[1,0] neg_lo:[0,1]
	v_pk_add_f32 v[32:33], v[10:11], v[14:15]
	v_pk_add_f32 v[10:11], v[10:11], v[14:15] neg_lo:[0,1] neg_hi:[0,1]
	v_pk_add_f32 v[14:15], v[12:13], v[16:17]
	v_pk_add_f32 v[12:13], v[12:13], v[16:17] neg_lo:[0,1] neg_hi:[0,1]
	v_pk_add_f32 v[24:25], v[74:75], v[30:31]
	v_pk_add_f32 v[30:31], v[74:75], v[30:31] neg_lo:[0,1] neg_hi:[0,1]
	v_pk_add_f32 v[74:75], v[10:11], v[12:13] op_sel:[0,1] op_sel_hi:[1,0] neg_hi:[0,1]
	v_pk_add_f32 v[10:11], v[10:11], v[12:13] op_sel:[0,1] op_sel_hi:[1,0] neg_lo:[0,1]
	v_xor_b32_e32 v16, 0x80000000, v79
	v_mov_b32_e32 v17, v78
	v_pk_mul_f32 v[16:17], v[16:17], v[20:21] op_sel:[0,1]
	v_pk_add_f32 v[12:13], v[32:33], v[14:15]
	v_pk_fma_f32 v[16:17], v[78:79], v[20:21], v[16:17] op_sel_hi:[1,0,1]
	v_pk_mul_f32 v[20:21], v[80:81], v[70:71] op_sel:[1,1] op_sel_hi:[0,1] neg_lo:[1,0]
	v_pk_add_f32 v[14:15], v[32:33], v[14:15] neg_lo:[0,1] neg_hi:[0,1]
	v_pk_fma_f32 v[20:21], v[80:81], v[70:71], v[20:21] op_sel_hi:[1,0,1]
	ds_write2_b64 v104, v[16:17], v[20:21] offset1:17
	v_pk_mul_f32 v[16:17], v[82:83], v[24:25] op_sel:[1,1] op_sel_hi:[0,1] neg_lo:[1,0]
	v_pk_mul_f32 v[20:21], v[84:85], v[12:13] op_sel:[1,1] op_sel_hi:[0,1] neg_lo:[1,0]
	v_pk_fma_f32 v[16:17], v[82:83], v[24:25], v[16:17] op_sel_hi:[1,0,1]
	v_pk_fma_f32 v[12:13], v[84:85], v[12:13], v[20:21] op_sel_hi:[1,0,1]
	ds_write2_b64 v104, v[16:17], v[12:13] offset0:34 offset1:51
	v_pk_mul_f32 v[12:13], v[86:87], v[100:101] op_sel:[1,1] op_sel_hi:[0,1] neg_lo:[1,0]
	v_pk_mul_f32 v[16:17], v[88:89], v[102:103] op_sel:[1,1] op_sel_hi:[0,1] neg_lo:[1,0]
	v_pk_fma_f32 v[12:13], v[86:87], v[100:101], v[12:13] op_sel_hi:[1,0,1]
	v_pk_fma_f32 v[16:17], v[88:89], v[102:103], v[16:17] op_sel_hi:[1,0,1]
	ds_write2_b64 v104, v[12:13], v[16:17] offset0:68 offset1:85
	v_pk_mul_f32 v[12:13], v[90:91], v[76:77] op_sel:[1,1] op_sel_hi:[0,1] neg_lo:[1,0]
	v_pk_mul_f32 v[16:17], v[92:93], v[74:75] op_sel:[1,1] op_sel_hi:[0,1] neg_lo:[1,0]
	v_pk_fma_f32 v[12:13], v[90:91], v[76:77], v[12:13] op_sel_hi:[1,0,1]
	v_pk_fma_f32 v[16:17], v[92:93], v[74:75], v[16:17] op_sel_hi:[1,0,1]
	ds_write2_b64 v104, v[12:13], v[16:17] offset0:102 offset1:119
	v_pk_mul_f32 v[12:13], v[94:95], v[26:27] op_sel:[1,1] op_sel_hi:[0,1] neg_lo:[1,0]
	v_pk_mul_f32 v[16:17], v[96:97], v[28:29] op_sel:[1,1] op_sel_hi:[0,1] neg_lo:[1,0]
	v_pk_fma_f32 v[12:13], v[94:95], v[26:27], v[12:13] op_sel_hi:[1,0,1]
	v_pk_fma_f32 v[16:17], v[96:97], v[28:29], v[16:17] op_sel_hi:[1,0,1]
	ds_write2_b64 v104, v[12:13], v[16:17] offset0:136 offset1:153
	v_pk_mul_f32 v[12:13], v[98:99], v[30:31] op_sel:[1,1] op_sel_hi:[0,1] neg_lo:[1,0]
	v_pk_mul_f32 v[16:17], v[8:9], v[14:15] op_sel:[1,1] op_sel_hi:[0,1] neg_lo:[1,0]
	v_pk_fma_f32 v[12:13], v[98:99], v[30:31], v[12:13] op_sel_hi:[1,0,1]
	v_pk_fma_f32 v[8:9], v[8:9], v[14:15], v[16:17] op_sel_hi:[1,0,1]
	ds_write2_b64 v104, v[12:13], v[8:9] offset0:170 offset1:187
	v_pk_mul_f32 v[8:9], v[6:7], v[18:19] op_sel:[1,1] op_sel_hi:[0,1] neg_lo:[1,0]
	v_pk_fma_f32 v[6:7], v[6:7], v[18:19], v[8:9] op_sel_hi:[1,0,1]
	v_pk_mul_f32 v[8:9], v[4:5], v[72:73] op_sel:[1,1] op_sel_hi:[0,1] neg_lo:[1,0]
	v_pk_fma_f32 v[4:5], v[4:5], v[72:73], v[8:9] op_sel_hi:[1,0,1]
	ds_write2_b64 v104, v[6:7], v[4:5] offset0:204 offset1:221
	v_pk_mul_f32 v[4:5], v[2:3], v[22:23] op_sel:[1,1] op_sel_hi:[0,1] neg_lo:[1,0]
	v_pk_fma_f32 v[2:3], v[2:3], v[22:23], v[4:5] op_sel_hi:[1,0,1]
	v_pk_mul_f32 v[4:5], v[0:1], v[10:11] op_sel:[1,1] op_sel_hi:[0,1] neg_lo:[1,0]
	v_pk_fma_f32 v[0:1], v[0:1], v[10:11], v[4:5] op_sel_hi:[1,0,1]
	ds_write2_b64 v104, v[2:3], v[0:1] offset0:238 offset1:255
	s_waitcnt lgkmcnt(0)
	s_barrier
	s_nop 0
	v_and_b32_e32 v0, 0xff, v206
	v_mad_u32_u24 v28, v0, s19, v207
	ds_read2_b64 v[0:3], v28 offset1:1
	ds_read2_b64 v[4:7], v28 offset0:2 offset1:3
	ds_read2_b64 v[8:11], v28 offset0:8 offset1:9
	ds_read2_b64 v[12:15], v28 offset0:4 offset1:5
	ds_read2_b64 v[16:19], v28 offset0:6 offset1:7
	ds_read2_b64 v[20:23], v28 offset0:12 offset1:13
	ds_read2_b64 v[24:27], v28 offset0:10 offset1:11
	ds_read2_b64 v[28:31], v28 offset0:14 offset1:15
	s_waitcnt lgkmcnt(5)
	v_pk_add_f32 v[32:33], v[0:1], v[8:9]
	v_pk_add_f32 v[0:1], v[0:1], v[8:9] neg_lo:[0,1] neg_hi:[0,1]
	s_waitcnt lgkmcnt(2)
	v_pk_add_f32 v[8:9], v[12:13], v[20:21]
	v_pk_add_f32 v[12:13], v[12:13], v[20:21] neg_lo:[0,1] neg_hi:[0,1]
	s_waitcnt lgkmcnt(0)
	v_pk_add_f32 v[70:71], v[0:1], v[12:13] op_sel:[0,1] op_sel_hi:[1,0] neg_hi:[0,1]
	v_pk_add_f32 v[0:1], v[0:1], v[12:13] op_sel:[0,1] op_sel_hi:[1,0] neg_lo:[0,1]
	v_pk_add_f32 v[20:21], v[2:3], v[10:11]
	v_pk_add_f32 v[2:3], v[2:3], v[10:11] neg_lo:[0,1] neg_hi:[0,1]
	v_pk_add_f32 v[10:11], v[14:15], v[22:23]
	v_pk_add_f32 v[14:15], v[14:15], v[22:23] neg_lo:[0,1] neg_hi:[0,1]
	v_pk_add_f32 v[12:13], v[32:33], v[8:9]
	v_pk_add_f32 v[8:9], v[32:33], v[8:9] neg_lo:[0,1] neg_hi:[0,1]
	v_pk_add_f32 v[32:33], v[2:3], v[14:15] op_sel:[0,1] op_sel_hi:[1,0] neg_hi:[0,1]
	v_pk_add_f32 v[2:3], v[2:3], v[14:15] op_sel:[0,1] op_sel_hi:[1,0] neg_lo:[0,1]
	v_pk_add_f32 v[22:23], v[16:17], v[28:29]
	v_pk_add_f32 v[16:17], v[16:17], v[28:29] neg_lo:[0,1] neg_hi:[0,1]
	v_pk_add_f32 v[14:15], v[20:21], v[10:11]
	v_pk_add_f32 v[10:11], v[20:21], v[10:11] neg_lo:[0,1] neg_hi:[0,1]
	v_pk_add_f32 v[20:21], v[4:5], v[24:25]
	v_pk_add_f32 v[4:5], v[4:5], v[24:25] neg_lo:[0,1] neg_hi:[0,1]
	s_nop 0
	v_pk_add_f32 v[28:29], v[4:5], v[16:17] op_sel:[0,1] op_sel_hi:[1,0] neg_hi:[0,1]
	v_pk_add_f32 v[4:5], v[4:5], v[16:17] op_sel:[0,1] op_sel_hi:[1,0] neg_lo:[0,1]
	v_pk_add_f32 v[24:25], v[18:19], v[30:31]
	v_pk_add_f32 v[18:19], v[18:19], v[30:31] neg_lo:[0,1] neg_hi:[0,1]
	v_pk_add_f32 v[16:17], v[20:21], v[22:23]
	v_pk_add_f32 v[20:21], v[20:21], v[22:23] neg_lo:[0,1] neg_hi:[0,1]
	v_pk_add_f32 v[22:23], v[6:7], v[26:27]
	v_pk_add_f32 v[6:7], v[6:7], v[26:27] neg_lo:[0,1] neg_hi:[0,1]
	s_nop 0
	v_pk_add_f32 v[30:31], v[6:7], v[18:19] op_sel:[0,1] op_sel_hi:[1,0] neg_hi:[0,1]
	v_pk_add_f32 v[6:7], v[6:7], v[18:19] op_sel:[0,1] op_sel_hi:[1,0] neg_lo:[0,1]
	v_pk_mul_f32 v[26:27], v[10:11], s[12:13] op_sel:[1,0] op_sel_hi:[0,0] neg_lo:[1,0]
	v_pk_add_f32 v[18:19], v[22:23], v[24:25]
	v_pk_fma_f32 v[10:11], v[10:11], s[12:13], v[26:27] op_sel_hi:[1,0,1] neg_lo:[0,0,1] neg_hi:[0,0,1]
	v_pk_mul_f32 v[26:27], v[2:3], s[36:37] op_sel:[1,0] op_sel_hi:[0,0] neg_lo:[1,0]
	v_pk_add_f32 v[22:23], v[22:23], v[24:25] neg_lo:[0,1] neg_hi:[0,1]
	v_pk_fma_f32 v[2:3], v[2:3], s[22:23], v[26:27] op_sel_hi:[1,0,1] neg_lo:[0,0,1] neg_hi:[0,0,1]
	v_pk_mul_f32 v[26:27], v[28:29], s[12:13] op_sel:[1,0] op_sel_hi:[0,0] neg_lo:[1,0]
	v_pk_fma_f32 v[26:27], v[28:29], s[12:13], v[26:27] op_sel_hi:[1,0,1] neg_lo:[0,0,1] neg_hi:[0,0,1]
	v_pk_fma_f32 v[20:21], v[20:21], 0, v[20:21] op_sel:[0,0,1] op_sel_hi:[1,0,0] neg_hi:[0,0,1]
	v_pk_mul_f32 v[28:29], v[4:5], s[12:13] op_sel:[1,0] op_sel_hi:[0,0] neg_lo:[1,0]
	v_pk_fma_f32 v[4:5], v[4:5], s[18:19], v[28:29] op_sel_hi:[1,0,1] neg_lo:[0,0,1] neg_hi:[0,0,1]
	v_pk_mul_f32 v[28:29], v[30:31], s[36:37] op_sel:[1,0] op_sel_hi:[0,0] neg_lo:[1,0]
	v_pk_mul_f32 v[24:25], v[32:33], s[22:23] op_sel:[1,0] op_sel_hi:[0,0] neg_lo:[1,0]
	v_pk_fma_f32 v[28:29], v[30:31], s[22:23], v[28:29] op_sel_hi:[1,0,1] neg_lo:[0,0,1] neg_hi:[0,0,1]
	v_pk_mul_f32 v[30:31], v[22:23], s[12:13] op_sel:[1,0] op_sel_hi:[0,0] neg_lo:[1,0]
	v_pk_fma_f32 v[24:25], v[32:33], s[36:37], v[24:25] op_sel_hi:[1,0,1] neg_lo:[0,0,1] neg_hi:[0,0,1]
	v_pk_fma_f32 v[22:23], v[22:23], s[18:19], v[30:31] op_sel_hi:[1,0,1] neg_lo:[0,0,1] neg_hi:[0,0,1]
	v_xor_b32_e32 v30, 0x80000000, v7
	v_mov_b32_e32 v31, v6
	v_pk_mul_f32 v[6:7], v[6:7], s[36:37] op_sel_hi:[1,0]
	s_barrier
	v_pk_fma_f32 v[6:7], v[30:31], s[22:23], v[6:7] op_sel_hi:[1,0,1] neg_lo:[0,0,1] neg_hi:[0,0,1]
	v_pk_add_f32 v[30:31], v[12:13], v[16:17]
	v_pk_add_f32 v[12:13], v[12:13], v[16:17] neg_lo:[0,1] neg_hi:[0,1]
	v_pk_add_f32 v[16:17], v[14:15], v[18:19]
	v_pk_add_f32 v[14:15], v[14:15], v[18:19] neg_lo:[0,1] neg_hi:[0,1]
	s_nop 0
	v_xor_b32_e32 v19, 0x80000000, v14
	v_mov_b32_e32 v18, v15
	v_pk_add_f32 v[14:15], v[30:31], v[16:17]
	v_pk_add_f32 v[16:17], v[30:31], v[16:17] neg_lo:[0,1] neg_hi:[0,1]
	v_pk_add_f32 v[30:31], v[24:25], v[28:29]
	v_pk_add_f32 v[24:25], v[24:25], v[28:29] neg_lo:[0,1] neg_hi:[0,1]
	v_pk_add_f32 v[32:33], v[12:13], v[18:19]
	v_pk_add_f32 v[12:13], v[12:13], v[18:19] neg_lo:[0,1] neg_hi:[0,1]
	v_pk_add_f32 v[18:19], v[70:71], v[26:27]
	v_pk_add_f32 v[26:27], v[70:71], v[26:27] neg_lo:[0,1] neg_hi:[0,1]
	s_nop 0
	v_pk_add_f32 v[70:71], v[26:27], v[24:25] op_sel:[0,1] op_sel_hi:[1,0] neg_hi:[0,1]
	v_pk_add_f32 v[26:27], v[26:27], v[24:25] op_sel:[0,1] op_sel_hi:[1,0] neg_lo:[0,1]
	v_pk_add_f32 v[28:29], v[8:9], v[20:21]
	v_pk_add_f32 v[8:9], v[8:9], v[20:21] neg_lo:[0,1] neg_hi:[0,1]
	v_pk_add_f32 v[20:21], v[10:11], v[22:23]
	v_pk_add_f32 v[10:11], v[10:11], v[22:23] neg_lo:[0,1] neg_hi:[0,1]
	v_pk_add_f32 v[24:25], v[18:19], v[30:31]
	v_pk_add_f32 v[18:19], v[18:19], v[30:31] neg_lo:[0,1] neg_hi:[0,1]
	v_pk_add_f32 v[30:31], v[8:9], v[10:11] op_sel:[0,1] op_sel_hi:[1,0] neg_hi:[0,1]
	v_pk_add_f32 v[8:9], v[8:9], v[10:11] op_sel:[0,1] op_sel_hi:[1,0] neg_lo:[0,1]
	v_pk_add_f32 v[22:23], v[0:1], v[4:5]
	v_pk_add_f32 v[0:1], v[0:1], v[4:5] neg_lo:[0,1] neg_hi:[0,1]
	v_pk_add_f32 v[4:5], v[2:3], v[6:7]
	v_pk_add_f32 v[2:3], v[2:3], v[6:7] neg_lo:[0,1] neg_hi:[0,1]
	v_pk_add_f32 v[10:11], v[28:29], v[20:21]
	v_pk_add_f32 v[20:21], v[28:29], v[20:21] neg_lo:[0,1] neg_hi:[0,1]
	v_pk_add_f32 v[28:29], v[0:1], v[2:3] op_sel:[0,1] op_sel_hi:[1,0] neg_hi:[0,1]
	v_pk_add_f32 v[0:1], v[0:1], v[2:3] op_sel:[0,1] op_sel_hi:[1,0] neg_lo:[0,1]
	v_pk_add_f32 v[2:3], v[22:23], v[4:5]
	v_and_b32_e32 v7, 15, v206
	v_lshrrev_b32_e32 v6, 1, v206
	v_and_b32_e32 v6, 0x78, v6
	v_mul_u32_u24_e32 v7, 0x88, v7
	v_pk_add_f32 v[4:5], v[22:23], v[4:5] neg_lo:[0,1] neg_hi:[0,1]
	v_add3_u32 v6, v207, v6, v7
	ds_write_b64 v6, v[14:15]
	ds_write_b64 v6, v[32:33] offset:8704
	ds_write_b64 v6, v[16:17] offset:17408
	ds_write_b64 v6, v[12:13] offset:26112
	ds_write_b64 v6, v[24:25] offset:2176
	ds_write_b64 v6, v[70:71] offset:10880
	ds_write_b64 v6, v[18:19] offset:19584
	ds_write_b64 v6, v[26:27] offset:28288
	ds_write_b64 v6, v[10:11] offset:4352
	ds_write_b64 v6, v[30:31] offset:13056
	ds_write_b64 v6, v[20:21] offset:21760
	ds_write_b64 v6, v[8:9] offset:30464
	ds_write_b64 v6, v[2:3] offset:6528
	ds_write_b64 v6, v[28:29] offset:15232
	ds_write_b64 v6, v[4:5] offset:23936
	ds_write_b64 v6, v[0:1] offset:32640
	s_waitcnt lgkmcnt(0)
	s_barrier
	v_and_b32_e32 v12, 31, v69
	v_and_b32_e32 v4, 0xff, v206
	v_sub_u32_e32 v6, 0x100, v4
	v_lshrrev_b32_e32 v5, 1, v206
	v_lshlrev_b32_e32 v7, 3, v4
	v_and_b32_e32 v5, 0x78, v5
	v_lshrrev_b32_e32 v6, 1, v6
	v_add3_u32 v5, v207, v7, v5
	v_sub_u32_e32 v7, v207, v7
	v_and_b32_e32 v6, 0xf8, v6
	v_add_u32_e32 v14, v7, v6
	ds_read_b64 v[10:11], v5
	ds_read_b64 v[6:7], v14 offset:34688
	v_and_b32_e32 v13, 0x1c0, v52
	v_or_b32_sdwa v176, v13, v12 dst_sel:WORD_1 dst_unused:UNUSED_PAD src0_sel:DWORD src1_sel:DWORD
	v_and_b32_e32 v2, 0xfffff000, v49
	v_lshl_add_u64 v[0:1], s[48:49], 0, v[176:177]
	v_ashrrev_i32_e32 v3, 31, v2
	v_cmp_eq_u32_e64 s[38:39], 0, v4
	v_lshl_add_u64 v[0:1], v[2:3], 1, v[0:1]
	v_cmp_eq_u32_e64 s[0:1], 0, v12
	v_cmp_ne_u32_e32 vcc, 0, v12
	s_waitcnt lgkmcnt(0)
	v_cndmask_b32_e64 v9, v7, v11, s[38:39]
	v_cndmask_b32_e64 v8, v6, v10, s[38:39]
	v_lshlrev_b32_e32 v6, 1, v4
	s_and_saveexec_b64 s[20:21], vcc
	s_xor_b64 s[28:29], exec, s[20:21]
	s_cbranch_execz .LBB0_216
	v_bfe_u32 v7, v10, 16, 1
	v_add3_u32 v9, v10, v7, s13
	v_mov_b32_e32 v7, v177
	v_lshl_add_u64 v[10:11], v[0:1], 0, v[6:7]
	global_store_short_d16_hi v[10:11], v9, off
